# softmax VALU trims: cross-half max via max(lo,hi) dup, drop canonicalising max, fold rs=0+p0; on top of copy eliminations
# speedup vs baseline: 1.0179x; 1.0002x over previous
; #define LAS __attribute__((address_space(3)))
; DI float ex2(float x) { return __builtin_amdgcn_exp2f(x); }
; template <int MM> DI void smax_step_nb(const f32x16& s, unsigned vm, float& m, float& l, f32x16 (&o)[2], bf16x8 (&pf)[2], int lane) {
;     float mx = -1e30f;
; #pragma unroll
;     for (int i = 0; i < 16; ++i) mx = fmaxf(mx, s[i]);
;     if (MM == 1) mx = vm ? mx : -1e30f;
;     mx = fmaxf(mx, shx32(mx, lane));
;     const float mn = (mx > m + 8.0f) ? mx : m;
;     float mref = fmaxf(mn, -1e29f);
;     if (MM == 1) mref = vm ? mref : 3e38f;
;     const float alpha = ex2(m - mn);
;     float p[16], rs = 0.f;
; #pragma unroll
;     for (int i = 0; i < 16; ++i) { p[i] = ex2(s[i] - mref); rs += p[i]; }
;     rs += shx32(rs, lane);
;     l = l * alpha + rs;
;     if (__builtin_amdgcn_ballot_w64(mn != m) != 0ull) {
; #pragma unroll
;         for (int i = 0; i < 16; ++i) { o[0][i] *= alpha; o[1][i] *= alpha; }
;     }
;     m = mn;
;     pack_p(p, pf);
; }
; template <int MODE, bool PRE = false> ...
;     ...
;         if (MODE != MODE_DIFF) {
;             const int kt0 = kt_lo + 2 * sti;
;             bool both = (kt0 + 1 <= kt_hi) && (64 * kt0 + 127 <= q0w);
;             if (MODE == MODE_NWIN) both = both && (64 * kt0 > q0w + 31 - 512);
;             if (both) {
;                 bool ls0 = true, ls1 = true;
;                 if (MODE == MODE_MOBA) { ls0 = ((sel >> (kt0 >> 2)) & 1ull) != 0ull; ls1 = ((sel >> ((kt0 + 1) >> 2)) & 1ull) != 0ull; }
;                 if (MODE == MODE_NSEL) { ls0 = ((sel >> kt0) & 1ull) != 0ull; ls1 = ((sel >> (kt0 + 1)) & 1ull) != 0ull; }
;                 const unsigned long long b0 = __builtin_amdgcn_ballot_w64(ls0), b1 = __builtin_amdgcn_ballot_w64(ls1);
;                 if (b0 != 0ull && b1 != 0ull) {
;                     LAS char* K0 = lds + (sti & 1) * 4 * TILE_B;
;                     if ((b0 & b1) == ~0ull) tile128_pipe<0>(K0, K0 + TILE_B, K0 + 2 * TILE_B, K0 + 3 * TILE_B, qf, 1u, 1u, m1, l1, o1, r, h, lane);
;                     else tile128_pipe<1>(K0, K0 + TILE_B, K0 + 2 * TILE_B, K0 + 3 * TILE_B, qf, ls0 ? 1u : 0u, ls1 ? 1u : 0u, m1, l1, o1, r, h, lane);
;                     goto step_done;
.LBB0_589:
	s_lshl_b32 s64, s48, 1
	s_cmp_lt_u32 s64, s58
	s_cselect_b64 s[0:1], -1, 0
	s_lshl_b32 s10, s48, 7
	s_or_b32 s10, s10, 0x7f
	s_cmp_le_i32 s10, s59
	s_cselect_b64 s[10:11], -1, 0
	s_and_b64 s[0:1], s[0:1], s[10:11]
	s_andn2_b64 vcc, exec, s[0:1]
	s_mov_b32 s10, 0
	s_cbranch_vccnz .LBB0_612
	s_or_b32 s0, s64, 1
	v_lshrrev_b64 v[32:33], s64, v[164:165]
	v_and_b32_e32 v34, 1, v32
	v_lshrrev_b64 v[32:33], s0, v[164:165]
	v_and_b32_e32 v32, 1, v32
	v_cmp_ne_u32_e64 s[40:41], 0, v34
	v_cmp_ne_u32_e64 s[42:43], 0, v32
	s_cmp_eq_u64 s[40:41], 0
	s_cselect_b64 s[34:35], -1, 0
	s_cmp_eq_u64 s[42:43], 0
	s_cselect_b64 s[56:57], -1, 0
	s_or_b64 s[34:35], s[34:35], s[56:57]
	v_cmp_eq_u32_e64 s[38:39], 1, v34
	v_cmp_eq_u32_e64 s[0:1], 1, v32
	s_and_b64 vcc, exec, s[34:35]
	s_cbranch_vccnz .LBB0_612
	s_lshl_b32 s10, s48, 2
	s_and_b32 s10, s10, 4
	s_mulk_i32 s10, 0x2400
	s_add_i32 s10, s10, 0
	v_add_u32_e32 v32, s10, v190
	v_add_u32_e32 v215, v32, v168
	s_waitcnt lgkmcnt(7)
	ds_read_b128 v[140:143], v215
	s_waitcnt lgkmcnt(7)
	ds_read_b128 v[136:139], v215 offset:32
	s_waitcnt lgkmcnt(7)
	ds_read_b128 v[132:135], v215 offset:64
	s_waitcnt lgkmcnt(7)
	ds_read_b128 v[128:131], v215 offset:96
	s_and_b64 s[34:35], s[42:43], s[40:41]
	s_cmp_lg_u64 s[34:35], -1
	s_setprio 1
	s_setprio 0
	s_waitcnt lgkmcnt(7)
	ds_read_b128 v[144:147], v215 offset:4608
	s_waitcnt lgkmcnt(7)
	ds_read_b128 v[148:151], v215 offset:4640
	s_waitcnt lgkmcnt(7)
	ds_read_b128 v[152:155], v215 offset:4672
	s_waitcnt lgkmcnt(7)
	ds_read_b128 v[156:159], v215 offset:4704
	s_setprio 1
	s_setprio 0
	v_add_f32_e32 v216, 0x41000000, v214
	s_cbranch_scc0 .LBB0_601
	s_waitcnt lgkmcnt(7)
	v_mfma_f32_32x32x16_bf16 v[32:47], v[140:143], v[96:99], 0
	s_waitcnt lgkmcnt(6)
	v_mfma_f32_32x32x16_bf16 v[32:47], v[136:139], v[100:103], v[32:47]
	s_waitcnt lgkmcnt(5)
	v_mfma_f32_32x32x16_bf16 v[32:47], v[132:135], v[104:107], v[32:47]
	s_waitcnt lgkmcnt(4)
	v_mfma_f32_32x32x16_bf16 v[32:47], v[128:131], v[108:111], v[32:47]
	s_waitcnt lgkmcnt(3)
	v_mfma_f32_32x32x16_bf16 v[64:79], v[144:147], v[96:99], 0
	s_nop 9
	v_max3_f32 v48, v32, s15, v33
	v_max3_f32 v48, v48, v34, v35
	v_max3_f32 v48, v48, v36, v37
	v_max3_f32 v48, v48, v38, v39
	v_max3_f32 v48, v48, v40, v41
	v_max3_f32 v48, v48, v42, v43
	v_max3_f32 v48, v48, v44, v45
	v_max3_f32 v48, v48, v46, v47
	v_cndmask_b32_e64 v48, v208, v48, s[38:39]
	v_mov_b32_e32 v49, v48
	v_mov_b32_e32 v50, v48
	s_nop 1
	v_permlane32_swap_b32_e32 v49, v50
	v_max_f32_e32 v48, v49, v50
	v_cmp_gt_f32_e32 vcc, v48, v216
	s_waitcnt lgkmcnt(2)
	v_mfma_f32_32x32x16_bf16 v[64:79], v[148:151], v[100:103], v[64:79]
	v_cndmask_b32_e32 v224, v214, v48, vcc
	v_max_f32_e32 v48, 0xefa18f08, v224
	v_cndmask_b32_e64 v48, v209, v48, s[38:39]
	v_sub_f32_e32 v32, v32, v48
	v_sub_f32_e32 v33, v33, v48
	v_exp_f32_e32 v80, v32
	v_sub_f32_e32 v34, v34, v48
	v_exp_f32_e32 v81, v33
	v_sub_f32_e32 v35, v35, v48
	v_exp_f32_e32 v82, v34
	v_sub_f32_e32 v36, v36, v48
	v_exp_f32_e32 v83, v35
	v_sub_f32_e32 v37, v37, v48
	v_exp_f32_e32 v84, v36
	v_sub_f32_e32 v38, v38, v48
	v_exp_f32_e32 v85, v37
	v_add_f32_e32 v32, v81, v80
	v_sub_f32_e32 v39, v39, v48
	v_exp_f32_e32 v86, v38
	s_waitcnt lgkmcnt(1)
	v_mfma_f32_32x32x16_bf16 v[64:79], v[152:155], v[104:107], v[64:79]
	v_add_f32_e32 v32, v82, v32
	v_sub_f32_e32 v40, v40, v48
	v_exp_f32_e32 v87, v39
	v_add_f32_e32 v32, v83, v32
	v_sub_f32_e32 v41, v41, v48
	v_exp_f32_e32 v88, v40
	v_add_f32_e32 v32, v84, v32
	v_sub_f32_e32 v42, v42, v48
	v_exp_f32_e32 v89, v41
	v_add_f32_e32 v32, v85, v32
	v_sub_f32_e32 v43, v43, v48
	v_exp_f32_e32 v90, v42
	v_add_f32_e32 v32, v86, v32
	v_sub_f32_e32 v44, v44, v48
	v_exp_f32_e32 v91, v43
	v_add_f32_e32 v32, v87, v32
	v_add_f32_e32 v32, v88, v32
	v_exp_f32_e32 v92, v44
	v_sub_f32_e32 v33, v45, v48
	v_add_f32_e32 v32, v89, v32
	v_exp_f32_e32 v93, v33
	v_sub_f32_e32 v33, v46, v48
	s_waitcnt lgkmcnt(0)
	v_mfma_f32_32x32x16_bf16 v[64:79], v[156:159], v[108:111], v[64:79]
	v_add_f32_e32 v32, v90, v32
	v_exp_f32_e32 v94, v33
	v_sub_f32_e32 v33, v47, v48
	v_add_f32_e32 v32, v91, v32
	v_exp_f32_e32 v95, v33
	v_add_f32_e32 v32, v92, v32
	v_sub_f32_e32 v49, v214, v224
	v_add_f32_e32 v32, v93, v32
	v_add_f32_e32 v32, v94, v32
	v_exp_f32_e32 v166, v49
	v_add_f32_e32 v217, v95, v32
	v_mov_b32_e32 v218, v217
	v_mov_b32_e32 v219, v217
	s_nop 0
	s_nop 0
	v_permlane32_swap_b32_e32 v218, v219
	v_cmp_neq_f32_e32 vcc, v224, v214
	s_cbranch_vccz .LBB0_594
	v_pk_mul_f32 v[30:31], v[30:31], v[166:167] op_sel_hi:[1,0]
	v_pk_mul_f32 v[28:29], v[28:29], v[166:167] op_sel_hi:[1,0]
	v_pk_mul_f32 v[26:27], v[26:27], v[166:167] op_sel_hi:[1,0]
	v_pk_mul_f32 v[24:25], v[24:25], v[166:167] op_sel_hi:[1,0]
	v_pk_mul_f32 v[22:23], v[22:23], v[166:167] op_sel_hi:[1,0]
	v_pk_mul_f32 v[20:21], v[20:21], v[166:167] op_sel_hi:[1,0]
	v_pk_mul_f32 v[18:19], v[18:19], v[166:167] op_sel_hi:[1,0]
	v_pk_mul_f32 v[16:17], v[16:17], v[166:167] op_sel_hi:[1,0]
	v_pk_mul_f32 v[14:15], v[14:15], v[166:167] op_sel_hi:[1,0]
	v_pk_mul_f32 v[12:13], v[12:13], v[166:167] op_sel_hi:[1,0]
	v_pk_mul_f32 v[10:11], v[10:11], v[166:167] op_sel_hi:[1,0]
	v_pk_mul_f32 v[8:9], v[8:9], v[166:167] op_sel_hi:[1,0]
	v_pk_mul_f32 v[6:7], v[6:7], v[166:167] op_sel_hi:[1,0]
	v_pk_mul_f32 v[4:5], v[4:5], v[166:167] op_sel_hi:[1,0]
	v_pk_mul_f32 v[2:3], v[2:3], v[166:167] op_sel_hi:[1,0]
	v_pk_mul_f32 v[0:1], v[0:1], v[166:167] op_sel_hi:[1,0]
; #define LAS __attribute__((address_space(3)))
; DI float ex2(float x) { return __builtin_amdgcn_exp2f(x); }
; template <int MM> DI void smax_step_nb(const f32x16& s, unsigned vm, float& m, float& l, f32x16 (&o)[2], bf16x8 (&pf)[2], int lane) {
;     float mx = -1e30f;
; #pragma unroll
;     for (int i = 0; i < 16; ++i) mx = fmaxf(mx, s[i]);
;     if (MM == 1) mx = vm ? mx : -1e30f;
;     mx = fmaxf(mx, shx32(mx, lane));
;     const float mn = (mx > m + 8.0f) ? mx : m;
;     float mref = fmaxf(mn, -1e29f);
;     if (MM == 1) mref = vm ? mref : 3e38f;
;     const float alpha = ex2(m - mn);
;     float p[16], rs = 0.f;
; #pragma unroll
;     for (int i = 0; i < 16; ++i) { p[i] = ex2(s[i] - mref); rs += p[i]; }
;     rs += shx32(rs, lane);
;     l = l * alpha + rs;
;     if (__builtin_amdgcn_ballot_w64(mn != m) != 0ull) {
; #pragma unroll
;         for (int i = 0; i < 16; ++i) { o[0][i] *= alpha; o[1][i] *= alpha; }
;     }
;     m = mn;
;     pack_p(p, pf);
; }
; template <int MM> DI void tile128_pipe(LAS const char* K0, LAS const char* V0, LAS const char* K1, LAS const char* V1, const bf16x8 (&qf)[4], unsigned vm0, unsigned vm1,
;                                        float& m, float& l, f32x16 (&o)[2], int r, int h, int lane) {
;     f32x16 sa = qk_rows<0, 4>(K0, 0, qf, r, h), sb = qk_rows<0, 4>(K0, 32, qf, r, h);
;     bf16x8 pfa[2], pfb[2];
;     smax_step_nb<MM>(sa, vm0, m, l, o, pfa, lane);
;     sa = qk_rows<0, 4>(K1, 0, qf, r, h);
;     pv_rows(o, V0, 0, pfa, lane);
;     smax_step_nb<MM>(sb, vm0, m, l, o, pfb, lane);
;     sb = qk_rows<0, 4>(K1, 32, qf, r, h);
;     pv_rows(o, V0, 32, pfb, lane);
;     smax_step_nb<MM>(sa, vm1, m, l, o, pfa, lane);
;     pv_rows(o, V1, 0, pfa, lane);
;     smax_step_nb<MM>(sb, vm1, m, l, o, pfb, lane);
;     pv_rows(o, V1, 32, pfb, lane);
; }
.LBB0_594:
	v_cvt_pk_bf16_f32 v226, v80, v81
	v_cvt_pk_bf16_f32 v227, v82, v83
	ds_read_b128 v[80:83], v215 offset:18432
	ds_read_b128 v[220:223], v215 offset:18464
	ds_read_b128 v[234:237], v215 offset:18496
	ds_read_b128 v[238:241], v215 offset:18528
	v_cvt_pk_bf16_f32 v228, v84, v85
	v_cvt_pk_bf16_f32 v229, v86, v87
	v_cvt_pk_bf16_f32 v230, v88, v89
	v_cvt_pk_bf16_f32 v231, v90, v91
	v_cvt_pk_bf16_f32 v232, v92, v93
	v_cvt_pk_bf16_f32 v233, v94, v95
	s_setprio 1
	s_waitcnt lgkmcnt(3)
	v_mfma_f32_32x32x16_bf16 v[80:95], v[80:83], v[96:99], 0
	s_waitcnt lgkmcnt(2)
	v_mfma_f32_32x32x16_bf16 v[80:95], v[220:223], v[100:103], v[80:95]
	s_waitcnt lgkmcnt(1)
	v_mfma_f32_32x32x16_bf16 v[80:95], v[234:237], v[104:107], v[80:95]
	s_waitcnt lgkmcnt(0)
	v_mfma_f32_32x32x16_bf16 v[80:95], v[238:241], v[108:111], v[80:95]
	s_setprio 0
	v_add3_u32 v172, s10, v191, v171
	v_add_u32_e32 v220, v172, v186
	ds_read_b64_tr_b16 v[234:235], v220 offset:9216
	ds_read_b64_tr_b16 v[236:237], v220 offset:10368
	ds_read_b64_tr_b16 v[240:241], v220 offset:10432
	ds_read_b64_tr_b16 v[238:239], v220 offset:9280
	ds_read_b64_tr_b16 v[242:243], v220 offset:11520
	ds_read_b64_tr_b16 v[244:245], v220 offset:12672
	ds_read_b64_tr_b16 v[248:249], v220 offset:12736
	ds_read_b64_tr_b16 v[246:247], v220 offset:11584
	s_setprio 1
	s_waitcnt lgkmcnt(6)
	v_mfma_f32_32x32x16_bf16 v[0:15], v[234:237], v[226:229], v[0:15]
	s_waitcnt lgkmcnt(4)
	v_mfma_f32_32x32x16_bf16 v[16:31], v[238:241], v[226:229], v[16:31]
	s_waitcnt lgkmcnt(2)
	v_mfma_f32_32x32x16_bf16 v[0:15], v[242:245], v[230:233], v[0:15]
	s_waitcnt lgkmcnt(0)
	v_mfma_f32_32x32x16_bf16 v[16:31], v[246:249], v[230:233], v[16:31]
	s_setprio 0
	v_max3_f32 v172, v64, s15, v65
	v_max3_f32 v172, v172, v66, v67
	v_max3_f32 v172, v172, v68, v69
	v_max3_f32 v172, v172, v70, v71
	v_max3_f32 v172, v172, v72, v73
	v_max3_f32 v172, v172, v74, v75
	v_max3_f32 v172, v172, v76, v77
	v_max3_f32 v172, v172, v78, v79
	v_cndmask_b32_e64 v172, v208, v172, s[38:39]
	v_mov_b32_e32 v173, v172
	v_mov_b32_e32 v184, v172
	s_nop 1
	v_permlane32_swap_b32_e32 v173, v184
	v_max_f32_e32 v172, v173, v184
	v_add_f32_e32 v173, 0x41000000, v224
	v_cmp_gt_f32_e32 vcc, v172, v173
	s_nop 1
	v_cndmask_b32_e32 v225, v224, v172, vcc
	v_max_f32_e32 v172, 0xefa18f08, v225
	v_cndmask_b32_e64 v172, v209, v172, s[38:39]
	v_sub_f32_e32 v64, v64, v172
	v_exp_f32_e32 v64, v64
	v_sub_f32_e32 v65, v65, v172
	v_exp_f32_e32 v65, v65
	v_sub_f32_e32 v66, v66, v172
	v_exp_f32_e32 v66, v66
	v_sub_f32_e32 v67, v67, v172
	v_exp_f32_e32 v67, v67
	v_sub_f32_e32 v68, v68, v172
	v_exp_f32_e32 v68, v68
	v_sub_f32_e32 v69, v69, v172
	v_add_f32_e32 v184, v65, v64
	v_exp_f32_e32 v69, v69
	v_sub_f32_e32 v70, v70, v172
	v_add_f32_e32 v184, v66, v184
	v_exp_f32_e32 v70, v70
	v_sub_f32_e32 v71, v71, v172
	v_add_f32_e32 v184, v67, v184
	v_exp_f32_e32 v71, v71
	v_sub_f32_e32 v72, v72, v172
	v_add_f32_e32 v184, v68, v184
	v_exp_f32_e32 v72, v72
	v_sub_f32_e32 v73, v73, v172
	v_add_f32_e32 v184, v69, v184
	v_exp_f32_e32 v73, v73
	v_sub_f32_e32 v74, v74, v172
	v_add_f32_e32 v184, v70, v184
	v_exp_f32_e32 v74, v74
	v_sub_f32_e32 v75, v75, v172
	v_add_f32_e32 v184, v71, v184
	v_exp_f32_e32 v75, v75
	v_sub_f32_e32 v76, v76, v172
	v_add_f32_e32 v184, v72, v184
	v_exp_f32_e32 v76, v76
	v_sub_f32_e32 v77, v77, v172
	v_add_f32_e32 v184, v73, v184
	v_exp_f32_e32 v77, v77
	v_sub_f32_e32 v78, v78, v172
	v_add_f32_e32 v184, v74, v184
	v_exp_f32_e32 v78, v78
	v_sub_f32_e32 v79, v79, v172
	v_add_f32_e32 v184, v75, v184
	v_exp_f32_e32 v79, v79
	v_add_f32_e32 v172, v76, v184
	v_sub_f32_e32 v173, v224, v225
	v_add_f32_e32 v172, v77, v172
	v_add_f32_e32 v172, v78, v172
	v_exp_f32_e32 v184, v173
	v_add_f32_e32 v221, v79, v172
	v_mov_b32_e32 v222, v221
	v_mov_b32_e32 v223, v221
	s_nop 1
	v_permlane32_swap_b32_e32 v222, v223
	v_cmp_neq_f32_e32 vcc, v225, v224
	s_cbranch_vccz .LBB0_596
	v_pk_mul_f32 v[30:31], v[30:31], v[184:185] op_sel_hi:[1,0]
	v_pk_mul_f32 v[28:29], v[28:29], v[184:185] op_sel_hi:[1,0]
	v_pk_mul_f32 v[26:27], v[26:27], v[184:185] op_sel_hi:[1,0]
	v_pk_mul_f32 v[24:25], v[24:25], v[184:185] op_sel_hi:[1,0]
	v_pk_mul_f32 v[22:23], v[22:23], v[184:185] op_sel_hi:[1,0]
	v_pk_mul_f32 v[20:21], v[20:21], v[184:185] op_sel_hi:[1,0]
	v_pk_mul_f32 v[18:19], v[18:19], v[184:185] op_sel_hi:[1,0]
	v_pk_mul_f32 v[16:17], v[16:17], v[184:185] op_sel_hi:[1,0]
	v_pk_mul_f32 v[14:15], v[14:15], v[184:185] op_sel_hi:[1,0]
	v_pk_mul_f32 v[12:13], v[12:13], v[184:185] op_sel_hi:[1,0]
	v_pk_mul_f32 v[10:11], v[10:11], v[184:185] op_sel_hi:[1,0]
	v_pk_mul_f32 v[8:9], v[8:9], v[184:185] op_sel_hi:[1,0]
	v_pk_mul_f32 v[6:7], v[6:7], v[184:185] op_sel_hi:[1,0]
	v_pk_mul_f32 v[4:5], v[4:5], v[184:185] op_sel_hi:[1,0]
	v_pk_mul_f32 v[2:3], v[2:3], v[184:185] op_sel_hi:[1,0]
	v_pk_mul_f32 v[0:1], v[0:1], v[184:185] op_sel_hi:[1,0]
; #define LAS __attribute__((address_space(3)))
; DI float ex2(float x) { return __builtin_amdgcn_exp2f(x); }
; template <int MM> DI void smax_step_nb(const f32x16& s, unsigned vm, float& m, float& l, f32x16 (&o)[2], bf16x8 (&pf)[2], int lane) {
;     float mx = -1e30f;
; #pragma unroll
;     for (int i = 0; i < 16; ++i) mx = fmaxf(mx, s[i]);
;     if (MM == 1) mx = vm ? mx : -1e30f;
;     mx = fmaxf(mx, shx32(mx, lane));
;     const float mn = (mx > m + 8.0f) ? mx : m;
;     float mref = fmaxf(mn, -1e29f);
;     if (MM == 1) mref = vm ? mref : 3e38f;
;     const float alpha = ex2(m - mn);
;     float p[16], rs = 0.f;
; #pragma unroll
;     for (int i = 0; i < 16; ++i) { p[i] = ex2(s[i] - mref); rs += p[i]; }
;     rs += shx32(rs, lane);
;     l = l * alpha + rs;
;     if (__builtin_amdgcn_ballot_w64(mn != m) != 0ull) {
; #pragma unroll
;         for (int i = 0; i < 16; ++i) { o[0][i] *= alpha; o[1][i] *= alpha; }
;     }
;     m = mn;
;     pack_p(p, pf);
; }
; template <int MM> DI void tile128_pipe(LAS const char* K0, LAS const char* V0, LAS const char* K1, LAS const char* V1, const bf16x8 (&qf)[4], unsigned vm0, unsigned vm1,
;                                        float& m, float& l, f32x16 (&o)[2], int r, int h, int lane) {
;     f32x16 sa = qk_rows<0, 4>(K0, 0, qf, r, h), sb = qk_rows<0, 4>(K0, 32, qf, r, h);
;     bf16x8 pfa[2], pfb[2];
;     smax_step_nb<MM>(sa, vm0, m, l, o, pfa, lane);
;     sa = qk_rows<0, 4>(K1, 0, qf, r, h);
;     pv_rows(o, V0, 0, pfa, lane);
;     smax_step_nb<MM>(sb, vm0, m, l, o, pfb, lane);
;     sb = qk_rows<0, 4>(K1, 32, qf, r, h);
;     pv_rows(o, V0, 32, pfb, lane);
;     smax_step_nb<MM>(sa, vm1, m, l, o, pfa, lane);
;     pv_rows(o, V1, 0, pfa, lane);
;     smax_step_nb<MM>(sb, vm1, m, l, o, pfb, lane);
;     pv_rows(o, V1, 32, pfb, lane);
; }
.LBB0_596:
	v_cvt_pk_bf16_f32 v226, v64, v65
	v_cvt_pk_bf16_f32 v227, v66, v67
	ds_read_b128 v[64:67], v215 offset:23040
	ds_read_b128 v[234:237], v215 offset:23072
	ds_read_b128 v[238:241], v215 offset:23104
	ds_read_b128 v[242:245], v215 offset:23136
	v_cvt_pk_bf16_f32 v228, v68, v69
	v_cvt_pk_bf16_f32 v229, v70, v71
	v_cvt_pk_bf16_f32 v230, v72, v73
	v_cvt_pk_bf16_f32 v231, v74, v75
	v_cvt_pk_bf16_f32 v232, v76, v77
	v_cvt_pk_bf16_f32 v233, v78, v79
	s_setprio 1
	s_waitcnt lgkmcnt(3)
	v_mfma_f32_32x32x16_bf16 v[64:79], v[64:67], v[96:99], 0
	s_waitcnt lgkmcnt(2)
	v_mfma_f32_32x32x16_bf16 v[64:79], v[234:237], v[100:103], v[64:79]
	s_waitcnt lgkmcnt(1)
	v_mfma_f32_32x32x16_bf16 v[64:79], v[238:241], v[104:107], v[64:79]
	s_waitcnt lgkmcnt(0)
	v_mfma_f32_32x32x16_bf16 v[64:79], v[242:245], v[108:111], v[64:79]
	s_setprio 0
	ds_read_b64_tr_b16 v[234:235], v220 offset:13824
	ds_read_b64_tr_b16 v[236:237], v220 offset:14976
	ds_read_b64_tr_b16 v[240:241], v220 offset:15040
	ds_read_b64_tr_b16 v[238:239], v220 offset:13888
	ds_read_b64_tr_b16 v[242:243], v220 offset:16128
	ds_read_b64_tr_b16 v[244:245], v220 offset:17280
	ds_read_b64_tr_b16 v[248:249], v220 offset:17344
	ds_read_b64_tr_b16 v[246:247], v220 offset:16192
	s_setprio 1
	s_waitcnt lgkmcnt(6)
	v_mfma_f32_32x32x16_bf16 v[0:15], v[234:237], v[226:229], v[0:15]
	s_waitcnt lgkmcnt(4)
	v_mfma_f32_32x32x16_bf16 v[16:31], v[238:241], v[226:229], v[16:31]
	s_waitcnt lgkmcnt(2)
	v_mfma_f32_32x32x16_bf16 v[0:15], v[242:245], v[230:233], v[0:15]
	s_waitcnt lgkmcnt(0)
	v_mfma_f32_32x32x16_bf16 v[16:31], v[246:249], v[230:233], v[16:31]
	s_setprio 0
	v_max3_f32 v172, v80, s15, v81
	v_max3_f32 v172, v172, v82, v83
	v_max3_f32 v172, v172, v84, v85
	v_max3_f32 v172, v172, v86, v87
	v_max3_f32 v172, v172, v88, v89
	v_max3_f32 v172, v172, v90, v91
	v_max3_f32 v172, v172, v92, v93
	v_max3_f32 v172, v172, v94, v95
	v_cndmask_b32_e64 v172, v208, v172, s[0:1]
	v_mov_b32_e32 v173, v172
	v_mov_b32_e32 v206, v172
	s_nop 1
	v_permlane32_swap_b32_e32 v173, v206
	v_cndmask_b32_e64 v173, v173, v206, s[36:37]
	v_max_f32_e32 v173, v173, v173
	v_max_f32_e32 v172, v172, v173
	v_add_f32_e32 v173, 0x41000000, v225
	v_cmp_gt_f32_e32 vcc, v172, v173
	s_nop 1
	v_cndmask_b32_e32 v224, v225, v172, vcc
	v_max_f32_e32 v172, 0xefa18f08, v224
	v_cndmask_b32_e64 v172, v209, v172, s[0:1]
	v_sub_f32_e32 v80, v80, v172
	v_exp_f32_e32 v226, v80
	v_sub_f32_e32 v80, v81, v172
	v_exp_f32_e32 v81, v80
	v_sub_f32_e32 v80, v82, v172
	v_exp_f32_e32 v227, v80
	v_sub_f32_e32 v80, v83, v172
	v_exp_f32_e32 v228, v80
	v_sub_f32_e32 v82, v84, v172
	v_exp_f32_e32 v229, v82
	v_sub_f32_e32 v82, v85, v172
	v_add_f32_e32 v80, v81, v226
	v_exp_f32_e32 v85, v82
	v_sub_f32_e32 v82, v86, v172
	v_add_f32_e32 v80, v227, v80
	v_exp_f32_e32 v86, v82
	v_sub_f32_e32 v82, v87, v172
	v_add_f32_e32 v80, v228, v80
	v_exp_f32_e32 v87, v82
	v_sub_f32_e32 v82, v88, v172
	v_add_f32_e32 v80, v229, v80
	v_exp_f32_e32 v88, v82
	v_sub_f32_e32 v82, v89, v172
	v_add_f32_e32 v80, v85, v80
	v_exp_f32_e32 v89, v82
	v_sub_f32_e32 v82, v90, v172
	v_add_f32_e32 v80, v86, v80
	v_exp_f32_e32 v90, v82
	v_sub_f32_e32 v82, v91, v172
	v_add_f32_e32 v80, v87, v80
	v_exp_f32_e32 v91, v82
	v_sub_f32_e32 v82, v92, v172
	v_add_f32_e32 v80, v88, v80
	v_exp_f32_e32 v92, v82
	v_sub_f32_e32 v82, v93, v172
	v_add_f32_e32 v80, v89, v80
	v_exp_f32_e32 v93, v82
	v_sub_f32_e32 v82, v94, v172
	v_add_f32_e32 v80, v90, v80
	v_exp_f32_e32 v94, v82
	v_sub_f32_e32 v82, v95, v172
	v_add_f32_e32 v80, v91, v80
	v_exp_f32_e32 v95, v82
	v_add_f32_e32 v80, v92, v80
	v_add_f32_e32 v80, v93, v80
	v_sub_f32_e32 v173, v225, v224
	v_add_f32_e32 v80, v94, v80
	v_add_f32_e32 v82, v95, v80
	v_exp_f32_e32 v80, v173
	v_mov_b32_e32 v83, v82
	v_mov_b32_e32 v84, v82
	s_nop 1
	v_permlane32_swap_b32_e32 v83, v84
	v_cmp_neq_f32_e32 vcc, v224, v225
	s_cbranch_vccz .LBB0_598
	v_pk_mul_f32 v[30:31], v[30:31], v[80:81] op_sel_hi:[1,0]
	v_pk_mul_f32 v[28:29], v[28:29], v[80:81] op_sel_hi:[1,0]
	v_pk_mul_f32 v[26:27], v[26:27], v[80:81] op_sel_hi:[1,0]
	v_pk_mul_f32 v[24:25], v[24:25], v[80:81] op_sel_hi:[1,0]
	v_pk_mul_f32 v[22:23], v[22:23], v[80:81] op_sel_hi:[1,0]
	v_pk_mul_f32 v[20:21], v[20:21], v[80:81] op_sel_hi:[1,0]
	v_pk_mul_f32 v[18:19], v[18:19], v[80:81] op_sel_hi:[1,0]
	v_pk_mul_f32 v[16:17], v[16:17], v[80:81] op_sel_hi:[1,0]
	v_pk_mul_f32 v[14:15], v[14:15], v[80:81] op_sel_hi:[1,0]
	v_pk_mul_f32 v[12:13], v[12:13], v[80:81] op_sel_hi:[1,0]
	v_pk_mul_f32 v[10:11], v[10:11], v[80:81] op_sel_hi:[1,0]
	v_pk_mul_f32 v[8:9], v[8:9], v[80:81] op_sel_hi:[1,0]
	v_pk_mul_f32 v[6:7], v[6:7], v[80:81] op_sel_hi:[1,0]
	v_pk_mul_f32 v[4:5], v[4:5], v[80:81] op_sel_hi:[1,0]
	v_pk_mul_f32 v[2:3], v[2:3], v[80:81] op_sel_hi:[1,0]
	v_pk_mul_f32 v[0:1], v[0:1], v[80:81] op_sel_hi:[1,0]
; #define LAS __attribute__((address_space(3)))
; DI float ex2(float x) { return __builtin_amdgcn_exp2f(x); }
; template <int MM> DI void smax_step_nb(const f32x16& s, unsigned vm, float& m, float& l, f32x16 (&o)[2], bf16x8 (&pf)[2], int lane) {
;     float mx = -1e30f;
; #pragma unroll
;     for (int i = 0; i < 16; ++i) mx = fmaxf(mx, s[i]);
;     if (MM == 1) mx = vm ? mx : -1e30f;
;     mx = fmaxf(mx, shx32(mx, lane));
;     const float mn = (mx > m + 8.0f) ? mx : m;
;     float mref = fmaxf(mn, -1e29f);
;     if (MM == 1) mref = vm ? mref : 3e38f;
;     const float alpha = ex2(m - mn);
;     float p[16], rs = 0.f;
; #pragma unroll
;     for (int i = 0; i < 16; ++i) { p[i] = ex2(s[i] - mref); rs += p[i]; }
;     rs += shx32(rs, lane);
;     l = l * alpha + rs;
;     if (__builtin_amdgcn_ballot_w64(mn != m) != 0ull) {
; #pragma unroll
;         for (int i = 0; i < 16; ++i) { o[0][i] *= alpha; o[1][i] *= alpha; }
;     }
;     m = mn;
;     pack_p(p, pf);
; }
; template <int MM> DI void tile128_pipe(LAS const char* K0, LAS const char* V0, LAS const char* K1, LAS const char* V1, const bf16x8 (&qf)[4], unsigned vm0, unsigned vm1,
;                                        float& m, float& l, f32x16 (&o)[2], int r, int h, int lane) {
;     f32x16 sa = qk_rows<0, 4>(K0, 0, qf, r, h), sb = qk_rows<0, 4>(K0, 32, qf, r, h);
;     bf16x8 pfa[2], pfb[2];
;     smax_step_nb<MM>(sa, vm0, m, l, o, pfa, lane);
;     sa = qk_rows<0, 4>(K1, 0, qf, r, h);
;     pv_rows(o, V0, 0, pfa, lane);
;     smax_step_nb<MM>(sb, vm0, m, l, o, pfb, lane);
;     sb = qk_rows<0, 4>(K1, 32, qf, r, h);
;     pv_rows(o, V0, 32, pfb, lane);
;     smax_step_nb<MM>(sa, vm1, m, l, o, pfa, lane);
;     pv_rows(o, V1, 0, pfa, lane);
;     smax_step_nb<MM>(sb, vm1, m, l, o, pfb, lane);
;     pv_rows(o, V1, 32, pfb, lane);
; }
.LBB0_598:
	v_cvt_pk_bf16_f32 v227, v227, v228
	v_cvt_pk_bf16_f32 v228, v229, v85
	v_cvt_pk_bf16_f32 v229, v86, v87
	v_cvt_pk_bf16_f32 v86, v88, v89
	v_cvt_pk_bf16_f32 v87, v90, v91
	v_cvt_pk_bf16_f32 v88, v92, v93
	ds_read_b64_tr_b16 v[90:91], v220 offset:27648
	ds_read_b64_tr_b16 v[92:93], v220 offset:28800
	ds_read_b64_tr_b16 v[230:231], v220 offset:29952
	ds_read_b64_tr_b16 v[232:233], v220 offset:31104
	ds_read_b64_tr_b16 v[234:235], v220 offset:27712
	ds_read_b64_tr_b16 v[236:237], v220 offset:28864
	ds_read_b64_tr_b16 v[238:239], v220 offset:30016
	ds_read_b64_tr_b16 v[240:241], v220 offset:31168
	v_cvt_pk_bf16_f32 v89, v94, v95
	v_cvt_pk_bf16_f32 v226, v226, v81
	s_setprio 1
	s_waitcnt lgkmcnt(6)
	v_mfma_f32_32x32x16_bf16 v[0:15], v[90:93], v[226:229], v[0:15]
	s_waitcnt lgkmcnt(2)
	v_mfma_f32_32x32x16_bf16 v[16:31], v[234:237], v[226:229], v[16:31]
	v_mfma_f32_32x32x16_bf16 v[0:15], v[230:233], v[86:89], v[0:15]
	s_waitcnt lgkmcnt(0)
	v_mfma_f32_32x32x16_bf16 v[16:31], v[238:241], v[86:89], v[16:31]
	s_setprio 0
	v_max3_f32 v81, v64, s15, v65
	v_max3_f32 v81, v81, v66, v67
	v_max3_f32 v81, v81, v68, v69
	v_max3_f32 v81, v81, v70, v71
	v_max3_f32 v81, v81, v72, v73
	v_max3_f32 v81, v81, v74, v75
	v_max3_f32 v81, v81, v76, v77
	v_max3_f32 v81, v81, v78, v79
	v_cndmask_b32_e64 v81, v208, v81, s[0:1]
	v_mov_b32_e32 v85, v81
	v_mov_b32_e32 v86, v81
	s_nop 1
	v_permlane32_swap_b32_e32 v85, v86
	v_max_f32_e32 v81, v85, v86
	v_add_f32_e32 v85, 0x41000000, v224
	v_cmp_gt_f32_e32 vcc, v81, v85
	s_nop 1
	v_cndmask_b32_e32 v81, v224, v81, vcc
	v_max_f32_e32 v85, 0xefa18f08, v81
	v_cndmask_b32_e64 v93, v209, v85, s[0:1]
	v_sub_f32_e32 v64, v64, v93
	v_exp_f32_e32 v85, v64
	v_sub_f32_e32 v64, v65, v93
	v_exp_f32_e32 v86, v64
	v_sub_f32_e32 v64, v66, v93
	v_exp_f32_e32 v87, v64
	v_sub_f32_e32 v64, v67, v93
	v_exp_f32_e32 v88, v64
	v_sub_f32_e32 v65, v68, v93
	v_exp_f32_e32 v89, v65
	v_sub_f32_e32 v65, v69, v93
	v_add_f32_e32 v64, v86, v85
	v_exp_f32_e32 v90, v65
	v_sub_f32_e32 v65, v70, v93
	v_add_f32_e32 v64, v87, v64
	v_exp_f32_e32 v91, v65
	v_sub_f32_e32 v65, v71, v93
	v_add_f32_e32 v64, v88, v64
	v_exp_f32_e32 v92, v65
	v_sub_f32_e32 v65, v72, v93
	v_add_f32_e32 v64, v89, v64
	v_exp_f32_e32 v66, v65
	v_sub_f32_e32 v65, v73, v93
	v_add_f32_e32 v64, v90, v64
	v_exp_f32_e32 v67, v65
	v_sub_f32_e32 v65, v74, v93
	v_add_f32_e32 v64, v91, v64
	v_exp_f32_e32 v68, v65
	v_sub_f32_e32 v65, v75, v93
	v_add_f32_e32 v64, v92, v64
	v_exp_f32_e32 v69, v65
	v_sub_f32_e32 v65, v76, v93
	v_add_f32_e32 v64, v66, v64
	v_exp_f32_e32 v70, v65
	v_sub_f32_e32 v65, v77, v93
	v_add_f32_e32 v64, v67, v64
	v_exp_f32_e32 v71, v65
	v_sub_f32_e32 v65, v78, v93
	v_add_f32_e32 v64, v68, v64
	v_exp_f32_e32 v72, v65
	v_sub_f32_e32 v65, v79, v93
	v_add_f32_e32 v64, v69, v64
	v_exp_f32_e32 v73, v65
	v_add_f32_e32 v64, v70, v64
	v_add_f32_e32 v64, v71, v64
	v_sub_f32_e32 v94, v224, v81
	v_add_f32_e32 v64, v72, v64
	v_add_f32_e32 v65, v73, v64
	v_exp_f32_e32 v64, v94
	v_mov_b32_e32 v74, v65
	v_mov_b32_e32 v75, v65
	s_nop 1
	v_permlane32_swap_b32_e32 v74, v75
	v_cmp_neq_f32_e32 vcc, v81, v224
	s_cbranch_vccz .LBB0_600
	v_pk_mul_f32 v[30:31], v[30:31], v[64:65] op_sel_hi:[1,0]
	v_pk_mul_f32 v[28:29], v[28:29], v[64:65] op_sel_hi:[1,0]
	v_pk_mul_f32 v[26:27], v[26:27], v[64:65] op_sel_hi:[1,0]
	v_pk_mul_f32 v[24:25], v[24:25], v[64:65] op_sel_hi:[1,0]
	v_pk_mul_f32 v[22:23], v[22:23], v[64:65] op_sel_hi:[1,0]
	v_pk_mul_f32 v[20:21], v[20:21], v[64:65] op_sel_hi:[1,0]
	v_pk_mul_f32 v[18:19], v[18:19], v[64:65] op_sel_hi:[1,0]
	v_pk_mul_f32 v[16:17], v[16:17], v[64:65] op_sel_hi:[1,0]
	v_pk_mul_f32 v[14:15], v[14:15], v[64:65] op_sel_hi:[1,0]
	v_pk_mul_f32 v[12:13], v[12:13], v[64:65] op_sel_hi:[1,0]
	v_pk_mul_f32 v[10:11], v[10:11], v[64:65] op_sel_hi:[1,0]
	v_pk_mul_f32 v[8:9], v[8:9], v[64:65] op_sel_hi:[1,0]
	v_pk_mul_f32 v[6:7], v[6:7], v[64:65] op_sel_hi:[1,0]
	v_pk_mul_f32 v[4:5], v[4:5], v[64:65] op_sel_hi:[1,0]
	v_pk_mul_f32 v[2:3], v[2:3], v[64:65] op_sel_hi:[1,0]
	v_pk_mul_f32 v[0:1], v[0:1], v[64:65] op_sel_hi:[1,0]

; #define LAS __attribute__((address_space(3)))
; DI float ex2(float x) { return __builtin_amdgcn_exp2f(x); }
; template <int MM> DI void smax_step_nb(const f32x16& s, unsigned vm, float& m, float& l, f32x16 (&o)[2], bf16x8 (&pf)[2], int lane) {
;     float mx = -1e30f;
; #pragma unroll
;     for (int i = 0; i < 16; ++i) mx = fmaxf(mx, s[i]);
;     if (MM == 1) mx = vm ? mx : -1e30f;
;     mx = fmaxf(mx, shx32(mx, lane));
;     const float mn = (mx > m + 8.0f) ? mx : m;
;     float mref = fmaxf(mn, -1e29f);
;     if (MM == 1) mref = vm ? mref : 3e38f;
;     const float alpha = ex2(m - mn);
;     float p[16], rs = 0.f;
; #pragma unroll
;     for (int i = 0; i < 16; ++i) { p[i] = ex2(s[i] - mref); rs += p[i]; }
;     rs += shx32(rs, lane);
;     l = l * alpha + rs;
;     if (__builtin_amdgcn_ballot_w64(mn != m) != 0ull) {
; #pragma unroll
;         for (int i = 0; i < 16; ++i) { o[0][i] *= alpha; o[1][i] *= alpha; }
;     }
;     m = mn;
;     pack_p(p, pf);
; }
; template <int MM> DI void tile128_pipe(LAS const char* K0, LAS const char* V0, LAS const char* K1, LAS const char* V1, const bf16x8 (&qf)[4], unsigned vm0, unsigned vm1,
;                                        float& m, float& l, f32x16 (&o)[2], int r, int h, int lane) {
;     f32x16 sa = qk_rows<0, 4>(K0, 0, qf, r, h), sb = qk_rows<0, 4>(K0, 32, qf, r, h);
;     bf16x8 pfa[2], pfb[2];
;     smax_step_nb<MM>(sa, vm0, m, l, o, pfa, lane);
;     sa = qk_rows<0, 4>(K1, 0, qf, r, h);
;     pv_rows(o, V0, 0, pfa, lane);
;     smax_step_nb<MM>(sb, vm0, m, l, o, pfb, lane);
;     sb = qk_rows<0, 4>(K1, 32, qf, r, h);
;     pv_rows(o, V0, 32, pfb, lane);
;     smax_step_nb<MM>(sa, vm1, m, l, o, pfa, lane);
;     pv_rows(o, V1, 0, pfa, lane);
;     smax_step_nb<MM>(sb, vm1, m, l, o, pfb, lane);
;     pv_rows(o, V1, 32, pfb, lane);
; }
.LBB0_601:
	s_cbranch_execz .LBB0_611
	s_waitcnt lgkmcnt(7)
	v_mfma_f32_32x32x16_bf16 v[48:63], v[140:143], v[96:99], 0
	s_waitcnt lgkmcnt(6)
	v_mfma_f32_32x32x16_bf16 v[48:63], v[136:139], v[100:103], v[48:63]
	s_waitcnt lgkmcnt(5)
	v_mfma_f32_32x32x16_bf16 v[48:63], v[132:135], v[104:107], v[48:63]
	s_waitcnt lgkmcnt(4)
	v_mfma_f32_32x32x16_bf16 v[48:63], v[128:131], v[108:111], v[48:63]
	s_waitcnt lgkmcnt(3)
	v_mfma_f32_32x32x16_bf16 v[32:47], v[144:147], v[96:99], 0
	s_nop 9
	v_max3_f32 v64, v48, s15, v49
	v_max3_f32 v64, v64, v50, v51
	v_max3_f32 v64, v64, v52, v53
	v_max3_f32 v64, v64, v54, v55
	v_max3_f32 v64, v64, v56, v57
	v_max3_f32 v64, v64, v58, v59
	v_max3_f32 v64, v64, v60, v61
	v_max3_f32 v64, v64, v62, v63
	v_mov_b32_e32 v65, v64
	v_mov_b32_e32 v66, v64
	s_nop 1
	v_permlane32_swap_b32_e32 v65, v66
	v_max_f32_e32 v64, v65, v66
	v_cmp_gt_f32_e32 vcc, v64, v216
	s_waitcnt lgkmcnt(2)
	v_mfma_f32_32x32x16_bf16 v[32:47], v[148:151], v[100:103], v[32:47]
	v_cndmask_b32_e32 v73, v214, v64, vcc
	v_max_f32_e32 v64, 0xefa18f08, v73
	v_sub_f32_e32 v48, v48, v64
	v_exp_f32_e32 v48, v48
	v_sub_f32_e32 v49, v49, v64
	v_exp_f32_e32 v49, v49
	v_sub_f32_e32 v50, v50, v64
	v_exp_f32_e32 v50, v50
	v_sub_f32_e32 v51, v51, v64
	v_exp_f32_e32 v51, v51
	v_sub_f32_e32 v52, v52, v64
	v_exp_f32_e32 v52, v52
	v_sub_f32_e32 v53, v53, v64
	v_add_f32_e32 v65, v49, v48
	v_exp_f32_e32 v53, v53
	v_sub_f32_e32 v54, v54, v64
	s_waitcnt lgkmcnt(1)
	v_mfma_f32_32x32x16_bf16 v[32:47], v[152:155], v[104:107], v[32:47]
	v_add_f32_e32 v65, v50, v65
	v_exp_f32_e32 v54, v54
	v_sub_f32_e32 v55, v55, v64
	v_add_f32_e32 v65, v51, v65
	v_exp_f32_e32 v55, v55
	v_sub_f32_e32 v56, v56, v64
	v_add_f32_e32 v65, v52, v65
	v_exp_f32_e32 v56, v56
	v_sub_f32_e32 v57, v57, v64
	v_add_f32_e32 v65, v53, v65
	v_exp_f32_e32 v57, v57
	v_sub_f32_e32 v58, v58, v64
	v_add_f32_e32 v65, v54, v65
	v_exp_f32_e32 v58, v58
	v_sub_f32_e32 v59, v59, v64
	v_add_f32_e32 v65, v55, v65
	v_exp_f32_e32 v59, v59
	v_sub_f32_e32 v60, v60, v64
	v_add_f32_e32 v65, v56, v65
	v_exp_f32_e32 v60, v60
	v_sub_f32_e32 v61, v61, v64
	v_add_f32_e32 v65, v57, v65
	v_exp_f32_e32 v61, v61
	v_sub_f32_e32 v62, v62, v64
	s_waitcnt lgkmcnt(0)
	v_mfma_f32_32x32x16_bf16 v[32:47], v[156:159], v[108:111], v[32:47]
	v_add_f32_e32 v65, v58, v65
	v_exp_f32_e32 v62, v62
	v_sub_f32_e32 v63, v63, v64
	v_add_f32_e32 v65, v59, v65
	v_exp_f32_e32 v63, v63
	v_add_f32_e32 v65, v60, v65
	v_sub_f32_e32 v66, v214, v73
	v_add_f32_e32 v65, v61, v65
	v_add_f32_e32 v65, v62, v65
	v_exp_f32_e32 v64, v66
	v_add_f32_e32 v65, v63, v65
	v_mov_b32_e32 v67, v65
	v_mov_b32_e32 v68, v65
	s_nop 1
	v_permlane32_swap_b32_e32 v67, v68
	v_cmp_neq_f32_e32 vcc, v73, v214
	s_cbranch_vccz .LBB0_604
	v_pk_mul_f32 v[30:31], v[30:31], v[64:65] op_sel_hi:[1,0]
	v_pk_mul_f32 v[28:29], v[28:29], v[64:65] op_sel_hi:[1,0]
	v_pk_mul_f32 v[26:27], v[26:27], v[64:65] op_sel_hi:[1,0]
	v_pk_mul_f32 v[24:25], v[24:25], v[64:65] op_sel_hi:[1,0]
	v_pk_mul_f32 v[22:23], v[22:23], v[64:65] op_sel_hi:[1,0]
	v_pk_mul_f32 v[20:21], v[20:21], v[64:65] op_sel_hi:[1,0]
	v_pk_mul_f32 v[18:19], v[18:19], v[64:65] op_sel_hi:[1,0]
	v_pk_mul_f32 v[16:17], v[16:17], v[64:65] op_sel_hi:[1,0]
	v_pk_mul_f32 v[14:15], v[14:15], v[64:65] op_sel_hi:[1,0]
	v_pk_mul_f32 v[12:13], v[12:13], v[64:65] op_sel_hi:[1,0]
	v_pk_mul_f32 v[10:11], v[10:11], v[64:65] op_sel_hi:[1,0]
	v_pk_mul_f32 v[8:9], v[8:9], v[64:65] op_sel_hi:[1,0]
	v_pk_mul_f32 v[6:7], v[6:7], v[64:65] op_sel_hi:[1,0]
	v_pk_mul_f32 v[4:5], v[4:5], v[64:65] op_sel_hi:[1,0]
	v_pk_mul_f32 v[2:3], v[2:3], v[64:65] op_sel_hi:[1,0]
	v_pk_mul_f32 v[0:1], v[0:1], v[64:65] op_sel_hi:[1,0]
.LBB0_604:
	v_cvt_pk_bf16_f32 v74, v48, v49
	v_cvt_pk_bf16_f32 v75, v50, v51
	ds_read_b128 v[48:51], v215 offset:18432
	ds_read_b128 v[82:85], v215 offset:18464
	ds_read_b128 v[86:89], v215 offset:18496
	ds_read_b128 v[90:93], v215 offset:18528
	v_cvt_pk_bf16_f32 v76, v52, v53
	v_cvt_pk_bf16_f32 v77, v54, v55
	v_cvt_pk_bf16_f32 v78, v56, v57
	v_cvt_pk_bf16_f32 v79, v58, v59
	v_cvt_pk_bf16_f32 v80, v60, v61
	v_cvt_pk_bf16_f32 v81, v62, v63
	s_setprio 1
	s_waitcnt lgkmcnt(3)
	v_mfma_f32_32x32x16_bf16 v[48:63], v[48:51], v[96:99], 0
	s_waitcnt lgkmcnt(2)
	v_mfma_f32_32x32x16_bf16 v[48:63], v[82:85], v[100:103], v[48:63]
	s_waitcnt lgkmcnt(1)
	v_mfma_f32_32x32x16_bf16 v[48:63], v[86:89], v[104:107], v[48:63]
	s_waitcnt lgkmcnt(0)
	v_mfma_f32_32x32x16_bf16 v[48:63], v[90:93], v[108:111], v[48:63]
	s_setprio 0
	v_add3_u32 v66, s10, v191, v171
	v_add_u32_e32 v69, v66, v186
	ds_read_b64_tr_b16 v[82:83], v69 offset:9216
	ds_read_b64_tr_b16 v[84:85], v69 offset:10368
	ds_read_b64_tr_b16 v[88:89], v69 offset:10432
	ds_read_b64_tr_b16 v[86:87], v69 offset:9280
	ds_read_b64_tr_b16 v[90:91], v69 offset:11520
	ds_read_b64_tr_b16 v[92:93], v69 offset:12672
	ds_read_b64_tr_b16 v[130:131], v69 offset:12736
	ds_read_b64_tr_b16 v[128:129], v69 offset:11584
	s_setprio 1
	s_waitcnt lgkmcnt(6)
	v_mfma_f32_32x32x16_bf16 v[0:15], v[82:85], v[74:77], v[0:15]
	s_waitcnt lgkmcnt(4)
	v_mfma_f32_32x32x16_bf16 v[16:31], v[86:89], v[74:77], v[16:31]
	s_waitcnt lgkmcnt(2)
	v_mfma_f32_32x32x16_bf16 v[0:15], v[90:93], v[78:81], v[0:15]
	s_waitcnt lgkmcnt(0)
; #define LAS __attribute__((address_space(3)))
; DI float ex2(float x) { return __builtin_amdgcn_exp2f(x); }
; template <int MM> DI void smax_step_nb(const f32x16& s, unsigned vm, float& m, float& l, f32x16 (&o)[2], bf16x8 (&pf)[2], int lane) {
;     float mx = -1e30f;
; #pragma unroll
;     for (int i = 0; i < 16; ++i) mx = fmaxf(mx, s[i]);
;     if (MM == 1) mx = vm ? mx : -1e30f;
;     mx = fmaxf(mx, shx32(mx, lane));
;     const float mn = (mx > m + 8.0f) ? mx : m;
;     float mref = fmaxf(mn, -1e29f);
;     if (MM == 1) mref = vm ? mref : 3e38f;
;     const float alpha = ex2(m - mn);
;     float p[16], rs = 0.f;
; #pragma unroll
;     for (int i = 0; i < 16; ++i) { p[i] = ex2(s[i] - mref); rs += p[i]; }
;     rs += shx32(rs, lane);
;     l = l * alpha + rs;
;     if (__builtin_amdgcn_ballot_w64(mn != m) != 0ull) {
; #pragma unroll
;         for (int i = 0; i < 16; ++i) { o[0][i] *= alpha; o[1][i] *= alpha; }
;     }
;     m = mn;
;     pack_p(p, pf);
; }
; template <int MM> DI void tile128_pipe(LAS const char* K0, LAS const char* V0, LAS const char* K1, LAS const char* V1, const bf16x8 (&qf)[4], unsigned vm0, unsigned vm1,
;                                        float& m, float& l, f32x16 (&o)[2], int r, int h, int lane) {
;     f32x16 sa = qk_rows<0, 4>(K0, 0, qf, r, h), sb = qk_rows<0, 4>(K0, 32, qf, r, h);
;     bf16x8 pfa[2], pfb[2];
;     smax_step_nb<MM>(sa, vm0, m, l, o, pfa, lane);
;     sa = qk_rows<0, 4>(K1, 0, qf, r, h);
;     pv_rows(o, V0, 0, pfa, lane);
;     smax_step_nb<MM>(sb, vm0, m, l, o, pfb, lane);
;     sb = qk_rows<0, 4>(K1, 32, qf, r, h);
;     pv_rows(o, V0, 32, pfb, lane);
;     smax_step_nb<MM>(sa, vm1, m, l, o, pfa, lane);
;     pv_rows(o, V1, 0, pfa, lane);
;     smax_step_nb<MM>(sb, vm1, m, l, o, pfb, lane);
;     pv_rows(o, V1, 32, pfb, lane);
; }
	v_mfma_f32_32x32x16_bf16 v[16:31], v[128:131], v[78:81], v[16:31]
	s_setprio 0
	v_max3_f32 v66, v32, s15, v33
	v_max3_f32 v66, v66, v34, v35
	v_max3_f32 v66, v66, v36, v37
	v_max3_f32 v66, v66, v38, v39
	v_max3_f32 v66, v66, v40, v41
	v_max3_f32 v66, v66, v42, v43
	v_max3_f32 v66, v66, v44, v45
	v_max3_f32 v66, v66, v46, v47
	v_mov_b32_e32 v70, v66
	v_mov_b32_e32 v71, v66
	s_nop 1
	v_permlane32_swap_b32_e32 v70, v71
	v_max_f32_e32 v66, v70, v71
	v_add_f32_e32 v70, 0x41000000, v73
	v_cmp_gt_f32_e32 vcc, v66, v70
	s_nop 1
	v_cndmask_b32_e32 v74, v73, v66, vcc
	v_max_f32_e32 v66, 0xefa18f08, v74
	v_sub_f32_e32 v32, v32, v66
	v_exp_f32_e32 v32, v32
	v_sub_f32_e32 v33, v33, v66
	v_exp_f32_e32 v33, v33
	v_sub_f32_e32 v34, v34, v66
	v_exp_f32_e32 v34, v34
	v_sub_f32_e32 v35, v35, v66
	v_exp_f32_e32 v35, v35
	v_sub_f32_e32 v36, v36, v66
	v_exp_f32_e32 v36, v36
	v_sub_f32_e32 v37, v37, v66
	v_add_f32_e32 v70, v33, v32
	v_exp_f32_e32 v37, v37
	v_sub_f32_e32 v38, v38, v66
	v_add_f32_e32 v70, v34, v70
	v_exp_f32_e32 v38, v38
	v_sub_f32_e32 v39, v39, v66
	v_add_f32_e32 v70, v35, v70
	v_exp_f32_e32 v39, v39
	v_sub_f32_e32 v40, v40, v66
	v_add_f32_e32 v70, v36, v70
	v_exp_f32_e32 v40, v40
	v_sub_f32_e32 v41, v41, v66
	v_add_f32_e32 v70, v37, v70
	v_exp_f32_e32 v41, v41
	v_sub_f32_e32 v42, v42, v66
	v_add_f32_e32 v70, v38, v70
	v_exp_f32_e32 v42, v42
	v_sub_f32_e32 v43, v43, v66
	v_add_f32_e32 v70, v39, v70
	v_exp_f32_e32 v43, v43
	v_sub_f32_e32 v44, v44, v66
	v_add_f32_e32 v70, v40, v70
	v_exp_f32_e32 v44, v44
	v_sub_f32_e32 v45, v45, v66
	v_add_f32_e32 v70, v41, v70
	v_exp_f32_e32 v45, v45
	v_sub_f32_e32 v46, v46, v66
	v_add_f32_e32 v70, v42, v70
	v_exp_f32_e32 v46, v46
	v_sub_f32_e32 v47, v47, v66
	v_add_f32_e32 v70, v43, v70
	v_exp_f32_e32 v47, v47
	v_add_f32_e32 v66, v44, v70
	v_add_f32_e32 v66, v45, v66
	v_sub_f32_e32 v71, v73, v74
	v_add_f32_e32 v66, v46, v66
	v_add_f32_e32 v70, v47, v66
	v_exp_f32_e32 v66, v71
	v_mov_b32_e32 v71, v70
	v_mov_b32_e32 v72, v70
	s_nop 1
	v_permlane32_swap_b32_e32 v71, v72
	v_cmp_neq_f32_e32 vcc, v74, v73
	s_cbranch_vccz .LBB0_606
	v_pk_mul_f32 v[30:31], v[30:31], v[66:67] op_sel_hi:[1,0]
	v_pk_mul_f32 v[28:29], v[28:29], v[66:67] op_sel_hi:[1,0]
	v_pk_mul_f32 v[26:27], v[26:27], v[66:67] op_sel_hi:[1,0]
	v_pk_mul_f32 v[24:25], v[24:25], v[66:67] op_sel_hi:[1,0]
	v_pk_mul_f32 v[22:23], v[22:23], v[66:67] op_sel_hi:[1,0]
	v_pk_mul_f32 v[20:21], v[20:21], v[66:67] op_sel_hi:[1,0]
	v_pk_mul_f32 v[18:19], v[18:19], v[66:67] op_sel_hi:[1,0]
	v_pk_mul_f32 v[16:17], v[16:17], v[66:67] op_sel_hi:[1,0]
	v_pk_mul_f32 v[14:15], v[14:15], v[66:67] op_sel_hi:[1,0]
	v_pk_mul_f32 v[12:13], v[12:13], v[66:67] op_sel_hi:[1,0]
	v_pk_mul_f32 v[10:11], v[10:11], v[66:67] op_sel_hi:[1,0]
	v_pk_mul_f32 v[8:9], v[8:9], v[66:67] op_sel_hi:[1,0]
	v_pk_mul_f32 v[6:7], v[6:7], v[66:67] op_sel_hi:[1,0]
	v_pk_mul_f32 v[4:5], v[4:5], v[66:67] op_sel_hi:[1,0]
	v_pk_mul_f32 v[2:3], v[2:3], v[66:67] op_sel_hi:[1,0]
	v_pk_mul_f32 v[0:1], v[0:1], v[66:67] op_sel_hi:[1,0]
.LBB0_606:
	v_cvt_pk_bf16_f32 v76, v32, v33
	v_cvt_pk_bf16_f32 v77, v34, v35
	ds_read_b128 v[32:35], v215 offset:23040
	ds_read_b128 v[84:87], v215 offset:23072
	ds_read_b128 v[88:91], v215 offset:23104
	ds_read_b128 v[92:95], v215 offset:23136
	v_cvt_pk_bf16_f32 v78, v36, v37
	v_cvt_pk_bf16_f32 v79, v38, v39
	v_cvt_pk_bf16_f32 v80, v40, v41
	v_cvt_pk_bf16_f32 v81, v42, v43
	v_cvt_pk_bf16_f32 v82, v44, v45
	v_cvt_pk_bf16_f32 v83, v46, v47
	s_setprio 1
	s_waitcnt lgkmcnt(3)
	v_mfma_f32_32x32x16_bf16 v[32:47], v[32:35], v[96:99], 0
	s_waitcnt lgkmcnt(2)
	v_mfma_f32_32x32x16_bf16 v[32:47], v[84:87], v[100:103], v[32:47]
	s_waitcnt lgkmcnt(1)
	v_mfma_f32_32x32x16_bf16 v[32:47], v[88:91], v[104:107], v[32:47]
	s_waitcnt lgkmcnt(0)
	v_mfma_f32_32x32x16_bf16 v[32:47], v[92:95], v[108:111], v[32:47]
	s_setprio 0
	ds_read_b64_tr_b16 v[84:85], v69 offset:13824
	ds_read_b64_tr_b16 v[86:87], v69 offset:14976
	ds_read_b64_tr_b16 v[90:91], v69 offset:15040
	ds_read_b64_tr_b16 v[88:89], v69 offset:13888
	ds_read_b64_tr_b16 v[92:93], v69 offset:16128
	ds_read_b64_tr_b16 v[94:95], v69 offset:17280
	ds_read_b64_tr_b16 v[130:131], v69 offset:17344
	ds_read_b64_tr_b16 v[128:129], v69 offset:16192
	s_setprio 1
	s_waitcnt lgkmcnt(6)
	v_mfma_f32_32x32x16_bf16 v[0:15], v[84:87], v[76:79], v[0:15]
	s_waitcnt lgkmcnt(4)
	v_mfma_f32_32x32x16_bf16 v[16:31], v[88:91], v[76:79], v[16:31]
	s_waitcnt lgkmcnt(2)
	v_mfma_f32_32x32x16_bf16 v[0:15], v[92:95], v[80:83], v[0:15]
	s_waitcnt lgkmcnt(0)
	v_mfma_f32_32x32x16_bf16 v[16:31], v[128:131], v[80:83], v[16:31]
	s_setprio 0
	v_max3_f32 v73, v48, s15, v49
	v_max3_f32 v73, v73, v50, v51
	v_max3_f32 v73, v73, v52, v53
	v_max3_f32 v73, v73, v54, v55
	v_max3_f32 v73, v73, v56, v57
	v_max3_f32 v73, v73, v58, v59
	v_max3_f32 v73, v73, v60, v61
	v_max3_f32 v73, v73, v62, v63
	v_mov_b32_e32 v75, v73
	v_mov_b32_e32 v76, v73
	s_nop 1
	v_permlane32_swap_b32_e32 v75, v76
	v_max_f32_e32 v73, v75, v76
	v_add_f32_e32 v75, 0x41000000, v74
	v_cmp_gt_f32_e32 vcc, v73, v75
	s_nop 1
	v_cndmask_b32_e32 v73, v74, v73, vcc
	v_max_f32_e32 v79, 0xefa18f08, v73
	v_sub_f32_e32 v48, v48, v79
	v_exp_f32_e32 v75, v48
	v_sub_f32_e32 v48, v49, v79
	v_exp_f32_e32 v76, v48
	v_sub_f32_e32 v48, v50, v79
	v_exp_f32_e32 v77, v48
	v_sub_f32_e32 v48, v51, v79
	v_exp_f32_e32 v78, v48
	v_sub_f32_e32 v49, v52, v79
	v_exp_f32_e32 v52, v49
	v_sub_f32_e32 v49, v53, v79
	v_add_f32_e32 v48, v76, v75
	v_exp_f32_e32 v53, v49
	v_sub_f32_e32 v49, v54, v79
	v_add_f32_e32 v48, v77, v48
	v_exp_f32_e32 v54, v49
	v_sub_f32_e32 v49, v55, v79
	v_add_f32_e32 v48, v78, v48
	v_exp_f32_e32 v55, v49
	v_sub_f32_e32 v49, v56, v79
	v_add_f32_e32 v48, v52, v48
	v_exp_f32_e32 v56, v49
	v_sub_f32_e32 v49, v57, v79
	v_add_f32_e32 v48, v53, v48
	v_exp_f32_e32 v57, v49
	v_sub_f32_e32 v49, v58, v79
	v_add_f32_e32 v48, v54, v48
	v_exp_f32_e32 v58, v49
	v_sub_f32_e32 v49, v59, v79
	v_add_f32_e32 v48, v55, v48
	v_exp_f32_e32 v59, v49
	v_sub_f32_e32 v49, v60, v79
	v_add_f32_e32 v48, v56, v48
	v_exp_f32_e32 v60, v49
	v_sub_f32_e32 v49, v61, v79
	v_add_f32_e32 v48, v57, v48
	v_exp_f32_e32 v61, v49
	v_sub_f32_e32 v49, v62, v79
	v_add_f32_e32 v48, v58, v48
	v_exp_f32_e32 v62, v49
	v_sub_f32_e32 v49, v63, v79
	v_add_f32_e32 v48, v59, v48
	v_exp_f32_e32 v63, v49
	v_add_f32_e32 v48, v60, v48
	v_add_f32_e32 v48, v61, v48
	v_sub_f32_e32 v80, v74, v73
	v_add_f32_e32 v48, v62, v48
	v_add_f32_e32 v49, v63, v48
	v_exp_f32_e32 v48, v80
	v_mov_b32_e32 v50, v49
	v_mov_b32_e32 v51, v49
	s_nop 1
	v_permlane32_swap_b32_e32 v50, v51
	v_cmp_neq_f32_e32 vcc, v73, v74
	s_cbranch_vccz .LBB0_608
; #define LAS __attribute__((address_space(3)))
; DI float ex2(float x) { return __builtin_amdgcn_exp2f(x); }
; template <int MM> DI void smax_step_nb(const f32x16& s, unsigned vm, float& m, float& l, f32x16 (&o)[2], bf16x8 (&pf)[2], int lane) {
;     float mx = -1e30f;
; #pragma unroll
;     for (int i = 0; i < 16; ++i) mx = fmaxf(mx, s[i]);
;     if (MM == 1) mx = vm ? mx : -1e30f;
;     mx = fmaxf(mx, shx32(mx, lane));
;     const float mn = (mx > m + 8.0f) ? mx : m;
;     float mref = fmaxf(mn, -1e29f);
;     if (MM == 1) mref = vm ? mref : 3e38f;
;     const float alpha = ex2(m - mn);
;     float p[16], rs = 0.f;
; #pragma unroll
;     for (int i = 0; i < 16; ++i) { p[i] = ex2(s[i] - mref); rs += p[i]; }
;     rs += shx32(rs, lane);
;     l = l * alpha + rs;
;     if (__builtin_amdgcn_ballot_w64(mn != m) != 0ull) {
; #pragma unroll
;         for (int i = 0; i < 16; ++i) { o[0][i] *= alpha; o[1][i] *= alpha; }
;     }
;     m = mn;
;     pack_p(p, pf);
; }
; template <int MM> DI void tile128_pipe(LAS const char* K0, LAS const char* V0, LAS const char* K1, LAS const char* V1, const bf16x8 (&qf)[4], unsigned vm0, unsigned vm1,
;                                        float& m, float& l, f32x16 (&o)[2], int r, int h, int lane) {
;     f32x16 sa = qk_rows<0, 4>(K0, 0, qf, r, h), sb = qk_rows<0, 4>(K0, 32, qf, r, h);
;     bf16x8 pfa[2], pfb[2];
;     smax_step_nb<MM>(sa, vm0, m, l, o, pfa, lane);
;     sa = qk_rows<0, 4>(K1, 0, qf, r, h);
;     pv_rows(o, V0, 0, pfa, lane);
;     smax_step_nb<MM>(sb, vm0, m, l, o, pfb, lane);
;     sb = qk_rows<0, 4>(K1, 32, qf, r, h);
;     pv_rows(o, V0, 32, pfb, lane);
;     smax_step_nb<MM>(sa, vm1, m, l, o, pfa, lane);
;     pv_rows(o, V1, 0, pfa, lane);
;     smax_step_nb<MM>(sb, vm1, m, l, o, pfb, lane);
;     pv_rows(o, V1, 32, pfb, lane);
; }
	v_pk_mul_f32 v[30:31], v[30:31], v[48:49] op_sel_hi:[1,0]
	v_pk_mul_f32 v[28:29], v[28:29], v[48:49] op_sel_hi:[1,0]
	v_pk_mul_f32 v[26:27], v[26:27], v[48:49] op_sel_hi:[1,0]
	v_pk_mul_f32 v[24:25], v[24:25], v[48:49] op_sel_hi:[1,0]
	v_pk_mul_f32 v[22:23], v[22:23], v[48:49] op_sel_hi:[1,0]
	v_pk_mul_f32 v[20:21], v[20:21], v[48:49] op_sel_hi:[1,0]
	v_pk_mul_f32 v[18:19], v[18:19], v[48:49] op_sel_hi:[1,0]
	v_pk_mul_f32 v[16:17], v[16:17], v[48:49] op_sel_hi:[1,0]
	v_pk_mul_f32 v[14:15], v[14:15], v[48:49] op_sel_hi:[1,0]
	v_pk_mul_f32 v[12:13], v[12:13], v[48:49] op_sel_hi:[1,0]
	v_pk_mul_f32 v[10:11], v[10:11], v[48:49] op_sel_hi:[1,0]
	v_pk_mul_f32 v[8:9], v[8:9], v[48:49] op_sel_hi:[1,0]
	v_pk_mul_f32 v[6:7], v[6:7], v[48:49] op_sel_hi:[1,0]
	v_pk_mul_f32 v[4:5], v[4:5], v[48:49] op_sel_hi:[1,0]
	v_pk_mul_f32 v[2:3], v[2:3], v[48:49] op_sel_hi:[1,0]
	v_pk_mul_f32 v[0:1], v[0:1], v[48:49] op_sel_hi:[1,0]
.LBB0_608:
	v_cvt_pk_bf16_f32 v74, v75, v76
	v_cvt_pk_bf16_f32 v75, v77, v78
	v_cvt_pk_bf16_f32 v76, v52, v53
	v_cvt_pk_bf16_f32 v77, v54, v55
	v_cvt_pk_bf16_f32 v52, v56, v57
	v_cvt_pk_bf16_f32 v53, v58, v59
	v_cvt_pk_bf16_f32 v54, v60, v61
	v_cvt_pk_bf16_f32 v55, v62, v63
	ds_read_b64_tr_b16 v[56:57], v69 offset:27648
	ds_read_b64_tr_b16 v[58:59], v69 offset:28800
	ds_read_b64_tr_b16 v[60:61], v69 offset:29952
	ds_read_b64_tr_b16 v[62:63], v69 offset:31104
	ds_read_b64_tr_b16 v[78:79], v69 offset:27712
	ds_read_b64_tr_b16 v[80:81], v69 offset:28864
	ds_read_b64_tr_b16 v[82:83], v69 offset:30016
	ds_read_b64_tr_b16 v[84:85], v69 offset:31168
	s_setprio 1
	s_waitcnt lgkmcnt(6)
	v_mfma_f32_32x32x16_bf16 v[0:15], v[56:59], v[74:77], v[0:15]
	s_waitcnt lgkmcnt(2)
	v_mfma_f32_32x32x16_bf16 v[16:31], v[78:81], v[74:77], v[16:31]
	v_mfma_f32_32x32x16_bf16 v[0:15], v[60:63], v[52:55], v[0:15]
	s_waitcnt lgkmcnt(0)
	v_mfma_f32_32x32x16_bf16 v[16:31], v[82:85], v[52:55], v[16:31]
	s_setprio 0
	v_max3_f32 v52, v32, s15, v33
	v_max3_f32 v52, v52, v34, v35
	v_max3_f32 v52, v52, v36, v37
	v_max3_f32 v52, v52, v38, v39
	v_max3_f32 v52, v52, v40, v41
	v_max3_f32 v52, v52, v42, v43
	v_max3_f32 v52, v52, v44, v45
	v_max3_f32 v52, v52, v46, v47
	v_mov_b32_e32 v53, v52
	v_mov_b32_e32 v54, v52
	s_nop 1
	v_permlane32_swap_b32_e32 v53, v54
	v_max_f32_e32 v52, v53, v54
	v_add_f32_e32 v53, 0x41000000, v73
	v_cmp_gt_f32_e32 vcc, v52, v53
	s_nop 1
	v_cndmask_b32_e32 v81, v73, v52, vcc
	v_max_f32_e32 v60, 0xefa18f08, v81
	v_sub_f32_e32 v32, v32, v60
	v_exp_f32_e32 v52, v32
	v_sub_f32_e32 v32, v33, v60
	v_exp_f32_e32 v53, v32
	v_sub_f32_e32 v32, v34, v60
	v_exp_f32_e32 v54, v32
	v_sub_f32_e32 v32, v35, v60
	v_exp_f32_e32 v55, v32
	v_sub_f32_e32 v33, v36, v60
	v_exp_f32_e32 v56, v33
	v_sub_f32_e32 v33, v37, v60
	v_add_f32_e32 v32, v53, v52
	v_exp_f32_e32 v57, v33
	v_sub_f32_e32 v33, v38, v60
	v_add_f32_e32 v32, v54, v32
	v_exp_f32_e32 v58, v33
	v_sub_f32_e32 v33, v39, v60
	v_add_f32_e32 v32, v55, v32
	v_exp_f32_e32 v59, v33
	v_sub_f32_e32 v33, v40, v60
	v_add_f32_e32 v32, v56, v32
	v_exp_f32_e32 v33, v33
	v_sub_f32_e32 v34, v41, v60
	v_add_f32_e32 v32, v57, v32
	v_exp_f32_e32 v34, v34
	v_sub_f32_e32 v35, v42, v60
	v_add_f32_e32 v32, v58, v32
	v_exp_f32_e32 v35, v35
	v_sub_f32_e32 v36, v43, v60
	v_add_f32_e32 v32, v59, v32
	v_exp_f32_e32 v36, v36
	v_sub_f32_e32 v37, v44, v60
	v_add_f32_e32 v32, v33, v32
	v_exp_f32_e32 v37, v37
	v_sub_f32_e32 v38, v45, v60
	v_add_f32_e32 v32, v34, v32
	v_exp_f32_e32 v38, v38
	v_sub_f32_e32 v39, v46, v60
	v_add_f32_e32 v32, v35, v32
	v_exp_f32_e32 v39, v39
	v_sub_f32_e32 v40, v47, v60
	v_add_f32_e32 v32, v36, v32
	v_exp_f32_e32 v40, v40
	v_add_f32_e32 v32, v37, v32
	v_add_f32_e32 v32, v38, v32
	v_sub_f32_e32 v61, v73, v81
	v_add_f32_e32 v32, v39, v32
	v_add_f32_e32 v41, v40, v32
	v_exp_f32_e32 v32, v61
	v_mov_b32_e32 v42, v41
	v_mov_b32_e32 v43, v41
	s_nop 1
	v_permlane32_swap_b32_e32 v42, v43
	v_cmp_neq_f32_e32 vcc, v81, v73
	s_cbranch_vccz .LBB0_610
	v_pk_mul_f32 v[30:31], v[30:31], v[32:33] op_sel_hi:[1,0]
	v_pk_mul_f32 v[28:29], v[28:29], v[32:33] op_sel_hi:[1,0]
	v_pk_mul_f32 v[26:27], v[26:27], v[32:33] op_sel_hi:[1,0]
	v_pk_mul_f32 v[24:25], v[24:25], v[32:33] op_sel_hi:[1,0]
	v_pk_mul_f32 v[22:23], v[22:23], v[32:33] op_sel_hi:[1,0]
	v_pk_mul_f32 v[20:21], v[20:21], v[32:33] op_sel_hi:[1,0]
	v_pk_mul_f32 v[18:19], v[18:19], v[32:33] op_sel_hi:[1,0]
	v_pk_mul_f32 v[16:17], v[16:17], v[32:33] op_sel_hi:[1,0]
	v_pk_mul_f32 v[14:15], v[14:15], v[32:33] op_sel_hi:[1,0]
	v_pk_mul_f32 v[12:13], v[12:13], v[32:33] op_sel_hi:[1,0]
	v_pk_mul_f32 v[10:11], v[10:11], v[32:33] op_sel_hi:[1,0]
	v_pk_mul_f32 v[8:9], v[8:9], v[32:33] op_sel_hi:[1,0]
	v_pk_mul_f32 v[6:7], v[6:7], v[32:33] op_sel_hi:[1,0]
	v_pk_mul_f32 v[4:5], v[4:5], v[32:33] op_sel_hi:[1,0]
	v_pk_mul_f32 v[2:3], v[2:3], v[32:33] op_sel_hi:[1,0]
	v_pk_mul_f32 v[0:1], v[0:1], v[32:33] op_sel_hi:[1,0]

; #define LAS __attribute__((address_space(3)))
; DI float ex2(float x) { return __builtin_amdgcn_exp2f(x); }
; template <int MM> DI void smax_step_nb(const f32x16& s, unsigned vm, float& m, float& l, f32x16 (&o)[2], bf16x8 (&pf)[2], int lane) {
;     float mx = -1e30f;
; #pragma unroll
;     for (int i = 0; i < 16; ++i) mx = fmaxf(mx, s[i]);
;     if (MM == 1) mx = vm ? mx : -1e30f;
;     mx = fmaxf(mx, shx32(mx, lane));
;     const float mn = (mx > m + 8.0f) ? mx : m;
;     float mref = fmaxf(mn, -1e29f);
;     if (MM == 1) mref = vm ? mref : 3e38f;
;     const float alpha = ex2(m - mn);
;     float p[16], rs = 0.f;
; #pragma unroll
;     for (int i = 0; i < 16; ++i) { p[i] = ex2(s[i] - mref); rs += p[i]; }
;     rs += shx32(rs, lane);
;     l = l * alpha + rs;
;     if (__builtin_amdgcn_ballot_w64(mn != m) != 0ull) {
; #pragma unroll
;         for (int i = 0; i < 16; ++i) { o[0][i] *= alpha; o[1][i] *= alpha; }
;     }
;     m = mn;
;     pack_p(p, pf);
; }
; template <int MM> DI void tile64_pipe(LAS const char* Kl, LAS const char* Vl, const bf16x8 (&qf)[4], unsigned vm, float& m, float& l, f32x16 (&o)[2], int r, int h, int lane) {
;     const f32x16 sa = qk_rows<0, 4>(Kl, 0, qf, r, h), sb = qk_rows<0, 4>(Kl, 32, qf, r, h);
;     bf16x8 pfa[2], pfb[2];
;     smax_step_nb<MM>(sa, vm, m, l, o, pfa, lane);
;     pv_rows(o, Vl, 0, pfa, lane);
;     smax_step_nb<MM>(sb, vm, m, l, o, pfb, lane);
;     pv_rows(o, Vl, 32, pfb, lane);
; }
.LBB0_623:
	s_mov_b64 s[38:39], 0
	s_andn2_b64 vcc, exec, s[48:49]
	v_add3_u32 v83, s11, v190, v168
	v_mov_b32_e32 v65, v213
	v_mov_b32_e32 v82, v214
	s_cbranch_vccnz .LBB0_629
	ds_read_b128 v[32:35], v83
	ds_read_b128 v[48:51], v83 offset:32
	ds_read_b128 v[52:55], v83 offset:64
	ds_read_b128 v[56:59], v83 offset:96
	s_setprio 1
	s_waitcnt lgkmcnt(3)
	v_mfma_f32_32x32x16_bf16 v[32:47], v[32:35], v[96:99], 0
	s_waitcnt lgkmcnt(2)
	v_mfma_f32_32x32x16_bf16 v[32:47], v[48:51], v[100:103], v[32:47]
	s_waitcnt lgkmcnt(1)
	v_mfma_f32_32x32x16_bf16 v[32:47], v[52:55], v[104:107], v[32:47]
	s_waitcnt lgkmcnt(0)
	v_mfma_f32_32x32x16_bf16 v[32:47], v[56:59], v[108:111], v[32:47]
	s_setprio 0
	ds_read_b128 v[48:51], v83 offset:4608
	ds_read_b128 v[52:55], v83 offset:4640
	ds_read_b128 v[56:59], v83 offset:4672
	ds_read_b128 v[60:63], v83 offset:4704
	s_setprio 1
	s_waitcnt lgkmcnt(3)
	v_mfma_f32_32x32x16_bf16 v[64:79], v[48:51], v[96:99], 0
	s_waitcnt lgkmcnt(2)
	v_mfma_f32_32x32x16_bf16 v[64:79], v[52:55], v[100:103], v[64:79]
	s_waitcnt lgkmcnt(1)
	v_mfma_f32_32x32x16_bf16 v[64:79], v[56:59], v[104:107], v[64:79]
	s_waitcnt lgkmcnt(0)
	v_mfma_f32_32x32x16_bf16 v[64:79], v[60:63], v[108:111], v[64:79]
	s_setprio 0
	v_max3_f32 v48, v32, s15, v33
	v_max3_f32 v48, v48, v34, v35
	v_max3_f32 v48, v48, v36, v37
	v_max3_f32 v48, v48, v38, v39
	v_max3_f32 v48, v48, v40, v41
	v_max3_f32 v48, v48, v42, v43
	v_max3_f32 v48, v48, v44, v45
	v_max3_f32 v48, v48, v46, v47
	v_cndmask_b32_e64 v48, v208, v48, s[0:1]
	v_mov_b32_e32 v49, v48
	v_mov_b32_e32 v50, v48
	s_nop 1
	v_permlane32_swap_b32_e32 v49, v50
	v_max_f32_e32 v48, v49, v50
	v_add_f32_e32 v49, 0x41000000, v214
	v_cmp_gt_f32_e32 vcc, v48, v49
	s_nop 1
	v_cndmask_b32_e32 v88, v214, v48, vcc
	v_max_f32_e32 v48, 0xefa18f08, v88
	v_cndmask_b32_e64 v48, v209, v48, s[0:1]
	v_sub_f32_e32 v32, v32, v48
	v_exp_f32_e32 v82, v32
	v_sub_f32_e32 v32, v33, v48
	v_exp_f32_e32 v87, v32
	v_sub_f32_e32 v32, v34, v48
	v_exp_f32_e32 v89, v32
	v_sub_f32_e32 v32, v35, v48
	v_exp_f32_e32 v90, v32
	v_sub_f32_e32 v33, v36, v48
	v_exp_f32_e32 v91, v33
	v_sub_f32_e32 v33, v37, v48
	v_add_f32_e32 v32, v87, v82
	v_exp_f32_e32 v92, v33
	v_sub_f32_e32 v33, v38, v48
	v_add_f32_e32 v32, v89, v32
	v_exp_f32_e32 v93, v33
	v_sub_f32_e32 v33, v39, v48
	v_add_f32_e32 v32, v90, v32
	v_exp_f32_e32 v94, v33
	v_sub_f32_e32 v33, v40, v48
	v_add_f32_e32 v32, v91, v32
	v_exp_f32_e32 v95, v33
	v_sub_f32_e32 v33, v41, v48
	v_add_f32_e32 v32, v92, v32
	v_exp_f32_e32 v128, v33
	v_sub_f32_e32 v33, v42, v48
	v_add_f32_e32 v32, v93, v32
	v_exp_f32_e32 v129, v33
	v_sub_f32_e32 v33, v43, v48
	v_add_f32_e32 v32, v94, v32
	v_exp_f32_e32 v130, v33
	v_sub_f32_e32 v33, v44, v48
	v_add_f32_e32 v32, v95, v32
	v_exp_f32_e32 v131, v33
	v_sub_f32_e32 v33, v45, v48
	v_add_f32_e32 v32, v128, v32
	v_exp_f32_e32 v132, v33
	v_sub_f32_e32 v33, v46, v48
	v_add_f32_e32 v32, v129, v32
	v_exp_f32_e32 v133, v33
	v_sub_f32_e32 v33, v47, v48
	v_add_f32_e32 v32, v130, v32
	v_exp_f32_e32 v134, v33
	v_add_f32_e32 v32, v131, v32
	v_sub_f32_e32 v49, v214, v88
	v_add_f32_e32 v32, v132, v32
	v_add_f32_e32 v32, v133, v32
	v_exp_f32_e32 v80, v49
	v_add_f32_e32 v84, v134, v32
	v_mov_b32_e32 v85, v84
	v_mov_b32_e32 v86, v84
	v_mov_b64_e32 v[62:63], v[30:31]
	s_nop 0
	v_permlane32_swap_b32_e32 v85, v86
	v_cmp_neq_f32_e32 vcc, v88, v214
	v_mov_b64_e32 v[60:61], v[28:29]
	v_mov_b64_e32 v[58:59], v[26:27]
	v_mov_b64_e32 v[56:57], v[24:25]
	v_mov_b64_e32 v[54:55], v[22:23]
	v_mov_b64_e32 v[52:53], v[20:21]
	v_mov_b64_e32 v[50:51], v[18:19]
	v_mov_b64_e32 v[48:49], v[16:17]
	v_mov_b64_e32 v[46:47], v[14:15]
	v_mov_b64_e32 v[44:45], v[12:13]
	v_mov_b64_e32 v[42:43], v[10:11]
	v_mov_b64_e32 v[40:41], v[8:9]
	v_mov_b64_e32 v[38:39], v[6:7]
	v_mov_b64_e32 v[36:37], v[4:5]
	v_mov_b64_e32 v[34:35], v[2:3]
	v_mov_b64_e32 v[32:33], v[0:1]
	s_cbranch_vccz .LBB0_626
	v_pk_mul_f32 v[62:63], v[30:31], v[80:81] op_sel_hi:[1,0]
	v_pk_mul_f32 v[60:61], v[28:29], v[80:81] op_sel_hi:[1,0]
	v_pk_mul_f32 v[58:59], v[26:27], v[80:81] op_sel_hi:[1,0]
	v_pk_mul_f32 v[56:57], v[24:25], v[80:81] op_sel_hi:[1,0]
	v_pk_mul_f32 v[54:55], v[22:23], v[80:81] op_sel_hi:[1,0]
	v_pk_mul_f32 v[52:53], v[20:21], v[80:81] op_sel_hi:[1,0]
	v_pk_mul_f32 v[50:51], v[18:19], v[80:81] op_sel_hi:[1,0]
	v_pk_mul_f32 v[48:49], v[16:17], v[80:81] op_sel_hi:[1,0]
	v_pk_mul_f32 v[46:47], v[14:15], v[80:81] op_sel_hi:[1,0]
	v_pk_mul_f32 v[44:45], v[12:13], v[80:81] op_sel_hi:[1,0]
	v_pk_mul_f32 v[42:43], v[10:11], v[80:81] op_sel_hi:[1,0]
	v_pk_mul_f32 v[40:41], v[8:9], v[80:81] op_sel_hi:[1,0]
	v_pk_mul_f32 v[38:39], v[6:7], v[80:81] op_sel_hi:[1,0]
	v_pk_mul_f32 v[36:37], v[4:5], v[80:81] op_sel_hi:[1,0]
	v_pk_mul_f32 v[34:35], v[2:3], v[80:81] op_sel_hi:[1,0]
	v_pk_mul_f32 v[32:33], v[0:1], v[80:81] op_sel_hi:[1,0]
; #define LAS __attribute__((address_space(3)))
; DI float ex2(float x) { return __builtin_amdgcn_exp2f(x); }
; template <int MM> DI void smax_step_nb(const f32x16& s, unsigned vm, float& m, float& l, f32x16 (&o)[2], bf16x8 (&pf)[2], int lane) {
;     float mx = -1e30f;
; #pragma unroll
;     for (int i = 0; i < 16; ++i) mx = fmaxf(mx, s[i]);
;     if (MM == 1) mx = vm ? mx : -1e30f;
;     mx = fmaxf(mx, shx32(mx, lane));
;     const float mn = (mx > m + 8.0f) ? mx : m;
;     float mref = fmaxf(mn, -1e29f);
;     if (MM == 1) mref = vm ? mref : 3e38f;
;     const float alpha = ex2(m - mn);
;     float p[16], rs = 0.f;
; #pragma unroll
;     for (int i = 0; i < 16; ++i) { p[i] = ex2(s[i] - mref); rs += p[i]; }
;     rs += shx32(rs, lane);
;     l = l * alpha + rs;
;     if (__builtin_amdgcn_ballot_w64(mn != m) != 0ull) {
; #pragma unroll
;         for (int i = 0; i < 16; ++i) { o[0][i] *= alpha; o[1][i] *= alpha; }
;     }
;     m = mn;
;     pack_p(p, pf);
; }
; template <int MM> DI void tile64_pipe(LAS const char* Kl, LAS const char* Vl, const bf16x8 (&qf)[4], unsigned vm, float& m, float& l, f32x16 (&o)[2], int r, int h, int lane) {
;     const f32x16 sa = qk_rows<0, 4>(Kl, 0, qf, r, h), sb = qk_rows<0, 4>(Kl, 32, qf, r, h);
;     bf16x8 pfa[2], pfb[2];
;     smax_step_nb<MM>(sa, vm, m, l, o, pfa, lane);
;     pv_rows(o, Vl, 0, pfa, lane);
;     smax_step_nb<MM>(sb, vm, m, l, o, pfb, lane);
;     pv_rows(o, Vl, 32, pfb, lane);
; }
.LBB0_626:
	v_cvt_pk_bf16_f32 v136, v82, v87
	v_add3_u32 v82, s11, v191, v171
	v_add_u32_e32 v87, v82, v186
	v_cvt_pk_bf16_f32 v137, v89, v90
	v_cvt_pk_bf16_f32 v138, v91, v92
	v_cvt_pk_bf16_f32 v139, v93, v94
	v_cvt_pk_bf16_f32 v90, v95, v128
	v_cvt_pk_bf16_f32 v91, v129, v130
	v_cvt_pk_bf16_f32 v92, v131, v132
	v_cvt_pk_bf16_f32 v93, v133, v134
	ds_read_b64_tr_b16 v[128:129], v87 offset:9216
	ds_read_b64_tr_b16 v[130:131], v87 offset:10368
	ds_read_b64_tr_b16 v[132:133], v87 offset:11520
	ds_read_b64_tr_b16 v[134:135], v87 offset:12672
	ds_read_b64_tr_b16 v[140:141], v87 offset:9280
	ds_read_b64_tr_b16 v[142:143], v87 offset:10432
	ds_read_b64_tr_b16 v[144:145], v87 offset:11584
	ds_read_b64_tr_b16 v[146:147], v87 offset:12736
	s_setprio 1
	s_waitcnt lgkmcnt(6)
	v_mfma_f32_32x32x16_bf16 v[32:47], v[128:131], v[136:139], v[32:47]
	s_waitcnt lgkmcnt(2)
	v_mfma_f32_32x32x16_bf16 v[48:63], v[140:143], v[136:139], v[48:63]
	v_mfma_f32_32x32x16_bf16 v[32:47], v[132:135], v[90:93], v[32:47]
	s_waitcnt lgkmcnt(0)
	v_mfma_f32_32x32x16_bf16 v[48:63], v[144:147], v[90:93], v[48:63]
	s_setprio 0
	v_max3_f32 v82, v64, s15, v65
	v_max3_f32 v82, v82, v66, v67
	v_max3_f32 v82, v82, v68, v69
	v_max3_f32 v82, v82, v70, v71
	v_max3_f32 v82, v82, v72, v73
	v_max3_f32 v82, v82, v74, v75
	v_max3_f32 v82, v82, v76, v77
	v_max3_f32 v82, v82, v78, v79
	v_cndmask_b32_e64 v82, v208, v82, s[0:1]
	v_mov_b32_e32 v89, v82
	v_mov_b32_e32 v90, v82
	s_nop 1
	v_permlane32_swap_b32_e32 v89, v90
	v_max_f32_e32 v82, v89, v90
	v_add_f32_e32 v89, 0x41000000, v88
	v_cmp_gt_f32_e32 vcc, v82, v89
	s_nop 1
	v_cndmask_b32_e32 v82, v88, v82, vcc
	v_max_f32_e32 v89, 0xefa18f08, v82
	v_cndmask_b32_e64 v91, v209, v89, s[0:1]
	v_sub_f32_e32 v64, v64, v91
	v_exp_f32_e32 v89, v64
	v_sub_f32_e32 v64, v65, v91
	v_exp_f32_e32 v90, v64
	v_sub_f32_e32 v64, v66, v91
	v_exp_f32_e32 v66, v64
	v_sub_f32_e32 v64, v67, v91
	v_exp_f32_e32 v67, v64
	v_sub_f32_e32 v65, v68, v91
	v_exp_f32_e32 v68, v65
	v_sub_f32_e32 v65, v69, v91
	v_add_f32_e32 v64, v90, v89
	v_exp_f32_e32 v69, v65
	v_sub_f32_e32 v65, v70, v91
	v_add_f32_e32 v64, v66, v64
	v_exp_f32_e32 v70, v65
	v_sub_f32_e32 v65, v71, v91
	v_add_f32_e32 v64, v67, v64
	v_exp_f32_e32 v71, v65
	v_sub_f32_e32 v65, v72, v91
	v_add_f32_e32 v64, v68, v64
	v_exp_f32_e32 v72, v65
	v_sub_f32_e32 v65, v73, v91
	v_add_f32_e32 v64, v69, v64
	v_exp_f32_e32 v73, v65
	v_sub_f32_e32 v65, v74, v91
	v_add_f32_e32 v64, v70, v64
	v_exp_f32_e32 v74, v65
	v_sub_f32_e32 v65, v75, v91
	v_add_f32_e32 v64, v71, v64
	v_exp_f32_e32 v75, v65
	v_sub_f32_e32 v65, v76, v91
	v_add_f32_e32 v64, v72, v64
	v_exp_f32_e32 v76, v65
	v_sub_f32_e32 v65, v77, v91
	v_add_f32_e32 v64, v73, v64
	v_exp_f32_e32 v77, v65
	v_sub_f32_e32 v65, v78, v91
	v_add_f32_e32 v64, v74, v64
	v_exp_f32_e32 v78, v65
	v_sub_f32_e32 v65, v79, v91
	v_add_f32_e32 v64, v75, v64
	v_exp_f32_e32 v79, v65
	v_add_f32_e32 v64, v76, v64
	v_add_f32_e32 v64, v77, v64
	v_sub_f32_e32 v92, v88, v82
	v_add_f32_e32 v64, v78, v64
	v_add_f32_e32 v65, v79, v64
	v_exp_f32_e32 v64, v92
	v_mov_b32_e32 v91, v65
	v_mov_b32_e32 v92, v65
	s_nop 1
	v_permlane32_swap_b32_e32 v91, v92
	v_cmp_neq_f32_e32 vcc, v82, v88
	s_cbranch_vccz .LBB0_628
	v_pk_mul_f32 v[62:63], v[62:63], v[64:65] op_sel_hi:[1,0]
	v_pk_mul_f32 v[60:61], v[60:61], v[64:65] op_sel_hi:[1,0]
	v_pk_mul_f32 v[58:59], v[58:59], v[64:65] op_sel_hi:[1,0]
	v_pk_mul_f32 v[56:57], v[56:57], v[64:65] op_sel_hi:[1,0]
	v_pk_mul_f32 v[54:55], v[54:55], v[64:65] op_sel_hi:[1,0]
	v_pk_mul_f32 v[52:53], v[52:53], v[64:65] op_sel_hi:[1,0]
	v_pk_mul_f32 v[50:51], v[50:51], v[64:65] op_sel_hi:[1,0]
	v_pk_mul_f32 v[48:49], v[48:49], v[64:65] op_sel_hi:[1,0]
	v_pk_mul_f32 v[46:47], v[46:47], v[64:65] op_sel_hi:[1,0]
	v_pk_mul_f32 v[44:45], v[44:45], v[64:65] op_sel_hi:[1,0]
	v_pk_mul_f32 v[42:43], v[42:43], v[64:65] op_sel_hi:[1,0]
	v_pk_mul_f32 v[40:41], v[40:41], v[64:65] op_sel_hi:[1,0]
	v_pk_mul_f32 v[38:39], v[38:39], v[64:65] op_sel_hi:[1,0]
	v_pk_mul_f32 v[36:37], v[36:37], v[64:65] op_sel_hi:[1,0]
	v_pk_mul_f32 v[34:35], v[34:35], v[64:65] op_sel_hi:[1,0]
	v_pk_mul_f32 v[32:33], v[32:33], v[64:65] op_sel_hi:[1,0]

; #define LAS __attribute__((address_space(3)))
; DI float ex2(float x) { return __builtin_amdgcn_exp2f(x); }
; template <int MM> DI void smax_step_nb(const f32x16& s, unsigned vm, float& m, float& l, f32x16 (&o)[2], bf16x8 (&pf)[2], int lane) {
;     float mx = -1e30f;
; #pragma unroll
;     for (int i = 0; i < 16; ++i) mx = fmaxf(mx, s[i]);
;     if (MM == 1) mx = vm ? mx : -1e30f;
;     mx = fmaxf(mx, shx32(mx, lane));
;     const float mn = (mx > m + 8.0f) ? mx : m;
;     float mref = fmaxf(mn, -1e29f);
;     if (MM == 1) mref = vm ? mref : 3e38f;
;     const float alpha = ex2(m - mn);
;     float p[16], rs = 0.f;
; #pragma unroll
;     for (int i = 0; i < 16; ++i) { p[i] = ex2(s[i] - mref); rs += p[i]; }
;     rs += shx32(rs, lane);
;     l = l * alpha + rs;
;     if (__builtin_amdgcn_ballot_w64(mn != m) != 0ull) {
; #pragma unroll
;         for (int i = 0; i < 16; ++i) { o[0][i] *= alpha; o[1][i] *= alpha; }
;     }
;     m = mn;
;     pack_p(p, pf);
; }
; template <int MM> DI void tile64_pipe(LAS const char* Kl, LAS const char* Vl, const bf16x8 (&qf)[4], unsigned vm, float& m, float& l, f32x16 (&o)[2], int r, int h, int lane) {
;     const f32x16 sa = qk_rows<0, 4>(Kl, 0, qf, r, h), sb = qk_rows<0, 4>(Kl, 32, qf, r, h);
;     bf16x8 pfa[2], pfb[2];
;     smax_step_nb<MM>(sa, vm, m, l, o, pfa, lane);
;     pv_rows(o, Vl, 0, pfa, lane);
;     smax_step_nb<MM>(sb, vm, m, l, o, pfb, lane);
;     pv_rows(o, Vl, 32, pfb, lane);
; }
.LBB0_629:
	s_and_b64 vcc, exec, s[42:43]
	s_cbranch_vccz .LBB0_635
	s_nop 7
	ds_read_b128 v[32:35], v83
	s_nop 0
	ds_read_b128 v[48:51], v83 offset:32
	ds_read_b128 v[52:55], v83 offset:64
	ds_read_b128 v[56:59], v83 offset:96
	s_setprio 1
	s_waitcnt lgkmcnt(3)
	v_mfma_f32_32x32x16_bf16 v[32:47], v[32:35], v[96:99], 0
	s_waitcnt lgkmcnt(2)
	v_mfma_f32_32x32x16_bf16 v[32:47], v[48:51], v[100:103], v[32:47]
	s_waitcnt lgkmcnt(1)
	v_mfma_f32_32x32x16_bf16 v[32:47], v[52:55], v[104:107], v[32:47]
	s_waitcnt lgkmcnt(0)
	v_mfma_f32_32x32x16_bf16 v[32:47], v[56:59], v[108:111], v[32:47]
	s_setprio 0
	ds_read_b128 v[48:51], v83 offset:4608
	ds_read_b128 v[52:55], v83 offset:4640
	ds_read_b128 v[56:59], v83 offset:4672
	ds_read_b128 v[60:63], v83 offset:4704
	s_setprio 1
	s_waitcnt lgkmcnt(3)
	v_mfma_f32_32x32x16_bf16 v[64:79], v[48:51], v[96:99], 0
	s_waitcnt lgkmcnt(2)
	v_mfma_f32_32x32x16_bf16 v[64:79], v[52:55], v[100:103], v[64:79]
	s_waitcnt lgkmcnt(1)
	v_mfma_f32_32x32x16_bf16 v[64:79], v[56:59], v[104:107], v[64:79]
	s_waitcnt lgkmcnt(0)
	v_mfma_f32_32x32x16_bf16 v[64:79], v[60:63], v[108:111], v[64:79]
	s_setprio 0
	v_max3_f32 v48, v32, s15, v33
	v_max3_f32 v48, v48, v34, v35
	v_max3_f32 v48, v48, v36, v37
	v_max3_f32 v48, v48, v38, v39
	v_max3_f32 v48, v48, v40, v41
	v_max3_f32 v48, v48, v42, v43
	v_max3_f32 v48, v48, v44, v45
	v_max3_f32 v48, v48, v46, v47
	v_mov_b32_e32 v49, v48
	v_mov_b32_e32 v50, v48
	s_nop 1
	v_permlane32_swap_b32_e32 v49, v50
	v_max_f32_e32 v48, v49, v50
	v_add_f32_e32 v49, 0x41000000, v214
	v_cmp_gt_f32_e32 vcc, v48, v49
	s_nop 1
	v_cndmask_b32_e32 v87, v214, v48, vcc
	v_max_f32_e32 v48, 0xefa18f08, v87
	v_sub_f32_e32 v32, v32, v48
	v_exp_f32_e32 v82, v32
	v_sub_f32_e32 v32, v33, v48
	v_exp_f32_e32 v86, v32
	v_sub_f32_e32 v32, v34, v48
	v_exp_f32_e32 v88, v32
	v_sub_f32_e32 v32, v35, v48
	v_exp_f32_e32 v89, v32
	v_sub_f32_e32 v33, v36, v48
	v_exp_f32_e32 v90, v33
	v_sub_f32_e32 v33, v37, v48
	v_add_f32_e32 v32, v86, v82
	v_exp_f32_e32 v91, v33
	v_sub_f32_e32 v33, v38, v48
	v_add_f32_e32 v32, v88, v32
	v_exp_f32_e32 v92, v33
	v_sub_f32_e32 v33, v39, v48
	v_add_f32_e32 v32, v89, v32
	v_exp_f32_e32 v93, v33
	v_sub_f32_e32 v33, v40, v48
	v_add_f32_e32 v32, v90, v32
	v_exp_f32_e32 v94, v33
	v_sub_f32_e32 v33, v41, v48
	v_add_f32_e32 v32, v91, v32
	v_exp_f32_e32 v95, v33
	v_sub_f32_e32 v33, v42, v48
	v_add_f32_e32 v32, v92, v32
	v_exp_f32_e32 v128, v33
	v_sub_f32_e32 v33, v43, v48
	v_add_f32_e32 v32, v93, v32
	v_exp_f32_e32 v129, v33
	v_sub_f32_e32 v33, v44, v48
	v_add_f32_e32 v32, v94, v32
	v_exp_f32_e32 v130, v33
	v_sub_f32_e32 v33, v45, v48
	v_add_f32_e32 v32, v95, v32
	v_exp_f32_e32 v131, v33
	v_sub_f32_e32 v33, v46, v48
	v_add_f32_e32 v32, v128, v32
	v_exp_f32_e32 v132, v33
	v_sub_f32_e32 v33, v47, v48
	v_add_f32_e32 v32, v129, v32
	v_exp_f32_e32 v133, v33
	v_add_f32_e32 v32, v130, v32
	v_sub_f32_e32 v49, v214, v87
	v_add_f32_e32 v32, v131, v32
	v_add_f32_e32 v32, v132, v32
	v_exp_f32_e32 v80, v49
	v_add_f32_e32 v83, v133, v32
	v_mov_b32_e32 v84, v83
	v_mov_b32_e32 v85, v83
	v_mov_b64_e32 v[62:63], v[30:31]
	s_nop 0
	v_permlane32_swap_b32_e32 v84, v85
	v_cmp_neq_f32_e32 vcc, v87, v214
	v_mov_b64_e32 v[60:61], v[28:29]
	v_mov_b64_e32 v[58:59], v[26:27]
	v_mov_b64_e32 v[56:57], v[24:25]
	v_mov_b64_e32 v[54:55], v[22:23]
	v_mov_b64_e32 v[52:53], v[20:21]
	v_mov_b64_e32 v[50:51], v[18:19]
	v_mov_b64_e32 v[48:49], v[16:17]
	v_mov_b64_e32 v[46:47], v[14:15]
	v_mov_b64_e32 v[44:45], v[12:13]
	v_mov_b64_e32 v[42:43], v[10:11]
	v_mov_b64_e32 v[40:41], v[8:9]
	v_mov_b64_e32 v[38:39], v[6:7]
	v_mov_b64_e32 v[36:37], v[4:5]
	v_mov_b64_e32 v[34:35], v[2:3]
	v_mov_b64_e32 v[32:33], v[0:1]
	s_cbranch_vccz .LBB0_632
	v_pk_mul_f32 v[62:63], v[30:31], v[80:81] op_sel_hi:[1,0]
	v_pk_mul_f32 v[60:61], v[28:29], v[80:81] op_sel_hi:[1,0]
	v_pk_mul_f32 v[58:59], v[26:27], v[80:81] op_sel_hi:[1,0]
	v_pk_mul_f32 v[56:57], v[24:25], v[80:81] op_sel_hi:[1,0]
	v_pk_mul_f32 v[54:55], v[22:23], v[80:81] op_sel_hi:[1,0]
	v_pk_mul_f32 v[52:53], v[20:21], v[80:81] op_sel_hi:[1,0]
	v_pk_mul_f32 v[50:51], v[18:19], v[80:81] op_sel_hi:[1,0]
	v_pk_mul_f32 v[48:49], v[16:17], v[80:81] op_sel_hi:[1,0]
	v_pk_mul_f32 v[46:47], v[14:15], v[80:81] op_sel_hi:[1,0]
	v_pk_mul_f32 v[44:45], v[12:13], v[80:81] op_sel_hi:[1,0]
	v_pk_mul_f32 v[42:43], v[10:11], v[80:81] op_sel_hi:[1,0]
	v_pk_mul_f32 v[40:41], v[8:9], v[80:81] op_sel_hi:[1,0]
	v_pk_mul_f32 v[38:39], v[6:7], v[80:81] op_sel_hi:[1,0]
	v_pk_mul_f32 v[36:37], v[4:5], v[80:81] op_sel_hi:[1,0]
	v_pk_mul_f32 v[34:35], v[2:3], v[80:81] op_sel_hi:[1,0]
	v_pk_mul_f32 v[32:33], v[0:1], v[80:81] op_sel_hi:[1,0]
; #define LAS __attribute__((address_space(3)))
; DI float ex2(float x) { return __builtin_amdgcn_exp2f(x); }
; template <int MM> DI void smax_step_nb(const f32x16& s, unsigned vm, float& m, float& l, f32x16 (&o)[2], bf16x8 (&pf)[2], int lane) {
;     float mx = -1e30f;
; #pragma unroll
;     for (int i = 0; i < 16; ++i) mx = fmaxf(mx, s[i]);
;     if (MM == 1) mx = vm ? mx : -1e30f;
;     mx = fmaxf(mx, shx32(mx, lane));
;     const float mn = (mx > m + 8.0f) ? mx : m;
;     float mref = fmaxf(mn, -1e29f);
;     if (MM == 1) mref = vm ? mref : 3e38f;
;     const float alpha = ex2(m - mn);
;     float p[16], rs = 0.f;
; #pragma unroll
;     for (int i = 0; i < 16; ++i) { p[i] = ex2(s[i] - mref); rs += p[i]; }
;     rs += shx32(rs, lane);
;     l = l * alpha + rs;
;     if (__builtin_amdgcn_ballot_w64(mn != m) != 0ull) {
; #pragma unroll
;         for (int i = 0; i < 16; ++i) { o[0][i] *= alpha; o[1][i] *= alpha; }
;     }
;     m = mn;
;     pack_p(p, pf);
; }
; template <int MM> DI void tile64_pipe(LAS const char* Kl, LAS const char* Vl, const bf16x8 (&qf)[4], unsigned vm, float& m, float& l, f32x16 (&o)[2], int r, int h, int lane) {
;     const f32x16 sa = qk_rows<0, 4>(Kl, 0, qf, r, h), sb = qk_rows<0, 4>(Kl, 32, qf, r, h);
;     bf16x8 pfa[2], pfb[2];
;     smax_step_nb<MM>(sa, vm, m, l, o, pfa, lane);
;     pv_rows(o, Vl, 0, pfa, lane);
;     smax_step_nb<MM>(sb, vm, m, l, o, pfb, lane);
;     pv_rows(o, Vl, 32, pfb, lane);
; }
.LBB0_632:
	v_cvt_pk_bf16_f32 v134, v82, v86
	v_add3_u32 v82, s11, v191, v171
	v_add_u32_e32 v86, v82, v186
	v_cvt_pk_bf16_f32 v135, v88, v89
	v_cvt_pk_bf16_f32 v136, v90, v91
	v_cvt_pk_bf16_f32 v137, v92, v93
	v_cvt_pk_bf16_f32 v88, v94, v95
	v_cvt_pk_bf16_f32 v89, v128, v129
	v_cvt_pk_bf16_f32 v90, v130, v131
	ds_read_b64_tr_b16 v[92:93], v86 offset:9216
	ds_read_b64_tr_b16 v[94:95], v86 offset:10368
	ds_read_b64_tr_b16 v[128:129], v86 offset:11520
	ds_read_b64_tr_b16 v[130:131], v86 offset:12672
	ds_read_b64_tr_b16 v[138:139], v86 offset:9280
	ds_read_b64_tr_b16 v[140:141], v86 offset:10432
	ds_read_b64_tr_b16 v[142:143], v86 offset:11584
	ds_read_b64_tr_b16 v[144:145], v86 offset:12736
	v_cvt_pk_bf16_f32 v91, v132, v133
	s_setprio 1
	s_waitcnt lgkmcnt(6)
	v_mfma_f32_32x32x16_bf16 v[32:47], v[92:95], v[134:137], v[32:47]
	s_waitcnt lgkmcnt(2)
	v_mfma_f32_32x32x16_bf16 v[48:63], v[138:141], v[134:137], v[48:63]
	v_mfma_f32_32x32x16_bf16 v[32:47], v[128:131], v[88:91], v[32:47]
	s_waitcnt lgkmcnt(0)
	v_mfma_f32_32x32x16_bf16 v[48:63], v[142:145], v[88:91], v[48:63]
	s_setprio 0
	v_max3_f32 v82, v64, s15, v65
	v_max3_f32 v82, v82, v66, v67
	v_max3_f32 v82, v82, v68, v69
	v_max3_f32 v82, v82, v70, v71
	v_max3_f32 v82, v82, v72, v73
	v_max3_f32 v82, v82, v74, v75
	v_max3_f32 v82, v82, v76, v77
	v_max3_f32 v82, v82, v78, v79
	v_mov_b32_e32 v88, v82
	v_mov_b32_e32 v89, v82
	s_nop 1
	v_permlane32_swap_b32_e32 v88, v89
	v_max_f32_e32 v82, v88, v89
	v_add_f32_e32 v88, 0x41000000, v87
	v_cmp_gt_f32_e32 vcc, v82, v88
	s_nop 1
	v_cndmask_b32_e32 v82, v87, v82, vcc
	v_max_f32_e32 v90, 0xefa18f08, v82
	v_sub_f32_e32 v64, v64, v90
	v_exp_f32_e32 v88, v64
	v_sub_f32_e32 v64, v65, v90
	v_exp_f32_e32 v89, v64
	v_sub_f32_e32 v64, v66, v90
	v_exp_f32_e32 v66, v64
	v_sub_f32_e32 v64, v67, v90
	v_exp_f32_e32 v67, v64
	v_sub_f32_e32 v65, v68, v90
	v_exp_f32_e32 v68, v65
	v_sub_f32_e32 v65, v69, v90
	v_add_f32_e32 v64, v89, v88
	v_exp_f32_e32 v69, v65
	v_sub_f32_e32 v65, v70, v90
	v_add_f32_e32 v64, v66, v64
	v_exp_f32_e32 v70, v65
	v_sub_f32_e32 v65, v71, v90
	v_add_f32_e32 v64, v67, v64
	v_exp_f32_e32 v71, v65
	v_sub_f32_e32 v65, v72, v90
	v_add_f32_e32 v64, v68, v64
	v_exp_f32_e32 v72, v65
	v_sub_f32_e32 v65, v73, v90
	v_add_f32_e32 v64, v69, v64
	v_exp_f32_e32 v73, v65
	v_sub_f32_e32 v65, v74, v90
	v_add_f32_e32 v64, v70, v64
	v_exp_f32_e32 v74, v65
	v_sub_f32_e32 v65, v75, v90
	v_add_f32_e32 v64, v71, v64
	v_exp_f32_e32 v75, v65
	v_sub_f32_e32 v65, v76, v90
	v_add_f32_e32 v64, v72, v64
	v_exp_f32_e32 v76, v65
	v_sub_f32_e32 v65, v77, v90
	v_add_f32_e32 v64, v73, v64
	v_exp_f32_e32 v77, v65
	v_sub_f32_e32 v65, v78, v90
	v_add_f32_e32 v64, v74, v64
	v_exp_f32_e32 v78, v65
	v_sub_f32_e32 v65, v79, v90
	v_add_f32_e32 v64, v75, v64
	v_exp_f32_e32 v79, v65
	v_add_f32_e32 v64, v76, v64
	v_add_f32_e32 v64, v77, v64
	v_sub_f32_e32 v91, v87, v82
	v_add_f32_e32 v64, v78, v64
	v_add_f32_e32 v65, v79, v64
	v_exp_f32_e32 v64, v91
	v_mov_b32_e32 v90, v65
	v_mov_b32_e32 v91, v65
	s_nop 1
	v_permlane32_swap_b32_e32 v90, v91
	v_cmp_neq_f32_e32 vcc, v82, v87
	s_cbranch_vccz .LBB0_634
	v_pk_mul_f32 v[62:63], v[62:63], v[64:65] op_sel_hi:[1,0]
	v_pk_mul_f32 v[60:61], v[60:61], v[64:65] op_sel_hi:[1,0]
	v_pk_mul_f32 v[58:59], v[58:59], v[64:65] op_sel_hi:[1,0]
	v_pk_mul_f32 v[56:57], v[56:57], v[64:65] op_sel_hi:[1,0]
	v_pk_mul_f32 v[54:55], v[54:55], v[64:65] op_sel_hi:[1,0]
	v_pk_mul_f32 v[52:53], v[52:53], v[64:65] op_sel_hi:[1,0]
	v_pk_mul_f32 v[50:51], v[50:51], v[64:65] op_sel_hi:[1,0]
	v_pk_mul_f32 v[48:49], v[48:49], v[64:65] op_sel_hi:[1,0]
	v_pk_mul_f32 v[46:47], v[46:47], v[64:65] op_sel_hi:[1,0]
	v_pk_mul_f32 v[44:45], v[44:45], v[64:65] op_sel_hi:[1,0]
	v_pk_mul_f32 v[42:43], v[42:43], v[64:65] op_sel_hi:[1,0]
	v_pk_mul_f32 v[40:41], v[40:41], v[64:65] op_sel_hi:[1,0]
	v_pk_mul_f32 v[38:39], v[38:39], v[64:65] op_sel_hi:[1,0]
	v_pk_mul_f32 v[36:37], v[36:37], v[64:65] op_sel_hi:[1,0]
	v_pk_mul_f32 v[34:35], v[34:35], v[64:65] op_sel_hi:[1,0]
	v_pk_mul_f32 v[32:33], v[32:33], v[64:65] op_sel_hi:[1,0]

; DI float ex2(float x) { return __builtin_amdgcn_exp2f(x); }
; template <int MM> DI void smax_step(const f32x16& s, unsigned vm, float& m, float& l, f32x16 (&o)[2], bf16x8 (&pf)[2], int lane) {
;     float t[16], mx = -1e30f;
; #pragma unroll
;     for (int i = 0; i < 16; ++i) { t[i] = (MM == 0) ? s[i] : (MM == 1 ? (vm ? s[i] : -1e30f) : (((vm >> i) & 1u) ? s[i] : -1e30f)); mx = fmaxf(mx, t[i]); }
;     mx = fmaxf(mx, shx32(mx, lane));
;     const float mn = (mx > m + 8.0f) ? mx : m;
;     const float mref = fmaxf(mn, -1e29f);
;     float p[16], rs = 0.f;
; #pragma unroll
;     for (int i = 0; i < 16; ++i) { p[i] = ex2(t[i] - mref); rs += p[i]; }
;     rs += shx32(rs, lane);
;     if (__builtin_amdgcn_ballot_w64(mn != m) != 0ull) {
;         const float alpha = ex2(m - mn);
;         l *= alpha;
; #pragma unroll
;         for (int i = 0; i < 16; ++i) { o[0][i] *= alpha; o[1][i] *= alpha; }
;         m = mn;
;     }
;     l += rs;
;     pack_p(p, pf);
; }
; template <int MODE, bool PRE = false> ...
;     ...
;         for (int sub = 0; sub < 2; ++sub) {
;             const int kbase = 64 * kt + 32 * sub;
;             if (kbase > q0w + 31) continue;
;             if (MODE == MODE_NWIN && kbase + 31 <= q0w - 512) continue;
;             bool full = (kbase + 31 <= q0w);
;             if (MODE == MODE_NWIN) full = full && (kbase > q0w + 31 - 512);
;             bool lsel = true;
;             if (MODE == MODE_MOBA) lsel = ((sel >> (kbase >> 8)) & 1ull) != 0ull;
;             if (MODE == MODE_NSEL) lsel = ((sel >> kt) & 1ull) != 0ull;
;             const unsigned long long selb = __builtin_amdgcn_ballot_w64(lsel);
;             if (selb == 0ull) continue;
;             int mm; unsigned vm;
;             if (full) { mm = (selb == ~0ull) ? 0 : 1; vm = lsel ? 1u : 0u; }
;             else { mm = 2; vm = 0;
; #pragma unroll
;                 for (int i = 0; i < 16; ++i) { const int kidx = kbase + (i & 3) + 8 * (i >> 2) + 4 * h; bool ok = kidx <= qpos; if (MODE == MODE_NWIN) ok = ok && (kidx > qpos - 512); vm |= ok ? (1u << i) : 0u; }
;                 if (!lsel) vm = 0;
;                 if (__builtin_amdgcn_ballot_w64(vm != 0) == 0ull) continue; }
;             bf16x8 pf[2];
;             if (MODE == MODE_DIFF) {
;                 const f32x16 s1 = qk_rows<0, 2>(Kl, 32 * sub, qf, r, h), s2 = qk_rows<2, 4>(Kl, 32 * sub, qf, r, h);
;                 bf16x8 pf2[2];
.LBB0_646:
	s_andn2_b64 vcc, exec, s[42:43]
	s_cbranch_vccnz .LBB0_658
	v_add_u32_e32 v36, v48, v190
	ds_read_b128 v[32:35], v36
	ds_read_b128 v[50:53], v36 offset:32
	ds_read_b128 v[54:57], v36 offset:64
	ds_read_b128 v[58:61], v36 offset:96
	s_setprio 1
	s_waitcnt lgkmcnt(3)
	v_mfma_f32_32x32x16_bf16 v[32:47], v[32:35], v[96:99], 0
	s_waitcnt lgkmcnt(2)
	v_mfma_f32_32x32x16_bf16 v[32:47], v[50:53], v[100:103], v[32:47]
	s_waitcnt lgkmcnt(1)
	v_mfma_f32_32x32x16_bf16 v[32:47], v[54:57], v[104:107], v[32:47]
	s_waitcnt lgkmcnt(0)
	v_mfma_f32_32x32x16_bf16 v[32:47], v[58:61], v[108:111], v[32:47]
	s_setprio 0
	v_cmp_gt_i32_e32 vcc, 1, v49
	s_cbranch_vccnz .LBB0_650
	v_cmp_ne_u32_e32 vcc, 1, v49
	s_cbranch_vccz .LBB0_651
	v_and_b32_e32 v49, 1, v70
	v_cmp_eq_u32_e32 vcc, 1, v49
	v_and_b32_e32 v49, 2, v70
	v_and_b32_e32 v52, 4, v70
	s_nop 2
	v_cndmask_b32_e32 v50, v208, v32, vcc
	v_cmp_ne_u32_e32 vcc, 0, v49
	v_and_b32_e32 v53, 8, v70
	v_and_b32_e32 v54, 16, v70
	v_cndmask_b32_e32 v51, v208, v33, vcc
	v_cmp_ne_u32_e32 vcc, 0, v52
	v_and_b32_e32 v55, 32, v70
	v_and_b32_e32 v56, 64, v70
	v_cndmask_b32_e32 v52, v208, v34, vcc
	v_cmp_ne_u32_e32 vcc, 0, v53
	v_and_b32_e32 v57, 0x80, v70
	v_and_b32_e32 v58, 0x100, v70
	v_cndmask_b32_e32 v53, v208, v35, vcc
	v_cmp_ne_u32_e32 vcc, 0, v54
	v_and_b32_e32 v59, 0x200, v70
	v_and_b32_e32 v60, 0x400, v70
	v_cndmask_b32_e32 v54, v208, v36, vcc
	v_cmp_ne_u32_e32 vcc, 0, v55
	v_max3_f32 v49, v50, s15, v51
	v_and_b32_e32 v61, 0x800, v70
	v_cndmask_b32_e32 v55, v208, v37, vcc
	v_cmp_ne_u32_e32 vcc, 0, v56
	v_max3_f32 v49, v49, v52, v53
	v_and_b32_e32 v62, 0x1000, v70
	v_cndmask_b32_e32 v56, v208, v38, vcc
	v_cmp_ne_u32_e32 vcc, 0, v57
	v_max3_f32 v49, v49, v54, v55
	v_and_b32_e32 v63, 0x2000, v70
	v_cndmask_b32_e32 v57, v208, v39, vcc
	v_cmp_ne_u32_e32 vcc, 0, v58
	v_max3_f32 v49, v49, v56, v57
	v_and_b32_e32 v65, 0x4000, v70
	v_cndmask_b32_e32 v58, v208, v40, vcc
	v_cmp_ne_u32_e32 vcc, 0, v59
	v_and_b32_e32 v66, 0x8000, v70
	s_nop 0
	v_cndmask_b32_e32 v59, v208, v41, vcc
	v_cmp_ne_u32_e32 vcc, 0, v60
	v_max3_f32 v49, v49, v58, v59
	s_nop 0
	v_cndmask_b32_e32 v60, v208, v42, vcc
	v_cmp_ne_u32_e32 vcc, 0, v61
	s_nop 1
	v_cndmask_b32_e32 v61, v208, v43, vcc
	v_cmp_ne_u32_e32 vcc, 0, v62
	v_max3_f32 v49, v49, v60, v61
	s_nop 0
	v_cndmask_b32_e32 v62, v208, v44, vcc
	v_cmp_ne_u32_e32 vcc, 0, v63
	s_nop 1
	v_cndmask_b32_e32 v63, v208, v45, vcc
	v_cmp_ne_u32_e32 vcc, 0, v65
	v_max3_f32 v49, v49, v62, v63
	s_nop 0
	v_cndmask_b32_e32 v65, v208, v46, vcc
	v_cmp_ne_u32_e32 vcc, 0, v66
	s_nop 1
	v_cndmask_b32_e32 v66, v208, v47, vcc
	v_max3_f32 v49, v49, v65, v66
	v_mov_b32_e32 v67, v49
	v_mov_b32_e32 v68, v49
	s_nop 1
	v_permlane32_swap_b32_e32 v67, v68
	v_max_f32_e32 v49, v67, v68
	v_add_f32_e32 v67, 0x41000000, v214
	v_cmp_gt_f32_e32 vcc, v49, v67
	s_nop 1
	v_cndmask_b32_e32 v49, v214, v49, vcc
	v_max_f32_e32 v67, 0xefa18f08, v49
	v_sub_f32_e32 v50, v50, v67
	v_exp_f32_e32 v50, v50
	v_sub_f32_e32 v51, v51, v67
	v_exp_f32_e32 v51, v51
	v_sub_f32_e32 v52, v52, v67
	v_exp_f32_e32 v52, v52
	v_sub_f32_e32 v53, v53, v67
	v_exp_f32_e32 v53, v53
	v_sub_f32_e32 v54, v54, v67
	v_exp_f32_e32 v54, v54
	v_sub_f32_e32 v55, v55, v67
	v_add_f32_e32 v68, v51, v50
	v_exp_f32_e32 v55, v55
	v_sub_f32_e32 v56, v56, v67
	v_add_f32_e32 v68, v52, v68
	v_exp_f32_e32 v56, v56
	v_sub_f32_e32 v57, v57, v67
	v_add_f32_e32 v68, v53, v68
	v_exp_f32_e32 v57, v57
	v_sub_f32_e32 v58, v58, v67
	v_add_f32_e32 v68, v54, v68
	v_exp_f32_e32 v58, v58
	v_sub_f32_e32 v59, v59, v67
	v_add_f32_e32 v68, v55, v68
	v_exp_f32_e32 v59, v59
	v_sub_f32_e32 v60, v60, v67
	v_add_f32_e32 v68, v56, v68
	v_exp_f32_e32 v60, v60
	v_sub_f32_e32 v61, v61, v67
	v_add_f32_e32 v68, v57, v68
	v_exp_f32_e32 v61, v61
	v_sub_f32_e32 v62, v62, v67
	v_add_f32_e32 v68, v58, v68
	v_exp_f32_e32 v62, v62
	v_sub_f32_e32 v63, v63, v67
	v_add_f32_e32 v68, v59, v68
	v_exp_f32_e32 v63, v63
	v_sub_f32_e32 v65, v65, v67
	v_add_f32_e32 v68, v60, v68
	v_exp_f32_e32 v65, v65
	v_sub_f32_e32 v66, v66, v67
	v_add_f32_e32 v68, v61, v68
	v_exp_f32_e32 v66, v66
	v_add_f32_e32 v67, v62, v68
	v_add_f32_e32 v67, v63, v67
	v_add_f32_e32 v67, v65, v67
	v_add_f32_e32 v67, v66, v67
	v_cmp_neq_f32_e32 vcc, v49, v214
	v_mov_b32_e32 v68, v67
	v_mov_b32_e32 v69, v67
	s_cmp_lg_u64 vcc, 0
	s_nop 0
	v_permlane32_swap_b32_e32 v68, v69
	s_cselect_b64 s[42:43], -1, 0
	s_cbranch_execz .LBB0_652
	s_branch .LBB0_653

; DI float ex2(float x) { return __builtin_amdgcn_exp2f(x); }
; template <int MM> DI void smax_step(const f32x16& s, unsigned vm, float& m, float& l, f32x16 (&o)[2], bf16x8 (&pf)[2], int lane) {
;     float t[16], mx = -1e30f;
; #pragma unroll
;     for (int i = 0; i < 16; ++i) { t[i] = (MM == 0) ? s[i] : (MM == 1 ? (vm ? s[i] : -1e30f) : (((vm >> i) & 1u) ? s[i] : -1e30f)); mx = fmaxf(mx, t[i]); }
;     mx = fmaxf(mx, shx32(mx, lane));
;     const float mn = (mx > m + 8.0f) ? mx : m;
;     const float mref = fmaxf(mn, -1e29f);
;     float p[16], rs = 0.f;
; #pragma unroll
;     for (int i = 0; i < 16; ++i) { p[i] = ex2(t[i] - mref); rs += p[i]; }
;     rs += shx32(rs, lane);
;     if (__builtin_amdgcn_ballot_w64(mn != m) != 0ull) {
;         const float alpha = ex2(m - mn);
;         l *= alpha;
; #pragma unroll
;         for (int i = 0; i < 16; ++i) { o[0][i] *= alpha; o[1][i] *= alpha; }
;         m = mn;
;     }
;     l += rs;
;     pack_p(p, pf);
; }
.LBB0_652:
	v_cmp_eq_u32_e32 vcc, 0, v70
	s_nop 4
	v_cndmask_b32_e32 v50, v32, v208, vcc
	v_cndmask_b32_e32 v51, v33, v208, vcc
	v_max3_f32 v49, v50, s15, v51
	v_cndmask_b32_e32 v52, v34, v208, vcc
	v_cndmask_b32_e32 v53, v35, v208, vcc
	v_max3_f32 v49, v49, v52, v53
	v_cndmask_b32_e32 v54, v36, v208, vcc
	v_cndmask_b32_e32 v55, v37, v208, vcc
	v_max3_f32 v49, v49, v54, v55
	v_cndmask_b32_e32 v56, v38, v208, vcc
	v_cndmask_b32_e32 v57, v39, v208, vcc
	v_max3_f32 v49, v49, v56, v57
	v_cndmask_b32_e32 v58, v40, v208, vcc
	v_cndmask_b32_e32 v59, v41, v208, vcc
	v_max3_f32 v49, v49, v58, v59
	v_cndmask_b32_e32 v60, v42, v208, vcc
	v_cndmask_b32_e32 v61, v43, v208, vcc
	v_max3_f32 v49, v49, v60, v61
	v_cndmask_b32_e32 v62, v44, v208, vcc
	v_cndmask_b32_e32 v63, v45, v208, vcc
	v_max3_f32 v49, v49, v62, v63
	v_cndmask_b32_e32 v65, v46, v208, vcc
	v_cndmask_b32_e32 v66, v47, v208, vcc
	v_max3_f32 v49, v49, v65, v66
	v_mov_b32_e32 v67, v49
	v_mov_b32_e32 v68, v49
	s_nop 1
	v_permlane32_swap_b32_e32 v67, v68
	v_max_f32_e32 v49, v67, v68
	v_add_f32_e32 v67, 0x41000000, v214
	v_cmp_gt_f32_e32 vcc, v49, v67
	s_nop 1
	v_cndmask_b32_e32 v49, v214, v49, vcc
	v_max_f32_e32 v67, 0xefa18f08, v49
	v_sub_f32_e32 v50, v50, v67
	v_exp_f32_e32 v50, v50
	v_sub_f32_e32 v51, v51, v67
	v_exp_f32_e32 v51, v51
	v_sub_f32_e32 v52, v52, v67
	v_exp_f32_e32 v52, v52
	v_sub_f32_e32 v53, v53, v67
	v_exp_f32_e32 v53, v53
	v_sub_f32_e32 v54, v54, v67
	v_exp_f32_e32 v54, v54
	v_sub_f32_e32 v55, v55, v67
	v_add_f32_e32 v68, v51, v50
	v_exp_f32_e32 v55, v55
	v_sub_f32_e32 v56, v56, v67
	v_add_f32_e32 v68, v52, v68
	v_exp_f32_e32 v56, v56
	v_sub_f32_e32 v57, v57, v67
	v_add_f32_e32 v68, v53, v68
	v_exp_f32_e32 v57, v57
	v_sub_f32_e32 v58, v58, v67
	v_add_f32_e32 v68, v54, v68
	v_exp_f32_e32 v58, v58
	v_sub_f32_e32 v59, v59, v67
	v_add_f32_e32 v68, v55, v68
	v_exp_f32_e32 v59, v59
	v_sub_f32_e32 v60, v60, v67
	v_add_f32_e32 v68, v56, v68
	v_exp_f32_e32 v60, v60
	v_sub_f32_e32 v61, v61, v67
	v_add_f32_e32 v68, v57, v68
	v_exp_f32_e32 v61, v61
	v_sub_f32_e32 v62, v62, v67
	v_add_f32_e32 v68, v58, v68
	v_exp_f32_e32 v62, v62
	v_sub_f32_e32 v63, v63, v67
	v_add_f32_e32 v68, v59, v68
	v_exp_f32_e32 v63, v63
	v_sub_f32_e32 v65, v65, v67
	v_add_f32_e32 v68, v60, v68
	v_exp_f32_e32 v65, v65
	v_sub_f32_e32 v66, v66, v67
	v_add_f32_e32 v68, v61, v68
	v_exp_f32_e32 v66, v66
	v_add_f32_e32 v67, v62, v68
	v_add_f32_e32 v67, v63, v67
	v_add_f32_e32 v67, v65, v67
	v_add_f32_e32 v67, v66, v67
	v_cmp_neq_f32_e32 vcc, v49, v214
	v_mov_b32_e32 v68, v67
	v_mov_b32_e32 v69, v67
	s_cmp_lg_u64 vcc, 0
	s_nop 0
	v_permlane32_swap_b32_e32 v68, v69
	s_cselect_b64 s[42:43], -1, 0

; DI float ex2(float x) { return __builtin_amdgcn_exp2f(x); }
; template <int MM> DI void smax_step(const f32x16& s, unsigned vm, float& m, float& l, f32x16 (&o)[2], bf16x8 (&pf)[2], int lane) {
;     float t[16], mx = -1e30f;
; #pragma unroll
;     for (int i = 0; i < 16; ++i) { t[i] = (MM == 0) ? s[i] : (MM == 1 ? (vm ? s[i] : -1e30f) : (((vm >> i) & 1u) ? s[i] : -1e30f)); mx = fmaxf(mx, t[i]); }
;     mx = fmaxf(mx, shx32(mx, lane));
;     const float mn = (mx > m + 8.0f) ? mx : m;
;     const float mref = fmaxf(mn, -1e29f);
;     float p[16], rs = 0.f;
; #pragma unroll
;     for (int i = 0; i < 16; ++i) { p[i] = ex2(t[i] - mref); rs += p[i]; }
;     rs += shx32(rs, lane);
;     if (__builtin_amdgcn_ballot_w64(mn != m) != 0ull) {
;         const float alpha = ex2(m - mn);
;         l *= alpha;
; #pragma unroll
;         for (int i = 0; i < 16; ++i) { o[0][i] *= alpha; o[1][i] *= alpha; }
;         m = mn;
;     }
;     l += rs;
;     pack_p(p, pf);
; }
.LBB0_654:
	s_nop 5
	v_max3_f32 v49, v32, s15, v33
	v_max3_f32 v49, v49, v34, v35
	v_max3_f32 v49, v49, v36, v37
	v_max3_f32 v49, v49, v38, v39
	v_max3_f32 v49, v49, v40, v41
	v_max3_f32 v49, v49, v42, v43
	v_max3_f32 v49, v49, v44, v45
	v_max3_f32 v49, v49, v46, v47
	v_mov_b32_e32 v50, v49
	v_mov_b32_e32 v51, v49
	s_nop 1
	v_permlane32_swap_b32_e32 v50, v51
	v_max_f32_e32 v49, v50, v51
	v_add_f32_e32 v50, 0x41000000, v214
	v_cmp_gt_f32_e32 vcc, v49, v50
	s_nop 1
	v_cndmask_b32_e32 v49, v214, v49, vcc
	v_max_f32_e32 v66, 0xefa18f08, v49
	v_sub_f32_e32 v32, v32, v66
	v_exp_f32_e32 v50, v32
	v_sub_f32_e32 v32, v33, v66
	v_exp_f32_e32 v51, v32
	v_sub_f32_e32 v32, v34, v66
	v_exp_f32_e32 v52, v32
	v_sub_f32_e32 v32, v35, v66
	v_exp_f32_e32 v53, v32
	v_sub_f32_e32 v33, v36, v66
	v_exp_f32_e32 v54, v33
	v_sub_f32_e32 v33, v37, v66
	v_add_f32_e32 v32, v51, v50
	v_exp_f32_e32 v55, v33
	v_sub_f32_e32 v33, v38, v66
	v_add_f32_e32 v32, v52, v32
	v_exp_f32_e32 v56, v33
	v_sub_f32_e32 v33, v39, v66
	v_add_f32_e32 v32, v53, v32
	v_exp_f32_e32 v57, v33
	v_sub_f32_e32 v33, v40, v66
	v_add_f32_e32 v32, v54, v32
	v_exp_f32_e32 v58, v33
	v_sub_f32_e32 v33, v41, v66
	v_add_f32_e32 v32, v55, v32
	v_exp_f32_e32 v59, v33
	v_sub_f32_e32 v33, v42, v66
	v_add_f32_e32 v32, v56, v32
	v_exp_f32_e32 v60, v33
	v_sub_f32_e32 v33, v43, v66
	v_add_f32_e32 v32, v57, v32
	v_exp_f32_e32 v61, v33
	v_sub_f32_e32 v33, v44, v66
	v_add_f32_e32 v32, v58, v32
	v_exp_f32_e32 v62, v33
	v_sub_f32_e32 v33, v45, v66
	v_add_f32_e32 v32, v59, v32
	v_exp_f32_e32 v63, v33
	v_sub_f32_e32 v33, v46, v66
	v_add_f32_e32 v32, v60, v32
	v_exp_f32_e32 v65, v33
	v_sub_f32_e32 v33, v47, v66
	v_add_f32_e32 v32, v61, v32
	v_exp_f32_e32 v66, v33
	v_add_f32_e32 v32, v62, v32
	v_add_f32_e32 v32, v63, v32
	v_add_f32_e32 v32, v65, v32
	v_add_f32_e32 v67, v66, v32
	v_cmp_neq_f32_e32 vcc, v49, v214
	v_mov_b32_e32 v68, v67
	v_mov_b32_e32 v69, v67
	s_cmp_lg_u64 vcc, 0
	s_nop 0
	v_permlane32_swap_b32_e32 v68, v69
	s_cselect_b64 s[42:43], -1, 0

; template <int MODE, bool PRE = false> ...
;     ...
;         for (int sub = 0; sub < 2; ++sub) {
;             const int kbase = 64 * kt + 32 * sub;
;             if (kbase > q0w + 31) continue;
;             if (MODE == MODE_NWIN && kbase + 31 <= q0w - 512) continue;
;             bool full = (kbase + 31 <= q0w);
;             if (MODE == MODE_NWIN) full = full && (kbase > q0w + 31 - 512);
;             bool lsel = true;
;             if (MODE == MODE_MOBA) lsel = ((sel >> (kbase >> 8)) & 1ull) != 0ull;
;             if (MODE == MODE_NSEL) lsel = ((sel >> kt) & 1ull) != 0ull;
;             const unsigned long long selb = __builtin_amdgcn_ballot_w64(lsel);
;             if (selb == 0ull) continue;
;             int mm; unsigned vm;
;             if (full) { mm = (selb == ~0ull) ? 0 : 1; vm = lsel ? 1u : 0u; }
;             else { mm = 2; vm = 0;
; #pragma unroll
;                 for (int i = 0; i < 16; ++i) { const int kidx = kbase + (i & 3) + 8 * (i >> 2) + 4 * h; bool ok = kidx <= qpos; if (MODE == MODE_NWIN) ok = ok && (kidx > qpos - 512); vm |= ok ? (1u << i) : 0u; }
;                 if (!lsel) vm = 0;
;                 if (__builtin_amdgcn_ballot_w64(vm != 0) == 0ull) continue; }
.LBB0_658:
	s_or_b32 s10, s10, 32
	s_cmp_gt_i32 s10, s25
	s_cbranch_scc1 .LBB0_663
	v_cmp_ne_u32_e32 vcc, 0, v81
	s_cbranch_vccz .LBB0_663
	v_or_b32_e32 v32, s10, v167
	v_cmp_le_i32_e32 vcc, v32, v160
	v_or_b32_e32 v35, 3, v32
	s_nop 0
	v_cndmask_b32_e64 v33, 0, 1, vcc
	v_cmp_lt_i32_e32 vcc, v32, v160
	s_nop 1
	v_cndmask_b32_e64 v34, 0, 2, vcc
	v_or_b32_e32 v33, v34, v33
	v_or_b32_e32 v34, 2, v32
	v_cmp_gt_i32_e32 vcc, v34, v160
	s_nop 1
	v_cndmask_b32_e64 v34, 4, 0, vcc
	v_cmp_gt_i32_e32 vcc, v35, v160
	s_nop 1
	v_cndmask_b32_e64 v35, 8, 0, vcc
	v_or3_b32 v33, v33, v34, v35
	v_or_b32_e32 v34, 8, v32
	v_cmp_gt_i32_e32 vcc, v34, v160
	v_or_b32_e32 v35, 9, v32
	s_nop 0
	v_cndmask_b32_e64 v34, 16, 0, vcc
	v_cmp_gt_i32_e32 vcc, v35, v160
	s_nop 1
	v_cndmask_b32_e64 v35, 32, 0, vcc
	v_or3_b32 v33, v33, v34, v35
	v_or_b32_e32 v34, 10, v32
	v_cmp_gt_i32_e32 vcc, v34, v160
	v_or_b32_e32 v35, 11, v32
	s_nop 0
	v_cndmask_b32_e64 v34, 64, 0, vcc
	v_cmp_gt_i32_e32 vcc, v35, v160
	s_nop 1
	v_cndmask_b32_e64 v35, v196, 0, vcc
	v_or3_b32 v33, v33, v34, v35
	v_or_b32_e32 v34, 16, v32
	v_cmp_gt_i32_e32 vcc, v34, v160
	v_or_b32_e32 v35, 17, v32
	s_nop 0
	v_cndmask_b32_e64 v34, v197, 0, vcc
	v_cmp_gt_i32_e32 vcc, v35, v160
	s_nop 1
	v_cndmask_b32_e64 v35, v198, 0, vcc
	v_or3_b32 v33, v33, v34, v35
	v_or_b32_e32 v34, 18, v32
	v_cmp_gt_i32_e32 vcc, v34, v160
	v_or_b32_e32 v35, 19, v32
	s_nop 0
	v_cndmask_b32_e64 v34, v199, 0, vcc
	v_cmp_gt_i32_e32 vcc, v35, v160
	s_nop 1
	v_cndmask_b32_e64 v35, v200, 0, vcc
	v_or3_b32 v33, v33, v34, v35
	v_or_b32_e32 v34, 24, v32
	v_cmp_gt_i32_e32 vcc, v34, v160
	v_or_b32_e32 v35, 25, v32
	s_nop 0
	v_cndmask_b32_e64 v34, v201, 0, vcc
	v_cmp_gt_i32_e32 vcc, v35, v160
	s_nop 1
	v_cndmask_b32_e64 v35, v202, 0, vcc
	v_or3_b32 v33, v33, v34, v35
	v_or_b32_e32 v34, 26, v32
	v_cmp_gt_i32_e32 vcc, v34, v160
	v_or_b32_e32 v32, 27, v32
	s_nop 0
	v_cndmask_b32_e64 v34, v203, 0, vcc
	v_cmp_gt_i32_e32 vcc, v32, v160
	s_nop 1
	v_cndmask_b32_e64 v32, v204, 0, vcc
	v_or3_b32 v32, v33, v34, v32
	v_cndmask_b32_e64 v49, 0, v32, s[0:1]
	v_cmp_ne_u32_e32 vcc, 0, v49
	s_cbranch_vccz .LBB0_663
; DI float ex2(float x) { return __builtin_amdgcn_exp2f(x); }
; template <int MM> DI void smax_step(const f32x16& s, unsigned vm, float& m, float& l, f32x16 (&o)[2], bf16x8 (&pf)[2], int lane) {
;     float t[16], mx = -1e30f;
; #pragma unroll
;     for (int i = 0; i < 16; ++i) { t[i] = (MM == 0) ? s[i] : (MM == 1 ? (vm ? s[i] : -1e30f) : (((vm >> i) & 1u) ? s[i] : -1e30f)); mx = fmaxf(mx, t[i]); }
;     mx = fmaxf(mx, shx32(mx, lane));
;     const float mn = (mx > m + 8.0f) ? mx : m;
;     const float mref = fmaxf(mn, -1e29f);
;     float p[16], rs = 0.f;
; #pragma unroll
;     for (int i = 0; i < 16; ++i) { p[i] = ex2(t[i] - mref); rs += p[i]; }
;     rs += shx32(rs, lane);
;     if (__builtin_amdgcn_ballot_w64(mn != m) != 0ull) {
;         const float alpha = ex2(m - mn);
;         l *= alpha;
; #pragma unroll
;         for (int i = 0; i < 16; ++i) { o[0][i] *= alpha; o[1][i] *= alpha; }
;         m = mn;
;     }
;     l += rs;
;     pack_p(p, pf);
; }
; template <int MODE, bool PRE = false> ...
;     ...
;                 for (int i = 0; i < 16; ++i) { const int kidx = kbase + (i & 3) + 8 * (i >> 2) + 4 * h; bool ok = kidx <= qpos; if (MODE == MODE_NWIN) ok = ok && (kidx > qpos - 512); vm |= ok ? (1u << i) : 0u; }
;                 if (!lsel) vm = 0;
;                 if (__builtin_amdgcn_ballot_w64(vm != 0) == 0ull) continue; }
;             bf16x8 pf[2];
;             if (MODE == MODE_DIFF) {
;                 const f32x16 s1 = qk_rows<0, 2>(Kl, 32 * sub, qf, r, h), s2 = qk_rows<2, 4>(Kl, 32 * sub, qf, r, h);
;                 bf16x8 pf2[2];
;                 if (mm == 0) { smax_step<0>(s1, vm, m1, l1, o1, pf, lane); smax_step<0>(s2, vm, m2, l2, o2, pf2, lane); }
;                 else { smax_step<2>(s1, vm, m1, l1, o1, pf, lane); smax_step<2>(s2, vm, m2, l2, o2, pf2, lane); }
;                 pv_rows(o1, Vl, 32 * sub, pf, lane);
;                 pv_rows(o2, Vl, 32 * sub, pf2, lane);
;             } else {
;                 const f32x16 s = qk_rows<0, 4>(Kl, 32 * sub, qf, r, h);
;                 if (mm == 0) smax_step<0>(s, vm, m1, l1, o1, pf, lane); else if (mm == 1) smax_step<1>(s, vm, m1, l1, o1, pf, lane); else smax_step<2>(s, vm, m1, l1, o1, pf, lane);
;                 pv_rows(o1, Vl, 32 * sub, pf, lane);
	v_add_u32_e32 v36, v48, v192
	ds_read_b128 v[32:35], v36
	ds_read_b128 v[50:53], v36 offset:32
	ds_read_b128 v[54:57], v36 offset:64
	ds_read_b128 v[58:61], v36 offset:96
	s_setprio 1
	s_waitcnt lgkmcnt(3)
	v_mfma_f32_32x32x16_bf16 v[32:47], v[32:35], v[96:99], 0
	s_waitcnt lgkmcnt(2)
	v_mfma_f32_32x32x16_bf16 v[32:47], v[50:53], v[100:103], v[32:47]
	s_waitcnt lgkmcnt(1)
	v_mfma_f32_32x32x16_bf16 v[32:47], v[54:57], v[104:107], v[32:47]
	s_waitcnt lgkmcnt(0)
	v_mfma_f32_32x32x16_bf16 v[32:47], v[58:61], v[108:111], v[32:47]
	s_setprio 0
	v_and_b32_e32 v48, 1, v49
	v_cmp_eq_u32_e32 vcc, 1, v48
	v_and_b32_e32 v48, 2, v49
	v_and_b32_e32 v50, 4, v49
	s_nop 6
	v_cndmask_b32_e32 v32, v208, v32, vcc
	v_cmp_ne_u32_e32 vcc, 0, v48
	s_nop 1
	v_cndmask_b32_e32 v33, v208, v33, vcc
	v_cmp_ne_u32_e32 vcc, 0, v50
	v_and_b32_e32 v50, 8, v49
	v_max3_f32 v48, v32, s15, v33
	v_cndmask_b32_e32 v34, v208, v34, vcc
	v_cmp_ne_u32_e32 vcc, 0, v50
	v_and_b32_e32 v50, 16, v49
	s_nop 0
	v_cndmask_b32_e32 v35, v208, v35, vcc
	v_cmp_ne_u32_e32 vcc, 0, v50
	v_and_b32_e32 v50, 32, v49
	v_max3_f32 v48, v48, v34, v35
	v_cndmask_b32_e32 v36, v208, v36, vcc
	v_cmp_ne_u32_e32 vcc, 0, v50
	v_and_b32_e32 v50, 64, v49
	s_nop 0
	v_cndmask_b32_e32 v37, v208, v37, vcc
	v_cmp_ne_u32_e32 vcc, 0, v50
	v_and_b32_e32 v50, 0x80, v49
	v_max3_f32 v48, v48, v36, v37
	v_cndmask_b32_e32 v38, v208, v38, vcc
	v_cmp_ne_u32_e32 vcc, 0, v50
	v_and_b32_e32 v50, 0x100, v49
	s_nop 0
	v_cndmask_b32_e32 v39, v208, v39, vcc
	v_cmp_ne_u32_e32 vcc, 0, v50
	v_and_b32_e32 v50, 0x200, v49
	v_max3_f32 v48, v48, v38, v39
	v_cndmask_b32_e32 v40, v208, v40, vcc
	v_cmp_ne_u32_e32 vcc, 0, v50
	v_and_b32_e32 v50, 0x400, v49
	s_nop 0
	v_cndmask_b32_e32 v41, v208, v41, vcc
	v_cmp_ne_u32_e32 vcc, 0, v50
	v_and_b32_e32 v50, 0x800, v49
	v_max3_f32 v48, v48, v40, v41
	v_cndmask_b32_e32 v42, v208, v42, vcc
	v_cmp_ne_u32_e32 vcc, 0, v50
	v_and_b32_e32 v50, 0x1000, v49
	s_nop 0
	v_cndmask_b32_e32 v43, v208, v43, vcc
	v_cmp_ne_u32_e32 vcc, 0, v50
	v_and_b32_e32 v50, 0x2000, v49
	v_max3_f32 v48, v48, v42, v43
	v_cndmask_b32_e32 v44, v208, v44, vcc
	v_cmp_ne_u32_e32 vcc, 0, v50
	v_and_b32_e32 v50, 0x4000, v49
	v_and_b32_e32 v49, 0x8000, v49
	v_cndmask_b32_e32 v45, v208, v45, vcc
	v_cmp_ne_u32_e32 vcc, 0, v50
	v_max3_f32 v48, v48, v44, v45
	s_nop 0
	v_cndmask_b32_e32 v46, v208, v46, vcc
	v_cmp_ne_u32_e32 vcc, 0, v49
	s_nop 1
	v_cndmask_b32_e32 v47, v208, v47, vcc
	v_max3_f32 v48, v48, v46, v47
	v_mov_b32_e32 v49, v48
	v_mov_b32_e32 v50, v48
	s_nop 1
	v_permlane32_swap_b32_e32 v49, v50
	v_max_f32_e32 v48, v49, v50
	v_add_f32_e32 v49, 0x41000000, v214
	v_cmp_gt_f32_e32 vcc, v48, v49
	s_nop 1
	v_cndmask_b32_e32 v69, v214, v48, vcc
	v_max_f32_e32 v48, 0xefa18f08, v69
	v_sub_f32_e32 v32, v32, v48
	v_exp_f32_e32 v65, v32
	v_sub_f32_e32 v32, v33, v48
	v_exp_f32_e32 v66, v32
	v_sub_f32_e32 v32, v34, v48
	v_exp_f32_e32 v67, v32
	v_sub_f32_e32 v32, v35, v48
	v_exp_f32_e32 v68, v32
	v_sub_f32_e32 v33, v36, v48
	v_exp_f32_e32 v70, v33
	v_sub_f32_e32 v33, v37, v48
	v_add_f32_e32 v32, v66, v65
	v_exp_f32_e32 v71, v33
	v_sub_f32_e32 v33, v38, v48
	v_add_f32_e32 v32, v67, v32
	v_exp_f32_e32 v72, v33
	v_sub_f32_e32 v33, v39, v48
	v_add_f32_e32 v32, v68, v32
	v_exp_f32_e32 v73, v33
	v_sub_f32_e32 v33, v40, v48
	v_add_f32_e32 v32, v70, v32
	v_exp_f32_e32 v74, v33
	v_sub_f32_e32 v33, v41, v48
	v_add_f32_e32 v32, v71, v32
	v_exp_f32_e32 v75, v33
	v_sub_f32_e32 v33, v42, v48
	v_add_f32_e32 v32, v72, v32
	v_exp_f32_e32 v76, v33
	v_sub_f32_e32 v33, v43, v48
	v_add_f32_e32 v32, v73, v32
	v_exp_f32_e32 v77, v33
	v_sub_f32_e32 v33, v44, v48
	v_add_f32_e32 v32, v74, v32
	v_exp_f32_e32 v78, v33
	v_sub_f32_e32 v33, v45, v48
	v_add_f32_e32 v32, v75, v32
	v_exp_f32_e32 v79, v33
	v_sub_f32_e32 v33, v46, v48
	v_add_f32_e32 v32, v76, v32
	v_exp_f32_e32 v80, v33
	v_sub_f32_e32 v33, v47, v48
	v_add_f32_e32 v32, v77, v32
	v_exp_f32_e32 v81, v33
	v_add_f32_e32 v32, v78, v32
	v_add_f32_e32 v32, v79, v32
	v_add_f32_e32 v32, v80, v32
	v_add_f32_e32 v82, v81, v32
	v_mov_b32_e32 v83, v82
	v_mov_b32_e32 v84, v82
	s_nop 1
	v_permlane32_swap_b32_e32 v83, v84
	v_cmp_neq_f32_e32 vcc, v69, v214
	s_cbranch_vccz .LBB0_664
	v_sub_f32_e32 v32, v214, v69
	v_exp_f32_e32 v32, v32
	v_mov_b32_e32 v214, v69
	v_mul_f32_e32 v213, v213, v32
	v_pk_mul_f32 v[62:63], v[30:31], v[32:33] op_sel_hi:[1,0]
	v_pk_mul_f32 v[60:61], v[28:29], v[32:33] op_sel_hi:[1,0]
	v_pk_mul_f32 v[58:59], v[26:27], v[32:33] op_sel_hi:[1,0]
	v_pk_mul_f32 v[56:57], v[24:25], v[32:33] op_sel_hi:[1,0]
	v_pk_mul_f32 v[54:55], v[22:23], v[32:33] op_sel_hi:[1,0]
	v_pk_mul_f32 v[52:53], v[20:21], v[32:33] op_sel_hi:[1,0]
	v_pk_mul_f32 v[50:51], v[18:19], v[32:33] op_sel_hi:[1,0]
	v_pk_mul_f32 v[48:49], v[16:17], v[32:33] op_sel_hi:[1,0]
	v_pk_mul_f32 v[46:47], v[14:15], v[32:33] op_sel_hi:[1,0]
	v_pk_mul_f32 v[44:45], v[12:13], v[32:33] op_sel_hi:[1,0]
	v_pk_mul_f32 v[42:43], v[10:11], v[32:33] op_sel_hi:[1,0]
	v_pk_mul_f32 v[40:41], v[8:9], v[32:33] op_sel_hi:[1,0]
	v_pk_mul_f32 v[38:39], v[6:7], v[32:33] op_sel_hi:[1,0]
	v_pk_mul_f32 v[36:37], v[4:5], v[32:33] op_sel_hi:[1,0]
	v_pk_mul_f32 v[34:35], v[2:3], v[32:33] op_sel_hi:[1,0]
	v_pk_mul_f32 v[32:33], v[0:1], v[32:33] op_sel_hi:[1,0]
	s_branch .LBB0_665

; #define LAS __attribute__((address_space(3)))
; DI float ex2(float x) { return __builtin_amdgcn_exp2f(x); }
; template <int MM> DI void smax_step_nb(const f32x16& s, unsigned vm, float& m, float& l, f32x16 (&o)[2], bf16x8 (&pf)[2], int lane) {
;     float mx = -1e30f;
; #pragma unroll
;     for (int i = 0; i < 16; ++i) mx = fmaxf(mx, s[i]);
;     if (MM == 1) mx = vm ? mx : -1e30f;
;     mx = fmaxf(mx, shx32(mx, lane));
;     const float mn = (mx > m + 8.0f) ? mx : m;
;     float mref = fmaxf(mn, -1e29f);
;     if (MM == 1) mref = vm ? mref : 3e38f;
;     const float alpha = ex2(m - mn);
;     float p[16], rs = 0.f;
; #pragma unroll
;     for (int i = 0; i < 16; ++i) { p[i] = ex2(s[i] - mref); rs += p[i]; }
;     rs += shx32(rs, lane);
;     l = l * alpha + rs;
;     if (__builtin_amdgcn_ballot_w64(mn != m) != 0ull) {
; #pragma unroll
;         for (int i = 0; i < 16; ++i) { o[0][i] *= alpha; o[1][i] *= alpha; }
;     }
;     m = mn;
;     pack_p(p, pf);
; }
; template <int MM> DI void tile128_pipe(LAS const char* K0, LAS const char* V0, LAS const char* K1, LAS const char* V1, const bf16x8 (&qf)[4], unsigned vm0, unsigned vm1,
;                                        float& m, float& l, f32x16 (&o)[2], int r, int h, int lane) {
;     f32x16 sa = qk_rows<0, 4>(K0, 0, qf, r, h), sb = qk_rows<0, 4>(K0, 32, qf, r, h);
;     bf16x8 pfa[2], pfb[2];
;     smax_step_nb<MM>(sa, vm0, m, l, o, pfa, lane);
;     sa = qk_rows<0, 4>(K1, 0, qf, r, h);
.LBB0_675:
	s_lshl_b32 s62, s44, 1
	s_add_i32 s62, s62, s27
	s_cmp_lt_u32 s62, s58
	s_cselect_b64 s[0:1], -1, 0
	s_lshl_b32 s24, s62, 6
	s_add_i32 s10, s24, 0x7f
	s_cmp_le_i32 s10, s59
	s_cselect_b64 s[10:11], -1, 0
	s_and_b64 s[0:1], s[0:1], s[10:11]
	s_cmp_gt_i32 s24, s57
	s_cselect_b64 s[10:11], -1, 0
	s_and_b64 s[0:1], s[0:1], s[10:11]
	s_andn2_b64 vcc, exec, s[0:1]
	s_mov_b32 s0, 0
	s_cbranch_vccnz .LBB0_698
	s_cmp_eq_u64 exec, 0
	s_cbranch_scc1 .LBB0_698
	s_lshl_b32 s0, s44, 2
	s_and_b32 s0, s0, 4
	s_mulk_i32 s0, 0x2400
	s_add_i32 s10, s0, 0
	v_add_u32_e32 v32, s10, v190
	v_add_u32_e32 v212, v32, v168
	s_waitcnt lgkmcnt(7)
	ds_read_b128 v[140:143], v212
	s_waitcnt lgkmcnt(7)
	ds_read_b128 v[136:139], v212 offset:32
	s_waitcnt lgkmcnt(7)
	ds_read_b128 v[132:135], v212 offset:64
	s_waitcnt lgkmcnt(7)
	ds_read_b128 v[128:131], v212 offset:96
	s_cmp_lg_u64 exec, -1
	s_setprio 1
	s_setprio 0
	s_waitcnt lgkmcnt(7)
	ds_read_b128 v[144:147], v212 offset:4608
	s_waitcnt lgkmcnt(7)
	ds_read_b128 v[148:151], v212 offset:4640
	s_waitcnt lgkmcnt(7)
	ds_read_b128 v[152:155], v212 offset:4672
	s_waitcnt lgkmcnt(7)
	ds_read_b128 v[156:159], v212 offset:4704
	s_setprio 1
	s_setprio 0
	v_add_f32_e32 v213, 0x41000000, v193
	s_cbranch_scc0 .LBB0_687
	s_waitcnt lgkmcnt(7)
	v_mfma_f32_32x32x16_bf16 v[32:47], v[140:143], v[96:99], 0
	s_waitcnt lgkmcnt(6)
	v_mfma_f32_32x32x16_bf16 v[32:47], v[136:139], v[100:103], v[32:47]
	s_waitcnt lgkmcnt(5)
	v_mfma_f32_32x32x16_bf16 v[32:47], v[132:135], v[104:107], v[32:47]
	s_waitcnt lgkmcnt(4)
	v_mfma_f32_32x32x16_bf16 v[32:47], v[128:131], v[108:111], v[32:47]
	s_waitcnt lgkmcnt(3)
	v_mfma_f32_32x32x16_bf16 v[64:79], v[144:147], v[96:99], 0
	s_nop 9
	v_max3_f32 v48, v32, s15, v33
	v_max3_f32 v48, v48, v34, v35
	v_max3_f32 v48, v48, v36, v37
	v_max3_f32 v48, v48, v38, v39
	v_max3_f32 v48, v48, v40, v41
	v_max3_f32 v48, v48, v42, v43
	v_max3_f32 v48, v48, v44, v45
	v_max3_f32 v48, v48, v46, v47
	v_mov_b32_e32 v49, v48
	v_mov_b32_e32 v50, v48
	s_nop 1
	v_permlane32_swap_b32_e32 v49, v50
	v_max_f32_e32 v48, v49, v50
	v_cmp_gt_f32_e32 vcc, v48, v213
	s_waitcnt lgkmcnt(2)
	v_mfma_f32_32x32x16_bf16 v[64:79], v[148:151], v[100:103], v[64:79]
	v_cndmask_b32_e32 v221, v193, v48, vcc
	v_max_f32_e32 v48, 0xefa18f08, v221
	v_sub_f32_e32 v32, v32, v48
	v_sub_f32_e32 v33, v33, v48
	v_exp_f32_e32 v80, v32
	v_sub_f32_e32 v34, v34, v48
	v_exp_f32_e32 v81, v33
	v_sub_f32_e32 v35, v35, v48
	v_exp_f32_e32 v82, v34
	v_sub_f32_e32 v36, v36, v48
	v_exp_f32_e32 v83, v35
	v_sub_f32_e32 v37, v37, v48
	v_exp_f32_e32 v84, v36
	v_sub_f32_e32 v38, v38, v48
	v_exp_f32_e32 v85, v37
	v_add_f32_e32 v32, v81, v80
	v_sub_f32_e32 v39, v39, v48
	v_exp_f32_e32 v86, v38
	s_waitcnt lgkmcnt(1)
	v_mfma_f32_32x32x16_bf16 v[64:79], v[152:155], v[104:107], v[64:79]
	v_add_f32_e32 v32, v82, v32
	v_sub_f32_e32 v40, v40, v48
	v_exp_f32_e32 v87, v39
	v_add_f32_e32 v32, v83, v32
	v_sub_f32_e32 v41, v41, v48
	v_exp_f32_e32 v88, v40
	v_add_f32_e32 v32, v84, v32
	v_sub_f32_e32 v42, v42, v48
	v_exp_f32_e32 v89, v41
	v_add_f32_e32 v32, v85, v32
	v_sub_f32_e32 v43, v43, v48
	v_exp_f32_e32 v90, v42
	v_add_f32_e32 v32, v86, v32
	v_sub_f32_e32 v44, v44, v48
	v_exp_f32_e32 v91, v43
	v_add_f32_e32 v32, v87, v32
	v_add_f32_e32 v32, v88, v32
	v_exp_f32_e32 v92, v44
	v_sub_f32_e32 v33, v45, v48
	v_add_f32_e32 v32, v89, v32
	v_exp_f32_e32 v93, v33
	v_sub_f32_e32 v33, v46, v48
	s_waitcnt lgkmcnt(0)
	v_mfma_f32_32x32x16_bf16 v[64:79], v[156:159], v[108:111], v[64:79]
	v_add_f32_e32 v32, v90, v32
	v_exp_f32_e32 v94, v33
	v_sub_f32_e32 v33, v47, v48
	v_add_f32_e32 v32, v91, v32
	v_exp_f32_e32 v95, v33
	v_add_f32_e32 v32, v92, v32
	v_sub_f32_e32 v49, v193, v221
	v_add_f32_e32 v32, v93, v32
	v_add_f32_e32 v32, v94, v32
	v_exp_f32_e32 v164, v49
	v_add_f32_e32 v214, v95, v32
	v_mov_b32_e32 v215, v214
	v_mov_b32_e32 v216, v214
	s_nop 0
	s_nop 0
	v_permlane32_swap_b32_e32 v215, v216
	v_cmp_neq_f32_e32 vcc, v221, v193
	s_cbranch_vccz .LBB0_680
	v_pk_mul_f32 v[30:31], v[30:31], v[164:165] op_sel_hi:[1,0]
	v_pk_mul_f32 v[28:29], v[28:29], v[164:165] op_sel_hi:[1,0]
	v_pk_mul_f32 v[26:27], v[26:27], v[164:165] op_sel_hi:[1,0]
	v_pk_mul_f32 v[24:25], v[24:25], v[164:165] op_sel_hi:[1,0]
	v_pk_mul_f32 v[22:23], v[22:23], v[164:165] op_sel_hi:[1,0]
	v_pk_mul_f32 v[20:21], v[20:21], v[164:165] op_sel_hi:[1,0]
	v_pk_mul_f32 v[18:19], v[18:19], v[164:165] op_sel_hi:[1,0]
	v_pk_mul_f32 v[16:17], v[16:17], v[164:165] op_sel_hi:[1,0]
	v_pk_mul_f32 v[14:15], v[14:15], v[164:165] op_sel_hi:[1,0]
	v_pk_mul_f32 v[12:13], v[12:13], v[164:165] op_sel_hi:[1,0]
	v_pk_mul_f32 v[10:11], v[10:11], v[164:165] op_sel_hi:[1,0]
	v_pk_mul_f32 v[8:9], v[8:9], v[164:165] op_sel_hi:[1,0]
	v_pk_mul_f32 v[6:7], v[6:7], v[164:165] op_sel_hi:[1,0]
	v_pk_mul_f32 v[4:5], v[4:5], v[164:165] op_sel_hi:[1,0]
	v_pk_mul_f32 v[2:3], v[2:3], v[164:165] op_sel_hi:[1,0]
	v_pk_mul_f32 v[0:1], v[0:1], v[164:165] op_sel_hi:[1,0]
; #define LAS __attribute__((address_space(3)))
; DI float ex2(float x) { return __builtin_amdgcn_exp2f(x); }
; template <int MM> DI void smax_step_nb(const f32x16& s, unsigned vm, float& m, float& l, f32x16 (&o)[2], bf16x8 (&pf)[2], int lane) {
;     float mx = -1e30f;
; #pragma unroll
;     for (int i = 0; i < 16; ++i) mx = fmaxf(mx, s[i]);
;     if (MM == 1) mx = vm ? mx : -1e30f;
;     mx = fmaxf(mx, shx32(mx, lane));
;     const float mn = (mx > m + 8.0f) ? mx : m;
;     float mref = fmaxf(mn, -1e29f);
;     if (MM == 1) mref = vm ? mref : 3e38f;
;     const float alpha = ex2(m - mn);
;     float p[16], rs = 0.f;
; #pragma unroll
;     for (int i = 0; i < 16; ++i) { p[i] = ex2(s[i] - mref); rs += p[i]; }
;     rs += shx32(rs, lane);
;     l = l * alpha + rs;
;     if (__builtin_amdgcn_ballot_w64(mn != m) != 0ull) {
; #pragma unroll
;         for (int i = 0; i < 16; ++i) { o[0][i] *= alpha; o[1][i] *= alpha; }
;     }
;     m = mn;
;     pack_p(p, pf);
; }
; template <int MM> DI void tile128_pipe(LAS const char* K0, LAS const char* V0, LAS const char* K1, LAS const char* V1, const bf16x8 (&qf)[4], unsigned vm0, unsigned vm1,
;                                        float& m, float& l, f32x16 (&o)[2], int r, int h, int lane) {
;     f32x16 sa = qk_rows<0, 4>(K0, 0, qf, r, h), sb = qk_rows<0, 4>(K0, 32, qf, r, h);
;     bf16x8 pfa[2], pfb[2];
;     smax_step_nb<MM>(sa, vm0, m, l, o, pfa, lane);
;     sa = qk_rows<0, 4>(K1, 0, qf, r, h);
;     pv_rows(o, V0, 0, pfa, lane);
;     smax_step_nb<MM>(sb, vm0, m, l, o, pfb, lane);
;     sb = qk_rows<0, 4>(K1, 32, qf, r, h);
;     pv_rows(o, V0, 32, pfb, lane);
;     smax_step_nb<MM>(sa, vm1, m, l, o, pfa, lane);
;     pv_rows(o, V1, 0, pfa, lane);
;     smax_step_nb<MM>(sb, vm1, m, l, o, pfb, lane);
;     pv_rows(o, V1, 32, pfb, lane);
; }
.LBB0_680:
	v_cvt_pk_bf16_f32 v222, v80, v81
	v_cvt_pk_bf16_f32 v223, v82, v83
	ds_read_b128 v[80:83], v212 offset:18432
	ds_read_b128 v[230:233], v212 offset:18464
	ds_read_b128 v[234:237], v212 offset:18496
	ds_read_b128 v[238:241], v212 offset:18528
	v_cvt_pk_bf16_f32 v224, v84, v85
	v_cvt_pk_bf16_f32 v225, v86, v87
	v_cvt_pk_bf16_f32 v226, v88, v89
	v_cvt_pk_bf16_f32 v227, v90, v91
	v_cvt_pk_bf16_f32 v228, v92, v93
	v_cvt_pk_bf16_f32 v229, v94, v95
	s_setprio 1
	s_waitcnt lgkmcnt(3)
	v_mfma_f32_32x32x16_bf16 v[80:95], v[80:83], v[96:99], 0
	s_waitcnt lgkmcnt(2)
	v_mfma_f32_32x32x16_bf16 v[80:95], v[230:233], v[100:103], v[80:95]
	s_waitcnt lgkmcnt(1)
	v_mfma_f32_32x32x16_bf16 v[80:95], v[234:237], v[104:107], v[80:95]
	s_waitcnt lgkmcnt(0)
	v_mfma_f32_32x32x16_bf16 v[80:95], v[238:241], v[108:111], v[80:95]
	s_setprio 0
	v_add3_u32 v166, s10, v191, v171
	v_add_u32_e32 v217, v166, v186
	ds_read_b64_tr_b16 v[230:231], v217 offset:9216
	ds_read_b64_tr_b16 v[232:233], v217 offset:10368
	ds_read_b64_tr_b16 v[236:237], v217 offset:10432
	ds_read_b64_tr_b16 v[234:235], v217 offset:9280
	ds_read_b64_tr_b16 v[238:239], v217 offset:11520
	ds_read_b64_tr_b16 v[240:241], v217 offset:12672
	ds_read_b64_tr_b16 v[244:245], v217 offset:12736
	ds_read_b64_tr_b16 v[242:243], v217 offset:11584
	s_setprio 1
	s_waitcnt lgkmcnt(6)
	v_mfma_f32_32x32x16_bf16 v[0:15], v[230:233], v[222:225], v[0:15]
	s_waitcnt lgkmcnt(4)
	v_mfma_f32_32x32x16_bf16 v[16:31], v[234:237], v[222:225], v[16:31]
	s_waitcnt lgkmcnt(2)
	v_mfma_f32_32x32x16_bf16 v[0:15], v[238:241], v[226:229], v[0:15]
	s_waitcnt lgkmcnt(0)
	v_mfma_f32_32x32x16_bf16 v[16:31], v[242:245], v[226:229], v[16:31]
	s_setprio 0
	v_max3_f32 v166, v64, s15, v65
	v_max3_f32 v166, v166, v66, v67
	v_max3_f32 v166, v166, v68, v69
	v_max3_f32 v166, v166, v70, v71
	v_max3_f32 v166, v166, v72, v73
	v_max3_f32 v166, v166, v74, v75
	v_max3_f32 v166, v166, v76, v77
	v_max3_f32 v166, v166, v78, v79
	v_mov_b32_e32 v172, v166
	v_mov_b32_e32 v173, v166
	s_nop 1
	v_permlane32_swap_b32_e32 v172, v173
	v_max_f32_e32 v166, v172, v173
	v_add_f32_e32 v172, 0x41000000, v221
	v_cmp_gt_f32_e32 vcc, v166, v172
	s_nop 1
	v_cndmask_b32_e32 v222, v221, v166, vcc
	v_max_f32_e32 v166, 0xefa18f08, v222
	v_sub_f32_e32 v64, v64, v166
	v_exp_f32_e32 v64, v64
	v_sub_f32_e32 v65, v65, v166
	v_exp_f32_e32 v65, v65
	v_sub_f32_e32 v66, v66, v166
	v_exp_f32_e32 v66, v66
	v_sub_f32_e32 v67, v67, v166
	v_exp_f32_e32 v67, v67
	v_sub_f32_e32 v68, v68, v166
	v_exp_f32_e32 v68, v68
	v_sub_f32_e32 v69, v69, v166
	v_add_f32_e32 v173, v65, v64
	v_exp_f32_e32 v69, v69
	v_sub_f32_e32 v70, v70, v166
	v_add_f32_e32 v173, v66, v173
	v_exp_f32_e32 v70, v70
	v_sub_f32_e32 v71, v71, v166
	v_add_f32_e32 v173, v67, v173
	v_exp_f32_e32 v71, v71
	v_sub_f32_e32 v72, v72, v166
	v_add_f32_e32 v173, v68, v173
	v_exp_f32_e32 v72, v72
	v_sub_f32_e32 v73, v73, v166
	v_add_f32_e32 v173, v69, v173
	v_exp_f32_e32 v73, v73
	v_sub_f32_e32 v74, v74, v166
	v_add_f32_e32 v173, v70, v173
	v_exp_f32_e32 v74, v74
	v_sub_f32_e32 v75, v75, v166
	v_add_f32_e32 v173, v71, v173
	v_exp_f32_e32 v75, v75
	v_sub_f32_e32 v76, v76, v166
	v_add_f32_e32 v173, v72, v173
	v_exp_f32_e32 v76, v76
	v_sub_f32_e32 v77, v77, v166
	v_add_f32_e32 v173, v73, v173
	v_exp_f32_e32 v77, v77
	v_sub_f32_e32 v78, v78, v166
	v_add_f32_e32 v173, v74, v173
	v_exp_f32_e32 v78, v78
	v_sub_f32_e32 v79, v79, v166
	v_add_f32_e32 v173, v75, v173
	v_exp_f32_e32 v79, v79
	v_add_f32_e32 v166, v76, v173
	v_add_f32_e32 v166, v77, v166
	v_sub_f32_e32 v172, v221, v222
	v_add_f32_e32 v166, v78, v166
	v_add_f32_e32 v218, v79, v166
	v_exp_f32_e32 v166, v172
	v_mov_b32_e32 v219, v218
	v_mov_b32_e32 v220, v218
	s_nop 1
	v_permlane32_swap_b32_e32 v219, v220
	v_cmp_neq_f32_e32 vcc, v222, v221
	s_cbranch_vccz .LBB0_682
	v_pk_mul_f32 v[30:31], v[30:31], v[166:167] op_sel_hi:[1,0]
	v_pk_mul_f32 v[28:29], v[28:29], v[166:167] op_sel_hi:[1,0]
	v_pk_mul_f32 v[26:27], v[26:27], v[166:167] op_sel_hi:[1,0]
	v_pk_mul_f32 v[24:25], v[24:25], v[166:167] op_sel_hi:[1,0]
	v_pk_mul_f32 v[22:23], v[22:23], v[166:167] op_sel_hi:[1,0]
	v_pk_mul_f32 v[20:21], v[20:21], v[166:167] op_sel_hi:[1,0]
	v_pk_mul_f32 v[18:19], v[18:19], v[166:167] op_sel_hi:[1,0]
	v_pk_mul_f32 v[16:17], v[16:17], v[166:167] op_sel_hi:[1,0]
	v_pk_mul_f32 v[14:15], v[14:15], v[166:167] op_sel_hi:[1,0]
	v_pk_mul_f32 v[12:13], v[12:13], v[166:167] op_sel_hi:[1,0]
	v_pk_mul_f32 v[10:11], v[10:11], v[166:167] op_sel_hi:[1,0]
	v_pk_mul_f32 v[8:9], v[8:9], v[166:167] op_sel_hi:[1,0]
	v_pk_mul_f32 v[6:7], v[6:7], v[166:167] op_sel_hi:[1,0]
	v_pk_mul_f32 v[4:5], v[4:5], v[166:167] op_sel_hi:[1,0]
	v_pk_mul_f32 v[2:3], v[2:3], v[166:167] op_sel_hi:[1,0]
	v_pk_mul_f32 v[0:1], v[0:1], v[166:167] op_sel_hi:[1,0]
; #define LAS __attribute__((address_space(3)))
; DI float ex2(float x) { return __builtin_amdgcn_exp2f(x); }
; template <int MM> DI void smax_step_nb(const f32x16& s, unsigned vm, float& m, float& l, f32x16 (&o)[2], bf16x8 (&pf)[2], int lane) {
;     float mx = -1e30f;
; #pragma unroll
;     for (int i = 0; i < 16; ++i) mx = fmaxf(mx, s[i]);
;     if (MM == 1) mx = vm ? mx : -1e30f;
;     mx = fmaxf(mx, shx32(mx, lane));
;     const float mn = (mx > m + 8.0f) ? mx : m;
;     float mref = fmaxf(mn, -1e29f);
;     if (MM == 1) mref = vm ? mref : 3e38f;
;     const float alpha = ex2(m - mn);
;     float p[16], rs = 0.f;
; #pragma unroll
;     for (int i = 0; i < 16; ++i) { p[i] = ex2(s[i] - mref); rs += p[i]; }
;     rs += shx32(rs, lane);
;     l = l * alpha + rs;
;     if (__builtin_amdgcn_ballot_w64(mn != m) != 0ull) {
; #pragma unroll
;         for (int i = 0; i < 16; ++i) { o[0][i] *= alpha; o[1][i] *= alpha; }
;     }
;     m = mn;
;     pack_p(p, pf);
; }
; template <int MM> DI void tile128_pipe(LAS const char* K0, LAS const char* V0, LAS const char* K1, LAS const char* V1, const bf16x8 (&qf)[4], unsigned vm0, unsigned vm1,
;                                        float& m, float& l, f32x16 (&o)[2], int r, int h, int lane) {
;     f32x16 sa = qk_rows<0, 4>(K0, 0, qf, r, h), sb = qk_rows<0, 4>(K0, 32, qf, r, h);
;     bf16x8 pfa[2], pfb[2];
;     smax_step_nb<MM>(sa, vm0, m, l, o, pfa, lane);
;     sa = qk_rows<0, 4>(K1, 0, qf, r, h);
;     pv_rows(o, V0, 0, pfa, lane);
;     smax_step_nb<MM>(sb, vm0, m, l, o, pfb, lane);
;     sb = qk_rows<0, 4>(K1, 32, qf, r, h);
;     pv_rows(o, V0, 32, pfb, lane);
;     smax_step_nb<MM>(sa, vm1, m, l, o, pfa, lane);
;     pv_rows(o, V1, 0, pfa, lane);
;     smax_step_nb<MM>(sb, vm1, m, l, o, pfb, lane);
;     pv_rows(o, V1, 32, pfb, lane);
; }
.LBB0_682:
	v_cvt_pk_bf16_f32 v224, v64, v65
	v_cvt_pk_bf16_f32 v225, v66, v67
	ds_read_b128 v[64:67], v212 offset:23040
	ds_read_b128 v[232:235], v212 offset:23072
	ds_read_b128 v[236:239], v212 offset:23104
	ds_read_b128 v[240:243], v212 offset:23136
	v_cvt_pk_bf16_f32 v226, v68, v69
	v_cvt_pk_bf16_f32 v227, v70, v71
	v_cvt_pk_bf16_f32 v228, v72, v73
	v_cvt_pk_bf16_f32 v229, v74, v75
	v_cvt_pk_bf16_f32 v230, v76, v77
	v_cvt_pk_bf16_f32 v231, v78, v79
	s_setprio 1
	s_waitcnt lgkmcnt(3)
	v_mfma_f32_32x32x16_bf16 v[64:79], v[64:67], v[96:99], 0
	s_waitcnt lgkmcnt(2)
	v_mfma_f32_32x32x16_bf16 v[64:79], v[232:235], v[100:103], v[64:79]
	s_waitcnt lgkmcnt(1)
	v_mfma_f32_32x32x16_bf16 v[64:79], v[236:239], v[104:107], v[64:79]
	s_waitcnt lgkmcnt(0)
	v_mfma_f32_32x32x16_bf16 v[64:79], v[240:243], v[108:111], v[64:79]
	s_setprio 0
	ds_read_b64_tr_b16 v[232:233], v217 offset:13824
	ds_read_b64_tr_b16 v[234:235], v217 offset:14976
	ds_read_b64_tr_b16 v[238:239], v217 offset:15040
	ds_read_b64_tr_b16 v[236:237], v217 offset:13888
	ds_read_b64_tr_b16 v[240:241], v217 offset:16128
	ds_read_b64_tr_b16 v[242:243], v217 offset:17280
	ds_read_b64_tr_b16 v[246:247], v217 offset:17344
	ds_read_b64_tr_b16 v[244:245], v217 offset:16192
	s_setprio 1
	s_waitcnt lgkmcnt(6)
	v_mfma_f32_32x32x16_bf16 v[0:15], v[232:235], v[224:227], v[0:15]
	s_waitcnt lgkmcnt(4)
	v_mfma_f32_32x32x16_bf16 v[16:31], v[236:239], v[224:227], v[16:31]
	s_waitcnt lgkmcnt(2)
	v_mfma_f32_32x32x16_bf16 v[0:15], v[240:243], v[228:231], v[0:15]
	s_waitcnt lgkmcnt(0)
	v_mfma_f32_32x32x16_bf16 v[16:31], v[244:247], v[228:231], v[16:31]
	s_setprio 0
	v_max3_f32 v172, v80, s15, v81
	v_max3_f32 v172, v172, v82, v83
	v_max3_f32 v172, v172, v84, v85
	v_max3_f32 v172, v172, v86, v87
	v_max3_f32 v172, v172, v88, v89
	v_max3_f32 v172, v172, v90, v91
	v_max3_f32 v172, v172, v92, v93
	v_max3_f32 v172, v172, v94, v95
	v_mov_b32_e32 v173, v172
	v_mov_b32_e32 v206, v172
	s_nop 1
	v_permlane32_swap_b32_e32 v173, v206
	v_cndmask_b32_e64 v173, v173, v206, s[36:37]
	v_max_f32_e32 v173, v173, v173
	v_max_f32_e32 v172, v172, v173
	v_add_f32_e32 v173, 0x41000000, v222
	v_cmp_gt_f32_e32 vcc, v172, v173
	s_nop 1
	v_cndmask_b32_e32 v221, v222, v172, vcc
	v_max_f32_e32 v172, 0xefa18f08, v221
	v_sub_f32_e32 v80, v80, v172
	v_exp_f32_e32 v223, v80
	v_sub_f32_e32 v80, v81, v172
	v_exp_f32_e32 v81, v80
	v_sub_f32_e32 v80, v82, v172
	v_exp_f32_e32 v224, v80
	v_sub_f32_e32 v80, v83, v172
	v_exp_f32_e32 v225, v80
	v_sub_f32_e32 v82, v84, v172
	v_exp_f32_e32 v226, v82
	v_sub_f32_e32 v82, v85, v172
	v_add_f32_e32 v80, v81, v223
	v_exp_f32_e32 v85, v82
	v_sub_f32_e32 v82, v86, v172
	v_add_f32_e32 v80, v224, v80
	v_exp_f32_e32 v86, v82
	v_sub_f32_e32 v82, v87, v172
	v_add_f32_e32 v80, v225, v80
	v_exp_f32_e32 v87, v82
	v_sub_f32_e32 v82, v88, v172
	v_add_f32_e32 v80, v226, v80
	v_exp_f32_e32 v88, v82
	v_sub_f32_e32 v82, v89, v172
	v_add_f32_e32 v80, v85, v80
	v_exp_f32_e32 v89, v82
	v_sub_f32_e32 v82, v90, v172
	v_add_f32_e32 v80, v86, v80
	v_exp_f32_e32 v90, v82
	v_sub_f32_e32 v82, v91, v172
	v_add_f32_e32 v80, v87, v80
	v_exp_f32_e32 v91, v82
	v_sub_f32_e32 v82, v92, v172
	v_add_f32_e32 v80, v88, v80
	v_exp_f32_e32 v92, v82
	v_sub_f32_e32 v82, v93, v172
	v_add_f32_e32 v80, v89, v80
	v_exp_f32_e32 v93, v82
	v_sub_f32_e32 v82, v94, v172
	v_add_f32_e32 v80, v90, v80
	v_exp_f32_e32 v94, v82
	v_sub_f32_e32 v82, v95, v172
	v_add_f32_e32 v80, v91, v80
	v_exp_f32_e32 v95, v82
	v_add_f32_e32 v80, v92, v80
	v_add_f32_e32 v80, v93, v80
	v_sub_f32_e32 v173, v222, v221
	v_add_f32_e32 v80, v94, v80
	v_add_f32_e32 v82, v95, v80
	v_exp_f32_e32 v80, v173
	v_mov_b32_e32 v83, v82
	v_mov_b32_e32 v84, v82
	s_nop 1
	v_permlane32_swap_b32_e32 v83, v84
	v_cmp_neq_f32_e32 vcc, v221, v222
	s_cbranch_vccz .LBB0_684
	v_pk_mul_f32 v[30:31], v[30:31], v[80:81] op_sel_hi:[1,0]
	v_pk_mul_f32 v[28:29], v[28:29], v[80:81] op_sel_hi:[1,0]
	v_pk_mul_f32 v[26:27], v[26:27], v[80:81] op_sel_hi:[1,0]
	v_pk_mul_f32 v[24:25], v[24:25], v[80:81] op_sel_hi:[1,0]
	v_pk_mul_f32 v[22:23], v[22:23], v[80:81] op_sel_hi:[1,0]
	v_pk_mul_f32 v[20:21], v[20:21], v[80:81] op_sel_hi:[1,0]
	v_pk_mul_f32 v[18:19], v[18:19], v[80:81] op_sel_hi:[1,0]
	v_pk_mul_f32 v[16:17], v[16:17], v[80:81] op_sel_hi:[1,0]
	v_pk_mul_f32 v[14:15], v[14:15], v[80:81] op_sel_hi:[1,0]
	v_pk_mul_f32 v[12:13], v[12:13], v[80:81] op_sel_hi:[1,0]
	v_pk_mul_f32 v[10:11], v[10:11], v[80:81] op_sel_hi:[1,0]
	v_pk_mul_f32 v[8:9], v[8:9], v[80:81] op_sel_hi:[1,0]
	v_pk_mul_f32 v[6:7], v[6:7], v[80:81] op_sel_hi:[1,0]
	v_pk_mul_f32 v[4:5], v[4:5], v[80:81] op_sel_hi:[1,0]
	v_pk_mul_f32 v[2:3], v[2:3], v[80:81] op_sel_hi:[1,0]
	v_pk_mul_f32 v[0:1], v[0:1], v[80:81] op_sel_hi:[1,0]
; DI float ex2(float x) { return __builtin_amdgcn_exp2f(x); }
; template <int MM> DI void smax_step_nb(const f32x16& s, unsigned vm, float& m, float& l, f32x16 (&o)[2], bf16x8 (&pf)[2], int lane) {
;     float mx = -1e30f;
; #pragma unroll
;     for (int i = 0; i < 16; ++i) mx = fmaxf(mx, s[i]);
;     if (MM == 1) mx = vm ? mx : -1e30f;
;     mx = fmaxf(mx, shx32(mx, lane));
;     const float mn = (mx > m + 8.0f) ? mx : m;
;     float mref = fmaxf(mn, -1e29f);
;     if (MM == 1) mref = vm ? mref : 3e38f;
;     const float alpha = ex2(m - mn);
;     float p[16], rs = 0.f;
; #pragma unroll
;     for (int i = 0; i < 16; ++i) { p[i] = ex2(s[i] - mref); rs += p[i]; }
;     rs += shx32(rs, lane);
;     l = l * alpha + rs;
;     if (__builtin_amdgcn_ballot_w64(mn != m) != 0ull) {
; #pragma unroll
;         for (int i = 0; i < 16; ++i) { o[0][i] *= alpha; o[1][i] *= alpha; }
;     }
;     m = mn;
;     pack_p(p, pf);
; }
; template <int MM> DI void tile128_pipe(LAS const char* K0, LAS const char* V0, LAS const char* K1, LAS const char* V1, const bf16x8 (&qf)[4], unsigned vm0, unsigned vm1,
;                                        float& m, float& l, f32x16 (&o)[2], int r, int h, int lane) {
;     ...
;     pv_rows(o, V0, 0, pfa, lane);
;     smax_step_nb<MM>(sb, vm0, m, l, o, pfb, lane);
;     sb = qk_rows<0, 4>(K1, 32, qf, r, h);
;     pv_rows(o, V0, 32, pfb, lane);
;     smax_step_nb<MM>(sa, vm1, m, l, o, pfa, lane);
;     pv_rows(o, V1, 0, pfa, lane);
;     smax_step_nb<MM>(sb, vm1, m, l, o, pfb, lane);
;     pv_rows(o, V1, 32, pfb, lane);
; }
.LBB0_684:
	v_cvt_pk_bf16_f32 v222, v223, v81
	v_cvt_pk_bf16_f32 v223, v224, v225
	v_cvt_pk_bf16_f32 v224, v226, v85
	v_cvt_pk_bf16_f32 v225, v86, v87
	v_cvt_pk_bf16_f32 v86, v88, v89
	v_cvt_pk_bf16_f32 v87, v90, v91
	v_cvt_pk_bf16_f32 v88, v92, v93
	ds_read_b64_tr_b16 v[90:91], v217 offset:27648
	ds_read_b64_tr_b16 v[92:93], v217 offset:28800
	ds_read_b64_tr_b16 v[226:227], v217 offset:29952
	ds_read_b64_tr_b16 v[228:229], v217 offset:31104
	ds_read_b64_tr_b16 v[230:231], v217 offset:27712
	ds_read_b64_tr_b16 v[232:233], v217 offset:28864
	ds_read_b64_tr_b16 v[234:235], v217 offset:30016
	ds_read_b64_tr_b16 v[236:237], v217 offset:31168
	v_cvt_pk_bf16_f32 v89, v94, v95
	s_setprio 1
	s_waitcnt lgkmcnt(6)
	v_mfma_f32_32x32x16_bf16 v[0:15], v[90:93], v[222:225], v[0:15]
	s_waitcnt lgkmcnt(2)
	v_mfma_f32_32x32x16_bf16 v[16:31], v[230:233], v[222:225], v[16:31]
	v_mfma_f32_32x32x16_bf16 v[0:15], v[226:229], v[86:89], v[0:15]
	s_waitcnt lgkmcnt(0)
	v_mfma_f32_32x32x16_bf16 v[16:31], v[234:237], v[86:89], v[16:31]
	s_setprio 0
	v_max3_f32 v81, v64, s15, v65
	v_max3_f32 v81, v81, v66, v67
	v_max3_f32 v81, v81, v68, v69
	v_max3_f32 v81, v81, v70, v71
	v_max3_f32 v81, v81, v72, v73
	v_max3_f32 v81, v81, v74, v75
	v_max3_f32 v81, v81, v76, v77
	v_max3_f32 v81, v81, v78, v79
	v_mov_b32_e32 v85, v81
	v_mov_b32_e32 v86, v81
	s_nop 1
	v_permlane32_swap_b32_e32 v85, v86
	v_max_f32_e32 v81, v85, v86
	v_add_f32_e32 v85, 0x41000000, v221
	v_cmp_gt_f32_e32 vcc, v81, v85
	s_nop 1
	v_cndmask_b32_e32 v81, v221, v81, vcc
	v_max_f32_e32 v93, 0xefa18f08, v81
	v_sub_f32_e32 v64, v64, v93
	v_exp_f32_e32 v85, v64
	v_sub_f32_e32 v64, v65, v93
	v_exp_f32_e32 v86, v64
	v_sub_f32_e32 v64, v66, v93
	v_exp_f32_e32 v87, v64
	v_sub_f32_e32 v64, v67, v93
	v_exp_f32_e32 v88, v64
	v_sub_f32_e32 v65, v68, v93
	v_exp_f32_e32 v89, v65
	v_sub_f32_e32 v65, v69, v93
	v_add_f32_e32 v64, v86, v85
	v_exp_f32_e32 v90, v65
	v_sub_f32_e32 v65, v70, v93
	v_add_f32_e32 v64, v87, v64
	v_exp_f32_e32 v91, v65
	v_sub_f32_e32 v65, v71, v93
	v_add_f32_e32 v64, v88, v64
	v_exp_f32_e32 v92, v65
	v_sub_f32_e32 v65, v72, v93
	v_add_f32_e32 v64, v89, v64
	v_exp_f32_e32 v66, v65
	v_sub_f32_e32 v65, v73, v93
	v_add_f32_e32 v64, v90, v64
	v_exp_f32_e32 v67, v65
	v_sub_f32_e32 v65, v74, v93
	v_add_f32_e32 v64, v91, v64
	v_exp_f32_e32 v68, v65
	v_sub_f32_e32 v65, v75, v93
	v_add_f32_e32 v64, v92, v64
	v_exp_f32_e32 v69, v65
	v_sub_f32_e32 v65, v76, v93
	v_add_f32_e32 v64, v66, v64
	v_exp_f32_e32 v70, v65
	v_sub_f32_e32 v65, v77, v93
	v_add_f32_e32 v64, v67, v64
	v_exp_f32_e32 v71, v65
	v_sub_f32_e32 v65, v78, v93
	v_add_f32_e32 v64, v68, v64
	v_exp_f32_e32 v72, v65
	v_sub_f32_e32 v65, v79, v93
	v_add_f32_e32 v64, v69, v64
	v_exp_f32_e32 v73, v65
	v_add_f32_e32 v64, v70, v64
	v_add_f32_e32 v64, v71, v64
	v_sub_f32_e32 v94, v221, v81
	v_add_f32_e32 v64, v72, v64
	v_add_f32_e32 v65, v73, v64
	v_exp_f32_e32 v64, v94
	v_mov_b32_e32 v74, v65
	v_mov_b32_e32 v75, v65
	s_nop 1
	v_permlane32_swap_b32_e32 v74, v75
	v_cmp_neq_f32_e32 vcc, v81, v221
	s_cbranch_vccz .LBB0_686
	v_pk_mul_f32 v[30:31], v[30:31], v[64:65] op_sel_hi:[1,0]
	v_pk_mul_f32 v[28:29], v[28:29], v[64:65] op_sel_hi:[1,0]
	v_pk_mul_f32 v[26:27], v[26:27], v[64:65] op_sel_hi:[1,0]
	v_pk_mul_f32 v[24:25], v[24:25], v[64:65] op_sel_hi:[1,0]
	v_pk_mul_f32 v[22:23], v[22:23], v[64:65] op_sel_hi:[1,0]
	v_pk_mul_f32 v[20:21], v[20:21], v[64:65] op_sel_hi:[1,0]
	v_pk_mul_f32 v[18:19], v[18:19], v[64:65] op_sel_hi:[1,0]
	v_pk_mul_f32 v[16:17], v[16:17], v[64:65] op_sel_hi:[1,0]
	v_pk_mul_f32 v[14:15], v[14:15], v[64:65] op_sel_hi:[1,0]
	v_pk_mul_f32 v[12:13], v[12:13], v[64:65] op_sel_hi:[1,0]
	v_pk_mul_f32 v[10:11], v[10:11], v[64:65] op_sel_hi:[1,0]
	v_pk_mul_f32 v[8:9], v[8:9], v[64:65] op_sel_hi:[1,0]
	v_pk_mul_f32 v[6:7], v[6:7], v[64:65] op_sel_hi:[1,0]
	v_pk_mul_f32 v[4:5], v[4:5], v[64:65] op_sel_hi:[1,0]
	v_pk_mul_f32 v[2:3], v[2:3], v[64:65] op_sel_hi:[1,0]
	v_pk_mul_f32 v[0:1], v[0:1], v[64:65] op_sel_hi:[1,0]

; #define LAS __attribute__((address_space(3)))
; DI float ex2(float x) { return __builtin_amdgcn_exp2f(x); }
; template <int MM> DI void smax_step_nb(const f32x16& s, unsigned vm, float& m, float& l, f32x16 (&o)[2], bf16x8 (&pf)[2], int lane) {
;     float mx = -1e30f;
; #pragma unroll
;     for (int i = 0; i < 16; ++i) mx = fmaxf(mx, s[i]);
;     if (MM == 1) mx = vm ? mx : -1e30f;
;     mx = fmaxf(mx, shx32(mx, lane));
;     const float mn = (mx > m + 8.0f) ? mx : m;
;     float mref = fmaxf(mn, -1e29f);
;     if (MM == 1) mref = vm ? mref : 3e38f;
;     const float alpha = ex2(m - mn);
;     float p[16], rs = 0.f;
; #pragma unroll
;     for (int i = 0; i < 16; ++i) { p[i] = ex2(s[i] - mref); rs += p[i]; }
;     rs += shx32(rs, lane);
;     l = l * alpha + rs;
;     if (__builtin_amdgcn_ballot_w64(mn != m) != 0ull) {
; #pragma unroll
;         for (int i = 0; i < 16; ++i) { o[0][i] *= alpha; o[1][i] *= alpha; }
;     }
;     m = mn;
;     pack_p(p, pf);
; }
; template <int MM> DI void tile128_pipe(LAS const char* K0, LAS const char* V0, LAS const char* K1, LAS const char* V1, const bf16x8 (&qf)[4], unsigned vm0, unsigned vm1,
;                                        float& m, float& l, f32x16 (&o)[2], int r, int h, int lane) {
;     f32x16 sa = qk_rows<0, 4>(K0, 0, qf, r, h), sb = qk_rows<0, 4>(K0, 32, qf, r, h);
;     bf16x8 pfa[2], pfb[2];
;     smax_step_nb<MM>(sa, vm0, m, l, o, pfa, lane);
;     sa = qk_rows<0, 4>(K1, 0, qf, r, h);
;     pv_rows(o, V0, 0, pfa, lane);
;     smax_step_nb<MM>(sb, vm0, m, l, o, pfb, lane);
.LBB0_687:
	s_cbranch_execz .LBB0_697
	s_waitcnt lgkmcnt(7)
	v_mfma_f32_32x32x16_bf16 v[48:63], v[140:143], v[96:99], 0
	s_waitcnt lgkmcnt(6)
	v_mfma_f32_32x32x16_bf16 v[48:63], v[136:139], v[100:103], v[48:63]
	s_waitcnt lgkmcnt(5)
	v_mfma_f32_32x32x16_bf16 v[48:63], v[132:135], v[104:107], v[48:63]
	s_waitcnt lgkmcnt(4)
	v_mfma_f32_32x32x16_bf16 v[48:63], v[128:131], v[108:111], v[48:63]
	s_waitcnt lgkmcnt(3)
	v_mfma_f32_32x32x16_bf16 v[32:47], v[144:147], v[96:99], 0
	s_nop 9
	v_max3_f32 v64, v48, s15, v49
	v_max3_f32 v64, v64, v50, v51
	v_max3_f32 v64, v64, v52, v53
	v_max3_f32 v64, v64, v54, v55
	v_max3_f32 v64, v64, v56, v57
	v_max3_f32 v64, v64, v58, v59
	v_max3_f32 v64, v64, v60, v61
	v_max3_f32 v64, v64, v62, v63
	v_mov_b32_e32 v65, v64
	v_mov_b32_e32 v66, v64
	s_nop 1
	v_permlane32_swap_b32_e32 v65, v66
	v_max_f32_e32 v64, v65, v66
	v_cmp_gt_f32_e32 vcc, v64, v213
	s_waitcnt lgkmcnt(2)
	v_mfma_f32_32x32x16_bf16 v[32:47], v[148:151], v[100:103], v[32:47]
	v_cndmask_b32_e32 v73, v193, v64, vcc
	v_max_f32_e32 v64, 0xefa18f08, v73
	v_sub_f32_e32 v48, v48, v64
	v_exp_f32_e32 v48, v48
	v_sub_f32_e32 v49, v49, v64
	v_exp_f32_e32 v49, v49
	v_sub_f32_e32 v50, v50, v64
	v_exp_f32_e32 v50, v50
	v_sub_f32_e32 v51, v51, v64
	v_exp_f32_e32 v51, v51
	v_sub_f32_e32 v52, v52, v64
	v_exp_f32_e32 v52, v52
	v_sub_f32_e32 v53, v53, v64
	v_add_f32_e32 v65, v49, v48
	v_exp_f32_e32 v53, v53
	v_sub_f32_e32 v54, v54, v64
	s_waitcnt lgkmcnt(1)
	v_mfma_f32_32x32x16_bf16 v[32:47], v[152:155], v[104:107], v[32:47]
	v_add_f32_e32 v65, v50, v65
	v_exp_f32_e32 v54, v54
	v_sub_f32_e32 v55, v55, v64
	v_add_f32_e32 v65, v51, v65
	v_exp_f32_e32 v55, v55
	v_sub_f32_e32 v56, v56, v64
	v_add_f32_e32 v65, v52, v65
	v_exp_f32_e32 v56, v56
	v_sub_f32_e32 v57, v57, v64
	v_add_f32_e32 v65, v53, v65
	v_exp_f32_e32 v57, v57
	v_sub_f32_e32 v58, v58, v64
	v_add_f32_e32 v65, v54, v65
	v_exp_f32_e32 v58, v58
	v_sub_f32_e32 v59, v59, v64
	v_add_f32_e32 v65, v55, v65
	v_exp_f32_e32 v59, v59
	v_sub_f32_e32 v60, v60, v64
	v_add_f32_e32 v65, v56, v65
	v_exp_f32_e32 v60, v60
	v_sub_f32_e32 v61, v61, v64
	v_add_f32_e32 v65, v57, v65
	v_exp_f32_e32 v61, v61
	v_sub_f32_e32 v62, v62, v64
	s_waitcnt lgkmcnt(0)
	v_mfma_f32_32x32x16_bf16 v[32:47], v[156:159], v[108:111], v[32:47]
	v_add_f32_e32 v65, v58, v65
	v_exp_f32_e32 v62, v62
	v_sub_f32_e32 v63, v63, v64
	v_add_f32_e32 v65, v59, v65
	v_exp_f32_e32 v63, v63
	v_add_f32_e32 v65, v60, v65
	v_sub_f32_e32 v66, v193, v73
	v_add_f32_e32 v65, v61, v65
	v_add_f32_e32 v65, v62, v65
	v_exp_f32_e32 v64, v66
	v_add_f32_e32 v65, v63, v65
	v_mov_b32_e32 v67, v65
	v_mov_b32_e32 v68, v65
	s_nop 1
	v_permlane32_swap_b32_e32 v67, v68
	v_cmp_neq_f32_e32 vcc, v73, v193
	s_cbranch_vccz .LBB0_690
	v_pk_mul_f32 v[30:31], v[30:31], v[64:65] op_sel_hi:[1,0]
	v_pk_mul_f32 v[28:29], v[28:29], v[64:65] op_sel_hi:[1,0]
	v_pk_mul_f32 v[26:27], v[26:27], v[64:65] op_sel_hi:[1,0]
	v_pk_mul_f32 v[24:25], v[24:25], v[64:65] op_sel_hi:[1,0]
	v_pk_mul_f32 v[22:23], v[22:23], v[64:65] op_sel_hi:[1,0]
	v_pk_mul_f32 v[20:21], v[20:21], v[64:65] op_sel_hi:[1,0]
	v_pk_mul_f32 v[18:19], v[18:19], v[64:65] op_sel_hi:[1,0]
	v_pk_mul_f32 v[16:17], v[16:17], v[64:65] op_sel_hi:[1,0]
	v_pk_mul_f32 v[14:15], v[14:15], v[64:65] op_sel_hi:[1,0]
	v_pk_mul_f32 v[12:13], v[12:13], v[64:65] op_sel_hi:[1,0]
	v_pk_mul_f32 v[10:11], v[10:11], v[64:65] op_sel_hi:[1,0]
	v_pk_mul_f32 v[8:9], v[8:9], v[64:65] op_sel_hi:[1,0]
	v_pk_mul_f32 v[6:7], v[6:7], v[64:65] op_sel_hi:[1,0]
	v_pk_mul_f32 v[4:5], v[4:5], v[64:65] op_sel_hi:[1,0]
	v_pk_mul_f32 v[2:3], v[2:3], v[64:65] op_sel_hi:[1,0]
	v_pk_mul_f32 v[0:1], v[0:1], v[64:65] op_sel_hi:[1,0]
.LBB0_690:
	v_cvt_pk_bf16_f32 v74, v48, v49
	v_cvt_pk_bf16_f32 v75, v50, v51
	ds_read_b128 v[48:51], v212 offset:18432
	ds_read_b128 v[82:85], v212 offset:18464
	ds_read_b128 v[86:89], v212 offset:18496
	ds_read_b128 v[90:93], v212 offset:18528
	v_cvt_pk_bf16_f32 v76, v52, v53
	v_cvt_pk_bf16_f32 v77, v54, v55
	v_cvt_pk_bf16_f32 v78, v56, v57
	v_cvt_pk_bf16_f32 v79, v58, v59
	v_cvt_pk_bf16_f32 v80, v60, v61
	v_cvt_pk_bf16_f32 v81, v62, v63
	s_setprio 1
	s_waitcnt lgkmcnt(3)
	v_mfma_f32_32x32x16_bf16 v[48:63], v[48:51], v[96:99], 0
	s_waitcnt lgkmcnt(2)
	v_mfma_f32_32x32x16_bf16 v[48:63], v[82:85], v[100:103], v[48:63]
	s_waitcnt lgkmcnt(1)
	v_mfma_f32_32x32x16_bf16 v[48:63], v[86:89], v[104:107], v[48:63]
	s_waitcnt lgkmcnt(0)
	v_mfma_f32_32x32x16_bf16 v[48:63], v[90:93], v[108:111], v[48:63]
	s_setprio 0
	v_add3_u32 v66, s10, v191, v171
	v_add_u32_e32 v69, v66, v186
	ds_read_b64_tr_b16 v[82:83], v69 offset:9216
	ds_read_b64_tr_b16 v[84:85], v69 offset:10368
	ds_read_b64_tr_b16 v[88:89], v69 offset:10432
	ds_read_b64_tr_b16 v[86:87], v69 offset:9280
	ds_read_b64_tr_b16 v[90:91], v69 offset:11520
	ds_read_b64_tr_b16 v[92:93], v69 offset:12672
	ds_read_b64_tr_b16 v[130:131], v69 offset:12736
	ds_read_b64_tr_b16 v[128:129], v69 offset:11584
	s_setprio 1
	s_waitcnt lgkmcnt(6)
	v_mfma_f32_32x32x16_bf16 v[0:15], v[82:85], v[74:77], v[0:15]
	s_waitcnt lgkmcnt(4)
	v_mfma_f32_32x32x16_bf16 v[16:31], v[86:89], v[74:77], v[16:31]
	s_waitcnt lgkmcnt(2)
	v_mfma_f32_32x32x16_bf16 v[0:15], v[90:93], v[78:81], v[0:15]
	s_waitcnt lgkmcnt(0)
; DI float ex2(float x) { return __builtin_amdgcn_exp2f(x); }
; template <int MM> DI void smax_step_nb(const f32x16& s, unsigned vm, float& m, float& l, f32x16 (&o)[2], bf16x8 (&pf)[2], int lane) {
;     float mx = -1e30f;
; #pragma unroll
;     for (int i = 0; i < 16; ++i) mx = fmaxf(mx, s[i]);
;     if (MM == 1) mx = vm ? mx : -1e30f;
;     mx = fmaxf(mx, shx32(mx, lane));
;     const float mn = (mx > m + 8.0f) ? mx : m;
;     float mref = fmaxf(mn, -1e29f);
;     if (MM == 1) mref = vm ? mref : 3e38f;
;     const float alpha = ex2(m - mn);
;     float p[16], rs = 0.f;
; #pragma unroll
;     for (int i = 0; i < 16; ++i) { p[i] = ex2(s[i] - mref); rs += p[i]; }
;     rs += shx32(rs, lane);
;     l = l * alpha + rs;
;     if (__builtin_amdgcn_ballot_w64(mn != m) != 0ull) {
; #pragma unroll
;         for (int i = 0; i < 16; ++i) { o[0][i] *= alpha; o[1][i] *= alpha; }
;     }
;     m = mn;
;     pack_p(p, pf);
; }
; template <int MM> DI void tile128_pipe(LAS const char* K0, LAS const char* V0, LAS const char* K1, LAS const char* V1, const bf16x8 (&qf)[4], unsigned vm0, unsigned vm1,
;                                        float& m, float& l, f32x16 (&o)[2], int r, int h, int lane) {
;     ...
;     smax_step_nb<MM>(sb, vm0, m, l, o, pfb, lane);
;     sb = qk_rows<0, 4>(K1, 32, qf, r, h);
;     pv_rows(o, V0, 32, pfb, lane);
	v_mfma_f32_32x32x16_bf16 v[16:31], v[128:131], v[78:81], v[16:31]
	s_setprio 0
	v_max3_f32 v66, v32, s15, v33
	v_max3_f32 v66, v66, v34, v35
	v_max3_f32 v66, v66, v36, v37
	v_max3_f32 v66, v66, v38, v39
	v_max3_f32 v66, v66, v40, v41
	v_max3_f32 v66, v66, v42, v43
	v_max3_f32 v66, v66, v44, v45
	v_max3_f32 v66, v66, v46, v47
	v_mov_b32_e32 v70, v66
	v_mov_b32_e32 v71, v66
	s_nop 1
	v_permlane32_swap_b32_e32 v70, v71
	v_max_f32_e32 v66, v70, v71
	v_add_f32_e32 v70, 0x41000000, v73
	v_cmp_gt_f32_e32 vcc, v66, v70
	s_nop 1
	v_cndmask_b32_e32 v74, v73, v66, vcc
	v_max_f32_e32 v66, 0xefa18f08, v74
	v_sub_f32_e32 v32, v32, v66
	v_exp_f32_e32 v32, v32
	v_sub_f32_e32 v33, v33, v66
	v_exp_f32_e32 v33, v33
	v_sub_f32_e32 v34, v34, v66
	v_exp_f32_e32 v34, v34
	v_sub_f32_e32 v35, v35, v66
	v_exp_f32_e32 v35, v35
	v_sub_f32_e32 v36, v36, v66
	v_exp_f32_e32 v36, v36
	v_sub_f32_e32 v37, v37, v66
	v_add_f32_e32 v70, v33, v32
	v_exp_f32_e32 v37, v37
	v_sub_f32_e32 v38, v38, v66
	v_add_f32_e32 v70, v34, v70
	v_exp_f32_e32 v38, v38
	v_sub_f32_e32 v39, v39, v66
	v_add_f32_e32 v70, v35, v70
	v_exp_f32_e32 v39, v39
	v_sub_f32_e32 v40, v40, v66
	v_add_f32_e32 v70, v36, v70
	v_exp_f32_e32 v40, v40
	v_sub_f32_e32 v41, v41, v66
	v_add_f32_e32 v70, v37, v70
	v_exp_f32_e32 v41, v41
	v_sub_f32_e32 v42, v42, v66
	v_add_f32_e32 v70, v38, v70
	v_exp_f32_e32 v42, v42
	v_sub_f32_e32 v43, v43, v66
	v_add_f32_e32 v70, v39, v70
	v_exp_f32_e32 v43, v43
	v_sub_f32_e32 v44, v44, v66
	v_add_f32_e32 v70, v40, v70
	v_exp_f32_e32 v44, v44
	v_sub_f32_e32 v45, v45, v66
	v_add_f32_e32 v70, v41, v70
	v_exp_f32_e32 v45, v45
	v_sub_f32_e32 v46, v46, v66
	v_add_f32_e32 v70, v42, v70
	v_exp_f32_e32 v46, v46
	v_sub_f32_e32 v47, v47, v66
	v_add_f32_e32 v70, v43, v70
	v_exp_f32_e32 v47, v47
	v_add_f32_e32 v66, v44, v70
	v_add_f32_e32 v66, v45, v66
	v_sub_f32_e32 v71, v73, v74
	v_add_f32_e32 v66, v46, v66
	v_add_f32_e32 v70, v47, v66
	v_exp_f32_e32 v66, v71
	v_mov_b32_e32 v71, v70
	v_mov_b32_e32 v72, v70
	s_nop 1
	v_permlane32_swap_b32_e32 v71, v72
	v_cmp_neq_f32_e32 vcc, v74, v73
	s_cbranch_vccz .LBB0_692
	v_pk_mul_f32 v[30:31], v[30:31], v[66:67] op_sel_hi:[1,0]
	v_pk_mul_f32 v[28:29], v[28:29], v[66:67] op_sel_hi:[1,0]
	v_pk_mul_f32 v[26:27], v[26:27], v[66:67] op_sel_hi:[1,0]
	v_pk_mul_f32 v[24:25], v[24:25], v[66:67] op_sel_hi:[1,0]
	v_pk_mul_f32 v[22:23], v[22:23], v[66:67] op_sel_hi:[1,0]
	v_pk_mul_f32 v[20:21], v[20:21], v[66:67] op_sel_hi:[1,0]
	v_pk_mul_f32 v[18:19], v[18:19], v[66:67] op_sel_hi:[1,0]
	v_pk_mul_f32 v[16:17], v[16:17], v[66:67] op_sel_hi:[1,0]
	v_pk_mul_f32 v[14:15], v[14:15], v[66:67] op_sel_hi:[1,0]
	v_pk_mul_f32 v[12:13], v[12:13], v[66:67] op_sel_hi:[1,0]
	v_pk_mul_f32 v[10:11], v[10:11], v[66:67] op_sel_hi:[1,0]
	v_pk_mul_f32 v[8:9], v[8:9], v[66:67] op_sel_hi:[1,0]
	v_pk_mul_f32 v[6:7], v[6:7], v[66:67] op_sel_hi:[1,0]
	v_pk_mul_f32 v[4:5], v[4:5], v[66:67] op_sel_hi:[1,0]
	v_pk_mul_f32 v[2:3], v[2:3], v[66:67] op_sel_hi:[1,0]
	v_pk_mul_f32 v[0:1], v[0:1], v[66:67] op_sel_hi:[1,0]
; DI float ex2(float x) { return __builtin_amdgcn_exp2f(x); }
; template <int MM> DI void smax_step_nb(const f32x16& s, unsigned vm, float& m, float& l, f32x16 (&o)[2], bf16x8 (&pf)[2], int lane) {
;     float mx = -1e30f;
; #pragma unroll
;     for (int i = 0; i < 16; ++i) mx = fmaxf(mx, s[i]);
;     if (MM == 1) mx = vm ? mx : -1e30f;
;     mx = fmaxf(mx, shx32(mx, lane));
;     const float mn = (mx > m + 8.0f) ? mx : m;
;     float mref = fmaxf(mn, -1e29f);
;     if (MM == 1) mref = vm ? mref : 3e38f;
;     const float alpha = ex2(m - mn);
;     float p[16], rs = 0.f;
; #pragma unroll
;     for (int i = 0; i < 16; ++i) { p[i] = ex2(s[i] - mref); rs += p[i]; }
;     rs += shx32(rs, lane);
;     l = l * alpha + rs;
;     if (__builtin_amdgcn_ballot_w64(mn != m) != 0ull) {
; #pragma unroll
;         for (int i = 0; i < 16; ++i) { o[0][i] *= alpha; o[1][i] *= alpha; }
;     }
;     m = mn;
;     pack_p(p, pf);
; }
; template <int MM> DI void tile128_pipe(LAS const char* K0, LAS const char* V0, LAS const char* K1, LAS const char* V1, const bf16x8 (&qf)[4], unsigned vm0, unsigned vm1,
;                                        float& m, float& l, f32x16 (&o)[2], int r, int h, int lane) {
;     ...
;     sb = qk_rows<0, 4>(K1, 32, qf, r, h);
;     pv_rows(o, V0, 32, pfb, lane);
;     smax_step_nb<MM>(sa, vm1, m, l, o, pfa, lane);
;     pv_rows(o, V1, 0, pfa, lane);
;     smax_step_nb<MM>(sb, vm1, m, l, o, pfb, lane);
;     pv_rows(o, V1, 32, pfb, lane);
; }
.LBB0_692:
	v_cvt_pk_bf16_f32 v76, v32, v33
	v_cvt_pk_bf16_f32 v77, v34, v35
	ds_read_b128 v[32:35], v212 offset:23040
	ds_read_b128 v[84:87], v212 offset:23072
	ds_read_b128 v[88:91], v212 offset:23104
	ds_read_b128 v[92:95], v212 offset:23136
	v_cvt_pk_bf16_f32 v78, v36, v37
	v_cvt_pk_bf16_f32 v79, v38, v39
	v_cvt_pk_bf16_f32 v80, v40, v41
	v_cvt_pk_bf16_f32 v81, v42, v43
	v_cvt_pk_bf16_f32 v82, v44, v45
	v_cvt_pk_bf16_f32 v83, v46, v47
	s_setprio 1
	s_waitcnt lgkmcnt(3)
	v_mfma_f32_32x32x16_bf16 v[32:47], v[32:35], v[96:99], 0
	s_waitcnt lgkmcnt(2)
	v_mfma_f32_32x32x16_bf16 v[32:47], v[84:87], v[100:103], v[32:47]
	s_waitcnt lgkmcnt(1)
	v_mfma_f32_32x32x16_bf16 v[32:47], v[88:91], v[104:107], v[32:47]
	s_waitcnt lgkmcnt(0)
	v_mfma_f32_32x32x16_bf16 v[32:47], v[92:95], v[108:111], v[32:47]
	s_setprio 0
	ds_read_b64_tr_b16 v[84:85], v69 offset:13824
	ds_read_b64_tr_b16 v[86:87], v69 offset:14976
	ds_read_b64_tr_b16 v[90:91], v69 offset:15040
	ds_read_b64_tr_b16 v[88:89], v69 offset:13888
	ds_read_b64_tr_b16 v[92:93], v69 offset:16128
	ds_read_b64_tr_b16 v[94:95], v69 offset:17280
	ds_read_b64_tr_b16 v[130:131], v69 offset:17344
	ds_read_b64_tr_b16 v[128:129], v69 offset:16192
	s_setprio 1
	s_waitcnt lgkmcnt(6)
	v_mfma_f32_32x32x16_bf16 v[0:15], v[84:87], v[76:79], v[0:15]
	s_waitcnt lgkmcnt(4)
	v_mfma_f32_32x32x16_bf16 v[16:31], v[88:91], v[76:79], v[16:31]
	s_waitcnt lgkmcnt(2)
	v_mfma_f32_32x32x16_bf16 v[0:15], v[92:95], v[80:83], v[0:15]
	s_waitcnt lgkmcnt(0)
	v_mfma_f32_32x32x16_bf16 v[16:31], v[128:131], v[80:83], v[16:31]
	s_setprio 0
	v_max3_f32 v73, v48, s15, v49
	v_max3_f32 v73, v73, v50, v51
	v_max3_f32 v73, v73, v52, v53
	v_max3_f32 v73, v73, v54, v55
	v_max3_f32 v73, v73, v56, v57
	v_max3_f32 v73, v73, v58, v59
	v_max3_f32 v73, v73, v60, v61
	v_max3_f32 v73, v73, v62, v63
	v_mov_b32_e32 v75, v73
	v_mov_b32_e32 v76, v73
	s_nop 1
	v_permlane32_swap_b32_e32 v75, v76
	v_max_f32_e32 v73, v75, v76
	v_add_f32_e32 v75, 0x41000000, v74
	v_cmp_gt_f32_e32 vcc, v73, v75
	s_nop 1
	v_cndmask_b32_e32 v73, v74, v73, vcc
	v_max_f32_e32 v79, 0xefa18f08, v73
	v_sub_f32_e32 v48, v48, v79
	v_exp_f32_e32 v75, v48
	v_sub_f32_e32 v48, v49, v79
	v_exp_f32_e32 v76, v48
	v_sub_f32_e32 v48, v50, v79
	v_exp_f32_e32 v77, v48
	v_sub_f32_e32 v48, v51, v79
	v_exp_f32_e32 v78, v48
	v_sub_f32_e32 v49, v52, v79
	v_exp_f32_e32 v52, v49
	v_sub_f32_e32 v49, v53, v79
	v_add_f32_e32 v48, v76, v75
	v_exp_f32_e32 v53, v49
	v_sub_f32_e32 v49, v54, v79
	v_add_f32_e32 v48, v77, v48
	v_exp_f32_e32 v54, v49
	v_sub_f32_e32 v49, v55, v79
	v_add_f32_e32 v48, v78, v48
	v_exp_f32_e32 v55, v49
	v_sub_f32_e32 v49, v56, v79
	v_add_f32_e32 v48, v52, v48
	v_exp_f32_e32 v56, v49
	v_sub_f32_e32 v49, v57, v79
	v_add_f32_e32 v48, v53, v48
	v_exp_f32_e32 v57, v49
	v_sub_f32_e32 v49, v58, v79
	v_add_f32_e32 v48, v54, v48
	v_exp_f32_e32 v58, v49
	v_sub_f32_e32 v49, v59, v79
	v_add_f32_e32 v48, v55, v48
	v_exp_f32_e32 v59, v49
	v_sub_f32_e32 v49, v60, v79
	v_add_f32_e32 v48, v56, v48
	v_exp_f32_e32 v60, v49
	v_sub_f32_e32 v49, v61, v79
	v_add_f32_e32 v48, v57, v48
	v_exp_f32_e32 v61, v49
	v_sub_f32_e32 v49, v62, v79
	v_add_f32_e32 v48, v58, v48
	v_exp_f32_e32 v62, v49
	v_sub_f32_e32 v49, v63, v79
	v_add_f32_e32 v48, v59, v48
	v_exp_f32_e32 v63, v49
	v_add_f32_e32 v48, v60, v48
	v_add_f32_e32 v48, v61, v48
	v_sub_f32_e32 v80, v74, v73
	v_add_f32_e32 v48, v62, v48
	v_add_f32_e32 v49, v63, v48
	v_exp_f32_e32 v48, v80
	v_mov_b32_e32 v50, v49
	v_mov_b32_e32 v51, v49
	s_nop 1
	v_permlane32_swap_b32_e32 v50, v51
	v_cmp_neq_f32_e32 vcc, v73, v74
	s_cbranch_vccz .LBB0_694
	v_pk_mul_f32 v[30:31], v[30:31], v[48:49] op_sel_hi:[1,0]
	v_pk_mul_f32 v[28:29], v[28:29], v[48:49] op_sel_hi:[1,0]
	v_pk_mul_f32 v[26:27], v[26:27], v[48:49] op_sel_hi:[1,0]
	v_pk_mul_f32 v[24:25], v[24:25], v[48:49] op_sel_hi:[1,0]
	v_pk_mul_f32 v[22:23], v[22:23], v[48:49] op_sel_hi:[1,0]
	v_pk_mul_f32 v[20:21], v[20:21], v[48:49] op_sel_hi:[1,0]
	v_pk_mul_f32 v[18:19], v[18:19], v[48:49] op_sel_hi:[1,0]
	v_pk_mul_f32 v[16:17], v[16:17], v[48:49] op_sel_hi:[1,0]
	v_pk_mul_f32 v[14:15], v[14:15], v[48:49] op_sel_hi:[1,0]
	v_pk_mul_f32 v[12:13], v[12:13], v[48:49] op_sel_hi:[1,0]
	v_pk_mul_f32 v[10:11], v[10:11], v[48:49] op_sel_hi:[1,0]
	v_pk_mul_f32 v[8:9], v[8:9], v[48:49] op_sel_hi:[1,0]
	v_pk_mul_f32 v[6:7], v[6:7], v[48:49] op_sel_hi:[1,0]
	v_pk_mul_f32 v[4:5], v[4:5], v[48:49] op_sel_hi:[1,0]
	v_pk_mul_f32 v[2:3], v[2:3], v[48:49] op_sel_hi:[1,0]
	v_pk_mul_f32 v[0:1], v[0:1], v[48:49] op_sel_hi:[1,0]

; #define LAS __attribute__((address_space(3)))
; DI float ex2(float x) { return __builtin_amdgcn_exp2f(x); }
; template <int MM> DI void smax_step_nb(const f32x16& s, unsigned vm, float& m, float& l, f32x16 (&o)[2], bf16x8 (&pf)[2], int lane) {
;     float mx = -1e30f;
; #pragma unroll
;     for (int i = 0; i < 16; ++i) mx = fmaxf(mx, s[i]);
;     if (MM == 1) mx = vm ? mx : -1e30f;
;     mx = fmaxf(mx, shx32(mx, lane));
;     const float mn = (mx > m + 8.0f) ? mx : m;
;     float mref = fmaxf(mn, -1e29f);
;     if (MM == 1) mref = vm ? mref : 3e38f;
;     const float alpha = ex2(m - mn);
;     float p[16], rs = 0.f;
; #pragma unroll
;     for (int i = 0; i < 16; ++i) { p[i] = ex2(s[i] - mref); rs += p[i]; }
;     rs += shx32(rs, lane);
;     l = l * alpha + rs;
;     if (__builtin_amdgcn_ballot_w64(mn != m) != 0ull) {
; #pragma unroll
;         for (int i = 0; i < 16; ++i) { o[0][i] *= alpha; o[1][i] *= alpha; }
;     }
;     m = mn;
;     pack_p(p, pf);
; }
; template <int MM> DI void tile64_pipe(LAS const char* Kl, LAS const char* Vl, const bf16x8 (&qf)[4], unsigned vm, float& m, float& l, f32x16 (&o)[2], int r, int h, int lane) {
;     const f32x16 sa = qk_rows<0, 4>(Kl, 0, qf, r, h), sb = qk_rows<0, 4>(Kl, 32, qf, r, h);
;     bf16x8 pfa[2], pfb[2];
;     smax_step_nb<MM>(sa, vm, m, l, o, pfa, lane);
;     pv_rows(o, Vl, 0, pfa, lane);
;     smax_step_nb<MM>(sb, vm, m, l, o, pfb, lane);
;     pv_rows(o, Vl, 32, pfb, lane);
; }
.LBB0_715:
	s_andn2_b64 vcc, exec, s[52:53]
	v_add3_u32 v83, s64, v190, v168
	v_add_f32_e32 v82, 0x41000000, v193
	v_mov_b32_e32 v65, v184
	v_mov_b32_e32 v81, v193
	s_cbranch_vccnz .LBB0_721
	ds_read_b128 v[32:35], v83
	ds_read_b128 v[48:51], v83 offset:32
	ds_read_b128 v[52:55], v83 offset:64
	ds_read_b128 v[56:59], v83 offset:96
	s_setprio 1
	s_waitcnt lgkmcnt(3)
	v_mfma_f32_32x32x16_bf16 v[32:47], v[32:35], v[96:99], 0
	s_waitcnt lgkmcnt(2)
	v_mfma_f32_32x32x16_bf16 v[32:47], v[48:51], v[100:103], v[32:47]
	s_waitcnt lgkmcnt(1)
	v_mfma_f32_32x32x16_bf16 v[32:47], v[52:55], v[104:107], v[32:47]
	s_waitcnt lgkmcnt(0)
	v_mfma_f32_32x32x16_bf16 v[32:47], v[56:59], v[108:111], v[32:47]
	s_setprio 0
	ds_read_b128 v[48:51], v83 offset:4608
	ds_read_b128 v[52:55], v83 offset:4640
	ds_read_b128 v[56:59], v83 offset:4672
	ds_read_b128 v[60:63], v83 offset:4704
	s_setprio 1
	s_waitcnt lgkmcnt(3)
	v_mfma_f32_32x32x16_bf16 v[64:79], v[48:51], v[96:99], 0
	s_waitcnt lgkmcnt(2)
	v_mfma_f32_32x32x16_bf16 v[64:79], v[52:55], v[100:103], v[64:79]
	s_waitcnt lgkmcnt(1)
	v_mfma_f32_32x32x16_bf16 v[64:79], v[56:59], v[104:107], v[64:79]
	s_waitcnt lgkmcnt(0)
	v_mfma_f32_32x32x16_bf16 v[64:79], v[60:63], v[108:111], v[64:79]
	s_setprio 0
	v_max3_f32 v48, v32, s15, v33
	v_max3_f32 v48, v48, v34, v35
	v_max3_f32 v48, v48, v36, v37
	v_max3_f32 v48, v48, v38, v39
	v_max3_f32 v48, v48, v40, v41
	v_max3_f32 v48, v48, v42, v43
	v_max3_f32 v48, v48, v44, v45
	v_max3_f32 v48, v48, v46, v47
	v_mov_b32_e32 v49, v48
	v_mov_b32_e32 v50, v48
	s_nop 1
	v_permlane32_swap_b32_e32 v49, v50
	v_max_f32_e32 v48, v49, v50
	v_cmp_gt_f32_e32 vcc, v48, v82
	s_nop 1
	v_cndmask_b32_e32 v88, v193, v48, vcc
	v_max_f32_e32 v48, 0xefa18f08, v88
	v_sub_f32_e32 v32, v32, v48
	v_exp_f32_e32 v81, v32
	v_sub_f32_e32 v32, v33, v48
	v_exp_f32_e32 v87, v32
	v_sub_f32_e32 v32, v34, v48
	v_exp_f32_e32 v89, v32
	v_sub_f32_e32 v32, v35, v48
	v_exp_f32_e32 v90, v32
	v_sub_f32_e32 v33, v36, v48
	v_exp_f32_e32 v91, v33
	v_sub_f32_e32 v33, v37, v48
	v_add_f32_e32 v32, v87, v81
	v_exp_f32_e32 v92, v33
	v_sub_f32_e32 v33, v38, v48
	v_add_f32_e32 v32, v89, v32
	v_exp_f32_e32 v93, v33
	v_sub_f32_e32 v33, v39, v48
	v_add_f32_e32 v32, v90, v32
	v_exp_f32_e32 v94, v33
	v_sub_f32_e32 v33, v40, v48
	v_add_f32_e32 v32, v91, v32
	v_exp_f32_e32 v95, v33
	v_sub_f32_e32 v33, v41, v48
	v_add_f32_e32 v32, v92, v32
	v_exp_f32_e32 v128, v33
	v_sub_f32_e32 v33, v42, v48
	v_add_f32_e32 v32, v93, v32
	v_exp_f32_e32 v129, v33
	v_sub_f32_e32 v33, v43, v48
	v_add_f32_e32 v32, v94, v32
	v_exp_f32_e32 v130, v33
	v_sub_f32_e32 v33, v44, v48
	v_add_f32_e32 v32, v95, v32
	v_exp_f32_e32 v131, v33
	v_sub_f32_e32 v33, v45, v48
	v_add_f32_e32 v32, v128, v32
	v_exp_f32_e32 v132, v33
	v_sub_f32_e32 v33, v46, v48
	v_add_f32_e32 v32, v129, v32
	v_exp_f32_e32 v133, v33
	v_sub_f32_e32 v33, v47, v48
	v_add_f32_e32 v32, v130, v32
	v_exp_f32_e32 v134, v33
	v_add_f32_e32 v32, v131, v32
	v_sub_f32_e32 v49, v193, v88
	v_add_f32_e32 v32, v132, v32
	v_add_f32_e32 v32, v133, v32
	v_exp_f32_e32 v80, v49
	v_add_f32_e32 v84, v134, v32
	v_mov_b32_e32 v85, v84
	v_mov_b32_e32 v86, v84
	v_mov_b64_e32 v[62:63], v[30:31]
	s_nop 0
	v_permlane32_swap_b32_e32 v85, v86
	v_cmp_neq_f32_e32 vcc, v88, v193
	v_mov_b64_e32 v[60:61], v[28:29]
	v_mov_b64_e32 v[58:59], v[26:27]
	v_mov_b64_e32 v[56:57], v[24:25]
	v_mov_b64_e32 v[54:55], v[22:23]
	v_mov_b64_e32 v[52:53], v[20:21]
	v_mov_b64_e32 v[50:51], v[18:19]
	v_mov_b64_e32 v[48:49], v[16:17]
	v_mov_b64_e32 v[46:47], v[14:15]
	v_mov_b64_e32 v[44:45], v[12:13]
	v_mov_b64_e32 v[42:43], v[10:11]
	v_mov_b64_e32 v[40:41], v[8:9]
	v_mov_b64_e32 v[38:39], v[6:7]
	v_mov_b64_e32 v[36:37], v[4:5]
	v_mov_b64_e32 v[34:35], v[2:3]
	v_mov_b64_e32 v[32:33], v[0:1]
	s_cbranch_vccz .LBB0_718
	v_pk_mul_f32 v[62:63], v[30:31], v[80:81] op_sel_hi:[1,0]
	v_pk_mul_f32 v[60:61], v[28:29], v[80:81] op_sel_hi:[1,0]
	v_pk_mul_f32 v[58:59], v[26:27], v[80:81] op_sel_hi:[1,0]
	v_pk_mul_f32 v[56:57], v[24:25], v[80:81] op_sel_hi:[1,0]
	v_pk_mul_f32 v[54:55], v[22:23], v[80:81] op_sel_hi:[1,0]
	v_pk_mul_f32 v[52:53], v[20:21], v[80:81] op_sel_hi:[1,0]
	v_pk_mul_f32 v[50:51], v[18:19], v[80:81] op_sel_hi:[1,0]
	v_pk_mul_f32 v[48:49], v[16:17], v[80:81] op_sel_hi:[1,0]
	v_pk_mul_f32 v[46:47], v[14:15], v[80:81] op_sel_hi:[1,0]
	v_pk_mul_f32 v[44:45], v[12:13], v[80:81] op_sel_hi:[1,0]
	v_pk_mul_f32 v[42:43], v[10:11], v[80:81] op_sel_hi:[1,0]
	v_pk_mul_f32 v[40:41], v[8:9], v[80:81] op_sel_hi:[1,0]
	v_pk_mul_f32 v[38:39], v[6:7], v[80:81] op_sel_hi:[1,0]
	v_pk_mul_f32 v[36:37], v[4:5], v[80:81] op_sel_hi:[1,0]
	v_pk_mul_f32 v[34:35], v[2:3], v[80:81] op_sel_hi:[1,0]
	v_pk_mul_f32 v[32:33], v[0:1], v[80:81] op_sel_hi:[1,0]
; #define LAS __attribute__((address_space(3)))
; DI float ex2(float x) { return __builtin_amdgcn_exp2f(x); }
; template <int MM> DI void smax_step_nb(const f32x16& s, unsigned vm, float& m, float& l, f32x16 (&o)[2], bf16x8 (&pf)[2], int lane) {
;     float mx = -1e30f;
; #pragma unroll
;     for (int i = 0; i < 16; ++i) mx = fmaxf(mx, s[i]);
;     if (MM == 1) mx = vm ? mx : -1e30f;
;     mx = fmaxf(mx, shx32(mx, lane));
;     const float mn = (mx > m + 8.0f) ? mx : m;
;     float mref = fmaxf(mn, -1e29f);
;     if (MM == 1) mref = vm ? mref : 3e38f;
;     const float alpha = ex2(m - mn);
;     float p[16], rs = 0.f;
; #pragma unroll
;     for (int i = 0; i < 16; ++i) { p[i] = ex2(s[i] - mref); rs += p[i]; }
;     rs += shx32(rs, lane);
;     l = l * alpha + rs;
;     if (__builtin_amdgcn_ballot_w64(mn != m) != 0ull) {
; #pragma unroll
;         for (int i = 0; i < 16; ++i) { o[0][i] *= alpha; o[1][i] *= alpha; }
;     }
;     m = mn;
;     pack_p(p, pf);
; }
; template <int MM> DI void tile64_pipe(LAS const char* Kl, LAS const char* Vl, const bf16x8 (&qf)[4], unsigned vm, float& m, float& l, f32x16 (&o)[2], int r, int h, int lane) {
;     const f32x16 sa = qk_rows<0, 4>(Kl, 0, qf, r, h), sb = qk_rows<0, 4>(Kl, 32, qf, r, h);
;     bf16x8 pfa[2], pfb[2];
;     smax_step_nb<MM>(sa, vm, m, l, o, pfa, lane);
;     pv_rows(o, Vl, 0, pfa, lane);
;     smax_step_nb<MM>(sb, vm, m, l, o, pfb, lane);
;     pv_rows(o, Vl, 32, pfb, lane);
; }
.LBB0_718:
	v_cvt_pk_bf16_f32 v136, v81, v87
	v_add3_u32 v81, s64, v191, v171
	v_add_u32_e32 v87, v81, v186
	v_cvt_pk_bf16_f32 v137, v89, v90
	v_cvt_pk_bf16_f32 v138, v91, v92
	v_cvt_pk_bf16_f32 v139, v93, v94
	v_cvt_pk_bf16_f32 v90, v95, v128
	v_cvt_pk_bf16_f32 v91, v129, v130
	v_cvt_pk_bf16_f32 v92, v131, v132
	v_cvt_pk_bf16_f32 v93, v133, v134
	ds_read_b64_tr_b16 v[128:129], v87 offset:9216
	ds_read_b64_tr_b16 v[130:131], v87 offset:10368
	ds_read_b64_tr_b16 v[132:133], v87 offset:11520
	ds_read_b64_tr_b16 v[134:135], v87 offset:12672
	ds_read_b64_tr_b16 v[140:141], v87 offset:9280
	ds_read_b64_tr_b16 v[142:143], v87 offset:10432
	ds_read_b64_tr_b16 v[144:145], v87 offset:11584
	ds_read_b64_tr_b16 v[146:147], v87 offset:12736
	s_setprio 1
	s_waitcnt lgkmcnt(6)
	v_mfma_f32_32x32x16_bf16 v[32:47], v[128:131], v[136:139], v[32:47]
	s_waitcnt lgkmcnt(2)
	v_mfma_f32_32x32x16_bf16 v[48:63], v[140:143], v[136:139], v[48:63]
	v_mfma_f32_32x32x16_bf16 v[32:47], v[132:135], v[90:93], v[32:47]
	s_waitcnt lgkmcnt(0)
	v_mfma_f32_32x32x16_bf16 v[48:63], v[144:147], v[90:93], v[48:63]
	s_setprio 0
	v_max3_f32 v81, v64, s15, v65
	v_max3_f32 v81, v81, v66, v67
	v_max3_f32 v81, v81, v68, v69
	v_max3_f32 v81, v81, v70, v71
	v_max3_f32 v81, v81, v72, v73
	v_max3_f32 v81, v81, v74, v75
	v_max3_f32 v81, v81, v76, v77
	v_max3_f32 v81, v81, v78, v79
	v_mov_b32_e32 v89, v81
	v_mov_b32_e32 v90, v81
	s_nop 1
	v_permlane32_swap_b32_e32 v89, v90
	v_max_f32_e32 v81, v89, v90
	v_add_f32_e32 v89, 0x41000000, v88
	v_cmp_gt_f32_e32 vcc, v81, v89
	s_nop 1
	v_cndmask_b32_e32 v81, v88, v81, vcc
	v_max_f32_e32 v91, 0xefa18f08, v81
	v_sub_f32_e32 v64, v64, v91
	v_exp_f32_e32 v89, v64
	v_sub_f32_e32 v64, v65, v91
	v_exp_f32_e32 v90, v64
	v_sub_f32_e32 v64, v66, v91
	v_exp_f32_e32 v66, v64
	v_sub_f32_e32 v64, v67, v91
	v_exp_f32_e32 v67, v64
	v_sub_f32_e32 v65, v68, v91
	v_exp_f32_e32 v68, v65
	v_sub_f32_e32 v65, v69, v91
	v_add_f32_e32 v64, v90, v89
	v_exp_f32_e32 v69, v65
	v_sub_f32_e32 v65, v70, v91
	v_add_f32_e32 v64, v66, v64
	v_exp_f32_e32 v70, v65
	v_sub_f32_e32 v65, v71, v91
	v_add_f32_e32 v64, v67, v64
	v_exp_f32_e32 v71, v65
	v_sub_f32_e32 v65, v72, v91
	v_add_f32_e32 v64, v68, v64
	v_exp_f32_e32 v72, v65
	v_sub_f32_e32 v65, v73, v91
	v_add_f32_e32 v64, v69, v64
	v_exp_f32_e32 v73, v65
	v_sub_f32_e32 v65, v74, v91
	v_add_f32_e32 v64, v70, v64
	v_exp_f32_e32 v74, v65
	v_sub_f32_e32 v65, v75, v91
	v_add_f32_e32 v64, v71, v64
	v_exp_f32_e32 v75, v65
	v_sub_f32_e32 v65, v76, v91
	v_add_f32_e32 v64, v72, v64
	v_exp_f32_e32 v76, v65
	v_sub_f32_e32 v65, v77, v91
	v_add_f32_e32 v64, v73, v64
	v_exp_f32_e32 v77, v65
	v_sub_f32_e32 v65, v78, v91
	v_add_f32_e32 v64, v74, v64
	v_exp_f32_e32 v78, v65
	v_sub_f32_e32 v65, v79, v91
	v_add_f32_e32 v64, v75, v64
	v_exp_f32_e32 v79, v65
	v_add_f32_e32 v64, v76, v64
	v_add_f32_e32 v64, v77, v64
	v_sub_f32_e32 v92, v88, v81
	v_add_f32_e32 v64, v78, v64
	v_add_f32_e32 v65, v79, v64
	v_exp_f32_e32 v64, v92
	v_mov_b32_e32 v91, v65
	v_mov_b32_e32 v92, v65
	s_nop 1
	v_permlane32_swap_b32_e32 v91, v92
	v_cmp_neq_f32_e32 vcc, v81, v88
	s_cbranch_vccz .LBB0_720
	v_pk_mul_f32 v[62:63], v[62:63], v[64:65] op_sel_hi:[1,0]
	v_pk_mul_f32 v[60:61], v[60:61], v[64:65] op_sel_hi:[1,0]
	v_pk_mul_f32 v[58:59], v[58:59], v[64:65] op_sel_hi:[1,0]
	v_pk_mul_f32 v[56:57], v[56:57], v[64:65] op_sel_hi:[1,0]
	v_pk_mul_f32 v[54:55], v[54:55], v[64:65] op_sel_hi:[1,0]
	v_pk_mul_f32 v[52:53], v[52:53], v[64:65] op_sel_hi:[1,0]
	v_pk_mul_f32 v[50:51], v[50:51], v[64:65] op_sel_hi:[1,0]
	v_pk_mul_f32 v[48:49], v[48:49], v[64:65] op_sel_hi:[1,0]
	v_pk_mul_f32 v[46:47], v[46:47], v[64:65] op_sel_hi:[1,0]
	v_pk_mul_f32 v[44:45], v[44:45], v[64:65] op_sel_hi:[1,0]
	v_pk_mul_f32 v[42:43], v[42:43], v[64:65] op_sel_hi:[1,0]
	v_pk_mul_f32 v[40:41], v[40:41], v[64:65] op_sel_hi:[1,0]
	v_pk_mul_f32 v[38:39], v[38:39], v[64:65] op_sel_hi:[1,0]
	v_pk_mul_f32 v[36:37], v[36:37], v[64:65] op_sel_hi:[1,0]
	v_pk_mul_f32 v[34:35], v[34:35], v[64:65] op_sel_hi:[1,0]
	v_pk_mul_f32 v[32:33], v[32:33], v[64:65] op_sel_hi:[1,0]

; #define LAS __attribute__((address_space(3)))
; DI float ex2(float x) { return __builtin_amdgcn_exp2f(x); }
; template <int MM> DI void smax_step_nb(const f32x16& s, unsigned vm, float& m, float& l, f32x16 (&o)[2], bf16x8 (&pf)[2], int lane) {
;     float mx = -1e30f;
; #pragma unroll
;     for (int i = 0; i < 16; ++i) mx = fmaxf(mx, s[i]);
;     if (MM == 1) mx = vm ? mx : -1e30f;
;     mx = fmaxf(mx, shx32(mx, lane));
;     const float mn = (mx > m + 8.0f) ? mx : m;
;     float mref = fmaxf(mn, -1e29f);
;     if (MM == 1) mref = vm ? mref : 3e38f;
;     const float alpha = ex2(m - mn);
;     float p[16], rs = 0.f;
; #pragma unroll
;     for (int i = 0; i < 16; ++i) { p[i] = ex2(s[i] - mref); rs += p[i]; }
;     rs += shx32(rs, lane);
;     l = l * alpha + rs;
;     if (__builtin_amdgcn_ballot_w64(mn != m) != 0ull) {
; #pragma unroll
;         for (int i = 0; i < 16; ++i) { o[0][i] *= alpha; o[1][i] *= alpha; }
;     }
;     m = mn;
;     pack_p(p, pf);
; }
; template <int MM> DI void tile64_pipe(LAS const char* Kl, LAS const char* Vl, const bf16x8 (&qf)[4], unsigned vm, float& m, float& l, f32x16 (&o)[2], int r, int h, int lane) {
;     const f32x16 sa = qk_rows<0, 4>(Kl, 0, qf, r, h), sb = qk_rows<0, 4>(Kl, 32, qf, r, h);
;     bf16x8 pfa[2], pfb[2];
;     smax_step_nb<MM>(sa, vm, m, l, o, pfa, lane);
;     pv_rows(o, Vl, 0, pfa, lane);
;     smax_step_nb<MM>(sb, vm, m, l, o, pfb, lane);
;     pv_rows(o, Vl, 32, pfb, lane);
; }
.LBB0_721:
	s_and_b64 vcc, exec, s[48:49]
	s_cbranch_vccz .LBB0_727
	s_nop 7
	ds_read_b128 v[32:35], v83
	s_nop 0
	ds_read_b128 v[48:51], v83 offset:32
	ds_read_b128 v[52:55], v83 offset:64
	ds_read_b128 v[56:59], v83 offset:96
	s_setprio 1
	s_waitcnt lgkmcnt(3)
	v_mfma_f32_32x32x16_bf16 v[32:47], v[32:35], v[96:99], 0
	s_waitcnt lgkmcnt(2)
	v_mfma_f32_32x32x16_bf16 v[32:47], v[48:51], v[100:103], v[32:47]
	s_waitcnt lgkmcnt(1)
	v_mfma_f32_32x32x16_bf16 v[32:47], v[52:55], v[104:107], v[32:47]
	s_waitcnt lgkmcnt(0)
	v_mfma_f32_32x32x16_bf16 v[32:47], v[56:59], v[108:111], v[32:47]
	s_setprio 0
	ds_read_b128 v[48:51], v83 offset:4608
	ds_read_b128 v[52:55], v83 offset:4640
	ds_read_b128 v[56:59], v83 offset:4672
	ds_read_b128 v[60:63], v83 offset:4704
	s_setprio 1
	s_waitcnt lgkmcnt(3)
	v_mfma_f32_32x32x16_bf16 v[64:79], v[48:51], v[96:99], 0
	s_waitcnt lgkmcnt(2)
	v_mfma_f32_32x32x16_bf16 v[64:79], v[52:55], v[100:103], v[64:79]
	s_waitcnt lgkmcnt(1)
	v_mfma_f32_32x32x16_bf16 v[64:79], v[56:59], v[104:107], v[64:79]
	s_waitcnt lgkmcnt(0)
	v_mfma_f32_32x32x16_bf16 v[64:79], v[60:63], v[108:111], v[64:79]
	s_setprio 0
	v_max3_f32 v48, v32, s15, v33
	v_max3_f32 v48, v48, v34, v35
	v_max3_f32 v48, v48, v36, v37
	v_max3_f32 v48, v48, v38, v39
	v_max3_f32 v48, v48, v40, v41
	v_max3_f32 v48, v48, v42, v43
	v_max3_f32 v48, v48, v44, v45
	v_max3_f32 v48, v48, v46, v47
	v_mov_b32_e32 v49, v48
	v_mov_b32_e32 v50, v48
	s_nop 1
	v_permlane32_swap_b32_e32 v49, v50
	v_max_f32_e32 v48, v49, v50
	v_cmp_gt_f32_e32 vcc, v48, v82
	s_nop 1
	v_cndmask_b32_e32 v86, v193, v48, vcc
	v_max_f32_e32 v48, 0xefa18f08, v86
	v_sub_f32_e32 v32, v32, v48
	v_exp_f32_e32 v81, v32
	v_sub_f32_e32 v32, v33, v48
	v_exp_f32_e32 v85, v32
	v_sub_f32_e32 v32, v34, v48
	v_exp_f32_e32 v87, v32
	v_sub_f32_e32 v32, v35, v48
	v_exp_f32_e32 v88, v32
	v_sub_f32_e32 v33, v36, v48
	v_exp_f32_e32 v89, v33
	v_sub_f32_e32 v33, v37, v48
	v_add_f32_e32 v32, v85, v81
	v_exp_f32_e32 v90, v33
	v_sub_f32_e32 v33, v38, v48
	v_add_f32_e32 v32, v87, v32
	v_exp_f32_e32 v91, v33
	v_sub_f32_e32 v33, v39, v48
	v_add_f32_e32 v32, v88, v32
	v_exp_f32_e32 v92, v33
	v_sub_f32_e32 v33, v40, v48
	v_add_f32_e32 v32, v89, v32
	v_exp_f32_e32 v93, v33
	v_sub_f32_e32 v33, v41, v48
	v_add_f32_e32 v32, v90, v32
	v_exp_f32_e32 v94, v33
	v_sub_f32_e32 v33, v42, v48
	v_add_f32_e32 v32, v91, v32
	v_exp_f32_e32 v95, v33
	v_sub_f32_e32 v33, v43, v48
	v_add_f32_e32 v32, v92, v32
	v_exp_f32_e32 v128, v33
	v_sub_f32_e32 v33, v44, v48
	v_add_f32_e32 v32, v93, v32
	v_exp_f32_e32 v129, v33
	v_sub_f32_e32 v33, v45, v48
	v_add_f32_e32 v32, v94, v32
	v_exp_f32_e32 v130, v33
	v_sub_f32_e32 v33, v46, v48
	v_add_f32_e32 v32, v95, v32
	v_exp_f32_e32 v131, v33
	v_sub_f32_e32 v33, v47, v48
	v_add_f32_e32 v32, v128, v32
	v_exp_f32_e32 v132, v33
	v_add_f32_e32 v32, v129, v32
	v_sub_f32_e32 v49, v193, v86
	v_add_f32_e32 v32, v130, v32
	v_add_f32_e32 v32, v131, v32
	v_exp_f32_e32 v80, v49
	v_add_f32_e32 v82, v132, v32
	v_mov_b32_e32 v83, v82
	v_mov_b32_e32 v84, v82
	v_mov_b64_e32 v[62:63], v[30:31]
	s_nop 0
	v_permlane32_swap_b32_e32 v83, v84
	v_cmp_neq_f32_e32 vcc, v86, v193
	v_mov_b64_e32 v[60:61], v[28:29]
	v_mov_b64_e32 v[58:59], v[26:27]
	v_mov_b64_e32 v[56:57], v[24:25]
	v_mov_b64_e32 v[54:55], v[22:23]
	v_mov_b64_e32 v[52:53], v[20:21]
	v_mov_b64_e32 v[50:51], v[18:19]
	v_mov_b64_e32 v[48:49], v[16:17]
	v_mov_b64_e32 v[46:47], v[14:15]
	v_mov_b64_e32 v[44:45], v[12:13]
	v_mov_b64_e32 v[42:43], v[10:11]
	v_mov_b64_e32 v[40:41], v[8:9]
	v_mov_b64_e32 v[38:39], v[6:7]
	v_mov_b64_e32 v[36:37], v[4:5]
	v_mov_b64_e32 v[34:35], v[2:3]
	v_mov_b64_e32 v[32:33], v[0:1]
	s_cbranch_vccz .LBB0_724
	v_pk_mul_f32 v[62:63], v[30:31], v[80:81] op_sel_hi:[1,0]
	v_pk_mul_f32 v[60:61], v[28:29], v[80:81] op_sel_hi:[1,0]
	v_pk_mul_f32 v[58:59], v[26:27], v[80:81] op_sel_hi:[1,0]
	v_pk_mul_f32 v[56:57], v[24:25], v[80:81] op_sel_hi:[1,0]
	v_pk_mul_f32 v[54:55], v[22:23], v[80:81] op_sel_hi:[1,0]
	v_pk_mul_f32 v[52:53], v[20:21], v[80:81] op_sel_hi:[1,0]
	v_pk_mul_f32 v[50:51], v[18:19], v[80:81] op_sel_hi:[1,0]
	v_pk_mul_f32 v[48:49], v[16:17], v[80:81] op_sel_hi:[1,0]
	v_pk_mul_f32 v[46:47], v[14:15], v[80:81] op_sel_hi:[1,0]
	v_pk_mul_f32 v[44:45], v[12:13], v[80:81] op_sel_hi:[1,0]
	v_pk_mul_f32 v[42:43], v[10:11], v[80:81] op_sel_hi:[1,0]
	v_pk_mul_f32 v[40:41], v[8:9], v[80:81] op_sel_hi:[1,0]
	v_pk_mul_f32 v[38:39], v[6:7], v[80:81] op_sel_hi:[1,0]
	v_pk_mul_f32 v[36:37], v[4:5], v[80:81] op_sel_hi:[1,0]
	v_pk_mul_f32 v[34:35], v[2:3], v[80:81] op_sel_hi:[1,0]
	v_pk_mul_f32 v[32:33], v[0:1], v[80:81] op_sel_hi:[1,0]
; #define LAS __attribute__((address_space(3)))
; DI float ex2(float x) { return __builtin_amdgcn_exp2f(x); }
; template <int MM> DI void smax_step_nb(const f32x16& s, unsigned vm, float& m, float& l, f32x16 (&o)[2], bf16x8 (&pf)[2], int lane) {
;     float mx = -1e30f;
; #pragma unroll
;     for (int i = 0; i < 16; ++i) mx = fmaxf(mx, s[i]);
;     if (MM == 1) mx = vm ? mx : -1e30f;
;     mx = fmaxf(mx, shx32(mx, lane));
;     const float mn = (mx > m + 8.0f) ? mx : m;
;     float mref = fmaxf(mn, -1e29f);
;     if (MM == 1) mref = vm ? mref : 3e38f;
;     const float alpha = ex2(m - mn);
;     float p[16], rs = 0.f;
; #pragma unroll
;     for (int i = 0; i < 16; ++i) { p[i] = ex2(s[i] - mref); rs += p[i]; }
;     rs += shx32(rs, lane);
;     l = l * alpha + rs;
;     if (__builtin_amdgcn_ballot_w64(mn != m) != 0ull) {
; #pragma unroll
;         for (int i = 0; i < 16; ++i) { o[0][i] *= alpha; o[1][i] *= alpha; }
;     }
;     m = mn;
;     pack_p(p, pf);
; }
; template <int MM> DI void tile64_pipe(LAS const char* Kl, LAS const char* Vl, const bf16x8 (&qf)[4], unsigned vm, float& m, float& l, f32x16 (&o)[2], int r, int h, int lane) {
;     const f32x16 sa = qk_rows<0, 4>(Kl, 0, qf, r, h), sb = qk_rows<0, 4>(Kl, 32, qf, r, h);
;     bf16x8 pfa[2], pfb[2];
;     smax_step_nb<MM>(sa, vm, m, l, o, pfa, lane);
;     pv_rows(o, Vl, 0, pfa, lane);
;     smax_step_nb<MM>(sb, vm, m, l, o, pfb, lane);
;     pv_rows(o, Vl, 32, pfb, lane);
; }
.LBB0_724:
	v_cvt_pk_bf16_f32 v134, v81, v85
	v_add3_u32 v81, s64, v191, v171
	v_add_u32_e32 v85, v81, v186
	v_cvt_pk_bf16_f32 v135, v87, v88
	v_cvt_pk_bf16_f32 v136, v89, v90
	v_cvt_pk_bf16_f32 v137, v91, v92
	v_cvt_pk_bf16_f32 v88, v93, v94
	v_cvt_pk_bf16_f32 v89, v95, v128
	v_cvt_pk_bf16_f32 v90, v129, v130
	v_cvt_pk_bf16_f32 v91, v131, v132
	ds_read_b64_tr_b16 v[92:93], v85 offset:9216
	ds_read_b64_tr_b16 v[94:95], v85 offset:10368
	ds_read_b64_tr_b16 v[128:129], v85 offset:11520
	ds_read_b64_tr_b16 v[130:131], v85 offset:12672
	ds_read_b64_tr_b16 v[138:139], v85 offset:9280
	ds_read_b64_tr_b16 v[140:141], v85 offset:10432
	ds_read_b64_tr_b16 v[142:143], v85 offset:11584
	ds_read_b64_tr_b16 v[144:145], v85 offset:12736
	s_setprio 1
	s_waitcnt lgkmcnt(6)
	v_mfma_f32_32x32x16_bf16 v[32:47], v[92:95], v[134:137], v[32:47]
	s_waitcnt lgkmcnt(2)
	v_mfma_f32_32x32x16_bf16 v[48:63], v[138:141], v[134:137], v[48:63]
	v_mfma_f32_32x32x16_bf16 v[32:47], v[128:131], v[88:91], v[32:47]
	s_waitcnt lgkmcnt(0)
	v_mfma_f32_32x32x16_bf16 v[48:63], v[142:145], v[88:91], v[48:63]
	s_setprio 0
	v_max3_f32 v81, v64, s15, v65
	v_max3_f32 v81, v81, v66, v67
	v_max3_f32 v81, v81, v68, v69
	v_max3_f32 v81, v81, v70, v71
	v_max3_f32 v81, v81, v72, v73
	v_max3_f32 v81, v81, v74, v75
	v_max3_f32 v81, v81, v76, v77
	v_max3_f32 v81, v81, v78, v79
	v_mov_b32_e32 v87, v81
	v_mov_b32_e32 v88, v81
	s_nop 1
	v_permlane32_swap_b32_e32 v87, v88
	v_max_f32_e32 v81, v87, v88
	v_add_f32_e32 v87, 0x41000000, v86
	v_cmp_gt_f32_e32 vcc, v81, v87
	s_nop 1
	v_cndmask_b32_e32 v81, v86, v81, vcc
	v_max_f32_e32 v89, 0xefa18f08, v81
	v_sub_f32_e32 v64, v64, v89
	v_exp_f32_e32 v87, v64
	v_sub_f32_e32 v64, v65, v89
	v_exp_f32_e32 v88, v64
	v_sub_f32_e32 v64, v66, v89
	v_exp_f32_e32 v66, v64
	v_sub_f32_e32 v64, v67, v89
	v_exp_f32_e32 v67, v64
	v_sub_f32_e32 v65, v68, v89
	v_exp_f32_e32 v68, v65
	v_sub_f32_e32 v65, v69, v89
	v_add_f32_e32 v64, v88, v87
	v_exp_f32_e32 v69, v65
	v_sub_f32_e32 v65, v70, v89
	v_add_f32_e32 v64, v66, v64
	v_exp_f32_e32 v70, v65
	v_sub_f32_e32 v65, v71, v89
	v_add_f32_e32 v64, v67, v64
	v_exp_f32_e32 v71, v65
	v_sub_f32_e32 v65, v72, v89
	v_add_f32_e32 v64, v68, v64
	v_exp_f32_e32 v72, v65
	v_sub_f32_e32 v65, v73, v89
	v_add_f32_e32 v64, v69, v64
	v_exp_f32_e32 v73, v65
	v_sub_f32_e32 v65, v74, v89
	v_add_f32_e32 v64, v70, v64
	v_exp_f32_e32 v74, v65
	v_sub_f32_e32 v65, v75, v89
	v_add_f32_e32 v64, v71, v64
	v_exp_f32_e32 v75, v65
	v_sub_f32_e32 v65, v76, v89
	v_add_f32_e32 v64, v72, v64
	v_exp_f32_e32 v76, v65
	v_sub_f32_e32 v65, v77, v89
	v_add_f32_e32 v64, v73, v64
	v_exp_f32_e32 v77, v65
	v_sub_f32_e32 v65, v78, v89
	v_add_f32_e32 v64, v74, v64
	v_exp_f32_e32 v78, v65
	v_sub_f32_e32 v65, v79, v89
	v_add_f32_e32 v64, v75, v64
	v_exp_f32_e32 v79, v65
	v_add_f32_e32 v64, v76, v64
	v_add_f32_e32 v64, v77, v64
	v_sub_f32_e32 v90, v86, v81
	v_add_f32_e32 v64, v78, v64
	v_add_f32_e32 v65, v79, v64
	v_exp_f32_e32 v64, v90
	v_mov_b32_e32 v89, v65
	v_mov_b32_e32 v90, v65
	s_nop 1
	v_permlane32_swap_b32_e32 v89, v90
	v_cmp_neq_f32_e32 vcc, v81, v86
	s_cbranch_vccz .LBB0_726
	v_pk_mul_f32 v[62:63], v[62:63], v[64:65] op_sel_hi:[1,0]
	v_pk_mul_f32 v[60:61], v[60:61], v[64:65] op_sel_hi:[1,0]
	v_pk_mul_f32 v[58:59], v[58:59], v[64:65] op_sel_hi:[1,0]
	v_pk_mul_f32 v[56:57], v[56:57], v[64:65] op_sel_hi:[1,0]
	v_pk_mul_f32 v[54:55], v[54:55], v[64:65] op_sel_hi:[1,0]
	v_pk_mul_f32 v[52:53], v[52:53], v[64:65] op_sel_hi:[1,0]
	v_pk_mul_f32 v[50:51], v[50:51], v[64:65] op_sel_hi:[1,0]
	v_pk_mul_f32 v[48:49], v[48:49], v[64:65] op_sel_hi:[1,0]
	v_pk_mul_f32 v[46:47], v[46:47], v[64:65] op_sel_hi:[1,0]
	v_pk_mul_f32 v[44:45], v[44:45], v[64:65] op_sel_hi:[1,0]
	v_pk_mul_f32 v[42:43], v[42:43], v[64:65] op_sel_hi:[1,0]
	v_pk_mul_f32 v[40:41], v[40:41], v[64:65] op_sel_hi:[1,0]
	v_pk_mul_f32 v[38:39], v[38:39], v[64:65] op_sel_hi:[1,0]
	v_pk_mul_f32 v[36:37], v[36:37], v[64:65] op_sel_hi:[1,0]
	v_pk_mul_f32 v[34:35], v[34:35], v[64:65] op_sel_hi:[1,0]
	v_pk_mul_f32 v[32:33], v[32:33], v[64:65] op_sel_hi:[1,0]

; DI float ex2(float x) { return __builtin_amdgcn_exp2f(x); }
; template <int MM> DI void smax_step(const f32x16& s, unsigned vm, float& m, float& l, f32x16 (&o)[2], bf16x8 (&pf)[2], int lane) {
;     float t[16], mx = -1e30f;
; #pragma unroll
;     for (int i = 0; i < 16; ++i) { t[i] = (MM == 0) ? s[i] : (MM == 1 ? (vm ? s[i] : -1e30f) : (((vm >> i) & 1u) ? s[i] : -1e30f)); mx = fmaxf(mx, t[i]); }
;     mx = fmaxf(mx, shx32(mx, lane));
;     const float mn = (mx > m + 8.0f) ? mx : m;
;     const float mref = fmaxf(mn, -1e29f);
;     float p[16], rs = 0.f;
; #pragma unroll
;     for (int i = 0; i < 16; ++i) { p[i] = ex2(t[i] - mref); rs += p[i]; }
;     rs += shx32(rs, lane);
;     if (__builtin_amdgcn_ballot_w64(mn != m) != 0ull) {
;         const float alpha = ex2(m - mn);
;         l *= alpha;
; #pragma unroll
;         for (int i = 0; i < 16; ++i) { o[0][i] *= alpha; o[1][i] *= alpha; }
;         m = mn;
;     }
;     l += rs;
;     pack_p(p, pf);
; }
; template <int MODE, bool PRE = false> ...
;     ...
;             if (full) { mm = (selb == ~0ull) ? 0 : 1; vm = lsel ? 1u : 0u; }
;             else { mm = 2; vm = 0;
; #pragma unroll
;                 for (int i = 0; i < 16; ++i) { const int kidx = kbase + (i & 3) + 8 * (i >> 2) + 4 * h; bool ok = kidx <= qpos; if (MODE == MODE_NWIN) ok = ok && (kidx > qpos - 512); vm |= ok ? (1u << i) : 0u; }
;                 if (!lsel) vm = 0;
;                 if (__builtin_amdgcn_ballot_w64(vm != 0) == 0ull) continue; }
;             bf16x8 pf[2];
;             if (MODE == MODE_DIFF) {
;                 const f32x16 s1 = qk_rows<0, 2>(Kl, 32 * sub, qf, r, h), s2 = qk_rows<2, 4>(Kl, 32 * sub, qf, r, h);
;                 bf16x8 pf2[2];
;                 if (mm == 0) { smax_step<0>(s1, vm, m1, l1, o1, pf, lane); smax_step<0>(s2, vm, m2, l2, o2, pf2, lane); }
;                 else { smax_step<2>(s1, vm, m1, l1, o1, pf, lane); smax_step<2>(s2, vm, m2, l2, o2, pf2, lane); }
;                 pv_rows(o1, Vl, 32 * sub, pf, lane);
;                 pv_rows(o2, Vl, 32 * sub, pf2, lane);
;             } else {
;                 const f32x16 s = qk_rows<0, 4>(Kl, 32 * sub, qf, r, h);
;                 if (mm == 0) smax_step<0>(s, vm, m1, l1, o1, pf, lane); else if (mm == 1) smax_step<1>(s, vm, m1, l1, o1, pf, lane); else smax_step<2>(s, vm, m1, l1, o1, pf, lane);
.LBB0_732:
	v_mov_b64_e32 v[94:95], v[30:31]
	s_andn2_b64 vcc, exec, s[0:1]
	v_mov_b64_e32 v[92:93], v[28:29]
	v_mov_b64_e32 v[90:91], v[26:27]
	v_mov_b64_e32 v[88:89], v[24:25]
	v_mov_b64_e32 v[86:87], v[22:23]
	v_mov_b64_e32 v[84:85], v[20:21]
	v_mov_b64_e32 v[82:83], v[18:19]
	v_mov_b64_e32 v[80:81], v[16:17]
	v_mov_b64_e32 v[78:79], v[14:15]
	v_mov_b64_e32 v[76:77], v[12:13]
	v_mov_b64_e32 v[74:75], v[10:11]
	v_mov_b64_e32 v[72:73], v[8:9]
	v_mov_b64_e32 v[70:71], v[6:7]
	v_mov_b64_e32 v[68:69], v[4:5]
	v_mov_b64_e32 v[66:67], v[2:3]
	v_mov_b64_e32 v[64:65], v[0:1]
	v_mov_b32_e32 v129, v184
	v_mov_b32_e32 v130, v193
	s_cbranch_vccnz .LBB0_744
	v_add_u32_e32 v36, v48, v190
	ds_read_b128 v[32:35], v36
	ds_read_b128 v[50:53], v36 offset:32
	ds_read_b128 v[54:57], v36 offset:64
	ds_read_b128 v[58:61], v36 offset:96
	s_setprio 1
	s_waitcnt lgkmcnt(3)
	v_mfma_f32_32x32x16_bf16 v[32:47], v[32:35], v[96:99], 0
	s_waitcnt lgkmcnt(2)
	v_mfma_f32_32x32x16_bf16 v[32:47], v[50:53], v[100:103], v[32:47]
	s_waitcnt lgkmcnt(1)
	v_mfma_f32_32x32x16_bf16 v[32:47], v[54:57], v[104:107], v[32:47]
	s_waitcnt lgkmcnt(0)
	v_mfma_f32_32x32x16_bf16 v[32:47], v[58:61], v[108:111], v[32:47]
	s_setprio 0
	s_cmp_lt_i32 s24, 1
	s_cbranch_scc1 .LBB0_736
	s_cmp_lg_u32 s24, 1
	s_cbranch_scc0 .LBB0_737
	v_and_b32_e32 v49, 1, v135
	v_cmp_eq_u32_e32 vcc, 1, v49
	v_and_b32_e32 v49, 2, v135
	v_and_b32_e32 v52, 4, v135
	s_nop 2
	v_cndmask_b32_e32 v50, v208, v32, vcc
	v_cmp_ne_u32_e32 vcc, 0, v49
	v_and_b32_e32 v53, 8, v135
	v_and_b32_e32 v54, 16, v135
	v_cndmask_b32_e32 v51, v208, v33, vcc
	v_cmp_ne_u32_e32 vcc, 0, v52
	v_and_b32_e32 v55, 32, v135
	v_and_b32_e32 v56, 64, v135
	v_cndmask_b32_e32 v52, v208, v34, vcc
	v_cmp_ne_u32_e32 vcc, 0, v53
	v_and_b32_e32 v57, 0x80, v135
	v_and_b32_e32 v58, 0x100, v135
	v_cndmask_b32_e32 v53, v208, v35, vcc
	v_cmp_ne_u32_e32 vcc, 0, v54
	v_and_b32_e32 v59, 0x200, v135
	v_and_b32_e32 v60, 0x400, v135
	v_cndmask_b32_e32 v54, v208, v36, vcc
	v_cmp_ne_u32_e32 vcc, 0, v55
	v_max3_f32 v49, v50, s15, v51
	v_and_b32_e32 v61, 0x800, v135
	v_cndmask_b32_e32 v55, v208, v37, vcc
	v_cmp_ne_u32_e32 vcc, 0, v56
	v_max3_f32 v49, v49, v52, v53
	v_and_b32_e32 v62, 0x1000, v135
	v_cndmask_b32_e32 v56, v208, v38, vcc
	v_cmp_ne_u32_e32 vcc, 0, v57
	v_max3_f32 v49, v49, v54, v55
	v_and_b32_e32 v63, 0x2000, v135
	v_cndmask_b32_e32 v57, v208, v39, vcc
	v_cmp_ne_u32_e32 vcc, 0, v58
	v_max3_f32 v49, v49, v56, v57
	v_and_b32_e32 v64, 0x4000, v135
	v_cndmask_b32_e32 v58, v208, v40, vcc
	v_cmp_ne_u32_e32 vcc, 0, v59
	v_and_b32_e32 v65, 0x8000, v135
	s_nop 0
	v_cndmask_b32_e32 v59, v208, v41, vcc
	v_cmp_ne_u32_e32 vcc, 0, v60
	v_max3_f32 v49, v49, v58, v59
	s_nop 0
	v_cndmask_b32_e32 v60, v208, v42, vcc
	v_cmp_ne_u32_e32 vcc, 0, v61
	s_nop 1
	v_cndmask_b32_e32 v61, v208, v43, vcc
	v_cmp_ne_u32_e32 vcc, 0, v62
	v_max3_f32 v49, v49, v60, v61
	s_nop 0
	v_cndmask_b32_e32 v62, v208, v44, vcc
	v_cmp_ne_u32_e32 vcc, 0, v63
	s_nop 1
	v_cndmask_b32_e32 v63, v208, v45, vcc
	v_cmp_ne_u32_e32 vcc, 0, v64
	v_max3_f32 v49, v49, v62, v63
	s_nop 0
	v_cndmask_b32_e32 v64, v208, v46, vcc
	v_cmp_ne_u32_e32 vcc, 0, v65
	s_nop 1
	v_cndmask_b32_e32 v65, v208, v47, vcc
	v_max3_f32 v49, v49, v64, v65
	v_mov_b32_e32 v66, v49
	v_mov_b32_e32 v67, v49
	s_nop 1
	v_permlane32_swap_b32_e32 v66, v67
	v_max_f32_e32 v49, v66, v67
	v_add_f32_e32 v66, 0x41000000, v193
	v_cmp_gt_f32_e32 vcc, v49, v66
	s_nop 1
	v_cndmask_b32_e32 v49, v193, v49, vcc
	v_max_f32_e32 v66, 0xefa18f08, v49
	v_sub_f32_e32 v50, v50, v66
	v_exp_f32_e32 v50, v50
	v_sub_f32_e32 v51, v51, v66
	v_exp_f32_e32 v51, v51
	v_sub_f32_e32 v52, v52, v66
	v_exp_f32_e32 v52, v52
	v_sub_f32_e32 v53, v53, v66
	v_exp_f32_e32 v53, v53
	v_sub_f32_e32 v54, v54, v66
	v_exp_f32_e32 v54, v54
	v_sub_f32_e32 v55, v55, v66
	v_add_f32_e32 v67, v51, v50
	v_exp_f32_e32 v55, v55
	v_sub_f32_e32 v56, v56, v66
	v_add_f32_e32 v67, v52, v67
	v_exp_f32_e32 v56, v56
	v_sub_f32_e32 v57, v57, v66
	v_add_f32_e32 v67, v53, v67
	v_exp_f32_e32 v57, v57
	v_sub_f32_e32 v58, v58, v66
	v_add_f32_e32 v67, v54, v67
	v_exp_f32_e32 v58, v58
	v_sub_f32_e32 v59, v59, v66
	v_add_f32_e32 v67, v55, v67
	v_exp_f32_e32 v59, v59
	v_sub_f32_e32 v60, v60, v66
	v_add_f32_e32 v67, v56, v67
	v_exp_f32_e32 v60, v60
	v_sub_f32_e32 v61, v61, v66
	v_add_f32_e32 v67, v57, v67
	v_exp_f32_e32 v61, v61
	v_sub_f32_e32 v62, v62, v66
	v_add_f32_e32 v67, v58, v67
	v_exp_f32_e32 v62, v62
	v_sub_f32_e32 v63, v63, v66
	v_add_f32_e32 v67, v59, v67
	v_exp_f32_e32 v63, v63
	v_sub_f32_e32 v64, v64, v66
	v_add_f32_e32 v67, v60, v67
	v_exp_f32_e32 v131, v64
	v_sub_f32_e32 v64, v65, v66
	v_add_f32_e32 v67, v61, v67
	v_exp_f32_e32 v132, v64
	v_add_f32_e32 v64, v62, v67
	v_add_f32_e32 v64, v63, v64
	v_add_f32_e32 v64, v131, v64
	v_add_f32_e32 v129, v132, v64
	v_cmp_neq_f32_e32 vcc, v49, v193
	v_mov_b32_e32 v133, v129
	v_mov_b32_e32 v134, v129
	s_cmp_lg_u64 vcc, 0
	s_nop 0
	v_permlane32_swap_b32_e32 v133, v134
	s_cselect_b64 s[0:1], -1, 0
	s_cbranch_execz .LBB0_738
	s_branch .LBB0_739

; DI float ex2(float x) { return __builtin_amdgcn_exp2f(x); }
; template <int MM> DI void smax_step(const f32x16& s, unsigned vm, float& m, float& l, f32x16 (&o)[2], bf16x8 (&pf)[2], int lane) {
;     float t[16], mx = -1e30f;
; #pragma unroll
;     for (int i = 0; i < 16; ++i) { t[i] = (MM == 0) ? s[i] : (MM == 1 ? (vm ? s[i] : -1e30f) : (((vm >> i) & 1u) ? s[i] : -1e30f)); mx = fmaxf(mx, t[i]); }
;     mx = fmaxf(mx, shx32(mx, lane));
;     const float mn = (mx > m + 8.0f) ? mx : m;
;     const float mref = fmaxf(mn, -1e29f);
;     float p[16], rs = 0.f;
; #pragma unroll
;     for (int i = 0; i < 16; ++i) { p[i] = ex2(t[i] - mref); rs += p[i]; }
;     rs += shx32(rs, lane);
;     if (__builtin_amdgcn_ballot_w64(mn != m) != 0ull) {
;         const float alpha = ex2(m - mn);
;         l *= alpha;
; #pragma unroll
;         for (int i = 0; i < 16; ++i) { o[0][i] *= alpha; o[1][i] *= alpha; }
;         m = mn;
;     }
;     l += rs;
;     pack_p(p, pf);
; }
.LBB0_738:
	v_cmp_eq_u32_e32 vcc, 0, v135
	s_nop 4
	v_cndmask_b32_e32 v50, v32, v208, vcc
	v_cndmask_b32_e32 v51, v33, v208, vcc
	v_max3_f32 v49, v50, s15, v51
	v_cndmask_b32_e32 v52, v34, v208, vcc
	v_cndmask_b32_e32 v53, v35, v208, vcc
	v_max3_f32 v49, v49, v52, v53
	v_cndmask_b32_e32 v54, v36, v208, vcc
	v_cndmask_b32_e32 v55, v37, v208, vcc
	v_max3_f32 v49, v49, v54, v55
	v_cndmask_b32_e32 v56, v38, v208, vcc
	v_cndmask_b32_e32 v57, v39, v208, vcc
	v_max3_f32 v49, v49, v56, v57
	v_cndmask_b32_e32 v58, v40, v208, vcc
	v_cndmask_b32_e32 v59, v41, v208, vcc
	v_max3_f32 v49, v49, v58, v59
	v_cndmask_b32_e32 v60, v42, v208, vcc
	v_cndmask_b32_e32 v61, v43, v208, vcc
	v_max3_f32 v49, v49, v60, v61
	v_cndmask_b32_e32 v62, v44, v208, vcc
	v_cndmask_b32_e32 v63, v45, v208, vcc
	v_max3_f32 v49, v49, v62, v63
	v_cndmask_b32_e32 v64, v46, v208, vcc
	v_cndmask_b32_e32 v65, v47, v208, vcc
	v_max3_f32 v49, v49, v64, v65
	v_mov_b32_e32 v66, v49
	v_mov_b32_e32 v67, v49
	s_nop 1
	v_permlane32_swap_b32_e32 v66, v67
	v_max_f32_e32 v49, v66, v67
	v_add_f32_e32 v66, 0x41000000, v193
	v_cmp_gt_f32_e32 vcc, v49, v66
	s_nop 1
	v_cndmask_b32_e32 v49, v193, v49, vcc
	v_max_f32_e32 v66, 0xefa18f08, v49
	v_sub_f32_e32 v50, v50, v66
	v_exp_f32_e32 v50, v50
	v_sub_f32_e32 v51, v51, v66
	v_exp_f32_e32 v51, v51
	v_sub_f32_e32 v52, v52, v66
	v_exp_f32_e32 v52, v52
	v_sub_f32_e32 v53, v53, v66
	v_exp_f32_e32 v53, v53
	v_sub_f32_e32 v54, v54, v66
	v_exp_f32_e32 v54, v54
	v_sub_f32_e32 v55, v55, v66
	v_add_f32_e32 v67, v51, v50
	v_exp_f32_e32 v55, v55
	v_sub_f32_e32 v56, v56, v66
	v_add_f32_e32 v67, v52, v67
	v_exp_f32_e32 v56, v56
	v_sub_f32_e32 v57, v57, v66
	v_add_f32_e32 v67, v53, v67
	v_exp_f32_e32 v57, v57
	v_sub_f32_e32 v58, v58, v66
	v_add_f32_e32 v67, v54, v67
	v_exp_f32_e32 v58, v58
	v_sub_f32_e32 v59, v59, v66
	v_add_f32_e32 v67, v55, v67
	v_exp_f32_e32 v59, v59
	v_sub_f32_e32 v60, v60, v66
	v_add_f32_e32 v67, v56, v67
	v_exp_f32_e32 v60, v60
	v_sub_f32_e32 v61, v61, v66
	v_add_f32_e32 v67, v57, v67
	v_exp_f32_e32 v61, v61
	v_sub_f32_e32 v62, v62, v66
	v_add_f32_e32 v67, v58, v67
	v_exp_f32_e32 v62, v62
	v_sub_f32_e32 v63, v63, v66
	v_add_f32_e32 v67, v59, v67
	v_exp_f32_e32 v63, v63
	v_sub_f32_e32 v64, v64, v66
	v_add_f32_e32 v67, v60, v67
	v_exp_f32_e32 v131, v64
	v_sub_f32_e32 v64, v65, v66
	v_add_f32_e32 v67, v61, v67
	v_exp_f32_e32 v132, v64
	v_add_f32_e32 v64, v62, v67
	v_add_f32_e32 v64, v63, v64
	v_add_f32_e32 v64, v131, v64
	v_add_f32_e32 v129, v132, v64
	v_cmp_neq_f32_e32 vcc, v49, v193
	v_mov_b32_e32 v133, v129
	v_mov_b32_e32 v134, v129
	s_cmp_lg_u64 vcc, 0
	s_nop 0
	v_permlane32_swap_b32_e32 v133, v134
	s_cselect_b64 s[0:1], -1, 0

; DI float ex2(float x) { return __builtin_amdgcn_exp2f(x); }
; template <int MM> DI void smax_step(const f32x16& s, unsigned vm, float& m, float& l, f32x16 (&o)[2], bf16x8 (&pf)[2], int lane) {
;     float t[16], mx = -1e30f;
; #pragma unroll
;     for (int i = 0; i < 16; ++i) { t[i] = (MM == 0) ? s[i] : (MM == 1 ? (vm ? s[i] : -1e30f) : (((vm >> i) & 1u) ? s[i] : -1e30f)); mx = fmaxf(mx, t[i]); }
;     mx = fmaxf(mx, shx32(mx, lane));
;     const float mn = (mx > m + 8.0f) ? mx : m;
;     const float mref = fmaxf(mn, -1e29f);
;     float p[16], rs = 0.f;
; #pragma unroll
;     for (int i = 0; i < 16; ++i) { p[i] = ex2(t[i] - mref); rs += p[i]; }
;     rs += shx32(rs, lane);
;     if (__builtin_amdgcn_ballot_w64(mn != m) != 0ull) {
;         const float alpha = ex2(m - mn);
;         l *= alpha;
; #pragma unroll
;         for (int i = 0; i < 16; ++i) { o[0][i] *= alpha; o[1][i] *= alpha; }
;         m = mn;
;     }
;     l += rs;
;     pack_p(p, pf);
; }
.LBB0_740:
	s_nop 5
	v_max3_f32 v49, v32, s15, v33
	v_max3_f32 v49, v49, v34, v35
	v_max3_f32 v49, v49, v36, v37
	v_max3_f32 v49, v49, v38, v39
	v_max3_f32 v49, v49, v40, v41
	v_max3_f32 v49, v49, v42, v43
	v_max3_f32 v49, v49, v44, v45
	v_max3_f32 v49, v49, v46, v47
	v_mov_b32_e32 v50, v49
	v_mov_b32_e32 v51, v49
	s_nop 1
	v_permlane32_swap_b32_e32 v50, v51
	v_max_f32_e32 v49, v50, v51
	v_add_f32_e32 v50, 0x41000000, v193
	v_cmp_gt_f32_e32 vcc, v49, v50
	s_nop 1
	v_cndmask_b32_e32 v49, v193, v49, vcc
	v_max_f32_e32 v64, 0xefa18f08, v49
	v_sub_f32_e32 v32, v32, v64
	v_exp_f32_e32 v50, v32
	v_sub_f32_e32 v32, v33, v64
	v_exp_f32_e32 v51, v32
	v_sub_f32_e32 v32, v34, v64
	v_exp_f32_e32 v52, v32
	v_sub_f32_e32 v32, v35, v64
	v_exp_f32_e32 v53, v32
	v_sub_f32_e32 v33, v36, v64
	v_exp_f32_e32 v54, v33
	v_sub_f32_e32 v33, v37, v64
	v_add_f32_e32 v32, v51, v50
	v_exp_f32_e32 v55, v33
	v_sub_f32_e32 v33, v38, v64
	v_add_f32_e32 v32, v52, v32
	v_exp_f32_e32 v56, v33
	v_sub_f32_e32 v33, v39, v64
	v_add_f32_e32 v32, v53, v32
	v_exp_f32_e32 v57, v33
	v_sub_f32_e32 v33, v40, v64
	v_add_f32_e32 v32, v54, v32
	v_exp_f32_e32 v58, v33
	v_sub_f32_e32 v33, v41, v64
	v_add_f32_e32 v32, v55, v32
	v_exp_f32_e32 v59, v33
	v_sub_f32_e32 v33, v42, v64
	v_add_f32_e32 v32, v56, v32
	v_exp_f32_e32 v60, v33
	v_sub_f32_e32 v33, v43, v64
	v_add_f32_e32 v32, v57, v32
	v_exp_f32_e32 v61, v33
	v_sub_f32_e32 v33, v44, v64
	v_add_f32_e32 v32, v58, v32
	v_exp_f32_e32 v62, v33
	v_sub_f32_e32 v33, v45, v64
	v_add_f32_e32 v32, v59, v32
	v_exp_f32_e32 v63, v33
	v_sub_f32_e32 v33, v46, v64
	v_add_f32_e32 v32, v60, v32
	v_exp_f32_e32 v131, v33
	v_sub_f32_e32 v33, v47, v64
	v_add_f32_e32 v32, v61, v32
	v_exp_f32_e32 v132, v33
	v_add_f32_e32 v32, v62, v32
	v_add_f32_e32 v32, v63, v32
	v_add_f32_e32 v32, v131, v32
	v_add_f32_e32 v129, v132, v32
	v_cmp_neq_f32_e32 vcc, v49, v193
	v_mov_b32_e32 v133, v129
	v_mov_b32_e32 v134, v129
	s_cmp_lg_u64 vcc, 0
	s_nop 0
	v_permlane32_swap_b32_e32 v133, v134
	s_cselect_b64 s[0:1], -1, 0

; DI float ex2(float x) { return __builtin_amdgcn_exp2f(x); }
; template <int MM> DI void smax_step(const f32x16& s, unsigned vm, float& m, float& l, f32x16 (&o)[2], bf16x8 (&pf)[2], int lane) {
;     float t[16], mx = -1e30f;
; #pragma unroll
;     for (int i = 0; i < 16; ++i) { t[i] = (MM == 0) ? s[i] : (MM == 1 ? (vm ? s[i] : -1e30f) : (((vm >> i) & 1u) ? s[i] : -1e30f)); mx = fmaxf(mx, t[i]); }
;     mx = fmaxf(mx, shx32(mx, lane));
;     const float mn = (mx > m + 8.0f) ? mx : m;
;     const float mref = fmaxf(mn, -1e29f);
;     float p[16], rs = 0.f;
; #pragma unroll
;     for (int i = 0; i < 16; ++i) { p[i] = ex2(t[i] - mref); rs += p[i]; }
;     rs += shx32(rs, lane);
;     if (__builtin_amdgcn_ballot_w64(mn != m) != 0ull) {
;         const float alpha = ex2(m - mn);
;         l *= alpha;
; #pragma unroll
;         for (int i = 0; i < 16; ++i) { o[0][i] *= alpha; o[1][i] *= alpha; }
;         m = mn;
;     }
;     l += rs;
;     pack_p(p, pf);
; }
; template <int MODE, bool PRE = false> ...
;     ...
;             if (full) { mm = (selb == ~0ull) ? 0 : 1; vm = lsel ? 1u : 0u; }
;             else { mm = 2; vm = 0;
; #pragma unroll
;                 for (int i = 0; i < 16; ++i) { const int kidx = kbase + (i & 3) + 8 * (i >> 2) + 4 * h; bool ok = kidx <= qpos; if (MODE == MODE_NWIN) ok = ok && (kidx > qpos - 512); vm |= ok ? (1u << i) : 0u; }
;                 if (!lsel) vm = 0;
;                 if (__builtin_amdgcn_ballot_w64(vm != 0) == 0ull) continue; }
;             bf16x8 pf[2];
;             if (MODE == MODE_DIFF) {
;                 const f32x16 s1 = qk_rows<0, 2>(Kl, 32 * sub, qf, r, h), s2 = qk_rows<2, 4>(Kl, 32 * sub, qf, r, h);
;                 bf16x8 pf2[2];
;                 if (mm == 0) { smax_step<0>(s1, vm, m1, l1, o1, pf, lane); smax_step<0>(s2, vm, m2, l2, o2, pf2, lane); }
;                 else { smax_step<2>(s1, vm, m1, l1, o1, pf, lane); smax_step<2>(s2, vm, m2, l2, o2, pf2, lane); }
;                 pv_rows(o1, Vl, 32 * sub, pf, lane);
;                 pv_rows(o2, Vl, 32 * sub, pf2, lane);
;             } else {
;                 const f32x16 s = qk_rows<0, 4>(Kl, 32 * sub, qf, r, h);
;                 if (mm == 0) smax_step<0>(s, vm, m1, l1, o1, pf, lane); else if (mm == 1) smax_step<1>(s, vm, m1, l1, o1, pf, lane); else smax_step<2>(s, vm, m1, l1, o1, pf, lane);
.LBB0_753:
	s_andn2_b64 vcc, exec, s[0:1]
	s_mov_b64 s[0:1], 0
	s_cbranch_vccnz .LBB0_757
	v_add_u32_e32 v36, v48, v192
	ds_read_b128 v[32:35], v36
	ds_read_b128 v[50:53], v36 offset:32
	ds_read_b128 v[54:57], v36 offset:64
	ds_read_b128 v[58:61], v36 offset:96
	s_setprio 1
	s_waitcnt lgkmcnt(3)
	v_mfma_f32_32x32x16_bf16 v[32:47], v[32:35], v[96:99], 0
	s_waitcnt lgkmcnt(2)
	v_mfma_f32_32x32x16_bf16 v[32:47], v[50:53], v[100:103], v[32:47]
	s_waitcnt lgkmcnt(1)
	v_mfma_f32_32x32x16_bf16 v[32:47], v[54:57], v[104:107], v[32:47]
	s_waitcnt lgkmcnt(0)
	v_mfma_f32_32x32x16_bf16 v[32:47], v[58:61], v[108:111], v[32:47]
	s_setprio 0
	s_cmp_lt_i32 s10, 1
	s_cbranch_scc1 .LBB0_758
	s_cmp_lg_u32 s10, 1
	s_cbranch_scc0 .LBB0_759
	v_and_b32_e32 v48, 1, v49
	v_cmp_eq_u32_e32 vcc, 1, v48
	v_and_b32_e32 v50, 2, v49
	v_and_b32_e32 v52, 4, v49
	s_nop 2
	v_cndmask_b32_e32 v48, v208, v32, vcc
	v_cmp_ne_u32_e32 vcc, 0, v50
	v_and_b32_e32 v53, 8, v49
	v_and_b32_e32 v54, 16, v49
	v_cndmask_b32_e32 v50, v208, v33, vcc
	v_cmp_ne_u32_e32 vcc, 0, v52
	v_and_b32_e32 v55, 32, v49
	v_and_b32_e32 v56, 64, v49
	v_cndmask_b32_e32 v52, v208, v34, vcc
	v_cmp_ne_u32_e32 vcc, 0, v53
	v_and_b32_e32 v57, 0x80, v49
	v_and_b32_e32 v58, 0x100, v49
	v_cndmask_b32_e32 v53, v208, v35, vcc
	v_cmp_ne_u32_e32 vcc, 0, v54
	v_and_b32_e32 v59, 0x200, v49
	v_and_b32_e32 v60, 0x400, v49
	v_cndmask_b32_e32 v54, v208, v36, vcc
	v_cmp_ne_u32_e32 vcc, 0, v55
	v_max3_f32 v51, v48, s15, v50
	v_and_b32_e32 v61, 0x800, v49
	v_cndmask_b32_e32 v55, v208, v37, vcc
	v_cmp_ne_u32_e32 vcc, 0, v56
	v_max3_f32 v51, v51, v52, v53
	v_and_b32_e32 v62, 0x1000, v49
	v_cndmask_b32_e32 v56, v208, v38, vcc
	v_cmp_ne_u32_e32 vcc, 0, v57
	v_max3_f32 v51, v51, v54, v55
	v_and_b32_e32 v63, 0x2000, v49
	v_cndmask_b32_e32 v57, v208, v39, vcc
	v_cmp_ne_u32_e32 vcc, 0, v58
	v_max3_f32 v51, v51, v56, v57
	v_and_b32_e32 v131, 0x4000, v49
	v_cndmask_b32_e32 v58, v208, v40, vcc
	v_cmp_ne_u32_e32 vcc, 0, v59
	s_nop 1
	v_cndmask_b32_e32 v59, v208, v41, vcc
	v_cmp_ne_u32_e32 vcc, 0, v60
	v_max3_f32 v51, v51, v58, v59
	s_nop 0
	v_cndmask_b32_e32 v60, v208, v42, vcc
	v_cmp_ne_u32_e32 vcc, 0, v61
	s_nop 1
	v_cndmask_b32_e32 v61, v208, v43, vcc
	v_cmp_ne_u32_e32 vcc, 0, v62
	v_max3_f32 v51, v51, v60, v61
	s_nop 0
	v_cndmask_b32_e32 v62, v208, v44, vcc
	v_cmp_ne_u32_e32 vcc, 0, v63
	s_nop 1
	v_cndmask_b32_e32 v63, v208, v45, vcc
	v_cmp_ne_u32_e32 vcc, 0, v131
	v_and_b32_e32 v131, 0x8000, v49
	v_max3_f32 v51, v51, v62, v63
	v_cndmask_b32_e32 v146, v208, v46, vcc
	v_cmp_ne_u32_e32 vcc, 0, v131
	s_nop 1
	v_cndmask_b32_e32 v147, v208, v47, vcc
	v_max3_f32 v51, v51, v146, v147
	v_mov_b32_e32 v131, v51
	v_mov_b32_e32 v132, v51
	s_nop 1
	v_permlane32_swap_b32_e32 v131, v132
	v_max_f32_e32 v51, v131, v132
	v_add_f32_e32 v131, 0x41000000, v130
	v_cmp_gt_f32_e32 vcc, v51, v131
	s_nop 1
	v_cndmask_b32_e32 v131, v130, v51, vcc
	v_max_f32_e32 v51, 0xefa18f08, v131
	v_sub_f32_e32 v48, v48, v51
	v_exp_f32_e32 v132, v48
	v_sub_f32_e32 v48, v50, v51
	v_exp_f32_e32 v133, v48
	v_sub_f32_e32 v48, v52, v51
	v_exp_f32_e32 v134, v48
	v_sub_f32_e32 v48, v53, v51
	v_exp_f32_e32 v135, v48
	v_sub_f32_e32 v50, v54, v51
	v_exp_f32_e32 v136, v50
	v_sub_f32_e32 v50, v55, v51
	v_add_f32_e32 v48, v133, v132
	v_exp_f32_e32 v137, v50
	v_sub_f32_e32 v50, v56, v51
	v_add_f32_e32 v48, v134, v48
	v_exp_f32_e32 v138, v50
	v_sub_f32_e32 v50, v57, v51
	v_add_f32_e32 v48, v135, v48
	v_exp_f32_e32 v139, v50
	v_sub_f32_e32 v50, v58, v51
	v_add_f32_e32 v48, v136, v48
	v_exp_f32_e32 v140, v50
	v_sub_f32_e32 v50, v59, v51
	v_add_f32_e32 v48, v137, v48
	v_exp_f32_e32 v141, v50
	v_sub_f32_e32 v50, v60, v51
	v_add_f32_e32 v48, v138, v48
	v_exp_f32_e32 v142, v50
	v_sub_f32_e32 v50, v61, v51
	v_add_f32_e32 v48, v139, v48
	v_exp_f32_e32 v143, v50
	v_sub_f32_e32 v50, v62, v51
	v_add_f32_e32 v48, v140, v48
	v_exp_f32_e32 v144, v50
	v_sub_f32_e32 v50, v63, v51
	v_add_f32_e32 v48, v141, v48
	v_exp_f32_e32 v145, v50
	v_sub_f32_e32 v50, v146, v51
	v_add_f32_e32 v48, v142, v48
	v_exp_f32_e32 v146, v50
	v_sub_f32_e32 v50, v147, v51
	v_add_f32_e32 v48, v143, v48
	v_exp_f32_e32 v147, v50
	v_add_f32_e32 v48, v144, v48
	v_add_f32_e32 v48, v145, v48
	v_add_f32_e32 v48, v146, v48
	v_add_f32_e32 v148, v147, v48
	v_cmp_neq_f32_e32 vcc, v131, v130
	v_mov_b32_e32 v149, v148
	v_mov_b32_e32 v150, v148
	s_cmp_lg_u64 vcc, 0
	s_nop 0
	v_permlane32_swap_b32_e32 v149, v150
	s_cselect_b64 s[0:1], -1, 0
	s_cbranch_execz .LBB0_760
	s_branch .LBB0_761

; DI float ex2(float x) { return __builtin_amdgcn_exp2f(x); }
; template <int MM> DI void smax_step(const f32x16& s, unsigned vm, float& m, float& l, f32x16 (&o)[2], bf16x8 (&pf)[2], int lane) {
;     float t[16], mx = -1e30f;
; #pragma unroll
;     for (int i = 0; i < 16; ++i) { t[i] = (MM == 0) ? s[i] : (MM == 1 ? (vm ? s[i] : -1e30f) : (((vm >> i) & 1u) ? s[i] : -1e30f)); mx = fmaxf(mx, t[i]); }
;     mx = fmaxf(mx, shx32(mx, lane));
;     const float mn = (mx > m + 8.0f) ? mx : m;
;     const float mref = fmaxf(mn, -1e29f);
;     float p[16], rs = 0.f;
; #pragma unroll
;     for (int i = 0; i < 16; ++i) { p[i] = ex2(t[i] - mref); rs += p[i]; }
;     rs += shx32(rs, lane);
;     if (__builtin_amdgcn_ballot_w64(mn != m) != 0ull) {
;         const float alpha = ex2(m - mn);
;         l *= alpha;
; #pragma unroll
;         for (int i = 0; i < 16; ++i) { o[0][i] *= alpha; o[1][i] *= alpha; }
;         m = mn;
;     }
;     l += rs;
;     pack_p(p, pf);
; }
.LBB0_759:
.LBB0_760:
	v_cmp_eq_u32_e32 vcc, 0, v49
	s_nop 5
	v_cndmask_b32_e32 v48, v32, v208, vcc
	v_cndmask_b32_e32 v49, v33, v208, vcc
	v_max3_f32 v50, v48, s15, v49
	v_cndmask_b32_e32 v51, v34, v208, vcc
	v_cndmask_b32_e32 v52, v35, v208, vcc
	v_max3_f32 v50, v50, v51, v52
	v_cndmask_b32_e32 v53, v36, v208, vcc
	v_cndmask_b32_e32 v54, v37, v208, vcc
	v_max3_f32 v50, v50, v53, v54
	v_cndmask_b32_e32 v55, v38, v208, vcc
	v_cndmask_b32_e32 v56, v39, v208, vcc
	v_max3_f32 v50, v50, v55, v56
	v_cndmask_b32_e32 v57, v40, v208, vcc
	v_cndmask_b32_e32 v58, v41, v208, vcc
	v_max3_f32 v50, v50, v57, v58
	v_cndmask_b32_e32 v59, v42, v208, vcc
	v_cndmask_b32_e32 v60, v43, v208, vcc
	v_max3_f32 v50, v50, v59, v60
	v_cndmask_b32_e32 v61, v44, v208, vcc
	v_cndmask_b32_e32 v62, v45, v208, vcc
	v_max3_f32 v50, v50, v61, v62
	v_cndmask_b32_e32 v63, v46, v208, vcc
	v_cndmask_b32_e32 v147, v47, v208, vcc
	v_max3_f32 v50, v50, v63, v147
	v_mov_b32_e32 v131, v50
	v_mov_b32_e32 v132, v50
	s_nop 1
	v_permlane32_swap_b32_e32 v131, v132
	v_max_f32_e32 v50, v131, v132
	v_add_f32_e32 v131, 0x41000000, v130
	v_cmp_gt_f32_e32 vcc, v50, v131
	s_nop 1
	v_cndmask_b32_e32 v131, v130, v50, vcc
	v_max_f32_e32 v50, 0xefa18f08, v131
	v_sub_f32_e32 v48, v48, v50
	v_exp_f32_e32 v132, v48
	v_sub_f32_e32 v48, v49, v50
	v_exp_f32_e32 v133, v48
	v_sub_f32_e32 v48, v51, v50
	v_exp_f32_e32 v134, v48
	v_sub_f32_e32 v48, v52, v50
	v_exp_f32_e32 v135, v48
	v_sub_f32_e32 v49, v53, v50
	v_exp_f32_e32 v136, v49
	v_sub_f32_e32 v49, v54, v50
	v_add_f32_e32 v48, v133, v132
	v_exp_f32_e32 v137, v49
	v_sub_f32_e32 v49, v55, v50
	v_add_f32_e32 v48, v134, v48
	v_exp_f32_e32 v138, v49
	v_sub_f32_e32 v49, v56, v50
	v_add_f32_e32 v48, v135, v48
	v_exp_f32_e32 v139, v49
	v_sub_f32_e32 v49, v57, v50
	v_add_f32_e32 v48, v136, v48
	v_exp_f32_e32 v140, v49
	v_sub_f32_e32 v49, v58, v50
	v_add_f32_e32 v48, v137, v48
	v_exp_f32_e32 v141, v49
	v_sub_f32_e32 v49, v59, v50
	v_add_f32_e32 v48, v138, v48
	v_exp_f32_e32 v142, v49
	v_sub_f32_e32 v49, v60, v50
	v_add_f32_e32 v48, v139, v48
	v_exp_f32_e32 v143, v49
	v_sub_f32_e32 v49, v61, v50
	v_add_f32_e32 v48, v140, v48
	v_exp_f32_e32 v144, v49
	v_sub_f32_e32 v49, v62, v50
	v_add_f32_e32 v48, v141, v48
	v_exp_f32_e32 v145, v49
	v_sub_f32_e32 v49, v63, v50
	v_add_f32_e32 v48, v142, v48
	v_exp_f32_e32 v146, v49
	v_sub_f32_e32 v49, v147, v50
	v_add_f32_e32 v48, v143, v48
	v_exp_f32_e32 v147, v49
	v_add_f32_e32 v48, v144, v48
	v_add_f32_e32 v48, v145, v48
	v_add_f32_e32 v48, v146, v48
	v_add_f32_e32 v148, v147, v48
	v_cmp_neq_f32_e32 vcc, v131, v130
	v_mov_b32_e32 v149, v148
	v_mov_b32_e32 v150, v148
	s_cmp_lg_u64 vcc, 0
	s_nop 0
	v_permlane32_swap_b32_e32 v149, v150
	s_cselect_b64 s[0:1], -1, 0

; DI float ex2(float x) { return __builtin_amdgcn_exp2f(x); }
; template <int MM> DI void smax_step(const f32x16& s, unsigned vm, float& m, float& l, f32x16 (&o)[2], bf16x8 (&pf)[2], int lane) {
;     float t[16], mx = -1e30f;
; #pragma unroll
;     for (int i = 0; i < 16; ++i) { t[i] = (MM == 0) ? s[i] : (MM == 1 ? (vm ? s[i] : -1e30f) : (((vm >> i) & 1u) ? s[i] : -1e30f)); mx = fmaxf(mx, t[i]); }
;     mx = fmaxf(mx, shx32(mx, lane));
;     const float mn = (mx > m + 8.0f) ? mx : m;
;     const float mref = fmaxf(mn, -1e29f);
;     float p[16], rs = 0.f;
; #pragma unroll
;     for (int i = 0; i < 16; ++i) { p[i] = ex2(t[i] - mref); rs += p[i]; }
;     rs += shx32(rs, lane);
;     if (__builtin_amdgcn_ballot_w64(mn != m) != 0ull) {
;         const float alpha = ex2(m - mn);
;         l *= alpha;
; #pragma unroll
;         for (int i = 0; i < 16; ++i) { o[0][i] *= alpha; o[1][i] *= alpha; }
;         m = mn;
;     }
;     l += rs;
;     pack_p(p, pf);
; }
.LBB0_762:
	s_nop 6
	v_max3_f32 v48, v32, s15, v33
	v_max3_f32 v48, v48, v34, v35
	v_max3_f32 v48, v48, v36, v37
	v_max3_f32 v48, v48, v38, v39
	v_max3_f32 v48, v48, v40, v41
	v_max3_f32 v48, v48, v42, v43
	v_max3_f32 v48, v48, v44, v45
	v_max3_f32 v48, v48, v46, v47
	v_mov_b32_e32 v49, v48
	v_mov_b32_e32 v50, v48
	s_nop 1
	v_permlane32_swap_b32_e32 v49, v50
	v_max_f32_e32 v48, v49, v50
	v_add_f32_e32 v49, 0x41000000, v130
	v_cmp_gt_f32_e32 vcc, v48, v49
	s_nop 1
	v_cndmask_b32_e32 v131, v130, v48, vcc
	v_max_f32_e32 v48, 0xefa18f08, v131
	v_sub_f32_e32 v32, v32, v48
	v_exp_f32_e32 v132, v32
	v_sub_f32_e32 v32, v33, v48
	v_exp_f32_e32 v133, v32
	v_sub_f32_e32 v32, v34, v48
	v_exp_f32_e32 v134, v32
	v_sub_f32_e32 v32, v35, v48
	v_exp_f32_e32 v135, v32
	v_sub_f32_e32 v33, v36, v48
	v_exp_f32_e32 v136, v33
	v_sub_f32_e32 v33, v37, v48
	v_add_f32_e32 v32, v133, v132
	v_exp_f32_e32 v137, v33
	v_sub_f32_e32 v33, v38, v48
	v_add_f32_e32 v32, v134, v32
	v_exp_f32_e32 v138, v33
	v_sub_f32_e32 v33, v39, v48
	v_add_f32_e32 v32, v135, v32
	v_exp_f32_e32 v139, v33
	v_sub_f32_e32 v33, v40, v48
	v_add_f32_e32 v32, v136, v32
	v_exp_f32_e32 v140, v33
	v_sub_f32_e32 v33, v41, v48
	v_add_f32_e32 v32, v137, v32
	v_exp_f32_e32 v141, v33
	v_sub_f32_e32 v33, v42, v48
	v_add_f32_e32 v32, v138, v32
	v_exp_f32_e32 v142, v33
	v_sub_f32_e32 v33, v43, v48
	v_add_f32_e32 v32, v139, v32
	v_exp_f32_e32 v143, v33
	v_sub_f32_e32 v33, v44, v48
	v_add_f32_e32 v32, v140, v32
	v_exp_f32_e32 v144, v33
	v_sub_f32_e32 v33, v45, v48
	v_add_f32_e32 v32, v141, v32
	v_exp_f32_e32 v145, v33
	v_sub_f32_e32 v33, v46, v48
	v_add_f32_e32 v32, v142, v32
	v_exp_f32_e32 v146, v33
	v_sub_f32_e32 v33, v47, v48
	v_add_f32_e32 v32, v143, v32
	v_exp_f32_e32 v147, v33
	v_add_f32_e32 v32, v144, v32
	v_add_f32_e32 v32, v145, v32
	v_add_f32_e32 v32, v146, v32
	v_add_f32_e32 v148, v147, v32
	v_cmp_neq_f32_e32 vcc, v131, v130
	v_mov_b32_e32 v149, v148
	v_mov_b32_e32 v150, v148
	s_cmp_lg_u64 vcc, 0
	s_nop 0
	v_permlane32_swap_b32_e32 v149, v150
	s_cselect_b64 s[0:1], -1, 0

; DI float ex2(float x) { return __builtin_amdgcn_exp2f(x); }
; template <int MM> DI void smax_step(const f32x16& s, unsigned vm, float& m, float& l, f32x16 (&o)[2], bf16x8 (&pf)[2], int lane) {
;     float t[16], mx = -1e30f;
; #pragma unroll
;     for (int i = 0; i < 16; ++i) { t[i] = (MM == 0) ? s[i] : (MM == 1 ? (vm ? s[i] : -1e30f) : (((vm >> i) & 1u) ? s[i] : -1e30f)); mx = fmaxf(mx, t[i]); }
;     mx = fmaxf(mx, shx32(mx, lane));
;     const float mn = (mx > m + 8.0f) ? mx : m;
;     const float mref = fmaxf(mn, -1e29f);
;     float p[16], rs = 0.f;
; #pragma unroll
;     for (int i = 0; i < 16; ++i) { p[i] = ex2(t[i] - mref); rs += p[i]; }
;     rs += shx32(rs, lane);
;     if (__builtin_amdgcn_ballot_w64(mn != m) != 0ull) {
;         const float alpha = ex2(m - mn);
;         l *= alpha;
; #pragma unroll
;         for (int i = 0; i < 16; ++i) { o[0][i] *= alpha; o[1][i] *= alpha; }
;         m = mn;
;     }
;     l += rs;
;     pack_p(p, pf);
; }
; template <int MODE, bool PRE = false> ...
;     ...
;             else { mm = 2; vm = 0;
; #pragma unroll
;                 for (int i = 0; i < 16; ++i) { const int kidx = kbase + (i & 3) + 8 * (i >> 2) + 4 * h; bool ok = kidx <= qpos; if (MODE == MODE_NWIN) ok = ok && (kidx > qpos - 512); vm |= ok ? (1u << i) : 0u; }
;                 if (!lsel) vm = 0;
;                 if (__builtin_amdgcn_ballot_w64(vm != 0) == 0ull) continue; }
;             bf16x8 pf[2];
;             if (MODE == MODE_DIFF) {
;                 const f32x16 s1 = qk_rows<0, 2>(Kl, 32 * sub, qf, r, h), s2 = qk_rows<2, 4>(Kl, 32 * sub, qf, r, h);
;                 bf16x8 pf2[2];
;                 if (mm == 0) { smax_step<0>(s1, vm, m1, l1, o1, pf, lane); smax_step<0>(s2, vm, m2, l2, o2, pf2, lane); }
;                 else { smax_step<2>(s1, vm, m1, l1, o1, pf, lane); smax_step<2>(s2, vm, m2, l2, o2, pf2, lane); }
.LBB0_791:
	s_andn2_b64 vcc, exec, s[38:39]
	s_cbranch_vccnz .LBB0_804
	v_add_u32_e32 v33, v227, v221
	ds_read_b128 v[34:37], v33
	ds_read_b128 v[38:41], v33 offset:32
	s_setprio 1
	s_waitcnt lgkmcnt(1)
	v_mfma_f32_32x32x16_bf16 v[112:127], v[34:37], v[152:155], 0
	s_waitcnt lgkmcnt(0)
	v_mfma_f32_32x32x16_bf16 v[112:127], v[38:41], v[156:159], v[112:127]
	s_setprio 0
	ds_read_b128 v[34:37], v33 offset:64
	ds_read_b128 v[38:41], v33 offset:96
	s_setprio 1
	s_waitcnt lgkmcnt(1)
	v_mfma_f32_32x32x16_bf16 v[96:111], v[34:37], v[160:163], 0
	s_waitcnt lgkmcnt(0)
	v_mfma_f32_32x32x16_bf16 v[96:111], v[38:41], v[164:167], v[96:111]
	s_setprio 0
	s_andn2_b64 vcc, exec, s[0:1]
	v_add_f32_e32 v229, 0x41000000, v226
	s_cbranch_vccz .LBB0_796
	v_and_b32_e32 v33, 1, v32
	v_and_b32_e32 v34, 2, v32
	v_cmp_eq_u32_e64 s[0:1], 0, v33
	v_cmp_eq_u32_e64 s[38:39], 0, v34
	v_and_b32_e32 v36, 4, v32
	v_and_b32_e32 v37, 8, v32
	v_cndmask_b32_e64 v33, v112, v208, s[0:1]
	v_cndmask_b32_e64 v34, v113, v208, s[38:39]
	v_cmp_eq_u32_e64 s[40:41], 0, v36
	v_cmp_eq_u32_e64 s[42:43], 0, v37
	v_and_b32_e32 v38, 16, v32
	v_and_b32_e32 v39, 32, v32
	v_max3_f32 v35, v33, s15, v34
	v_cndmask_b32_e64 v36, v114, v208, s[40:41]
	v_cndmask_b32_e64 v37, v115, v208, s[42:43]
	v_cmp_eq_u32_e64 s[44:45], 0, v38
	v_cmp_eq_u32_e64 s[48:49], 0, v39
	v_and_b32_e32 v40, 64, v32
	v_and_b32_e32 v41, 0x80, v32
	v_max3_f32 v35, v35, v36, v37
	v_cndmask_b32_e64 v38, v116, v208, s[44:45]
	v_cndmask_b32_e64 v39, v117, v208, s[48:49]
	v_cmp_eq_u32_e64 s[50:51], 0, v40
	v_cmp_eq_u32_e64 s[52:53], 0, v41
	v_and_b32_e32 v42, 0x100, v32
	v_and_b32_e32 v43, 0x200, v32
	v_max3_f32 v35, v35, v38, v39
	v_cndmask_b32_e64 v40, v118, v208, s[50:51]
	v_cndmask_b32_e64 v41, v119, v208, s[52:53]
	v_cmp_eq_u32_e64 s[54:55], 0, v42
	v_cmp_eq_u32_e64 s[56:57], 0, v43
	v_and_b32_e32 v44, 0x400, v32
	v_and_b32_e32 v45, 0x800, v32
	v_max3_f32 v35, v35, v40, v41
	v_cndmask_b32_e64 v42, v120, v208, s[54:55]
	v_cndmask_b32_e64 v43, v121, v208, s[56:57]
	v_cmp_eq_u32_e64 s[58:59], 0, v44
	v_cmp_eq_u32_e64 s[60:61], 0, v45
	v_and_b32_e32 v46, 0x1000, v32
	v_and_b32_e32 v47, 0x2000, v32
	v_max3_f32 v35, v35, v42, v43
	v_cndmask_b32_e64 v44, v122, v208, s[58:59]
	v_cndmask_b32_e64 v45, v123, v208, s[60:61]
	v_cmp_eq_u32_e64 s[62:63], 0, v46
	v_cmp_eq_u32_e64 s[64:65], 0, v47
	v_and_b32_e32 v48, 0x4000, v32
	v_and_b32_e32 v32, 0x8000, v32
	v_max3_f32 v35, v35, v44, v45
	v_cndmask_b32_e64 v46, v124, v208, s[62:63]
	v_cndmask_b32_e64 v47, v125, v208, s[64:65]
	v_cmp_eq_u32_e64 s[66:67], 0, v48
	v_cmp_eq_u32_e64 s[68:69], 0, v32
	v_max3_f32 v35, v35, v46, v47
	v_cndmask_b32_e64 v48, v126, v208, s[66:67]
	v_cndmask_b32_e64 v32, v127, v208, s[68:69]
	v_max3_f32 v35, v35, v48, v32
	v_mov_b32_e32 v49, v35
	v_mov_b32_e32 v50, v35
	s_nop 1
	v_permlane32_swap_b32_e32 v49, v50
	v_max_f32_e32 v35, v49, v50
	v_cmp_gt_f32_e32 vcc, v35, v229
	v_mov_b32_e32 v228, v226
	v_mov_b32_e32 v192, v186
	v_cndmask_b32_e32 v130, v226, v35, vcc
	v_max_f32_e32 v35, 0xefa18f08, v130
	v_sub_f32_e32 v33, v33, v35
	v_exp_f32_e32 v128, v33
	v_sub_f32_e32 v33, v34, v35
	v_exp_f32_e32 v129, v33
	v_sub_f32_e32 v33, v36, v35
	v_exp_f32_e32 v131, v33
	v_sub_f32_e32 v33, v37, v35
	v_exp_f32_e32 v132, v33
	v_sub_f32_e32 v34, v38, v35
	v_exp_f32_e32 v133, v34
	v_sub_f32_e32 v34, v39, v35
	v_add_f32_e32 v33, v129, v128
	v_exp_f32_e32 v134, v34
	v_sub_f32_e32 v34, v40, v35
	v_add_f32_e32 v33, v131, v33
	v_exp_f32_e32 v135, v34
	v_sub_f32_e32 v34, v41, v35
	v_add_f32_e32 v33, v132, v33
	v_exp_f32_e32 v187, v34
	v_sub_f32_e32 v34, v42, v35
	v_add_f32_e32 v33, v133, v33
	v_exp_f32_e32 v189, v34
	v_sub_f32_e32 v34, v43, v35
	v_add_f32_e32 v33, v134, v33
	v_exp_f32_e32 v190, v34
	v_sub_f32_e32 v34, v44, v35
	v_add_f32_e32 v33, v135, v33
	v_exp_f32_e32 v191, v34
	v_sub_f32_e32 v34, v45, v35
	v_add_f32_e32 v33, v187, v33
	v_exp_f32_e32 v193, v34
	v_sub_f32_e32 v34, v46, v35
	v_add_f32_e32 v33, v189, v33
	v_exp_f32_e32 v230, v34
	v_sub_f32_e32 v34, v47, v35
	v_add_f32_e32 v33, v190, v33
	v_exp_f32_e32 v231, v34
	v_sub_f32_e32 v34, v48, v35
	v_add_f32_e32 v33, v191, v33
	v_exp_f32_e32 v232, v34
	v_sub_f32_e32 v32, v32, v35
	v_add_f32_e32 v33, v193, v33
	v_exp_f32_e32 v233, v32
	v_add_f32_e32 v32, v230, v33
	v_add_f32_e32 v32, v231, v32
	v_add_f32_e32 v32, v232, v32
	v_add_f32_e32 v188, v233, v32
	v_mov_b32_e32 v234, v188
	v_mov_b32_e32 v235, v188
	s_nop 0
	s_nop 0
	v_permlane32_swap_b32_e32 v234, v235
	v_cmp_neq_f32_e32 vcc, v130, v226
	s_cbranch_vccz .LBB0_795
	v_sub_f32_e32 v32, v226, v130
	v_exp_f32_e32 v32, v32
	v_mov_b32_e32 v228, v130
	v_mul_f32_e32 v192, v186, v32
	v_pk_mul_f32 v[30:31], v[30:31], v[32:33] op_sel_hi:[1,0]
	v_pk_mul_f32 v[28:29], v[28:29], v[32:33] op_sel_hi:[1,0]
	v_pk_mul_f32 v[26:27], v[26:27], v[32:33] op_sel_hi:[1,0]
	v_pk_mul_f32 v[24:25], v[24:25], v[32:33] op_sel_hi:[1,0]
	v_pk_mul_f32 v[22:23], v[22:23], v[32:33] op_sel_hi:[1,0]
	v_pk_mul_f32 v[20:21], v[20:21], v[32:33] op_sel_hi:[1,0]
	v_pk_mul_f32 v[18:19], v[18:19], v[32:33] op_sel_hi:[1,0]
	v_pk_mul_f32 v[16:17], v[16:17], v[32:33] op_sel_hi:[1,0]
	v_pk_mul_f32 v[14:15], v[14:15], v[32:33] op_sel_hi:[1,0]
	v_pk_mul_f32 v[12:13], v[12:13], v[32:33] op_sel_hi:[1,0]
	v_pk_mul_f32 v[10:11], v[10:11], v[32:33] op_sel_hi:[1,0]
	v_pk_mul_f32 v[8:9], v[8:9], v[32:33] op_sel_hi:[1,0]
	v_pk_mul_f32 v[6:7], v[6:7], v[32:33] op_sel_hi:[1,0]
	v_pk_mul_f32 v[4:5], v[4:5], v[32:33] op_sel_hi:[1,0]
	v_pk_mul_f32 v[2:3], v[2:3], v[32:33] op_sel_hi:[1,0]
	v_pk_mul_f32 v[0:1], v[0:1], v[32:33] op_sel_hi:[1,0]
; DI float ex2(float x) { return __builtin_amdgcn_exp2f(x); }
; template <int MM> DI void smax_step(const f32x16& s, unsigned vm, float& m, float& l, f32x16 (&o)[2], bf16x8 (&pf)[2], int lane) {
;     float t[16], mx = -1e30f;
; #pragma unroll
;     for (int i = 0; i < 16; ++i) { t[i] = (MM == 0) ? s[i] : (MM == 1 ? (vm ? s[i] : -1e30f) : (((vm >> i) & 1u) ? s[i] : -1e30f)); mx = fmaxf(mx, t[i]); }
;     mx = fmaxf(mx, shx32(mx, lane));
;     const float mn = (mx > m + 8.0f) ? mx : m;
;     const float mref = fmaxf(mn, -1e29f);
;     float p[16], rs = 0.f;
; #pragma unroll
;     for (int i = 0; i < 16; ++i) { p[i] = ex2(t[i] - mref); rs += p[i]; }
;     rs += shx32(rs, lane);
;     if (__builtin_amdgcn_ballot_w64(mn != m) != 0ull) {
;         const float alpha = ex2(m - mn);
;         l *= alpha;
; #pragma unroll
;         for (int i = 0; i < 16; ++i) { o[0][i] *= alpha; o[1][i] *= alpha; }
;         m = mn;
;     }
;     l += rs;
;     pack_p(p, pf);
; }
; template <int MODE, bool PRE = false> ...
;     ...
;             if (MODE == MODE_DIFF) {
;                 const f32x16 s1 = qk_rows<0, 2>(Kl, 32 * sub, qf, r, h), s2 = qk_rows<2, 4>(Kl, 32 * sub, qf, r, h);
;                 bf16x8 pf2[2];
;                 if (mm == 0) { smax_step<0>(s1, vm, m1, l1, o1, pf, lane); smax_step<0>(s2, vm, m2, l2, o2, pf2, lane); }
;                 else { smax_step<2>(s1, vm, m1, l1, o1, pf, lane); smax_step<2>(s2, vm, m2, l2, o2, pf2, lane); }
.LBB0_795:
	v_cvt_pk_bf16_f32 v128, v128, v129
	v_cvt_pk_bf16_f32 v129, v131, v132
	v_cvt_pk_bf16_f32 v131, v135, v187
	v_cndmask_b32_e64 v173, v96, v208, s[0:1]
	v_cndmask_b32_e64 v187, v97, v208, s[38:39]
	v_cvt_pk_bf16_f32 v130, v133, v134
	v_cvt_pk_bf16_f32 v132, v189, v190
	v_cvt_pk_bf16_f32 v133, v191, v193
	v_max3_f32 v189, v173, s15, v187
	v_cndmask_b32_e64 v190, v98, v208, s[40:41]
	v_cndmask_b32_e64 v191, v99, v208, s[42:43]
	v_max3_f32 v189, v189, v190, v191
	v_cndmask_b32_e64 v193, v100, v208, s[44:45]
	v_cndmask_b32_e64 v206, v101, v208, s[48:49]
	v_max3_f32 v189, v189, v193, v206
	v_cndmask_b32_e64 v207, v102, v208, s[50:51]
	v_cndmask_b32_e64 v238, v103, v208, s[52:53]
	v_max3_f32 v189, v189, v207, v238
	v_cndmask_b32_e64 v239, v104, v208, s[54:55]
	v_cndmask_b32_e64 v240, v105, v208, s[56:57]
	v_max3_f32 v189, v189, v239, v240
	v_cndmask_b32_e64 v241, v106, v208, s[58:59]
	v_cndmask_b32_e64 v242, v107, v208, s[60:61]
	v_max3_f32 v189, v189, v241, v242
	v_cndmask_b32_e64 v243, v108, v208, s[62:63]
	v_cndmask_b32_e64 v244, v109, v208, s[64:65]
	v_max3_f32 v189, v189, v243, v244
	v_cndmask_b32_e64 v245, v110, v208, s[66:67]
	v_cndmask_b32_e64 v246, v111, v208, s[68:69]
	v_max3_f32 v189, v189, v245, v246
	v_cvt_pk_bf16_f32 v134, v230, v231
	v_mov_b32_e32 v230, v189
	v_mov_b32_e32 v231, v189
	s_nop 1
	v_permlane32_swap_b32_e32 v230, v231
	v_max_f32_e32 v189, v230, v231
	v_add_f32_e32 v230, 0x41000000, v224
	v_cmp_gt_f32_e32 vcc, v189, v230
	v_cvt_pk_bf16_f32 v135, v232, v233
	v_cndmask_b32_e64 v172, v234, v235, s[36:37]
	v_cndmask_b32_e32 v230, v224, v189, vcc
	v_max_f32_e32 v247, 0xefa18f08, v230
	v_sub_f32_e32 v173, v173, v247
	v_exp_f32_e32 v231, v173
	v_sub_f32_e32 v173, v187, v247
	v_exp_f32_e32 v232, v173
	v_sub_f32_e32 v173, v190, v247
	v_exp_f32_e32 v233, v173
	v_sub_f32_e32 v173, v191, v247
	v_exp_f32_e32 v234, v173
	v_sub_f32_e32 v187, v193, v247
	v_exp_f32_e32 v235, v187
	v_sub_f32_e32 v187, v206, v247
	v_add_f32_e32 v173, v232, v231
	v_exp_f32_e32 v236, v187
	v_sub_f32_e32 v187, v207, v247
	v_add_f32_e32 v173, v233, v173
	v_exp_f32_e32 v237, v187
	v_sub_f32_e32 v187, v238, v247
	v_add_f32_e32 v173, v234, v173
	v_exp_f32_e32 v238, v187
	v_sub_f32_e32 v187, v239, v247
	v_add_f32_e32 v173, v235, v173
	v_exp_f32_e32 v239, v187
	v_sub_f32_e32 v187, v240, v247
	v_add_f32_e32 v173, v236, v173
	v_exp_f32_e32 v240, v187
	v_sub_f32_e32 v187, v241, v247
	v_add_f32_e32 v173, v237, v173
	v_exp_f32_e32 v241, v187
	v_sub_f32_e32 v187, v242, v247
	v_add_f32_e32 v173, v238, v173
	v_exp_f32_e32 v242, v187
	v_sub_f32_e32 v187, v243, v247
	v_add_f32_e32 v173, v239, v173
	v_exp_f32_e32 v243, v187
	v_sub_f32_e32 v187, v244, v247
	v_add_f32_e32 v173, v240, v173
	v_exp_f32_e32 v244, v187
	v_sub_f32_e32 v187, v245, v247
	v_add_f32_e32 v173, v241, v173
	v_exp_f32_e32 v189, v187
	v_sub_f32_e32 v187, v246, v247
	v_add_f32_e32 v173, v242, v173
	v_exp_f32_e32 v193, v187
	v_add_f32_e32 v173, v243, v173
	v_add_f32_e32 v173, v244, v173
	v_pk_add_f32 v[172:173], v[188:189], v[172:173]
	v_cmp_neq_f32_e32 vcc, v230, v224
	v_pk_add_f32 v[190:191], v[172:173], v[192:193]
	s_cmp_lg_u64 vcc, 0
	v_mov_b32_e32 v188, v191
	v_mov_b32_e32 v192, v191
	s_nop 1
	v_permlane32_swap_b32_e32 v188, v192
	s_cselect_b64 s[0:1], -1, 0
	v_mov_b32_e32 v187, v193
	s_branch .LBB0_801
.LBB0_796:
	s_mov_b64 s[0:1], 0
	s_cbranch_execz .LBB0_801
	v_max3_f32 v32, v112, s15, v113
	v_max3_f32 v32, v32, v114, v115
	v_max3_f32 v32, v32, v116, v117
	v_max3_f32 v32, v32, v118, v119
	v_max3_f32 v32, v32, v120, v121
	v_max3_f32 v32, v32, v122, v123
	v_max3_f32 v32, v32, v124, v125
	v_max3_f32 v32, v32, v126, v127
	v_mov_b32_e32 v33, v32
	v_mov_b32_e32 v34, v32
	s_nop 1
	v_permlane32_swap_b32_e32 v33, v34
	v_max_f32_e32 v32, v33, v34
	v_cmp_gt_f32_e32 vcc, v32, v229
	s_nop 1
	v_cndmask_b32_e32 v228, v226, v32, vcc
	v_max_f32_e32 v47, 0xefa18f08, v228
	v_sub_f32_e32 v32, v112, v47
	v_exp_f32_e32 v32, v32
	v_sub_f32_e32 v33, v113, v47
	v_exp_f32_e32 v33, v33
	v_sub_f32_e32 v34, v114, v47
	v_exp_f32_e32 v34, v34
	v_sub_f32_e32 v35, v115, v47
	v_exp_f32_e32 v35, v35
	v_add_f32_e32 v36, v33, v32
	v_add_f32_e32 v36, v34, v36
	v_add_f32_e32 v40, v35, v36
	v_sub_f32_e32 v36, v116, v47
	v_exp_f32_e32 v36, v36
	v_sub_f32_e32 v37, v117, v47
	v_exp_f32_e32 v37, v37
	v_sub_f32_e32 v38, v118, v47
	v_exp_f32_e32 v38, v38
	v_sub_f32_e32 v39, v119, v47
	v_exp_f32_e32 v39, v39
	v_add_f32_e32 v40, v36, v40
	v_add_f32_e32 v40, v37, v40
	v_add_f32_e32 v40, v38, v40
	v_add_f32_e32 v44, v39, v40
	v_sub_f32_e32 v40, v120, v47
	v_exp_f32_e32 v40, v40
	v_sub_f32_e32 v41, v121, v47
	v_exp_f32_e32 v41, v41
	v_sub_f32_e32 v42, v122, v47
	v_exp_f32_e32 v42, v42
	v_sub_f32_e32 v43, v123, v47
	v_exp_f32_e32 v43, v43
	v_add_f32_e32 v44, v40, v44
	v_add_f32_e32 v44, v41, v44
	v_add_f32_e32 v44, v42, v44
	v_add_f32_e32 v48, v43, v44
	v_sub_f32_e32 v44, v124, v47
	v_exp_f32_e32 v44, v44
	v_sub_f32_e32 v45, v125, v47
	v_exp_f32_e32 v45, v45
	v_sub_f32_e32 v46, v126, v47
	v_exp_f32_e32 v46, v46
	v_sub_f32_e32 v47, v127, v47
	v_exp_f32_e32 v47, v47
	v_add_f32_e32 v48, v44, v48
	v_add_f32_e32 v48, v45, v48
	v_add_f32_e32 v48, v46, v48
	v_add_f32_e32 v188, v47, v48
	v_mov_b32_e32 v48, v188
	v_mov_b32_e32 v49, v188
	s_nop 1
	v_permlane32_swap_b32_e32 v48, v49
	v_cmp_neq_f32_e32 vcc, v228, v226
	s_cbranch_vccz .LBB0_799
	v_sub_f32_e32 v50, v226, v228
	v_exp_f32_e32 v50, v50
	s_nop 0
	v_mul_f32_e32 v186, v186, v50
	v_pk_mul_f32 v[30:31], v[30:31], v[50:51] op_sel_hi:[1,0]
	v_pk_mul_f32 v[28:29], v[28:29], v[50:51] op_sel_hi:[1,0]
	v_pk_mul_f32 v[26:27], v[26:27], v[50:51] op_sel_hi:[1,0]
	v_pk_mul_f32 v[24:25], v[24:25], v[50:51] op_sel_hi:[1,0]
	v_pk_mul_f32 v[22:23], v[22:23], v[50:51] op_sel_hi:[1,0]
	v_pk_mul_f32 v[20:21], v[20:21], v[50:51] op_sel_hi:[1,0]
	v_pk_mul_f32 v[18:19], v[18:19], v[50:51] op_sel_hi:[1,0]
	v_pk_mul_f32 v[16:17], v[16:17], v[50:51] op_sel_hi:[1,0]
	v_pk_mul_f32 v[14:15], v[14:15], v[50:51] op_sel_hi:[1,0]
	v_pk_mul_f32 v[12:13], v[12:13], v[50:51] op_sel_hi:[1,0]
	v_pk_mul_f32 v[10:11], v[10:11], v[50:51] op_sel_hi:[1,0]
	v_pk_mul_f32 v[8:9], v[8:9], v[50:51] op_sel_hi:[1,0]
	v_pk_mul_f32 v[6:7], v[6:7], v[50:51] op_sel_hi:[1,0]
	v_pk_mul_f32 v[4:5], v[4:5], v[50:51] op_sel_hi:[1,0]
	v_pk_mul_f32 v[2:3], v[2:3], v[50:51] op_sel_hi:[1,0]
	v_pk_mul_f32 v[0:1], v[0:1], v[50:51] op_sel_hi:[1,0]
	s_branch .LBB0_800

; DI float ex2(float x) { return __builtin_amdgcn_exp2f(x); }
; template <int MM> DI void smax_step(const f32x16& s, unsigned vm, float& m, float& l, f32x16 (&o)[2], bf16x8 (&pf)[2], int lane) {
;     float t[16], mx = -1e30f;
; #pragma unroll
;     for (int i = 0; i < 16; ++i) { t[i] = (MM == 0) ? s[i] : (MM == 1 ? (vm ? s[i] : -1e30f) : (((vm >> i) & 1u) ? s[i] : -1e30f)); mx = fmaxf(mx, t[i]); }
;     mx = fmaxf(mx, shx32(mx, lane));
;     const float mn = (mx > m + 8.0f) ? mx : m;
;     const float mref = fmaxf(mn, -1e29f);
;     float p[16], rs = 0.f;
; #pragma unroll
;     for (int i = 0; i < 16; ++i) { p[i] = ex2(t[i] - mref); rs += p[i]; }
;     rs += shx32(rs, lane);
;     if (__builtin_amdgcn_ballot_w64(mn != m) != 0ull) {
;         const float alpha = ex2(m - mn);
;         l *= alpha;
; #pragma unroll
;         for (int i = 0; i < 16; ++i) { o[0][i] *= alpha; o[1][i] *= alpha; }
;         m = mn;
;     }
;     l += rs;
;     pack_p(p, pf);
; }
.LBB0_800:
	v_cvt_pk_bf16_f32 v128, v32, v33
	v_max3_f32 v32, v96, s15, v97
	v_max3_f32 v32, v32, v98, v99
	v_max3_f32 v32, v32, v100, v101
	v_max3_f32 v32, v32, v102, v103
	v_max3_f32 v32, v32, v104, v105
	v_max3_f32 v32, v32, v106, v107
	v_max3_f32 v32, v32, v108, v109
	v_max3_f32 v32, v32, v110, v111
	v_cvt_pk_bf16_f32 v129, v34, v35
	v_mov_b32_e32 v33, v32
	v_mov_b32_e32 v34, v32
	s_nop 1
	v_permlane32_swap_b32_e32 v33, v34
	v_max_f32_e32 v32, v33, v34
	v_add_f32_e32 v33, 0x41000000, v224
	v_cmp_gt_f32_e32 vcc, v32, v33
	v_cndmask_b32_e64 v48, v48, v49, s[36:37]
	v_cvt_pk_bf16_f32 v130, v36, v37
	v_cndmask_b32_e32 v230, v224, v32, vcc
	v_max_f32_e32 v32, 0xefa18f08, v230
	v_sub_f32_e32 v33, v96, v32
	v_exp_f32_e32 v231, v33
	v_sub_f32_e32 v33, v97, v32
	v_exp_f32_e32 v232, v33
	v_sub_f32_e32 v33, v98, v32
	v_exp_f32_e32 v233, v33
	v_sub_f32_e32 v33, v99, v32
	v_exp_f32_e32 v234, v33
	v_sub_f32_e32 v34, v100, v32
	v_exp_f32_e32 v235, v34
	v_sub_f32_e32 v34, v101, v32
	v_add_f32_e32 v33, v232, v231
	v_exp_f32_e32 v236, v34
	v_sub_f32_e32 v34, v102, v32
	v_add_f32_e32 v33, v233, v33
	v_exp_f32_e32 v237, v34
	v_sub_f32_e32 v34, v103, v32
	v_add_f32_e32 v33, v234, v33
	v_exp_f32_e32 v238, v34
	v_sub_f32_e32 v34, v104, v32
	v_add_f32_e32 v33, v235, v33
	v_exp_f32_e32 v239, v34
	v_sub_f32_e32 v34, v105, v32
	v_add_f32_e32 v33, v236, v33
	v_exp_f32_e32 v240, v34
	v_sub_f32_e32 v34, v106, v32
	v_add_f32_e32 v33, v237, v33
	v_exp_f32_e32 v241, v34
	v_sub_f32_e32 v34, v107, v32
	v_add_f32_e32 v33, v238, v33
	v_exp_f32_e32 v242, v34
	v_sub_f32_e32 v34, v108, v32
	v_add_f32_e32 v33, v239, v33
	v_exp_f32_e32 v243, v34
	v_sub_f32_e32 v34, v109, v32
	v_add_f32_e32 v33, v240, v33
	v_exp_f32_e32 v244, v34
	v_sub_f32_e32 v34, v110, v32
	v_add_f32_e32 v33, v241, v33
	v_exp_f32_e32 v189, v34
	v_sub_f32_e32 v32, v111, v32
	v_add_f32_e32 v33, v242, v33
	v_exp_f32_e32 v187, v32
	v_add_f32_e32 v32, v243, v33
	v_add_f32_e32 v49, v244, v32
	v_pk_add_f32 v[32:33], v[188:189], v[48:49]
	v_cmp_neq_f32_e32 vcc, v230, v224
	v_pk_add_f32 v[190:191], v[32:33], v[186:187]
	v_cvt_pk_bf16_f32 v131, v38, v39
	v_cvt_pk_bf16_f32 v132, v40, v41
	v_cvt_pk_bf16_f32 v133, v42, v43
	v_cvt_pk_bf16_f32 v134, v44, v45
	v_cvt_pk_bf16_f32 v135, v46, v47
	v_mov_b32_e32 v188, v191
	v_mov_b32_e32 v192, v191
	s_cmp_lg_u64 vcc, 0
	s_nop 0
	v_permlane32_swap_b32_e32 v188, v192
	s_cselect_b64 s[0:1], -1, 0

; DI float ex2(float x) { return __builtin_amdgcn_exp2f(x); }
; template <int MM> DI void smax_step(const f32x16& s, unsigned vm, float& m, float& l, f32x16 (&o)[2], bf16x8 (&pf)[2], int lane) {
;     float t[16], mx = -1e30f;
; #pragma unroll
;     for (int i = 0; i < 16; ++i) { t[i] = (MM == 0) ? s[i] : (MM == 1 ? (vm ? s[i] : -1e30f) : (((vm >> i) & 1u) ? s[i] : -1e30f)); mx = fmaxf(mx, t[i]); }
;     mx = fmaxf(mx, shx32(mx, lane));
;     const float mn = (mx > m + 8.0f) ? mx : m;
;     const float mref = fmaxf(mn, -1e29f);
;     float p[16], rs = 0.f;
; #pragma unroll
;     for (int i = 0; i < 16; ++i) { p[i] = ex2(t[i] - mref); rs += p[i]; }
;     rs += shx32(rs, lane);
;     if (__builtin_amdgcn_ballot_w64(mn != m) != 0ull) {
;         const float alpha = ex2(m - mn);
;         l *= alpha;
; #pragma unroll
;         for (int i = 0; i < 16; ++i) { o[0][i] *= alpha; o[1][i] *= alpha; }
;         m = mn;
;     }
;     l += rs;
;     pack_p(p, pf);
; }
; template <int MODE, bool PRE = false> ...
;     ...
;             else { mm = 2; vm = 0;
; #pragma unroll
;                 for (int i = 0; i < 16; ++i) { const int kidx = kbase + (i & 3) + 8 * (i >> 2) + 4 * h; bool ok = kidx <= qpos; if (MODE == MODE_NWIN) ok = ok && (kidx > qpos - 512); vm |= ok ? (1u << i) : 0u; }
;                 if (!lsel) vm = 0;
;                 if (__builtin_amdgcn_ballot_w64(vm != 0) == 0ull) continue; }
;             bf16x8 pf[2];
;             if (MODE == MODE_DIFF) {
;                 const f32x16 s1 = qk_rows<0, 2>(Kl, 32 * sub, qf, r, h), s2 = qk_rows<2, 4>(Kl, 32 * sub, qf, r, h);
;                 bf16x8 pf2[2];
;                 if (mm == 0) { smax_step<0>(s1, vm, m1, l1, o1, pf, lane); smax_step<0>(s2, vm, m2, l2, o2, pf2, lane); }
;                 else { smax_step<2>(s1, vm, m1, l1, o1, pf, lane); smax_step<2>(s2, vm, m2, l2, o2, pf2, lane); }
.LBB0_810:
	s_andn2_b64 vcc, exec, s[38:39]
	s_cbranch_vccnz .LBB0_823
	v_add_u32_e32 v33, v227, v223
	ds_read_b128 v[34:37], v33
	ds_read_b128 v[38:41], v33 offset:32
	s_setprio 1
	s_waitcnt lgkmcnt(1)
	v_mfma_f32_32x32x16_bf16 v[112:127], v[34:37], v[152:155], 0
	s_waitcnt lgkmcnt(0)
	v_mfma_f32_32x32x16_bf16 v[112:127], v[38:41], v[156:159], v[112:127]
	s_setprio 0
	ds_read_b128 v[34:37], v33 offset:64
	ds_read_b128 v[38:41], v33 offset:96
	s_setprio 1
	s_waitcnt lgkmcnt(1)
	v_mfma_f32_32x32x16_bf16 v[96:111], v[34:37], v[160:163], 0
	s_waitcnt lgkmcnt(0)
	v_mfma_f32_32x32x16_bf16 v[96:111], v[38:41], v[164:167], v[96:111]
	s_setprio 0
	s_and_b64 vcc, exec, s[0:1]
	v_add_f32_e32 v187, 0x41000000, v226
	s_cbranch_vccnz .LBB0_815
	v_and_b32_e32 v33, 1, v32
	v_and_b32_e32 v34, 2, v32
	v_cmp_eq_u32_e64 s[0:1], 0, v33
	v_cmp_eq_u32_e64 s[38:39], 0, v34
	v_and_b32_e32 v36, 4, v32
	v_and_b32_e32 v37, 8, v32
	v_cndmask_b32_e64 v33, v112, v208, s[0:1]
	v_cndmask_b32_e64 v34, v113, v208, s[38:39]
	v_cmp_eq_u32_e64 s[40:41], 0, v36
	v_cmp_eq_u32_e64 s[42:43], 0, v37
	v_and_b32_e32 v38, 16, v32
	v_and_b32_e32 v39, 32, v32
	v_max3_f32 v35, v33, s15, v34
	v_cndmask_b32_e64 v36, v114, v208, s[40:41]
	v_cndmask_b32_e64 v37, v115, v208, s[42:43]
	v_cmp_eq_u32_e64 s[44:45], 0, v38
	v_cmp_eq_u32_e64 s[48:49], 0, v39
	v_and_b32_e32 v40, 64, v32
	v_and_b32_e32 v41, 0x80, v32
	v_max3_f32 v35, v35, v36, v37
	v_cndmask_b32_e64 v38, v116, v208, s[44:45]
	v_cndmask_b32_e64 v39, v117, v208, s[48:49]
	v_cmp_eq_u32_e64 s[50:51], 0, v40
	v_cmp_eq_u32_e64 s[52:53], 0, v41
	v_and_b32_e32 v42, 0x100, v32
	v_and_b32_e32 v43, 0x200, v32
	v_max3_f32 v35, v35, v38, v39
	v_cndmask_b32_e64 v40, v118, v208, s[50:51]
	v_cndmask_b32_e64 v41, v119, v208, s[52:53]
	v_cmp_eq_u32_e64 s[54:55], 0, v42
	v_cmp_eq_u32_e64 s[56:57], 0, v43
	v_and_b32_e32 v44, 0x400, v32
	v_and_b32_e32 v45, 0x800, v32
	v_max3_f32 v35, v35, v40, v41
	v_cndmask_b32_e64 v42, v120, v208, s[54:55]
	v_cndmask_b32_e64 v43, v121, v208, s[56:57]
	v_cmp_eq_u32_e64 s[58:59], 0, v44
	v_cmp_eq_u32_e64 s[60:61], 0, v45
	v_and_b32_e32 v46, 0x1000, v32
	v_and_b32_e32 v47, 0x2000, v32
	v_max3_f32 v35, v35, v42, v43
	v_cndmask_b32_e64 v44, v122, v208, s[58:59]
	v_cndmask_b32_e64 v45, v123, v208, s[60:61]
	v_cmp_eq_u32_e64 s[62:63], 0, v46
	v_cmp_eq_u32_e64 s[64:65], 0, v47
	v_and_b32_e32 v48, 0x4000, v32
	v_and_b32_e32 v32, 0x8000, v32
	v_max3_f32 v35, v35, v44, v45
	v_cndmask_b32_e64 v46, v124, v208, s[62:63]
	v_cndmask_b32_e64 v47, v125, v208, s[64:65]
	v_cmp_eq_u32_e64 s[66:67], 0, v48
	v_cmp_eq_u32_e64 s[68:69], 0, v32
	v_max3_f32 v35, v35, v46, v47
	v_cndmask_b32_e64 v48, v126, v208, s[66:67]
	v_cndmask_b32_e64 v32, v127, v208, s[68:69]
	v_max3_f32 v35, v35, v48, v32
	v_mov_b32_e32 v49, v35
	v_mov_b32_e32 v50, v35
	s_nop 1
	v_permlane32_swap_b32_e32 v49, v50
	v_max_f32_e32 v35, v49, v50
	v_cmp_gt_f32_e32 vcc, v35, v187
	v_mov_b32_e32 v227, v226
	v_mov_b32_e32 v192, v186
	v_cndmask_b32_e32 v130, v226, v35, vcc
	v_max_f32_e32 v35, 0xefa18f08, v130
	v_sub_f32_e32 v33, v33, v35
	v_exp_f32_e32 v128, v33
	v_sub_f32_e32 v33, v34, v35
	v_exp_f32_e32 v129, v33
	v_sub_f32_e32 v33, v36, v35
	v_exp_f32_e32 v131, v33
	v_sub_f32_e32 v33, v37, v35
	v_exp_f32_e32 v132, v33
	v_sub_f32_e32 v34, v38, v35
	v_exp_f32_e32 v133, v34
	v_sub_f32_e32 v34, v39, v35
	v_add_f32_e32 v33, v129, v128
	v_exp_f32_e32 v134, v34
	v_sub_f32_e32 v34, v40, v35
	v_add_f32_e32 v33, v131, v33
	v_exp_f32_e32 v135, v34
	v_sub_f32_e32 v34, v41, v35
	v_add_f32_e32 v33, v132, v33
	v_exp_f32_e32 v189, v34
	v_sub_f32_e32 v34, v42, v35
	v_add_f32_e32 v33, v133, v33
	v_exp_f32_e32 v190, v34
	v_sub_f32_e32 v34, v43, v35
	v_add_f32_e32 v33, v134, v33
	v_exp_f32_e32 v191, v34
	v_sub_f32_e32 v34, v44, v35
	v_add_f32_e32 v33, v135, v33
	v_exp_f32_e32 v193, v34
	v_sub_f32_e32 v34, v45, v35
	v_add_f32_e32 v33, v189, v33
	v_exp_f32_e32 v228, v34
	v_sub_f32_e32 v34, v46, v35
	v_add_f32_e32 v33, v190, v33
	v_exp_f32_e32 v229, v34
	v_sub_f32_e32 v34, v47, v35
	v_add_f32_e32 v33, v191, v33
	v_exp_f32_e32 v230, v34
	v_sub_f32_e32 v34, v48, v35
	v_add_f32_e32 v33, v193, v33
	v_exp_f32_e32 v231, v34
	v_sub_f32_e32 v32, v32, v35
	v_add_f32_e32 v33, v228, v33
	v_exp_f32_e32 v232, v32
	v_add_f32_e32 v32, v229, v33
	v_add_f32_e32 v32, v230, v32
	v_add_f32_e32 v32, v231, v32
	v_add_f32_e32 v188, v232, v32
	v_mov_b32_e32 v233, v188
	v_mov_b32_e32 v234, v188
	s_nop 0
	s_nop 0
	v_permlane32_swap_b32_e32 v233, v234
	v_cmp_neq_f32_e32 vcc, v130, v226
	s_cbranch_vccz .LBB0_814
	v_sub_f32_e32 v32, v226, v130
	v_exp_f32_e32 v32, v32
	v_mov_b32_e32 v227, v130
	v_mul_f32_e32 v192, v186, v32
	v_pk_mul_f32 v[30:31], v[30:31], v[32:33] op_sel_hi:[1,0]
	v_pk_mul_f32 v[28:29], v[28:29], v[32:33] op_sel_hi:[1,0]
	v_pk_mul_f32 v[26:27], v[26:27], v[32:33] op_sel_hi:[1,0]
	v_pk_mul_f32 v[24:25], v[24:25], v[32:33] op_sel_hi:[1,0]
	v_pk_mul_f32 v[22:23], v[22:23], v[32:33] op_sel_hi:[1,0]
	v_pk_mul_f32 v[20:21], v[20:21], v[32:33] op_sel_hi:[1,0]
	v_pk_mul_f32 v[18:19], v[18:19], v[32:33] op_sel_hi:[1,0]
	v_pk_mul_f32 v[16:17], v[16:17], v[32:33] op_sel_hi:[1,0]
	v_pk_mul_f32 v[14:15], v[14:15], v[32:33] op_sel_hi:[1,0]
	v_pk_mul_f32 v[12:13], v[12:13], v[32:33] op_sel_hi:[1,0]
	v_pk_mul_f32 v[10:11], v[10:11], v[32:33] op_sel_hi:[1,0]
	v_pk_mul_f32 v[8:9], v[8:9], v[32:33] op_sel_hi:[1,0]
	v_pk_mul_f32 v[6:7], v[6:7], v[32:33] op_sel_hi:[1,0]
	v_pk_mul_f32 v[4:5], v[4:5], v[32:33] op_sel_hi:[1,0]
	v_pk_mul_f32 v[2:3], v[2:3], v[32:33] op_sel_hi:[1,0]
	v_pk_mul_f32 v[0:1], v[0:1], v[32:33] op_sel_hi:[1,0]
; DI float ex2(float x) { return __builtin_amdgcn_exp2f(x); }
; template <int MM> DI void smax_step(const f32x16& s, unsigned vm, float& m, float& l, f32x16 (&o)[2], bf16x8 (&pf)[2], int lane) {
;     float t[16], mx = -1e30f;
; #pragma unroll
;     for (int i = 0; i < 16; ++i) { t[i] = (MM == 0) ? s[i] : (MM == 1 ? (vm ? s[i] : -1e30f) : (((vm >> i) & 1u) ? s[i] : -1e30f)); mx = fmaxf(mx, t[i]); }
;     mx = fmaxf(mx, shx32(mx, lane));
;     const float mn = (mx > m + 8.0f) ? mx : m;
;     const float mref = fmaxf(mn, -1e29f);
;     float p[16], rs = 0.f;
; #pragma unroll
;     for (int i = 0; i < 16; ++i) { p[i] = ex2(t[i] - mref); rs += p[i]; }
;     rs += shx32(rs, lane);
;     if (__builtin_amdgcn_ballot_w64(mn != m) != 0ull) {
;         const float alpha = ex2(m - mn);
;         l *= alpha;
; #pragma unroll
;         for (int i = 0; i < 16; ++i) { o[0][i] *= alpha; o[1][i] *= alpha; }
;         m = mn;
;     }
;     l += rs;
;     pack_p(p, pf);
; }
; template <int MODE, bool PRE = false> ...
;     ...
;             if (MODE == MODE_DIFF) {
;                 const f32x16 s1 = qk_rows<0, 2>(Kl, 32 * sub, qf, r, h), s2 = qk_rows<2, 4>(Kl, 32 * sub, qf, r, h);
;                 bf16x8 pf2[2];
;                 if (mm == 0) { smax_step<0>(s1, vm, m1, l1, o1, pf, lane); smax_step<0>(s2, vm, m2, l2, o2, pf2, lane); }
;                 else { smax_step<2>(s1, vm, m1, l1, o1, pf, lane); smax_step<2>(s2, vm, m2, l2, o2, pf2, lane); }
.LBB0_814:
	v_cvt_pk_bf16_f32 v128, v128, v129
	v_cvt_pk_bf16_f32 v129, v131, v132
	v_cvt_pk_bf16_f32 v131, v135, v189
	v_cndmask_b32_e64 v173, v96, v208, s[0:1]
	v_cndmask_b32_e64 v189, v97, v208, s[38:39]
	v_cvt_pk_bf16_f32 v130, v133, v134
	v_cvt_pk_bf16_f32 v132, v190, v191
	v_cvt_pk_bf16_f32 v133, v193, v228
	v_max3_f32 v190, v173, s15, v189
	v_cndmask_b32_e64 v191, v98, v208, s[40:41]
	v_cndmask_b32_e64 v193, v99, v208, s[42:43]
	v_max3_f32 v190, v190, v191, v193
	v_cndmask_b32_e64 v206, v100, v208, s[44:45]
	v_cndmask_b32_e64 v207, v101, v208, s[48:49]
	v_max3_f32 v190, v190, v206, v207
	v_cndmask_b32_e64 v235, v102, v208, s[50:51]
	v_cndmask_b32_e64 v236, v103, v208, s[52:53]
	v_max3_f32 v190, v190, v235, v236
	v_cndmask_b32_e64 v237, v104, v208, s[54:55]
	v_cndmask_b32_e64 v238, v105, v208, s[56:57]
	v_max3_f32 v190, v190, v237, v238
	v_cndmask_b32_e64 v239, v106, v208, s[58:59]
	v_cndmask_b32_e64 v240, v107, v208, s[60:61]
	v_max3_f32 v190, v190, v239, v240
	v_cndmask_b32_e64 v241, v108, v208, s[62:63]
	v_cndmask_b32_e64 v242, v109, v208, s[64:65]
	v_max3_f32 v190, v190, v241, v242
	v_cndmask_b32_e64 v243, v110, v208, s[66:67]
	v_cndmask_b32_e64 v244, v111, v208, s[68:69]
	v_max3_f32 v190, v190, v243, v244
	v_cvt_pk_bf16_f32 v134, v229, v230
	v_mov_b32_e32 v228, v190
	v_mov_b32_e32 v229, v190
	s_nop 1
	v_permlane32_swap_b32_e32 v228, v229
	v_max_f32_e32 v190, v228, v229
	v_add_f32_e32 v228, 0x41000000, v224
	v_cmp_gt_f32_e32 vcc, v190, v228
	v_cvt_pk_bf16_f32 v135, v231, v232
	v_cndmask_b32_e64 v172, v233, v234, s[36:37]
	v_cndmask_b32_e32 v228, v224, v190, vcc
	v_max_f32_e32 v190, 0xefa18f08, v228
	v_sub_f32_e32 v173, v173, v190
	v_exp_f32_e32 v229, v173
	v_sub_f32_e32 v173, v189, v190
	v_exp_f32_e32 v230, v173
	v_sub_f32_e32 v173, v191, v190
	v_exp_f32_e32 v231, v173
	v_sub_f32_e32 v173, v193, v190
	v_exp_f32_e32 v232, v173
	v_sub_f32_e32 v189, v206, v190
	v_exp_f32_e32 v233, v189
	v_sub_f32_e32 v189, v207, v190
	v_add_f32_e32 v173, v230, v229
	v_exp_f32_e32 v234, v189
	v_sub_f32_e32 v189, v235, v190
	v_add_f32_e32 v173, v231, v173
	v_exp_f32_e32 v235, v189
	v_sub_f32_e32 v189, v236, v190
	v_add_f32_e32 v173, v232, v173
	v_exp_f32_e32 v236, v189
	v_sub_f32_e32 v189, v237, v190
	v_add_f32_e32 v173, v233, v173
	v_exp_f32_e32 v237, v189
	v_sub_f32_e32 v189, v238, v190
	v_add_f32_e32 v173, v234, v173
	v_exp_f32_e32 v238, v189
	v_sub_f32_e32 v189, v239, v190
	v_add_f32_e32 v173, v235, v173
	v_exp_f32_e32 v239, v189
	v_sub_f32_e32 v189, v240, v190
	v_add_f32_e32 v173, v236, v173
	v_exp_f32_e32 v240, v189
	v_sub_f32_e32 v189, v241, v190
	v_add_f32_e32 v173, v237, v173
	v_exp_f32_e32 v241, v189
	v_sub_f32_e32 v189, v242, v190
	v_add_f32_e32 v173, v238, v173
	v_exp_f32_e32 v242, v189
	v_sub_f32_e32 v189, v243, v190
	v_add_f32_e32 v173, v239, v173
	v_exp_f32_e32 v189, v189
	v_sub_f32_e32 v190, v244, v190
	v_add_f32_e32 v173, v240, v173
	v_exp_f32_e32 v193, v190
	v_add_f32_e32 v173, v241, v173
	v_add_f32_e32 v173, v242, v173
	v_pk_add_f32 v[172:173], v[188:189], v[172:173]
	v_cmp_neq_f32_e32 vcc, v228, v224
	v_pk_add_f32 v[190:191], v[172:173], v[192:193]
	s_cmp_lg_u64 vcc, 0
	v_mov_b32_e32 v188, v191
	v_mov_b32_e32 v192, v191
	s_nop 1
	v_permlane32_swap_b32_e32 v188, v192
	s_cselect_b64 s[0:1], -1, 0
	s_branch .LBB0_820
.LBB0_815:
	s_mov_b64 s[0:1], 0
	s_cbranch_execz .LBB0_820
	v_max3_f32 v32, v112, s15, v113
	v_max3_f32 v32, v32, v114, v115
	v_max3_f32 v32, v32, v116, v117
	v_max3_f32 v32, v32, v118, v119
	v_max3_f32 v32, v32, v120, v121
	v_max3_f32 v32, v32, v122, v123
	v_max3_f32 v32, v32, v124, v125
	v_max3_f32 v32, v32, v126, v127
	v_mov_b32_e32 v33, v32
	v_mov_b32_e32 v34, v32
	s_nop 1
	v_permlane32_swap_b32_e32 v33, v34
	v_max_f32_e32 v32, v33, v34
	v_cmp_gt_f32_e32 vcc, v32, v187
	s_nop 1
	v_cndmask_b32_e32 v227, v226, v32, vcc
	v_max_f32_e32 v47, 0xefa18f08, v227
	v_sub_f32_e32 v32, v112, v47
	v_exp_f32_e32 v32, v32
	v_sub_f32_e32 v33, v113, v47
	v_exp_f32_e32 v33, v33
	v_sub_f32_e32 v34, v114, v47
	v_exp_f32_e32 v34, v34
	v_sub_f32_e32 v35, v115, v47
	v_exp_f32_e32 v35, v35
	v_add_f32_e32 v36, v33, v32
	v_add_f32_e32 v36, v34, v36
	v_add_f32_e32 v40, v35, v36
	v_sub_f32_e32 v36, v116, v47
	v_exp_f32_e32 v36, v36
	v_sub_f32_e32 v37, v117, v47
	v_exp_f32_e32 v37, v37
	v_sub_f32_e32 v38, v118, v47
	v_exp_f32_e32 v38, v38
	v_sub_f32_e32 v39, v119, v47
	v_exp_f32_e32 v39, v39
	v_add_f32_e32 v40, v36, v40
	v_add_f32_e32 v40, v37, v40
	v_add_f32_e32 v40, v38, v40
	v_add_f32_e32 v44, v39, v40
	v_sub_f32_e32 v40, v120, v47
	v_exp_f32_e32 v40, v40
	v_sub_f32_e32 v41, v121, v47
	v_exp_f32_e32 v41, v41
	v_sub_f32_e32 v42, v122, v47
	v_exp_f32_e32 v42, v42
	v_sub_f32_e32 v43, v123, v47
	v_exp_f32_e32 v43, v43
	v_add_f32_e32 v44, v40, v44
	v_add_f32_e32 v44, v41, v44
	v_add_f32_e32 v44, v42, v44
	v_add_f32_e32 v48, v43, v44
	v_sub_f32_e32 v44, v124, v47
	v_exp_f32_e32 v44, v44
	v_sub_f32_e32 v45, v125, v47
	v_exp_f32_e32 v45, v45
	v_sub_f32_e32 v46, v126, v47
	v_exp_f32_e32 v46, v46
	v_sub_f32_e32 v47, v127, v47
	v_exp_f32_e32 v47, v47
	v_add_f32_e32 v48, v44, v48
	v_add_f32_e32 v48, v45, v48
	v_add_f32_e32 v48, v46, v48
	v_add_f32_e32 v188, v47, v48
	v_mov_b32_e32 v48, v188
	v_mov_b32_e32 v49, v188
	s_nop 1
	v_permlane32_swap_b32_e32 v48, v49
	v_cmp_neq_f32_e32 vcc, v227, v226
	s_cbranch_vccz .LBB0_818
	v_sub_f32_e32 v50, v226, v227
	v_exp_f32_e32 v50, v50
	s_nop 0
	v_mul_f32_e32 v186, v186, v50
	v_pk_mul_f32 v[30:31], v[30:31], v[50:51] op_sel_hi:[1,0]
	v_pk_mul_f32 v[28:29], v[28:29], v[50:51] op_sel_hi:[1,0]
	v_pk_mul_f32 v[26:27], v[26:27], v[50:51] op_sel_hi:[1,0]
	v_pk_mul_f32 v[24:25], v[24:25], v[50:51] op_sel_hi:[1,0]
	v_pk_mul_f32 v[22:23], v[22:23], v[50:51] op_sel_hi:[1,0]
	v_pk_mul_f32 v[20:21], v[20:21], v[50:51] op_sel_hi:[1,0]
	v_pk_mul_f32 v[18:19], v[18:19], v[50:51] op_sel_hi:[1,0]
	v_pk_mul_f32 v[16:17], v[16:17], v[50:51] op_sel_hi:[1,0]
	v_pk_mul_f32 v[14:15], v[14:15], v[50:51] op_sel_hi:[1,0]
	v_pk_mul_f32 v[12:13], v[12:13], v[50:51] op_sel_hi:[1,0]
	v_pk_mul_f32 v[10:11], v[10:11], v[50:51] op_sel_hi:[1,0]
	v_pk_mul_f32 v[8:9], v[8:9], v[50:51] op_sel_hi:[1,0]
	v_pk_mul_f32 v[6:7], v[6:7], v[50:51] op_sel_hi:[1,0]
	v_pk_mul_f32 v[4:5], v[4:5], v[50:51] op_sel_hi:[1,0]
	v_pk_mul_f32 v[2:3], v[2:3], v[50:51] op_sel_hi:[1,0]
	v_pk_mul_f32 v[0:1], v[0:1], v[50:51] op_sel_hi:[1,0]
	s_branch .LBB0_819

; DI float ex2(float x) { return __builtin_amdgcn_exp2f(x); }
; template <int MM> DI void smax_step(const f32x16& s, unsigned vm, float& m, float& l, f32x16 (&o)[2], bf16x8 (&pf)[2], int lane) {
;     float t[16], mx = -1e30f;
; #pragma unroll
;     for (int i = 0; i < 16; ++i) { t[i] = (MM == 0) ? s[i] : (MM == 1 ? (vm ? s[i] : -1e30f) : (((vm >> i) & 1u) ? s[i] : -1e30f)); mx = fmaxf(mx, t[i]); }
;     mx = fmaxf(mx, shx32(mx, lane));
;     const float mn = (mx > m + 8.0f) ? mx : m;
;     const float mref = fmaxf(mn, -1e29f);
;     float p[16], rs = 0.f;
; #pragma unroll
;     for (int i = 0; i < 16; ++i) { p[i] = ex2(t[i] - mref); rs += p[i]; }
;     rs += shx32(rs, lane);
;     if (__builtin_amdgcn_ballot_w64(mn != m) != 0ull) {
;         const float alpha = ex2(m - mn);
;         l *= alpha;
; #pragma unroll
;         for (int i = 0; i < 16; ++i) { o[0][i] *= alpha; o[1][i] *= alpha; }
;         m = mn;
;     }
;     l += rs;
;     pack_p(p, pf);
; }
.LBB0_819:
	v_cvt_pk_bf16_f32 v128, v32, v33
	v_max3_f32 v32, v96, s15, v97
	v_max3_f32 v32, v32, v98, v99
	v_max3_f32 v32, v32, v100, v101
	v_max3_f32 v32, v32, v102, v103
	v_max3_f32 v32, v32, v104, v105
	v_max3_f32 v32, v32, v106, v107
	v_max3_f32 v32, v32, v108, v109
	v_max3_f32 v32, v32, v110, v111
	v_cvt_pk_bf16_f32 v129, v34, v35
	v_mov_b32_e32 v33, v32
	v_mov_b32_e32 v34, v32
	s_nop 1
	v_permlane32_swap_b32_e32 v33, v34
	v_max_f32_e32 v32, v33, v34
	v_add_f32_e32 v33, 0x41000000, v224
	v_cmp_gt_f32_e32 vcc, v32, v33
	v_cndmask_b32_e64 v48, v48, v49, s[36:37]
	v_cvt_pk_bf16_f32 v130, v36, v37
	v_cndmask_b32_e32 v228, v224, v32, vcc
	v_max_f32_e32 v32, 0xefa18f08, v228
	v_sub_f32_e32 v33, v96, v32
	v_exp_f32_e32 v229, v33
	v_sub_f32_e32 v33, v97, v32
	v_exp_f32_e32 v230, v33
	v_sub_f32_e32 v33, v98, v32
	v_exp_f32_e32 v231, v33
	v_sub_f32_e32 v33, v99, v32
	v_exp_f32_e32 v232, v33
	v_sub_f32_e32 v34, v100, v32
	v_exp_f32_e32 v233, v34
	v_sub_f32_e32 v34, v101, v32
	v_add_f32_e32 v33, v230, v229
	v_exp_f32_e32 v234, v34
	v_sub_f32_e32 v34, v102, v32
	v_add_f32_e32 v33, v231, v33
	v_exp_f32_e32 v235, v34
	v_sub_f32_e32 v34, v103, v32
	v_add_f32_e32 v33, v232, v33
	v_exp_f32_e32 v236, v34
	v_sub_f32_e32 v34, v104, v32
	v_add_f32_e32 v33, v233, v33
	v_exp_f32_e32 v237, v34
	v_sub_f32_e32 v34, v105, v32
	v_add_f32_e32 v33, v234, v33
	v_exp_f32_e32 v238, v34
	v_sub_f32_e32 v34, v106, v32
	v_add_f32_e32 v33, v235, v33
	v_exp_f32_e32 v239, v34
	v_sub_f32_e32 v34, v107, v32
	v_add_f32_e32 v33, v236, v33
	v_exp_f32_e32 v240, v34
	v_sub_f32_e32 v34, v108, v32
	v_add_f32_e32 v33, v237, v33
	v_exp_f32_e32 v241, v34
	v_sub_f32_e32 v34, v109, v32
	v_add_f32_e32 v33, v238, v33
	v_exp_f32_e32 v242, v34
	v_sub_f32_e32 v34, v110, v32
	v_add_f32_e32 v33, v239, v33
	v_exp_f32_e32 v189, v34
	v_sub_f32_e32 v32, v111, v32
	v_add_f32_e32 v33, v240, v33
	v_exp_f32_e32 v187, v32
	v_add_f32_e32 v32, v241, v33
	v_add_f32_e32 v49, v242, v32
	v_pk_add_f32 v[32:33], v[188:189], v[48:49]
	v_cmp_neq_f32_e32 vcc, v228, v224
	v_pk_add_f32 v[190:191], v[32:33], v[186:187]
	v_cvt_pk_bf16_f32 v131, v38, v39
	v_cvt_pk_bf16_f32 v132, v40, v41
	v_cvt_pk_bf16_f32 v133, v42, v43
	v_cvt_pk_bf16_f32 v134, v44, v45
	v_cvt_pk_bf16_f32 v135, v46, v47
	v_mov_b32_e32 v188, v191
	v_mov_b32_e32 v192, v191
	s_cmp_lg_u64 vcc, 0
	s_nop 0
	v_permlane32_swap_b32_e32 v188, v192
	s_cselect_b64 s[0:1], -1, 0
	v_mov_b32_e32 v193, v187

; #define LAS __attribute__((address_space(3)))
; DI float ex2(float x) { return __builtin_amdgcn_exp2f(x); }
; template <int MM> DI void smax_step_nb(const f32x16& s, unsigned vm, float& m, float& l, f32x16 (&o)[2], bf16x8 (&pf)[2], int lane) {
;     float mx = -1e30f;
; #pragma unroll
;     for (int i = 0; i < 16; ++i) mx = fmaxf(mx, s[i]);
;     if (MM == 1) mx = vm ? mx : -1e30f;
;     mx = fmaxf(mx, shx32(mx, lane));
;     const float mn = (mx > m + 8.0f) ? mx : m;
;     float mref = fmaxf(mn, -1e29f);
;     if (MM == 1) mref = vm ? mref : 3e38f;
;     const float alpha = ex2(m - mn);
;     float p[16], rs = 0.f;
; #pragma unroll
;     for (int i = 0; i < 16; ++i) { p[i] = ex2(s[i] - mref); rs += p[i]; }
;     rs += shx32(rs, lane);
;     l = l * alpha + rs;
;     if (__builtin_amdgcn_ballot_w64(mn != m) != 0ull) {
; #pragma unroll
;         for (int i = 0; i < 16; ++i) { o[0][i] *= alpha; o[1][i] *= alpha; }
;     }
;     m = mn;
;     pack_p(p, pf);
; }
; template <int MODE, bool PRE = false> ...
;     ...
;             const int kt0 = kt_lo + 2 * sti;
;             bool both = (kt0 + 1 <= kt_hi) && (64 * kt0 + 127 <= q0w);
;             if (MODE == MODE_NWIN) both = both && (64 * kt0 > q0w + 31 - 512);
;             if (both) {
;                 bool ls0 = true, ls1 = true;
;                 if (MODE == MODE_MOBA) { ls0 = ((sel >> (kt0 >> 2)) & 1ull) != 0ull; ls1 = ((sel >> ((kt0 + 1) >> 2)) & 1ull) != 0ull; }
;                 if (MODE == MODE_NSEL) { ls0 = ((sel >> kt0) & 1ull) != 0ull; ls1 = ((sel >> (kt0 + 1)) & 1ull) != 0ull; }
;                 const unsigned long long b0 = __builtin_amdgcn_ballot_w64(ls0), b1 = __builtin_amdgcn_ballot_w64(ls1);
;                 if (b0 != 0ull && b1 != 0ull) {
;                     LAS char* K0 = lds + (sti & 1) * 4 * TILE_B;
;                     if ((b0 & b1) == ~0ull) tile128_pipe<0>(K0, K0 + TILE_B, K0 + 2 * TILE_B, K0 + 3 * TILE_B, qf, 1u, 1u, m1, l1, o1, r, h, lane);
;                     else tile128_pipe<1>(K0, K0 + TILE_B, K0 + 2 * TILE_B, K0 + 3 * TILE_B, qf, ls0 ? 1u : 0u, ls1 ? 1u : 0u, m1, l1, o1, r, h, lane);
;                     goto step_done;
.LBB0_849:
	s_lshl_b32 s62, s38, 1
	s_cmp_lt_u32 s62, s58
	s_cselect_b64 s[0:1], -1, 0
	s_lshl_b32 s10, s38, 7
	s_or_b32 s10, s10, 0x7f
	s_cmp_le_i32 s10, s27
	s_cselect_b64 s[10:11], -1, 0
	s_and_b64 s[0:1], s[0:1], s[10:11]
	s_andn2_b64 vcc, exec, s[0:1]
	s_mov_b32 s10, 0
	s_cbranch_vccnz .LBB0_872
	s_lshr_b32 s0, s38, 1
	v_lshrrev_b64 v[32:33], s0, v[168:169]
	v_and_b32_e32 v32, 1, v32
	v_cmp_eq_u32_e64 s[0:1], 1, v32
	v_cmp_ne_u32_e32 vcc, 0, v32
	s_cbranch_vccz .LBB0_872
	s_lshl_b32 s10, s38, 2
	s_and_b32 s10, s10, 4
	s_mulk_i32 s10, 0x2400
	s_add_i32 s10, s10, 0
	v_add_u32_e32 v32, s10, v184
	v_add_u32_e32 v192, v32, v160
	s_waitcnt lgkmcnt(7)
	ds_read_b128 v[140:143], v192
	s_waitcnt lgkmcnt(7)
	ds_read_b128 v[136:139], v192 offset:32
	s_waitcnt lgkmcnt(7)
	ds_read_b128 v[132:135], v192 offset:64
	s_waitcnt lgkmcnt(7)
	ds_read_b128 v[128:131], v192 offset:96
	s_cmp_lg_u64 vcc, -1
	s_setprio 1
	s_setprio 0
	s_waitcnt lgkmcnt(7)
	ds_read_b128 v[144:147], v192 offset:4608
	s_waitcnt lgkmcnt(7)
	ds_read_b128 v[148:151], v192 offset:4640
	s_waitcnt lgkmcnt(7)
	ds_read_b128 v[152:155], v192 offset:4672
	s_waitcnt lgkmcnt(7)
	ds_read_b128 v[156:159], v192 offset:4704
	s_setprio 1
	s_setprio 0
	v_add_f32_e32 v193, 0x41000000, v191
	s_cbranch_scc0 .LBB0_861
	s_waitcnt lgkmcnt(7)
	v_mfma_f32_32x32x16_bf16 v[32:47], v[140:143], v[112:115], 0
	s_waitcnt lgkmcnt(6)
	v_mfma_f32_32x32x16_bf16 v[32:47], v[136:139], v[116:119], v[32:47]
	s_waitcnt lgkmcnt(5)
	v_mfma_f32_32x32x16_bf16 v[32:47], v[132:135], v[120:123], v[32:47]
	s_waitcnt lgkmcnt(4)
	v_mfma_f32_32x32x16_bf16 v[32:47], v[128:131], v[124:127], v[32:47]
	s_waitcnt lgkmcnt(3)
	v_mfma_f32_32x32x16_bf16 v[64:79], v[144:147], v[112:115], 0
	s_nop 9
	v_max3_f32 v48, v32, s15, v33
	v_max3_f32 v48, v48, v34, v35
	v_max3_f32 v48, v48, v36, v37
	v_max3_f32 v48, v48, v38, v39
	v_max3_f32 v48, v48, v40, v41
	v_max3_f32 v48, v48, v42, v43
	v_max3_f32 v48, v48, v44, v45
	v_max3_f32 v48, v48, v46, v47
	v_cndmask_b32_e64 v48, v208, v48, s[0:1]
	v_mov_b32_e32 v49, v48
	v_mov_b32_e32 v50, v48
	s_nop 1
	v_permlane32_swap_b32_e32 v49, v50
	v_max_f32_e32 v48, v49, v50
	v_cmp_gt_f32_e32 vcc, v48, v193
	s_waitcnt lgkmcnt(2)
	v_mfma_f32_32x32x16_bf16 v[64:79], v[148:151], v[116:119], v[64:79]
	v_cndmask_b32_e32 v219, v191, v48, vcc
	v_max_f32_e32 v48, 0xefa18f08, v219
	v_cndmask_b32_e64 v48, v209, v48, s[0:1]
	v_sub_f32_e32 v32, v32, v48
	v_sub_f32_e32 v33, v33, v48
	v_exp_f32_e32 v80, v32
	v_sub_f32_e32 v34, v34, v48
	v_exp_f32_e32 v81, v33
	v_sub_f32_e32 v35, v35, v48
	v_exp_f32_e32 v82, v34
	v_sub_f32_e32 v36, v36, v48
	v_exp_f32_e32 v83, v35
	v_sub_f32_e32 v37, v37, v48
	v_exp_f32_e32 v84, v36
	v_sub_f32_e32 v38, v38, v48
	v_exp_f32_e32 v85, v37
	v_add_f32_e32 v32, v81, v80
	v_sub_f32_e32 v39, v39, v48
	v_exp_f32_e32 v86, v38
	s_waitcnt lgkmcnt(1)
	v_mfma_f32_32x32x16_bf16 v[64:79], v[152:155], v[120:123], v[64:79]
	v_add_f32_e32 v32, v82, v32
	v_sub_f32_e32 v40, v40, v48
	v_exp_f32_e32 v87, v39
	v_add_f32_e32 v32, v83, v32
	v_sub_f32_e32 v41, v41, v48
	v_exp_f32_e32 v88, v40
	v_add_f32_e32 v32, v84, v32
	v_sub_f32_e32 v42, v42, v48
	v_exp_f32_e32 v89, v41
	v_add_f32_e32 v32, v85, v32
	v_sub_f32_e32 v43, v43, v48
	v_exp_f32_e32 v90, v42
	v_add_f32_e32 v32, v86, v32
	v_sub_f32_e32 v44, v44, v48
	v_exp_f32_e32 v91, v43
	v_add_f32_e32 v32, v87, v32
	v_add_f32_e32 v32, v88, v32
	v_exp_f32_e32 v92, v44
	v_sub_f32_e32 v33, v45, v48
	v_add_f32_e32 v32, v89, v32
	v_exp_f32_e32 v93, v33
	v_sub_f32_e32 v33, v46, v48
	s_waitcnt lgkmcnt(0)
	v_mfma_f32_32x32x16_bf16 v[64:79], v[156:159], v[124:127], v[64:79]
	v_add_f32_e32 v32, v90, v32
	v_exp_f32_e32 v94, v33
	v_sub_f32_e32 v33, v47, v48
	v_add_f32_e32 v32, v91, v32
	v_exp_f32_e32 v95, v33
	v_add_f32_e32 v32, v92, v32
	v_sub_f32_e32 v49, v191, v219
	v_add_f32_e32 v32, v93, v32
	v_add_f32_e32 v32, v94, v32
	v_exp_f32_e32 v164, v49
	v_add_f32_e32 v212, v95, v32
	v_mov_b32_e32 v213, v212
	v_mov_b32_e32 v214, v212
	s_nop 0
	s_nop 0
	v_permlane32_swap_b32_e32 v213, v214
	v_cmp_neq_f32_e32 vcc, v219, v191
	s_cbranch_vccz .LBB0_854
	v_pk_mul_f32 v[30:31], v[30:31], v[164:165] op_sel_hi:[1,0]
	v_pk_mul_f32 v[28:29], v[28:29], v[164:165] op_sel_hi:[1,0]
	v_pk_mul_f32 v[26:27], v[26:27], v[164:165] op_sel_hi:[1,0]
	v_pk_mul_f32 v[24:25], v[24:25], v[164:165] op_sel_hi:[1,0]
	v_pk_mul_f32 v[22:23], v[22:23], v[164:165] op_sel_hi:[1,0]
	v_pk_mul_f32 v[20:21], v[20:21], v[164:165] op_sel_hi:[1,0]
	v_pk_mul_f32 v[18:19], v[18:19], v[164:165] op_sel_hi:[1,0]
	v_pk_mul_f32 v[16:17], v[16:17], v[164:165] op_sel_hi:[1,0]
	v_pk_mul_f32 v[14:15], v[14:15], v[164:165] op_sel_hi:[1,0]
	v_pk_mul_f32 v[12:13], v[12:13], v[164:165] op_sel_hi:[1,0]
	v_pk_mul_f32 v[10:11], v[10:11], v[164:165] op_sel_hi:[1,0]
	v_pk_mul_f32 v[8:9], v[8:9], v[164:165] op_sel_hi:[1,0]
	v_pk_mul_f32 v[6:7], v[6:7], v[164:165] op_sel_hi:[1,0]
	v_pk_mul_f32 v[4:5], v[4:5], v[164:165] op_sel_hi:[1,0]
	v_pk_mul_f32 v[2:3], v[2:3], v[164:165] op_sel_hi:[1,0]
	v_pk_mul_f32 v[0:1], v[0:1], v[164:165] op_sel_hi:[1,0]
; #define LAS __attribute__((address_space(3)))
; DI float ex2(float x) { return __builtin_amdgcn_exp2f(x); }
; template <int MM> DI void smax_step_nb(const f32x16& s, unsigned vm, float& m, float& l, f32x16 (&o)[2], bf16x8 (&pf)[2], int lane) {
;     float mx = -1e30f;
; #pragma unroll
;     for (int i = 0; i < 16; ++i) mx = fmaxf(mx, s[i]);
;     if (MM == 1) mx = vm ? mx : -1e30f;
;     mx = fmaxf(mx, shx32(mx, lane));
;     const float mn = (mx > m + 8.0f) ? mx : m;
;     float mref = fmaxf(mn, -1e29f);
;     if (MM == 1) mref = vm ? mref : 3e38f;
;     const float alpha = ex2(m - mn);
;     float p[16], rs = 0.f;
; #pragma unroll
;     for (int i = 0; i < 16; ++i) { p[i] = ex2(s[i] - mref); rs += p[i]; }
;     rs += shx32(rs, lane);
;     l = l * alpha + rs;
;     if (__builtin_amdgcn_ballot_w64(mn != m) != 0ull) {
; #pragma unroll
;         for (int i = 0; i < 16; ++i) { o[0][i] *= alpha; o[1][i] *= alpha; }
;     }
;     m = mn;
;     pack_p(p, pf);
; }
; template <int MM> DI void tile128_pipe(LAS const char* K0, LAS const char* V0, LAS const char* K1, LAS const char* V1, const bf16x8 (&qf)[4], unsigned vm0, unsigned vm1,
;                                        float& m, float& l, f32x16 (&o)[2], int r, int h, int lane) {
;     f32x16 sa = qk_rows<0, 4>(K0, 0, qf, r, h), sb = qk_rows<0, 4>(K0, 32, qf, r, h);
;     bf16x8 pfa[2], pfb[2];
;     smax_step_nb<MM>(sa, vm0, m, l, o, pfa, lane);
;     sa = qk_rows<0, 4>(K1, 0, qf, r, h);
;     pv_rows(o, V0, 0, pfa, lane);
;     smax_step_nb<MM>(sb, vm0, m, l, o, pfb, lane);
;     sb = qk_rows<0, 4>(K1, 32, qf, r, h);
;     pv_rows(o, V0, 32, pfb, lane);
;     smax_step_nb<MM>(sa, vm1, m, l, o, pfa, lane);
;     pv_rows(o, V1, 0, pfa, lane);
;     smax_step_nb<MM>(sb, vm1, m, l, o, pfb, lane);
;     pv_rows(o, V1, 32, pfb, lane);
; }
.LBB0_854:
	v_cvt_pk_bf16_f32 v220, v80, v81
	v_cvt_pk_bf16_f32 v221, v82, v83
	ds_read_b128 v[80:83], v192 offset:18432
	ds_read_b128 v[228:231], v192 offset:18464
	ds_read_b128 v[232:235], v192 offset:18496
	ds_read_b128 v[236:239], v192 offset:18528
	v_cvt_pk_bf16_f32 v222, v84, v85
	v_cvt_pk_bf16_f32 v223, v86, v87
	v_cvt_pk_bf16_f32 v224, v88, v89
	v_cvt_pk_bf16_f32 v225, v90, v91
	v_cvt_pk_bf16_f32 v226, v92, v93
	v_cvt_pk_bf16_f32 v227, v94, v95
	s_setprio 1
	s_waitcnt lgkmcnt(3)
	v_mfma_f32_32x32x16_bf16 v[80:95], v[80:83], v[112:115], 0
	s_waitcnt lgkmcnt(2)
	v_mfma_f32_32x32x16_bf16 v[80:95], v[228:231], v[116:119], v[80:95]
	s_waitcnt lgkmcnt(1)
	v_mfma_f32_32x32x16_bf16 v[80:95], v[232:235], v[120:123], v[80:95]
	s_waitcnt lgkmcnt(0)
	v_mfma_f32_32x32x16_bf16 v[80:95], v[236:239], v[124:127], v[80:95]
	s_setprio 0
	v_add3_u32 v166, s10, v186, v187
	v_add_u32_e32 v215, v166, v188
	ds_read_b64_tr_b16 v[228:229], v215 offset:9216
	ds_read_b64_tr_b16 v[230:231], v215 offset:10368
	ds_read_b64_tr_b16 v[234:235], v215 offset:10432
	ds_read_b64_tr_b16 v[232:233], v215 offset:9280
	ds_read_b64_tr_b16 v[236:237], v215 offset:11520
	ds_read_b64_tr_b16 v[238:239], v215 offset:12672
	ds_read_b64_tr_b16 v[242:243], v215 offset:12736
	ds_read_b64_tr_b16 v[240:241], v215 offset:11584
	s_setprio 1
	s_waitcnt lgkmcnt(6)
	v_mfma_f32_32x32x16_bf16 v[0:15], v[228:231], v[220:223], v[0:15]
	s_waitcnt lgkmcnt(4)
	v_mfma_f32_32x32x16_bf16 v[16:31], v[232:235], v[220:223], v[16:31]
	s_waitcnt lgkmcnt(2)
	v_mfma_f32_32x32x16_bf16 v[0:15], v[236:239], v[224:227], v[0:15]
	s_waitcnt lgkmcnt(0)
	v_mfma_f32_32x32x16_bf16 v[16:31], v[240:243], v[224:227], v[16:31]
	s_setprio 0
	v_max3_f32 v166, v64, s15, v65
	v_max3_f32 v166, v166, v66, v67
	v_max3_f32 v166, v166, v68, v69
	v_max3_f32 v166, v166, v70, v71
	v_max3_f32 v166, v166, v72, v73
	v_max3_f32 v166, v166, v74, v75
	v_max3_f32 v166, v166, v76, v77
	v_max3_f32 v166, v166, v78, v79
	v_cndmask_b32_e64 v166, v208, v166, s[0:1]
	v_mov_b32_e32 v172, v166
	v_mov_b32_e32 v173, v166
	s_nop 1
	v_permlane32_swap_b32_e32 v172, v173
	v_max_f32_e32 v166, v172, v173
	v_add_f32_e32 v172, 0x41000000, v219
	v_cmp_gt_f32_e32 vcc, v166, v172
	s_nop 1
	v_cndmask_b32_e32 v220, v219, v166, vcc
	v_max_f32_e32 v166, 0xefa18f08, v220
	v_cndmask_b32_e64 v166, v209, v166, s[0:1]
	v_sub_f32_e32 v64, v64, v166
	v_exp_f32_e32 v64, v64
	v_sub_f32_e32 v65, v65, v166
	v_exp_f32_e32 v65, v65
	v_sub_f32_e32 v66, v66, v166
	v_exp_f32_e32 v66, v66
	v_sub_f32_e32 v67, v67, v166
	v_exp_f32_e32 v67, v67
	v_sub_f32_e32 v68, v68, v166
	v_exp_f32_e32 v68, v68
	v_sub_f32_e32 v69, v69, v166
	v_add_f32_e32 v173, v65, v64
	v_exp_f32_e32 v69, v69
	v_sub_f32_e32 v70, v70, v166
	v_add_f32_e32 v173, v66, v173
	v_exp_f32_e32 v70, v70
	v_sub_f32_e32 v71, v71, v166
	v_add_f32_e32 v173, v67, v173
	v_exp_f32_e32 v71, v71
	v_sub_f32_e32 v72, v72, v166
	v_add_f32_e32 v173, v68, v173
	v_exp_f32_e32 v72, v72
	v_sub_f32_e32 v73, v73, v166
	v_add_f32_e32 v173, v69, v173
	v_exp_f32_e32 v73, v73
	v_sub_f32_e32 v74, v74, v166
	v_add_f32_e32 v173, v70, v173
	v_exp_f32_e32 v74, v74
	v_sub_f32_e32 v75, v75, v166
	v_add_f32_e32 v173, v71, v173
	v_exp_f32_e32 v75, v75
	v_sub_f32_e32 v76, v76, v166
	v_add_f32_e32 v173, v72, v173
	v_exp_f32_e32 v76, v76
	v_sub_f32_e32 v77, v77, v166
	v_add_f32_e32 v173, v73, v173
	v_exp_f32_e32 v77, v77
	v_sub_f32_e32 v78, v78, v166
	v_add_f32_e32 v173, v74, v173
	v_exp_f32_e32 v78, v78
	v_sub_f32_e32 v79, v79, v166
	v_add_f32_e32 v173, v75, v173
	v_exp_f32_e32 v79, v79
	v_add_f32_e32 v166, v76, v173
	v_add_f32_e32 v166, v77, v166
	v_sub_f32_e32 v172, v219, v220
	v_add_f32_e32 v166, v78, v166
	v_add_f32_e32 v216, v79, v166
	v_exp_f32_e32 v166, v172
	v_mov_b32_e32 v217, v216
	v_mov_b32_e32 v218, v216
	s_nop 1
	v_permlane32_swap_b32_e32 v217, v218
	v_cmp_neq_f32_e32 vcc, v220, v219
	s_cbranch_vccz .LBB0_856
	v_pk_mul_f32 v[30:31], v[30:31], v[166:167] op_sel_hi:[1,0]
	v_pk_mul_f32 v[28:29], v[28:29], v[166:167] op_sel_hi:[1,0]
	v_pk_mul_f32 v[26:27], v[26:27], v[166:167] op_sel_hi:[1,0]
	v_pk_mul_f32 v[24:25], v[24:25], v[166:167] op_sel_hi:[1,0]
	v_pk_mul_f32 v[22:23], v[22:23], v[166:167] op_sel_hi:[1,0]
	v_pk_mul_f32 v[20:21], v[20:21], v[166:167] op_sel_hi:[1,0]
	v_pk_mul_f32 v[18:19], v[18:19], v[166:167] op_sel_hi:[1,0]
	v_pk_mul_f32 v[16:17], v[16:17], v[166:167] op_sel_hi:[1,0]
	v_pk_mul_f32 v[14:15], v[14:15], v[166:167] op_sel_hi:[1,0]
	v_pk_mul_f32 v[12:13], v[12:13], v[166:167] op_sel_hi:[1,0]
	v_pk_mul_f32 v[10:11], v[10:11], v[166:167] op_sel_hi:[1,0]
	v_pk_mul_f32 v[8:9], v[8:9], v[166:167] op_sel_hi:[1,0]
	v_pk_mul_f32 v[6:7], v[6:7], v[166:167] op_sel_hi:[1,0]
	v_pk_mul_f32 v[4:5], v[4:5], v[166:167] op_sel_hi:[1,0]
	v_pk_mul_f32 v[2:3], v[2:3], v[166:167] op_sel_hi:[1,0]
	v_pk_mul_f32 v[0:1], v[0:1], v[166:167] op_sel_hi:[1,0]
; #define LAS __attribute__((address_space(3)))
; DI float ex2(float x) { return __builtin_amdgcn_exp2f(x); }
; template <int MM> DI void smax_step_nb(const f32x16& s, unsigned vm, float& m, float& l, f32x16 (&o)[2], bf16x8 (&pf)[2], int lane) {
;     float mx = -1e30f;
; #pragma unroll
;     for (int i = 0; i < 16; ++i) mx = fmaxf(mx, s[i]);
;     if (MM == 1) mx = vm ? mx : -1e30f;
;     mx = fmaxf(mx, shx32(mx, lane));
;     const float mn = (mx > m + 8.0f) ? mx : m;
;     float mref = fmaxf(mn, -1e29f);
;     if (MM == 1) mref = vm ? mref : 3e38f;
;     const float alpha = ex2(m - mn);
;     float p[16], rs = 0.f;
; #pragma unroll
;     for (int i = 0; i < 16; ++i) { p[i] = ex2(s[i] - mref); rs += p[i]; }
;     rs += shx32(rs, lane);
;     l = l * alpha + rs;
;     if (__builtin_amdgcn_ballot_w64(mn != m) != 0ull) {
; #pragma unroll
;         for (int i = 0; i < 16; ++i) { o[0][i] *= alpha; o[1][i] *= alpha; }
;     }
;     m = mn;
;     pack_p(p, pf);
; }
; template <int MM> DI void tile128_pipe(LAS const char* K0, LAS const char* V0, LAS const char* K1, LAS const char* V1, const bf16x8 (&qf)[4], unsigned vm0, unsigned vm1,
;                                        float& m, float& l, f32x16 (&o)[2], int r, int h, int lane) {
;     f32x16 sa = qk_rows<0, 4>(K0, 0, qf, r, h), sb = qk_rows<0, 4>(K0, 32, qf, r, h);
;     bf16x8 pfa[2], pfb[2];
;     smax_step_nb<MM>(sa, vm0, m, l, o, pfa, lane);
;     sa = qk_rows<0, 4>(K1, 0, qf, r, h);
;     pv_rows(o, V0, 0, pfa, lane);
;     smax_step_nb<MM>(sb, vm0, m, l, o, pfb, lane);
;     sb = qk_rows<0, 4>(K1, 32, qf, r, h);
;     pv_rows(o, V0, 32, pfb, lane);
;     smax_step_nb<MM>(sa, vm1, m, l, o, pfa, lane);
;     pv_rows(o, V1, 0, pfa, lane);
;     smax_step_nb<MM>(sb, vm1, m, l, o, pfb, lane);
;     pv_rows(o, V1, 32, pfb, lane);
; }
.LBB0_856:
	v_cvt_pk_bf16_f32 v222, v64, v65
	v_cvt_pk_bf16_f32 v223, v66, v67
	ds_read_b128 v[64:67], v192 offset:23040
	ds_read_b128 v[230:233], v192 offset:23072
	ds_read_b128 v[234:237], v192 offset:23104
	ds_read_b128 v[238:241], v192 offset:23136
	v_cvt_pk_bf16_f32 v224, v68, v69
	v_cvt_pk_bf16_f32 v225, v70, v71
	v_cvt_pk_bf16_f32 v226, v72, v73
	v_cvt_pk_bf16_f32 v227, v74, v75
	v_cvt_pk_bf16_f32 v228, v76, v77
	v_cvt_pk_bf16_f32 v229, v78, v79
	s_setprio 1
	s_waitcnt lgkmcnt(3)
	v_mfma_f32_32x32x16_bf16 v[64:79], v[64:67], v[112:115], 0
	s_waitcnt lgkmcnt(2)
	v_mfma_f32_32x32x16_bf16 v[64:79], v[230:233], v[116:119], v[64:79]
	s_waitcnt lgkmcnt(1)
	v_mfma_f32_32x32x16_bf16 v[64:79], v[234:237], v[120:123], v[64:79]
	s_waitcnt lgkmcnt(0)
	v_mfma_f32_32x32x16_bf16 v[64:79], v[238:241], v[124:127], v[64:79]
	s_setprio 0
	ds_read_b64_tr_b16 v[230:231], v215 offset:13824
	ds_read_b64_tr_b16 v[232:233], v215 offset:14976
	ds_read_b64_tr_b16 v[236:237], v215 offset:15040
	ds_read_b64_tr_b16 v[234:235], v215 offset:13888
	ds_read_b64_tr_b16 v[238:239], v215 offset:16128
	ds_read_b64_tr_b16 v[240:241], v215 offset:17280
	ds_read_b64_tr_b16 v[244:245], v215 offset:17344
	ds_read_b64_tr_b16 v[242:243], v215 offset:16192
	s_setprio 1
	s_waitcnt lgkmcnt(6)
	v_mfma_f32_32x32x16_bf16 v[0:15], v[230:233], v[222:225], v[0:15]
	s_waitcnt lgkmcnt(4)
	v_mfma_f32_32x32x16_bf16 v[16:31], v[234:237], v[222:225], v[16:31]
	s_waitcnt lgkmcnt(2)
	v_mfma_f32_32x32x16_bf16 v[0:15], v[238:241], v[226:229], v[0:15]
	s_waitcnt lgkmcnt(0)
	v_mfma_f32_32x32x16_bf16 v[16:31], v[242:245], v[226:229], v[16:31]
	s_setprio 0
	v_max3_f32 v172, v80, s15, v81
	v_max3_f32 v172, v172, v82, v83
	v_max3_f32 v172, v172, v84, v85
	v_max3_f32 v172, v172, v86, v87
	v_max3_f32 v172, v172, v88, v89
	v_max3_f32 v172, v172, v90, v91
	v_max3_f32 v172, v172, v92, v93
	v_max3_f32 v172, v172, v94, v95
	v_cndmask_b32_e64 v172, v208, v172, s[0:1]
	v_mov_b32_e32 v173, v172
	v_mov_b32_e32 v206, v172
	s_nop 1
	v_permlane32_swap_b32_e32 v173, v206
	v_cndmask_b32_e64 v173, v173, v206, s[36:37]
	v_max_f32_e32 v173, v173, v173
	v_max_f32_e32 v172, v172, v173
	v_add_f32_e32 v173, 0x41000000, v220
	v_cmp_gt_f32_e32 vcc, v172, v173
	s_nop 1
	v_cndmask_b32_e32 v219, v220, v172, vcc
	v_max_f32_e32 v172, 0xefa18f08, v219
	v_cndmask_b32_e64 v172, v209, v172, s[0:1]
	v_sub_f32_e32 v80, v80, v172
	v_exp_f32_e32 v221, v80
	v_sub_f32_e32 v80, v81, v172
	v_exp_f32_e32 v81, v80
	v_sub_f32_e32 v80, v82, v172
	v_exp_f32_e32 v222, v80
	v_sub_f32_e32 v80, v83, v172
	v_exp_f32_e32 v223, v80
	v_sub_f32_e32 v82, v84, v172
	v_exp_f32_e32 v224, v82
	v_sub_f32_e32 v82, v85, v172
	v_add_f32_e32 v80, v81, v221
	v_exp_f32_e32 v85, v82
	v_sub_f32_e32 v82, v86, v172
	v_add_f32_e32 v80, v222, v80
	v_exp_f32_e32 v86, v82
	v_sub_f32_e32 v82, v87, v172
	v_add_f32_e32 v80, v223, v80
	v_exp_f32_e32 v87, v82
	v_sub_f32_e32 v82, v88, v172
	v_add_f32_e32 v80, v224, v80
	v_exp_f32_e32 v88, v82
	v_sub_f32_e32 v82, v89, v172
	v_add_f32_e32 v80, v85, v80
	v_exp_f32_e32 v89, v82
	v_sub_f32_e32 v82, v90, v172
	v_add_f32_e32 v80, v86, v80
	v_exp_f32_e32 v90, v82
	v_sub_f32_e32 v82, v91, v172
	v_add_f32_e32 v80, v87, v80
	v_exp_f32_e32 v91, v82
	v_sub_f32_e32 v82, v92, v172
	v_add_f32_e32 v80, v88, v80
	v_exp_f32_e32 v92, v82
	v_sub_f32_e32 v82, v93, v172
	v_add_f32_e32 v80, v89, v80
	v_exp_f32_e32 v93, v82
	v_sub_f32_e32 v82, v94, v172
	v_add_f32_e32 v80, v90, v80
	v_exp_f32_e32 v94, v82
	v_sub_f32_e32 v82, v95, v172
	v_add_f32_e32 v80, v91, v80
	v_exp_f32_e32 v95, v82
	v_add_f32_e32 v80, v92, v80
	v_add_f32_e32 v80, v93, v80
	v_sub_f32_e32 v173, v220, v219
	v_add_f32_e32 v80, v94, v80
	v_add_f32_e32 v82, v95, v80
	v_exp_f32_e32 v80, v173
	v_mov_b32_e32 v83, v82
	v_mov_b32_e32 v84, v82
	s_nop 1
	v_permlane32_swap_b32_e32 v83, v84
	v_cmp_neq_f32_e32 vcc, v219, v220
	s_cbranch_vccz .LBB0_858
	v_pk_mul_f32 v[30:31], v[30:31], v[80:81] op_sel_hi:[1,0]
	v_pk_mul_f32 v[28:29], v[28:29], v[80:81] op_sel_hi:[1,0]
	v_pk_mul_f32 v[26:27], v[26:27], v[80:81] op_sel_hi:[1,0]
	v_pk_mul_f32 v[24:25], v[24:25], v[80:81] op_sel_hi:[1,0]
	v_pk_mul_f32 v[22:23], v[22:23], v[80:81] op_sel_hi:[1,0]
	v_pk_mul_f32 v[20:21], v[20:21], v[80:81] op_sel_hi:[1,0]
	v_pk_mul_f32 v[18:19], v[18:19], v[80:81] op_sel_hi:[1,0]
	v_pk_mul_f32 v[16:17], v[16:17], v[80:81] op_sel_hi:[1,0]
	v_pk_mul_f32 v[14:15], v[14:15], v[80:81] op_sel_hi:[1,0]
	v_pk_mul_f32 v[12:13], v[12:13], v[80:81] op_sel_hi:[1,0]
	v_pk_mul_f32 v[10:11], v[10:11], v[80:81] op_sel_hi:[1,0]
	v_pk_mul_f32 v[8:9], v[8:9], v[80:81] op_sel_hi:[1,0]
	v_pk_mul_f32 v[6:7], v[6:7], v[80:81] op_sel_hi:[1,0]
	v_pk_mul_f32 v[4:5], v[4:5], v[80:81] op_sel_hi:[1,0]
	v_pk_mul_f32 v[2:3], v[2:3], v[80:81] op_sel_hi:[1,0]
	v_pk_mul_f32 v[0:1], v[0:1], v[80:81] op_sel_hi:[1,0]
; DI float ex2(float x) { return __builtin_amdgcn_exp2f(x); }
; template <int MM> DI void smax_step_nb(const f32x16& s, unsigned vm, float& m, float& l, f32x16 (&o)[2], bf16x8 (&pf)[2], int lane) {
;     float mx = -1e30f;
; #pragma unroll
;     for (int i = 0; i < 16; ++i) mx = fmaxf(mx, s[i]);
;     if (MM == 1) mx = vm ? mx : -1e30f;
;     mx = fmaxf(mx, shx32(mx, lane));
;     const float mn = (mx > m + 8.0f) ? mx : m;
;     float mref = fmaxf(mn, -1e29f);
;     if (MM == 1) mref = vm ? mref : 3e38f;
;     const float alpha = ex2(m - mn);
;     float p[16], rs = 0.f;
; #pragma unroll
;     for (int i = 0; i < 16; ++i) { p[i] = ex2(s[i] - mref); rs += p[i]; }
;     rs += shx32(rs, lane);
;     l = l * alpha + rs;
;     if (__builtin_amdgcn_ballot_w64(mn != m) != 0ull) {
; #pragma unroll
;         for (int i = 0; i < 16; ++i) { o[0][i] *= alpha; o[1][i] *= alpha; }
;     }
;     m = mn;
;     pack_p(p, pf);
; }
; template <int MM> DI void tile128_pipe(LAS const char* K0, LAS const char* V0, LAS const char* K1, LAS const char* V1, const bf16x8 (&qf)[4], unsigned vm0, unsigned vm1,
;                                        float& m, float& l, f32x16 (&o)[2], int r, int h, int lane) {
;     ...
;     pv_rows(o, V0, 0, pfa, lane);
;     smax_step_nb<MM>(sb, vm0, m, l, o, pfb, lane);
;     sb = qk_rows<0, 4>(K1, 32, qf, r, h);
;     pv_rows(o, V0, 32, pfb, lane);
;     smax_step_nb<MM>(sa, vm1, m, l, o, pfa, lane);
;     pv_rows(o, V1, 0, pfa, lane);
;     smax_step_nb<MM>(sb, vm1, m, l, o, pfb, lane);
;     pv_rows(o, V1, 32, pfb, lane);
; }
.LBB0_858:
	v_cvt_pk_bf16_f32 v220, v221, v81
	v_cvt_pk_bf16_f32 v221, v222, v223
	v_cvt_pk_bf16_f32 v222, v224, v85
	v_cvt_pk_bf16_f32 v223, v86, v87
	v_cvt_pk_bf16_f32 v86, v88, v89
	v_cvt_pk_bf16_f32 v87, v90, v91
	v_cvt_pk_bf16_f32 v88, v92, v93
	ds_read_b64_tr_b16 v[90:91], v215 offset:27648
	ds_read_b64_tr_b16 v[92:93], v215 offset:28800
	ds_read_b64_tr_b16 v[224:225], v215 offset:29952
	ds_read_b64_tr_b16 v[226:227], v215 offset:31104
	ds_read_b64_tr_b16 v[228:229], v215 offset:27712
	ds_read_b64_tr_b16 v[230:231], v215 offset:28864
	ds_read_b64_tr_b16 v[232:233], v215 offset:30016
	ds_read_b64_tr_b16 v[234:235], v215 offset:31168
	v_cvt_pk_bf16_f32 v89, v94, v95
	s_setprio 1
	s_waitcnt lgkmcnt(6)
	v_mfma_f32_32x32x16_bf16 v[0:15], v[90:93], v[220:223], v[0:15]
	s_waitcnt lgkmcnt(2)
	v_mfma_f32_32x32x16_bf16 v[16:31], v[228:231], v[220:223], v[16:31]
	v_mfma_f32_32x32x16_bf16 v[0:15], v[224:227], v[86:89], v[0:15]
	s_waitcnt lgkmcnt(0)
	v_mfma_f32_32x32x16_bf16 v[16:31], v[232:235], v[86:89], v[16:31]
	s_setprio 0
	v_max3_f32 v81, v64, s15, v65
	v_max3_f32 v81, v81, v66, v67
	v_max3_f32 v81, v81, v68, v69
	v_max3_f32 v81, v81, v70, v71
	v_max3_f32 v81, v81, v72, v73
	v_max3_f32 v81, v81, v74, v75
	v_max3_f32 v81, v81, v76, v77
	v_max3_f32 v81, v81, v78, v79
	v_cndmask_b32_e64 v81, v208, v81, s[0:1]
	v_mov_b32_e32 v85, v81
	v_mov_b32_e32 v86, v81
	s_nop 1
	v_permlane32_swap_b32_e32 v85, v86
	v_max_f32_e32 v81, v85, v86
	v_add_f32_e32 v85, 0x41000000, v219
	v_cmp_gt_f32_e32 vcc, v81, v85
	s_nop 1
	v_cndmask_b32_e32 v81, v219, v81, vcc
	v_max_f32_e32 v85, 0xefa18f08, v81
	v_cndmask_b32_e64 v93, v209, v85, s[0:1]
	v_sub_f32_e32 v64, v64, v93
	v_exp_f32_e32 v85, v64
	v_sub_f32_e32 v64, v65, v93
	v_exp_f32_e32 v86, v64
	v_sub_f32_e32 v64, v66, v93
	v_exp_f32_e32 v87, v64
	v_sub_f32_e32 v64, v67, v93
	v_exp_f32_e32 v88, v64
	v_sub_f32_e32 v65, v68, v93
	v_exp_f32_e32 v89, v65
	v_sub_f32_e32 v65, v69, v93
	v_add_f32_e32 v64, v86, v85
	v_exp_f32_e32 v90, v65
	v_sub_f32_e32 v65, v70, v93
	v_add_f32_e32 v64, v87, v64
	v_exp_f32_e32 v91, v65
	v_sub_f32_e32 v65, v71, v93
	v_add_f32_e32 v64, v88, v64
	v_exp_f32_e32 v92, v65
	v_sub_f32_e32 v65, v72, v93
	v_add_f32_e32 v64, v89, v64
	v_exp_f32_e32 v66, v65
	v_sub_f32_e32 v65, v73, v93
	v_add_f32_e32 v64, v90, v64
	v_exp_f32_e32 v67, v65
	v_sub_f32_e32 v65, v74, v93
	v_add_f32_e32 v64, v91, v64
	v_exp_f32_e32 v68, v65
	v_sub_f32_e32 v65, v75, v93
	v_add_f32_e32 v64, v92, v64
	v_exp_f32_e32 v69, v65
	v_sub_f32_e32 v65, v76, v93
	v_add_f32_e32 v64, v66, v64
	v_exp_f32_e32 v70, v65
	v_sub_f32_e32 v65, v77, v93
	v_add_f32_e32 v64, v67, v64
	v_exp_f32_e32 v71, v65
	v_sub_f32_e32 v65, v78, v93
	v_add_f32_e32 v64, v68, v64
	v_exp_f32_e32 v72, v65
	v_sub_f32_e32 v65, v79, v93
	v_add_f32_e32 v64, v69, v64
	v_exp_f32_e32 v73, v65
	v_add_f32_e32 v64, v70, v64
	v_add_f32_e32 v64, v71, v64
	v_sub_f32_e32 v94, v219, v81
	v_add_f32_e32 v64, v72, v64
	v_add_f32_e32 v65, v73, v64
	v_exp_f32_e32 v64, v94
	v_mov_b32_e32 v74, v65
	v_mov_b32_e32 v75, v65
	s_nop 1
	v_permlane32_swap_b32_e32 v74, v75
	v_cmp_neq_f32_e32 vcc, v81, v219
	s_cbranch_vccz .LBB0_860
	v_pk_mul_f32 v[30:31], v[30:31], v[64:65] op_sel_hi:[1,0]
	v_pk_mul_f32 v[28:29], v[28:29], v[64:65] op_sel_hi:[1,0]
	v_pk_mul_f32 v[26:27], v[26:27], v[64:65] op_sel_hi:[1,0]
	v_pk_mul_f32 v[24:25], v[24:25], v[64:65] op_sel_hi:[1,0]
	v_pk_mul_f32 v[22:23], v[22:23], v[64:65] op_sel_hi:[1,0]
	v_pk_mul_f32 v[20:21], v[20:21], v[64:65] op_sel_hi:[1,0]
	v_pk_mul_f32 v[18:19], v[18:19], v[64:65] op_sel_hi:[1,0]
	v_pk_mul_f32 v[16:17], v[16:17], v[64:65] op_sel_hi:[1,0]
	v_pk_mul_f32 v[14:15], v[14:15], v[64:65] op_sel_hi:[1,0]
	v_pk_mul_f32 v[12:13], v[12:13], v[64:65] op_sel_hi:[1,0]
	v_pk_mul_f32 v[10:11], v[10:11], v[64:65] op_sel_hi:[1,0]
	v_pk_mul_f32 v[8:9], v[8:9], v[64:65] op_sel_hi:[1,0]
	v_pk_mul_f32 v[6:7], v[6:7], v[64:65] op_sel_hi:[1,0]
	v_pk_mul_f32 v[4:5], v[4:5], v[64:65] op_sel_hi:[1,0]
	v_pk_mul_f32 v[2:3], v[2:3], v[64:65] op_sel_hi:[1,0]
	v_pk_mul_f32 v[0:1], v[0:1], v[64:65] op_sel_hi:[1,0]

; #define LAS __attribute__((address_space(3)))
; DI float ex2(float x) { return __builtin_amdgcn_exp2f(x); }
; template <int MM> DI void smax_step_nb(const f32x16& s, unsigned vm, float& m, float& l, f32x16 (&o)[2], bf16x8 (&pf)[2], int lane) {
;     float mx = -1e30f;
; #pragma unroll
;     for (int i = 0; i < 16; ++i) mx = fmaxf(mx, s[i]);
;     if (MM == 1) mx = vm ? mx : -1e30f;
;     mx = fmaxf(mx, shx32(mx, lane));
;     const float mn = (mx > m + 8.0f) ? mx : m;
;     float mref = fmaxf(mn, -1e29f);
;     if (MM == 1) mref = vm ? mref : 3e38f;
;     const float alpha = ex2(m - mn);
;     float p[16], rs = 0.f;
; #pragma unroll
;     for (int i = 0; i < 16; ++i) { p[i] = ex2(s[i] - mref); rs += p[i]; }
;     rs += shx32(rs, lane);
;     l = l * alpha + rs;
;     if (__builtin_amdgcn_ballot_w64(mn != m) != 0ull) {
; #pragma unroll
;         for (int i = 0; i < 16; ++i) { o[0][i] *= alpha; o[1][i] *= alpha; }
;     }
;     m = mn;
;     pack_p(p, pf);
; }
; template <int MM> DI void tile128_pipe(LAS const char* K0, LAS const char* V0, LAS const char* K1, LAS const char* V1, const bf16x8 (&qf)[4], unsigned vm0, unsigned vm1,
;                                        float& m, float& l, f32x16 (&o)[2], int r, int h, int lane) {
;     f32x16 sa = qk_rows<0, 4>(K0, 0, qf, r, h), sb = qk_rows<0, 4>(K0, 32, qf, r, h);
;     bf16x8 pfa[2], pfb[2];
;     smax_step_nb<MM>(sa, vm0, m, l, o, pfa, lane);
;     sa = qk_rows<0, 4>(K1, 0, qf, r, h);
;     pv_rows(o, V0, 0, pfa, lane);
.LBB0_861:
	s_cbranch_execz .LBB0_871
	s_waitcnt lgkmcnt(7)
	v_mfma_f32_32x32x16_bf16 v[48:63], v[140:143], v[112:115], 0
	s_waitcnt lgkmcnt(6)
	v_mfma_f32_32x32x16_bf16 v[48:63], v[136:139], v[116:119], v[48:63]
	s_waitcnt lgkmcnt(5)
	v_mfma_f32_32x32x16_bf16 v[48:63], v[132:135], v[120:123], v[48:63]
	s_waitcnt lgkmcnt(4)
	v_mfma_f32_32x32x16_bf16 v[48:63], v[128:131], v[124:127], v[48:63]
	s_waitcnt lgkmcnt(3)
	v_mfma_f32_32x32x16_bf16 v[32:47], v[144:147], v[112:115], 0
	s_nop 9
	v_max3_f32 v64, v48, s15, v49
	v_max3_f32 v64, v64, v50, v51
	v_max3_f32 v64, v64, v52, v53
	v_max3_f32 v64, v64, v54, v55
	v_max3_f32 v64, v64, v56, v57
	v_max3_f32 v64, v64, v58, v59
	v_max3_f32 v64, v64, v60, v61
	v_max3_f32 v64, v64, v62, v63
	v_mov_b32_e32 v65, v64
	v_mov_b32_e32 v66, v64
	s_nop 1
	v_permlane32_swap_b32_e32 v65, v66
	v_max_f32_e32 v64, v65, v66
	v_cmp_gt_f32_e32 vcc, v64, v193
	s_waitcnt lgkmcnt(2)
	v_mfma_f32_32x32x16_bf16 v[32:47], v[148:151], v[116:119], v[32:47]
	v_cndmask_b32_e32 v73, v191, v64, vcc
	v_max_f32_e32 v64, 0xefa18f08, v73
	v_sub_f32_e32 v48, v48, v64
	v_exp_f32_e32 v48, v48
	v_sub_f32_e32 v49, v49, v64
	v_exp_f32_e32 v49, v49
	v_sub_f32_e32 v50, v50, v64
	v_exp_f32_e32 v50, v50
	v_sub_f32_e32 v51, v51, v64
	v_exp_f32_e32 v51, v51
	v_sub_f32_e32 v52, v52, v64
	v_exp_f32_e32 v52, v52
	v_sub_f32_e32 v53, v53, v64
	v_add_f32_e32 v65, v49, v48
	v_exp_f32_e32 v53, v53
	v_sub_f32_e32 v54, v54, v64
	s_waitcnt lgkmcnt(1)
	v_mfma_f32_32x32x16_bf16 v[32:47], v[152:155], v[120:123], v[32:47]
	v_add_f32_e32 v65, v50, v65
	v_exp_f32_e32 v54, v54
	v_sub_f32_e32 v55, v55, v64
	v_add_f32_e32 v65, v51, v65
	v_exp_f32_e32 v55, v55
	v_sub_f32_e32 v56, v56, v64
	v_add_f32_e32 v65, v52, v65
	v_exp_f32_e32 v56, v56
	v_sub_f32_e32 v57, v57, v64
	v_add_f32_e32 v65, v53, v65
	v_exp_f32_e32 v57, v57
	v_sub_f32_e32 v58, v58, v64
	v_add_f32_e32 v65, v54, v65
	v_exp_f32_e32 v58, v58
	v_sub_f32_e32 v59, v59, v64
	v_add_f32_e32 v65, v55, v65
	v_exp_f32_e32 v59, v59
	v_sub_f32_e32 v60, v60, v64
	v_add_f32_e32 v65, v56, v65
	v_exp_f32_e32 v60, v60
	v_sub_f32_e32 v61, v61, v64
	v_add_f32_e32 v65, v57, v65
	v_exp_f32_e32 v61, v61
	v_sub_f32_e32 v62, v62, v64
	s_waitcnt lgkmcnt(0)
	v_mfma_f32_32x32x16_bf16 v[32:47], v[156:159], v[124:127], v[32:47]
	v_add_f32_e32 v65, v58, v65
	v_exp_f32_e32 v62, v62
	v_sub_f32_e32 v63, v63, v64
	v_add_f32_e32 v65, v59, v65
	v_exp_f32_e32 v63, v63
	v_add_f32_e32 v65, v60, v65
	v_sub_f32_e32 v66, v191, v73
	v_add_f32_e32 v65, v61, v65
	v_add_f32_e32 v65, v62, v65
	v_exp_f32_e32 v64, v66
	v_add_f32_e32 v65, v63, v65
	v_mov_b32_e32 v67, v65
	v_mov_b32_e32 v68, v65
	s_nop 1
	v_permlane32_swap_b32_e32 v67, v68
	v_cmp_neq_f32_e32 vcc, v73, v191
	s_cbranch_vccz .LBB0_864
	v_pk_mul_f32 v[30:31], v[30:31], v[64:65] op_sel_hi:[1,0]
	v_pk_mul_f32 v[28:29], v[28:29], v[64:65] op_sel_hi:[1,0]
	v_pk_mul_f32 v[26:27], v[26:27], v[64:65] op_sel_hi:[1,0]
	v_pk_mul_f32 v[24:25], v[24:25], v[64:65] op_sel_hi:[1,0]
	v_pk_mul_f32 v[22:23], v[22:23], v[64:65] op_sel_hi:[1,0]
	v_pk_mul_f32 v[20:21], v[20:21], v[64:65] op_sel_hi:[1,0]
	v_pk_mul_f32 v[18:19], v[18:19], v[64:65] op_sel_hi:[1,0]
	v_pk_mul_f32 v[16:17], v[16:17], v[64:65] op_sel_hi:[1,0]
	v_pk_mul_f32 v[14:15], v[14:15], v[64:65] op_sel_hi:[1,0]
	v_pk_mul_f32 v[12:13], v[12:13], v[64:65] op_sel_hi:[1,0]
	v_pk_mul_f32 v[10:11], v[10:11], v[64:65] op_sel_hi:[1,0]
	v_pk_mul_f32 v[8:9], v[8:9], v[64:65] op_sel_hi:[1,0]
	v_pk_mul_f32 v[6:7], v[6:7], v[64:65] op_sel_hi:[1,0]
	v_pk_mul_f32 v[4:5], v[4:5], v[64:65] op_sel_hi:[1,0]
	v_pk_mul_f32 v[2:3], v[2:3], v[64:65] op_sel_hi:[1,0]
	v_pk_mul_f32 v[0:1], v[0:1], v[64:65] op_sel_hi:[1,0]
.LBB0_864:
	v_cvt_pk_bf16_f32 v74, v48, v49
	v_cvt_pk_bf16_f32 v75, v50, v51
	ds_read_b128 v[48:51], v192 offset:18432
	ds_read_b128 v[82:85], v192 offset:18464
	ds_read_b128 v[86:89], v192 offset:18496
	ds_read_b128 v[90:93], v192 offset:18528
	v_cvt_pk_bf16_f32 v76, v52, v53
	v_cvt_pk_bf16_f32 v77, v54, v55
	v_cvt_pk_bf16_f32 v78, v56, v57
	v_cvt_pk_bf16_f32 v79, v58, v59
	v_cvt_pk_bf16_f32 v80, v60, v61
	v_cvt_pk_bf16_f32 v81, v62, v63
	s_setprio 1
	s_waitcnt lgkmcnt(3)
	v_mfma_f32_32x32x16_bf16 v[48:63], v[48:51], v[112:115], 0
	s_waitcnt lgkmcnt(2)
	v_mfma_f32_32x32x16_bf16 v[48:63], v[82:85], v[116:119], v[48:63]
	s_waitcnt lgkmcnt(1)
	v_mfma_f32_32x32x16_bf16 v[48:63], v[86:89], v[120:123], v[48:63]
	s_waitcnt lgkmcnt(0)
	v_mfma_f32_32x32x16_bf16 v[48:63], v[90:93], v[124:127], v[48:63]
	s_setprio 0
	v_add3_u32 v66, s10, v186, v187
	v_add_u32_e32 v69, v66, v188
	ds_read_b64_tr_b16 v[82:83], v69 offset:9216
	ds_read_b64_tr_b16 v[84:85], v69 offset:10368
	ds_read_b64_tr_b16 v[88:89], v69 offset:10432
	ds_read_b64_tr_b16 v[86:87], v69 offset:9280
	ds_read_b64_tr_b16 v[90:91], v69 offset:11520
	ds_read_b64_tr_b16 v[92:93], v69 offset:12672
	ds_read_b64_tr_b16 v[130:131], v69 offset:12736
	ds_read_b64_tr_b16 v[128:129], v69 offset:11584
	s_setprio 1
	s_waitcnt lgkmcnt(6)
	v_mfma_f32_32x32x16_bf16 v[0:15], v[82:85], v[74:77], v[0:15]
	s_waitcnt lgkmcnt(4)
	v_mfma_f32_32x32x16_bf16 v[16:31], v[86:89], v[74:77], v[16:31]
	s_waitcnt lgkmcnt(2)
	v_mfma_f32_32x32x16_bf16 v[0:15], v[90:93], v[78:81], v[0:15]
	s_waitcnt lgkmcnt(0)
; DI float ex2(float x) { return __builtin_amdgcn_exp2f(x); }
; template <int MM> DI void smax_step_nb(const f32x16& s, unsigned vm, float& m, float& l, f32x16 (&o)[2], bf16x8 (&pf)[2], int lane) {
;     float mx = -1e30f;
; #pragma unroll
;     for (int i = 0; i < 16; ++i) mx = fmaxf(mx, s[i]);
;     if (MM == 1) mx = vm ? mx : -1e30f;
;     mx = fmaxf(mx, shx32(mx, lane));
;     const float mn = (mx > m + 8.0f) ? mx : m;
;     float mref = fmaxf(mn, -1e29f);
;     if (MM == 1) mref = vm ? mref : 3e38f;
;     const float alpha = ex2(m - mn);
;     float p[16], rs = 0.f;
; #pragma unroll
;     for (int i = 0; i < 16; ++i) { p[i] = ex2(s[i] - mref); rs += p[i]; }
;     rs += shx32(rs, lane);
;     l = l * alpha + rs;
;     if (__builtin_amdgcn_ballot_w64(mn != m) != 0ull) {
; #pragma unroll
;         for (int i = 0; i < 16; ++i) { o[0][i] *= alpha; o[1][i] *= alpha; }
;     }
;     m = mn;
;     pack_p(p, pf);
; }
; template <int MM> DI void tile128_pipe(LAS const char* K0, LAS const char* V0, LAS const char* K1, LAS const char* V1, const bf16x8 (&qf)[4], unsigned vm0, unsigned vm1,
;                                        float& m, float& l, f32x16 (&o)[2], int r, int h, int lane) {
;     ...
;     smax_step_nb<MM>(sb, vm0, m, l, o, pfb, lane);
;     sb = qk_rows<0, 4>(K1, 32, qf, r, h);
;     pv_rows(o, V0, 32, pfb, lane);
	v_mfma_f32_32x32x16_bf16 v[16:31], v[128:131], v[78:81], v[16:31]
	s_setprio 0
	v_max3_f32 v66, v32, s15, v33
	v_max3_f32 v66, v66, v34, v35
	v_max3_f32 v66, v66, v36, v37
	v_max3_f32 v66, v66, v38, v39
	v_max3_f32 v66, v66, v40, v41
	v_max3_f32 v66, v66, v42, v43
	v_max3_f32 v66, v66, v44, v45
	v_max3_f32 v66, v66, v46, v47
	v_mov_b32_e32 v70, v66
	v_mov_b32_e32 v71, v66
	s_nop 1
	v_permlane32_swap_b32_e32 v70, v71
	v_max_f32_e32 v66, v70, v71
	v_add_f32_e32 v70, 0x41000000, v73
	v_cmp_gt_f32_e32 vcc, v66, v70
	s_nop 1
	v_cndmask_b32_e32 v74, v73, v66, vcc
	v_max_f32_e32 v66, 0xefa18f08, v74
	v_sub_f32_e32 v32, v32, v66
	v_exp_f32_e32 v32, v32
	v_sub_f32_e32 v33, v33, v66
	v_exp_f32_e32 v33, v33
	v_sub_f32_e32 v34, v34, v66
	v_exp_f32_e32 v34, v34
	v_sub_f32_e32 v35, v35, v66
	v_exp_f32_e32 v35, v35
	v_sub_f32_e32 v36, v36, v66
	v_exp_f32_e32 v36, v36
	v_sub_f32_e32 v37, v37, v66
	v_add_f32_e32 v70, v33, v32
	v_exp_f32_e32 v37, v37
	v_sub_f32_e32 v38, v38, v66
	v_add_f32_e32 v70, v34, v70
	v_exp_f32_e32 v38, v38
	v_sub_f32_e32 v39, v39, v66
	v_add_f32_e32 v70, v35, v70
	v_exp_f32_e32 v39, v39
	v_sub_f32_e32 v40, v40, v66
	v_add_f32_e32 v70, v36, v70
	v_exp_f32_e32 v40, v40
	v_sub_f32_e32 v41, v41, v66
	v_add_f32_e32 v70, v37, v70
	v_exp_f32_e32 v41, v41
	v_sub_f32_e32 v42, v42, v66
	v_add_f32_e32 v70, v38, v70
	v_exp_f32_e32 v42, v42
	v_sub_f32_e32 v43, v43, v66
	v_add_f32_e32 v70, v39, v70
	v_exp_f32_e32 v43, v43
	v_sub_f32_e32 v44, v44, v66
	v_add_f32_e32 v70, v40, v70
	v_exp_f32_e32 v44, v44
	v_sub_f32_e32 v45, v45, v66
	v_add_f32_e32 v70, v41, v70
	v_exp_f32_e32 v45, v45
	v_sub_f32_e32 v46, v46, v66
	v_add_f32_e32 v70, v42, v70
	v_exp_f32_e32 v46, v46
	v_sub_f32_e32 v47, v47, v66
	v_add_f32_e32 v70, v43, v70
	v_exp_f32_e32 v47, v47
	v_add_f32_e32 v66, v44, v70
	v_add_f32_e32 v66, v45, v66
	v_sub_f32_e32 v71, v73, v74
	v_add_f32_e32 v66, v46, v66
	v_add_f32_e32 v70, v47, v66
	v_exp_f32_e32 v66, v71
	v_mov_b32_e32 v71, v70
	v_mov_b32_e32 v72, v70
	s_nop 1
	v_permlane32_swap_b32_e32 v71, v72
	v_cmp_neq_f32_e32 vcc, v74, v73
	s_cbranch_vccz .LBB0_866
	v_pk_mul_f32 v[30:31], v[30:31], v[66:67] op_sel_hi:[1,0]
	v_pk_mul_f32 v[28:29], v[28:29], v[66:67] op_sel_hi:[1,0]
	v_pk_mul_f32 v[26:27], v[26:27], v[66:67] op_sel_hi:[1,0]
	v_pk_mul_f32 v[24:25], v[24:25], v[66:67] op_sel_hi:[1,0]
	v_pk_mul_f32 v[22:23], v[22:23], v[66:67] op_sel_hi:[1,0]
	v_pk_mul_f32 v[20:21], v[20:21], v[66:67] op_sel_hi:[1,0]
	v_pk_mul_f32 v[18:19], v[18:19], v[66:67] op_sel_hi:[1,0]
	v_pk_mul_f32 v[16:17], v[16:17], v[66:67] op_sel_hi:[1,0]
	v_pk_mul_f32 v[14:15], v[14:15], v[66:67] op_sel_hi:[1,0]
	v_pk_mul_f32 v[12:13], v[12:13], v[66:67] op_sel_hi:[1,0]
	v_pk_mul_f32 v[10:11], v[10:11], v[66:67] op_sel_hi:[1,0]
	v_pk_mul_f32 v[8:9], v[8:9], v[66:67] op_sel_hi:[1,0]
	v_pk_mul_f32 v[6:7], v[6:7], v[66:67] op_sel_hi:[1,0]
	v_pk_mul_f32 v[4:5], v[4:5], v[66:67] op_sel_hi:[1,0]
	v_pk_mul_f32 v[2:3], v[2:3], v[66:67] op_sel_hi:[1,0]
	v_pk_mul_f32 v[0:1], v[0:1], v[66:67] op_sel_hi:[1,0]
; #define LAS __attribute__((address_space(3)))
; #define MFMA32(a, b, c) __builtin_amdgcn_mfma_f32_32x32x16_bf16((a), (b), (c), 0, 0, 0)
; DI s16x4 vtr(LAS const char* p) { return __builtin_bit_cast(s16x4, __builtin_amdgcn_ds_read_tr16_b64_v4i16((LAS v4i16_t*)p)); }
; DI void pv_rows(f32x16 (&o)[2], LAS const char* Vl, int row0, const bf16x8 (&pf)[2], int lane) {
;     const int h = lane >> 5, i = lane & 15, grp = (lane >> 4) & 1;
;     LAS const char* base = Vl + (row0 + 4 * h + (i >> 2)) * KP + grp * 32 + (i & 3) * 8;
;     bf16x8 vf[2][2];
; #pragma unroll
;     for (int dt = 0; dt < 2; ++dt)
; #pragma unroll
;         for (int s2 = 0; s2 < 2; ++s2) {
;             const s16x4 lo = vtr(base + (16 * s2) * KP + dt * 64), hi = vtr(base + (16 * s2 + 8) * KP + dt * 64);
;             vf[dt][s2] = (bf16x8){lo[0], lo[1], lo[2], lo[3], hi[0], hi[1], hi[2], hi[3]};
;         }
;     __builtin_amdgcn_s_setprio(1);
; #pragma unroll
;     for (int s2 = 0; s2 < 2; ++s2)
; #pragma unroll
;         for (int dt = 0; dt < 2; ++dt) o[dt] = MFMA32(vf[dt][s2], pf[s2], o[dt]);
;     __builtin_amdgcn_s_setprio(0);
; template <int MM> DI void smax_step_nb(const f32x16& s, unsigned vm, float& m, float& l, f32x16 (&o)[2], bf16x8 (&pf)[2], int lane) {
;     float mx = -1e30f;
; #pragma unroll
;     for (int i = 0; i < 16; ++i) mx = fmaxf(mx, s[i]);
;     if (MM == 1) mx = vm ? mx : -1e30f;
;     mx = fmaxf(mx, shx32(mx, lane));
;     const float mn = (mx > m + 8.0f) ? mx : m;
;     float mref = fmaxf(mn, -1e29f);
;     if (MM == 1) mref = vm ? mref : 3e38f;
;     const float alpha = ex2(m - mn);
;     float p[16], rs = 0.f;
; #pragma unroll
;     for (int i = 0; i < 16; ++i) { p[i] = ex2(s[i] - mref); rs += p[i]; }
;     rs += shx32(rs, lane);
;     l = l * alpha + rs;
;     if (__builtin_amdgcn_ballot_w64(mn != m) != 0ull) {
; #pragma unroll
;         for (int i = 0; i < 16; ++i) { o[0][i] *= alpha; o[1][i] *= alpha; }
;     }
;     m = mn;
;     pack_p(p, pf);
; }
; template <int MM> DI void tile128_pipe(LAS const char* K0, LAS const char* V0, LAS const char* K1, LAS const char* V1, const bf16x8 (&qf)[4], unsigned vm0, unsigned vm1,
;                                        float& m, float& l, f32x16 (&o)[2], int r, int h, int lane) {
;     ...
;     sb = qk_rows<0, 4>(K1, 32, qf, r, h);
;     pv_rows(o, V0, 32, pfb, lane);
;     smax_step_nb<MM>(sa, vm1, m, l, o, pfa, lane);
.LBB0_866:
	v_cvt_pk_bf16_f32 v76, v32, v33
	v_cvt_pk_bf16_f32 v77, v34, v35
	ds_read_b128 v[32:35], v192 offset:23040
	ds_read_b128 v[84:87], v192 offset:23072
	ds_read_b128 v[88:91], v192 offset:23104
	ds_read_b128 v[92:95], v192 offset:23136
	v_cvt_pk_bf16_f32 v78, v36, v37
	v_cvt_pk_bf16_f32 v79, v38, v39
	v_cvt_pk_bf16_f32 v80, v40, v41
	v_cvt_pk_bf16_f32 v81, v42, v43
	v_cvt_pk_bf16_f32 v82, v44, v45
	v_cvt_pk_bf16_f32 v83, v46, v47
	s_setprio 1
	s_waitcnt lgkmcnt(3)
	v_mfma_f32_32x32x16_bf16 v[32:47], v[32:35], v[112:115], 0
	s_waitcnt lgkmcnt(2)
	v_mfma_f32_32x32x16_bf16 v[32:47], v[84:87], v[116:119], v[32:47]
	s_waitcnt lgkmcnt(1)
	v_mfma_f32_32x32x16_bf16 v[32:47], v[88:91], v[120:123], v[32:47]
	s_waitcnt lgkmcnt(0)
	v_mfma_f32_32x32x16_bf16 v[32:47], v[92:95], v[124:127], v[32:47]
	s_setprio 0
	ds_read_b64_tr_b16 v[84:85], v69 offset:13824
	ds_read_b64_tr_b16 v[86:87], v69 offset:14976
	ds_read_b64_tr_b16 v[90:91], v69 offset:15040
	ds_read_b64_tr_b16 v[88:89], v69 offset:13888
	ds_read_b64_tr_b16 v[92:93], v69 offset:16128
	ds_read_b64_tr_b16 v[94:95], v69 offset:17280
	ds_read_b64_tr_b16 v[130:131], v69 offset:17344
	ds_read_b64_tr_b16 v[128:129], v69 offset:16192
	s_setprio 1
	s_waitcnt lgkmcnt(6)
	v_mfma_f32_32x32x16_bf16 v[0:15], v[84:87], v[76:79], v[0:15]
	s_waitcnt lgkmcnt(4)
	v_mfma_f32_32x32x16_bf16 v[16:31], v[88:91], v[76:79], v[16:31]
	s_waitcnt lgkmcnt(2)
	v_mfma_f32_32x32x16_bf16 v[0:15], v[92:95], v[80:83], v[0:15]
	s_waitcnt lgkmcnt(0)
	v_mfma_f32_32x32x16_bf16 v[16:31], v[128:131], v[80:83], v[16:31]
	s_setprio 0
	v_max3_f32 v73, v48, s15, v49
	v_max3_f32 v73, v73, v50, v51
	v_max3_f32 v73, v73, v52, v53
	v_max3_f32 v73, v73, v54, v55
	v_max3_f32 v73, v73, v56, v57
	v_max3_f32 v73, v73, v58, v59
	v_max3_f32 v73, v73, v60, v61
	v_max3_f32 v73, v73, v62, v63
	v_mov_b32_e32 v75, v73
	v_mov_b32_e32 v76, v73
	s_nop 1
	v_permlane32_swap_b32_e32 v75, v76
	v_max_f32_e32 v73, v75, v76
	v_add_f32_e32 v75, 0x41000000, v74
	v_cmp_gt_f32_e32 vcc, v73, v75
	s_nop 1
	v_cndmask_b32_e32 v73, v74, v73, vcc
	v_max_f32_e32 v79, 0xefa18f08, v73
	v_sub_f32_e32 v48, v48, v79
	v_exp_f32_e32 v75, v48
	v_sub_f32_e32 v48, v49, v79
	v_exp_f32_e32 v76, v48
	v_sub_f32_e32 v48, v50, v79
	v_exp_f32_e32 v77, v48
	v_sub_f32_e32 v48, v51, v79
	v_exp_f32_e32 v78, v48
	v_sub_f32_e32 v49, v52, v79
	v_exp_f32_e32 v52, v49
	v_sub_f32_e32 v49, v53, v79
	v_add_f32_e32 v48, v76, v75
	v_exp_f32_e32 v53, v49
	v_sub_f32_e32 v49, v54, v79
	v_add_f32_e32 v48, v77, v48
	v_exp_f32_e32 v54, v49
	v_sub_f32_e32 v49, v55, v79
	v_add_f32_e32 v48, v78, v48
	v_exp_f32_e32 v55, v49
	v_sub_f32_e32 v49, v56, v79
	v_add_f32_e32 v48, v52, v48
	v_exp_f32_e32 v56, v49
	v_sub_f32_e32 v49, v57, v79
	v_add_f32_e32 v48, v53, v48
	v_exp_f32_e32 v57, v49
	v_sub_f32_e32 v49, v58, v79
	v_add_f32_e32 v48, v54, v48
	v_exp_f32_e32 v58, v49
	v_sub_f32_e32 v49, v59, v79
	v_add_f32_e32 v48, v55, v48
	v_exp_f32_e32 v59, v49
	v_sub_f32_e32 v49, v60, v79
	v_add_f32_e32 v48, v56, v48
	v_exp_f32_e32 v60, v49
	v_sub_f32_e32 v49, v61, v79
	v_add_f32_e32 v48, v57, v48
	v_exp_f32_e32 v61, v49
	v_sub_f32_e32 v49, v62, v79
	v_add_f32_e32 v48, v58, v48
	v_exp_f32_e32 v62, v49
	v_sub_f32_e32 v49, v63, v79
	v_add_f32_e32 v48, v59, v48
	v_exp_f32_e32 v63, v49
	v_add_f32_e32 v48, v60, v48
	v_add_f32_e32 v48, v61, v48
	v_sub_f32_e32 v80, v74, v73
	v_add_f32_e32 v48, v62, v48
	v_add_f32_e32 v49, v63, v48
	v_exp_f32_e32 v48, v80
	v_mov_b32_e32 v50, v49
	v_mov_b32_e32 v51, v49
	s_nop 1
	v_permlane32_swap_b32_e32 v50, v51
	v_cmp_neq_f32_e32 vcc, v73, v74
	s_cbranch_vccz .LBB0_868
	v_pk_mul_f32 v[30:31], v[30:31], v[48:49] op_sel_hi:[1,0]
	v_pk_mul_f32 v[28:29], v[28:29], v[48:49] op_sel_hi:[1,0]
	v_pk_mul_f32 v[26:27], v[26:27], v[48:49] op_sel_hi:[1,0]
	v_pk_mul_f32 v[24:25], v[24:25], v[48:49] op_sel_hi:[1,0]
	v_pk_mul_f32 v[22:23], v[22:23], v[48:49] op_sel_hi:[1,0]
	v_pk_mul_f32 v[20:21], v[20:21], v[48:49] op_sel_hi:[1,0]
	v_pk_mul_f32 v[18:19], v[18:19], v[48:49] op_sel_hi:[1,0]
	v_pk_mul_f32 v[16:17], v[16:17], v[48:49] op_sel_hi:[1,0]
	v_pk_mul_f32 v[14:15], v[14:15], v[48:49] op_sel_hi:[1,0]
	v_pk_mul_f32 v[12:13], v[12:13], v[48:49] op_sel_hi:[1,0]
	v_pk_mul_f32 v[10:11], v[10:11], v[48:49] op_sel_hi:[1,0]
	v_pk_mul_f32 v[8:9], v[8:9], v[48:49] op_sel_hi:[1,0]
	v_pk_mul_f32 v[6:7], v[6:7], v[48:49] op_sel_hi:[1,0]
	v_pk_mul_f32 v[4:5], v[4:5], v[48:49] op_sel_hi:[1,0]
	v_pk_mul_f32 v[2:3], v[2:3], v[48:49] op_sel_hi:[1,0]
	v_pk_mul_f32 v[0:1], v[0:1], v[48:49] op_sel_hi:[1,0]

; #define LAS __attribute__((address_space(3)))
; DI float ex2(float x) { return __builtin_amdgcn_exp2f(x); }
; template <int MM> DI void smax_step_nb(const f32x16& s, unsigned vm, float& m, float& l, f32x16 (&o)[2], bf16x8 (&pf)[2], int lane) {
;     float mx = -1e30f;
; #pragma unroll
;     for (int i = 0; i < 16; ++i) mx = fmaxf(mx, s[i]);
;     if (MM == 1) mx = vm ? mx : -1e30f;
;     mx = fmaxf(mx, shx32(mx, lane));
;     const float mn = (mx > m + 8.0f) ? mx : m;
;     float mref = fmaxf(mn, -1e29f);
;     if (MM == 1) mref = vm ? mref : 3e38f;
;     const float alpha = ex2(m - mn);
;     float p[16], rs = 0.f;
; #pragma unroll
;     for (int i = 0; i < 16; ++i) { p[i] = ex2(s[i] - mref); rs += p[i]; }
;     rs += shx32(rs, lane);
;     l = l * alpha + rs;
;     if (__builtin_amdgcn_ballot_w64(mn != m) != 0ull) {
; #pragma unroll
;         for (int i = 0; i < 16; ++i) { o[0][i] *= alpha; o[1][i] *= alpha; }
;     }
;     m = mn;
;     pack_p(p, pf);
; }
; template <int MM> DI void tile64_pipe(LAS const char* Kl, LAS const char* Vl, const bf16x8 (&qf)[4], unsigned vm, float& m, float& l, f32x16 (&o)[2], int r, int h, int lane) {
;     const f32x16 sa = qk_rows<0, 4>(Kl, 0, qf, r, h), sb = qk_rows<0, 4>(Kl, 32, qf, r, h);
;     bf16x8 pfa[2], pfb[2];
;     smax_step_nb<MM>(sa, vm, m, l, o, pfa, lane);
;     pv_rows(o, Vl, 0, pfa, lane);
.LBB0_883:
	s_mov_b64 s[52:53], 0
	s_andn2_b64 vcc, exec, s[56:57]
	v_add3_u32 v82, s11, v184, v160
	v_mov_b32_e32 v65, v190
	v_mov_b32_e32 v81, v191
	s_cbranch_vccnz .LBB0_889
	ds_read_b128 v[32:35], v82
	ds_read_b128 v[48:51], v82 offset:32
	ds_read_b128 v[52:55], v82 offset:64
	ds_read_b128 v[56:59], v82 offset:96
	s_setprio 1
	s_waitcnt lgkmcnt(3)
	v_mfma_f32_32x32x16_bf16 v[32:47], v[32:35], v[112:115], 0
	s_waitcnt lgkmcnt(2)
	v_mfma_f32_32x32x16_bf16 v[32:47], v[48:51], v[116:119], v[32:47]
	s_waitcnt lgkmcnt(1)
	v_mfma_f32_32x32x16_bf16 v[32:47], v[52:55], v[120:123], v[32:47]
	s_waitcnt lgkmcnt(0)
	v_mfma_f32_32x32x16_bf16 v[32:47], v[56:59], v[124:127], v[32:47]
	s_setprio 0
	ds_read_b128 v[48:51], v82 offset:4608
	ds_read_b128 v[52:55], v82 offset:4640
	ds_read_b128 v[56:59], v82 offset:4672
	ds_read_b128 v[60:63], v82 offset:4704
	s_setprio 1
	s_waitcnt lgkmcnt(3)
	v_mfma_f32_32x32x16_bf16 v[64:79], v[48:51], v[112:115], 0
	s_waitcnt lgkmcnt(2)
	v_mfma_f32_32x32x16_bf16 v[64:79], v[52:55], v[116:119], v[64:79]
	s_waitcnt lgkmcnt(1)
	v_mfma_f32_32x32x16_bf16 v[64:79], v[56:59], v[120:123], v[64:79]
	s_waitcnt lgkmcnt(0)
	v_mfma_f32_32x32x16_bf16 v[64:79], v[60:63], v[124:127], v[64:79]
	s_setprio 0
	v_max3_f32 v48, v32, s15, v33
	v_max3_f32 v48, v48, v34, v35
	v_max3_f32 v48, v48, v36, v37
	v_max3_f32 v48, v48, v38, v39
	v_max3_f32 v48, v48, v40, v41
	v_max3_f32 v48, v48, v42, v43
	v_max3_f32 v48, v48, v44, v45
	v_max3_f32 v48, v48, v46, v47
	v_cndmask_b32_e64 v48, v208, v48, s[38:39]
	v_mov_b32_e32 v49, v48
	v_mov_b32_e32 v50, v48
	s_nop 1
	v_permlane32_swap_b32_e32 v49, v50
	v_max_f32_e32 v48, v49, v50
	v_add_f32_e32 v49, 0x41000000, v191
	v_cmp_gt_f32_e32 vcc, v48, v49
	s_nop 1
	v_cndmask_b32_e32 v87, v191, v48, vcc
	v_max_f32_e32 v48, 0xefa18f08, v87
	v_cndmask_b32_e64 v48, v209, v48, s[38:39]
	v_sub_f32_e32 v32, v32, v48
	v_exp_f32_e32 v81, v32
	v_sub_f32_e32 v32, v33, v48
	v_exp_f32_e32 v86, v32
	v_sub_f32_e32 v32, v34, v48
	v_exp_f32_e32 v88, v32
	v_sub_f32_e32 v32, v35, v48
	v_exp_f32_e32 v89, v32
	v_sub_f32_e32 v33, v36, v48
	v_exp_f32_e32 v90, v33
	v_sub_f32_e32 v33, v37, v48
	v_add_f32_e32 v32, v86, v81
	v_exp_f32_e32 v91, v33
	v_sub_f32_e32 v33, v38, v48
	v_add_f32_e32 v32, v88, v32
	v_exp_f32_e32 v92, v33
	v_sub_f32_e32 v33, v39, v48
	v_add_f32_e32 v32, v89, v32
	v_exp_f32_e32 v93, v33
	v_sub_f32_e32 v33, v40, v48
	v_add_f32_e32 v32, v90, v32
	v_exp_f32_e32 v94, v33
	v_sub_f32_e32 v33, v41, v48
	v_add_f32_e32 v32, v91, v32
	v_exp_f32_e32 v95, v33
	v_sub_f32_e32 v33, v42, v48
	v_add_f32_e32 v32, v92, v32
	v_exp_f32_e32 v128, v33
	v_sub_f32_e32 v33, v43, v48
	v_add_f32_e32 v32, v93, v32
	v_exp_f32_e32 v129, v33
	v_sub_f32_e32 v33, v44, v48
	v_add_f32_e32 v32, v94, v32
	v_exp_f32_e32 v130, v33
	v_sub_f32_e32 v33, v45, v48
	v_add_f32_e32 v32, v95, v32
	v_exp_f32_e32 v131, v33
	v_sub_f32_e32 v33, v46, v48
	v_add_f32_e32 v32, v128, v32
	v_exp_f32_e32 v132, v33
	v_sub_f32_e32 v33, v47, v48
	v_add_f32_e32 v32, v129, v32
	v_exp_f32_e32 v133, v33
	v_add_f32_e32 v32, v130, v32
	v_sub_f32_e32 v49, v191, v87
	v_add_f32_e32 v32, v131, v32
	v_add_f32_e32 v32, v132, v32
	v_exp_f32_e32 v80, v49
	v_add_f32_e32 v83, v133, v32
	v_mov_b32_e32 v84, v83
	v_mov_b32_e32 v85, v83
	v_mov_b64_e32 v[62:63], v[30:31]
	s_nop 0
	v_permlane32_swap_b32_e32 v84, v85
	v_cmp_neq_f32_e32 vcc, v87, v191
	v_mov_b64_e32 v[60:61], v[28:29]
	v_mov_b64_e32 v[58:59], v[26:27]
	v_mov_b64_e32 v[56:57], v[24:25]
	v_mov_b64_e32 v[54:55], v[22:23]
	v_mov_b64_e32 v[52:53], v[20:21]
	v_mov_b64_e32 v[50:51], v[18:19]
	v_mov_b64_e32 v[48:49], v[16:17]
	v_mov_b64_e32 v[46:47], v[14:15]
	v_mov_b64_e32 v[44:45], v[12:13]
	v_mov_b64_e32 v[42:43], v[10:11]
	v_mov_b64_e32 v[40:41], v[8:9]
	v_mov_b64_e32 v[38:39], v[6:7]
	v_mov_b64_e32 v[36:37], v[4:5]
	v_mov_b64_e32 v[34:35], v[2:3]
	v_mov_b64_e32 v[32:33], v[0:1]
	s_cbranch_vccz .LBB0_886
	v_pk_mul_f32 v[62:63], v[30:31], v[80:81] op_sel_hi:[1,0]
	v_pk_mul_f32 v[60:61], v[28:29], v[80:81] op_sel_hi:[1,0]
	v_pk_mul_f32 v[58:59], v[26:27], v[80:81] op_sel_hi:[1,0]
	v_pk_mul_f32 v[56:57], v[24:25], v[80:81] op_sel_hi:[1,0]
	v_pk_mul_f32 v[54:55], v[22:23], v[80:81] op_sel_hi:[1,0]
	v_pk_mul_f32 v[52:53], v[20:21], v[80:81] op_sel_hi:[1,0]
	v_pk_mul_f32 v[50:51], v[18:19], v[80:81] op_sel_hi:[1,0]
	v_pk_mul_f32 v[48:49], v[16:17], v[80:81] op_sel_hi:[1,0]
	v_pk_mul_f32 v[46:47], v[14:15], v[80:81] op_sel_hi:[1,0]
	v_pk_mul_f32 v[44:45], v[12:13], v[80:81] op_sel_hi:[1,0]
	v_pk_mul_f32 v[42:43], v[10:11], v[80:81] op_sel_hi:[1,0]
	v_pk_mul_f32 v[40:41], v[8:9], v[80:81] op_sel_hi:[1,0]
	v_pk_mul_f32 v[38:39], v[6:7], v[80:81] op_sel_hi:[1,0]
	v_pk_mul_f32 v[36:37], v[4:5], v[80:81] op_sel_hi:[1,0]
	v_pk_mul_f32 v[34:35], v[2:3], v[80:81] op_sel_hi:[1,0]
	v_pk_mul_f32 v[32:33], v[0:1], v[80:81] op_sel_hi:[1,0]
; DI float ex2(float x) { return __builtin_amdgcn_exp2f(x); }
; template <int MM> DI void smax_step_nb(const f32x16& s, unsigned vm, float& m, float& l, f32x16 (&o)[2], bf16x8 (&pf)[2], int lane) {
;     float mx = -1e30f;
; #pragma unroll
;     for (int i = 0; i < 16; ++i) mx = fmaxf(mx, s[i]);
;     if (MM == 1) mx = vm ? mx : -1e30f;
;     mx = fmaxf(mx, shx32(mx, lane));
;     const float mn = (mx > m + 8.0f) ? mx : m;
;     float mref = fmaxf(mn, -1e29f);
;     if (MM == 1) mref = vm ? mref : 3e38f;
;     const float alpha = ex2(m - mn);
;     float p[16], rs = 0.f;
; #pragma unroll
;     for (int i = 0; i < 16; ++i) { p[i] = ex2(s[i] - mref); rs += p[i]; }
;     rs += shx32(rs, lane);
;     l = l * alpha + rs;
;     if (__builtin_amdgcn_ballot_w64(mn != m) != 0ull) {
; #pragma unroll
;         for (int i = 0; i < 16; ++i) { o[0][i] *= alpha; o[1][i] *= alpha; }
;     }
;     m = mn;
;     pack_p(p, pf);
; }
; template <int MM> DI void tile64_pipe(LAS const char* Kl, LAS const char* Vl, const bf16x8 (&qf)[4], unsigned vm, float& m, float& l, f32x16 (&o)[2], int r, int h, int lane) {
;     const f32x16 sa = qk_rows<0, 4>(Kl, 0, qf, r, h), sb = qk_rows<0, 4>(Kl, 32, qf, r, h);
;     bf16x8 pfa[2], pfb[2];
;     smax_step_nb<MM>(sa, vm, m, l, o, pfa, lane);
;     pv_rows(o, Vl, 0, pfa, lane);
;     smax_step_nb<MM>(sb, vm, m, l, o, pfb, lane);
;     pv_rows(o, Vl, 32, pfb, lane);
.LBB0_886:
	v_cvt_pk_bf16_f32 v134, v81, v86
	v_add3_u32 v81, s11, v186, v187
	v_add_u32_e32 v86, v81, v188
	v_cvt_pk_bf16_f32 v135, v88, v89
	v_cvt_pk_bf16_f32 v136, v90, v91
	v_cvt_pk_bf16_f32 v137, v92, v93
	v_cvt_pk_bf16_f32 v88, v94, v95
	v_cvt_pk_bf16_f32 v89, v128, v129
	v_cvt_pk_bf16_f32 v90, v130, v131
	ds_read_b64_tr_b16 v[92:93], v86 offset:9216
	ds_read_b64_tr_b16 v[94:95], v86 offset:10368
	ds_read_b64_tr_b16 v[128:129], v86 offset:11520
	ds_read_b64_tr_b16 v[130:131], v86 offset:12672
	ds_read_b64_tr_b16 v[138:139], v86 offset:9280
	ds_read_b64_tr_b16 v[140:141], v86 offset:10432
	ds_read_b64_tr_b16 v[142:143], v86 offset:11584
	ds_read_b64_tr_b16 v[144:145], v86 offset:12736
	v_cvt_pk_bf16_f32 v91, v132, v133
	s_setprio 1
	s_waitcnt lgkmcnt(6)
	v_mfma_f32_32x32x16_bf16 v[32:47], v[92:95], v[134:137], v[32:47]
	s_waitcnt lgkmcnt(2)
	v_mfma_f32_32x32x16_bf16 v[48:63], v[138:141], v[134:137], v[48:63]
	v_mfma_f32_32x32x16_bf16 v[32:47], v[128:131], v[88:91], v[32:47]
	s_waitcnt lgkmcnt(0)
	v_mfma_f32_32x32x16_bf16 v[48:63], v[142:145], v[88:91], v[48:63]
	s_setprio 0
	v_max3_f32 v81, v64, s15, v65
	v_max3_f32 v81, v81, v66, v67
	v_max3_f32 v81, v81, v68, v69
	v_max3_f32 v81, v81, v70, v71
	v_max3_f32 v81, v81, v72, v73
	v_max3_f32 v81, v81, v74, v75
	v_max3_f32 v81, v81, v76, v77
	v_max3_f32 v81, v81, v78, v79
	v_cndmask_b32_e64 v81, v208, v81, s[38:39]
	v_mov_b32_e32 v88, v81
	v_mov_b32_e32 v89, v81
	s_nop 1
	v_permlane32_swap_b32_e32 v88, v89
	v_max_f32_e32 v81, v88, v89
	v_add_f32_e32 v88, 0x41000000, v87
	v_cmp_gt_f32_e32 vcc, v81, v88
	s_nop 1
	v_cndmask_b32_e32 v81, v87, v81, vcc
	v_max_f32_e32 v88, 0xefa18f08, v81
	v_cndmask_b32_e64 v90, v209, v88, s[38:39]
	v_sub_f32_e32 v64, v64, v90
	v_exp_f32_e32 v88, v64
	v_sub_f32_e32 v64, v65, v90
	v_exp_f32_e32 v89, v64
	v_sub_f32_e32 v64, v66, v90
	v_exp_f32_e32 v66, v64
	v_sub_f32_e32 v64, v67, v90
	v_exp_f32_e32 v67, v64
	v_sub_f32_e32 v65, v68, v90
	v_exp_f32_e32 v68, v65
	v_sub_f32_e32 v65, v69, v90
	v_add_f32_e32 v64, v89, v88
	v_exp_f32_e32 v69, v65
	v_sub_f32_e32 v65, v70, v90
	v_add_f32_e32 v64, v66, v64
	v_exp_f32_e32 v70, v65
	v_sub_f32_e32 v65, v71, v90
	v_add_f32_e32 v64, v67, v64
	v_exp_f32_e32 v71, v65
	v_sub_f32_e32 v65, v72, v90
	v_add_f32_e32 v64, v68, v64
	v_exp_f32_e32 v72, v65
	v_sub_f32_e32 v65, v73, v90
	v_add_f32_e32 v64, v69, v64
	v_exp_f32_e32 v73, v65
	v_sub_f32_e32 v65, v74, v90
	v_add_f32_e32 v64, v70, v64
	v_exp_f32_e32 v74, v65
	v_sub_f32_e32 v65, v75, v90
	v_add_f32_e32 v64, v71, v64
	v_exp_f32_e32 v75, v65
	v_sub_f32_e32 v65, v76, v90
	v_add_f32_e32 v64, v72, v64
	v_exp_f32_e32 v76, v65
	v_sub_f32_e32 v65, v77, v90
	v_add_f32_e32 v64, v73, v64
	v_exp_f32_e32 v77, v65
	v_sub_f32_e32 v65, v78, v90
	v_add_f32_e32 v64, v74, v64
	v_exp_f32_e32 v78, v65
	v_sub_f32_e32 v65, v79, v90
	v_add_f32_e32 v64, v75, v64
	v_exp_f32_e32 v79, v65
	v_add_f32_e32 v64, v76, v64
	v_add_f32_e32 v64, v77, v64
	v_sub_f32_e32 v91, v87, v81
	v_add_f32_e32 v64, v78, v64
	v_add_f32_e32 v65, v79, v64
	v_exp_f32_e32 v64, v91
	v_mov_b32_e32 v90, v65
	v_mov_b32_e32 v91, v65
	s_nop 1
	v_permlane32_swap_b32_e32 v90, v91
	v_cmp_neq_f32_e32 vcc, v81, v87
	s_cbranch_vccz .LBB0_888
	v_pk_mul_f32 v[62:63], v[62:63], v[64:65] op_sel_hi:[1,0]
	v_pk_mul_f32 v[60:61], v[60:61], v[64:65] op_sel_hi:[1,0]
	v_pk_mul_f32 v[58:59], v[58:59], v[64:65] op_sel_hi:[1,0]
	v_pk_mul_f32 v[56:57], v[56:57], v[64:65] op_sel_hi:[1,0]
	v_pk_mul_f32 v[54:55], v[54:55], v[64:65] op_sel_hi:[1,0]
	v_pk_mul_f32 v[52:53], v[52:53], v[64:65] op_sel_hi:[1,0]
	v_pk_mul_f32 v[50:51], v[50:51], v[64:65] op_sel_hi:[1,0]
	v_pk_mul_f32 v[48:49], v[48:49], v[64:65] op_sel_hi:[1,0]
	v_pk_mul_f32 v[46:47], v[46:47], v[64:65] op_sel_hi:[1,0]
	v_pk_mul_f32 v[44:45], v[44:45], v[64:65] op_sel_hi:[1,0]
	v_pk_mul_f32 v[42:43], v[42:43], v[64:65] op_sel_hi:[1,0]
	v_pk_mul_f32 v[40:41], v[40:41], v[64:65] op_sel_hi:[1,0]
	v_pk_mul_f32 v[38:39], v[38:39], v[64:65] op_sel_hi:[1,0]
	v_pk_mul_f32 v[36:37], v[36:37], v[64:65] op_sel_hi:[1,0]
	v_pk_mul_f32 v[34:35], v[34:35], v[64:65] op_sel_hi:[1,0]
	v_pk_mul_f32 v[32:33], v[32:33], v[64:65] op_sel_hi:[1,0]

; #define LAS __attribute__((address_space(3)))
; DI float ex2(float x) { return __builtin_amdgcn_exp2f(x); }
; template <int MM> DI void smax_step_nb(const f32x16& s, unsigned vm, float& m, float& l, f32x16 (&o)[2], bf16x8 (&pf)[2], int lane) {
;     float mx = -1e30f;
; #pragma unroll
;     for (int i = 0; i < 16; ++i) mx = fmaxf(mx, s[i]);
;     if (MM == 1) mx = vm ? mx : -1e30f;
;     mx = fmaxf(mx, shx32(mx, lane));
;     const float mn = (mx > m + 8.0f) ? mx : m;
;     float mref = fmaxf(mn, -1e29f);
;     if (MM == 1) mref = vm ? mref : 3e38f;
;     const float alpha = ex2(m - mn);
;     float p[16], rs = 0.f;
; #pragma unroll
;     for (int i = 0; i < 16; ++i) { p[i] = ex2(s[i] - mref); rs += p[i]; }
;     rs += shx32(rs, lane);
;     l = l * alpha + rs;
;     if (__builtin_amdgcn_ballot_w64(mn != m) != 0ull) {
; #pragma unroll
;         for (int i = 0; i < 16; ++i) { o[0][i] *= alpha; o[1][i] *= alpha; }
;     }
;     m = mn;
;     pack_p(p, pf);
; }
; template <int MM> DI void tile64_pipe(LAS const char* Kl, LAS const char* Vl, const bf16x8 (&qf)[4], unsigned vm, float& m, float& l, f32x16 (&o)[2], int r, int h, int lane) {
;     const f32x16 sa = qk_rows<0, 4>(Kl, 0, qf, r, h), sb = qk_rows<0, 4>(Kl, 32, qf, r, h);
;     bf16x8 pfa[2], pfb[2];
;     smax_step_nb<MM>(sa, vm, m, l, o, pfa, lane);
;     pv_rows(o, Vl, 0, pfa, lane);
.LBB0_889:
	s_and_b64 vcc, exec, s[54:55]
	s_cbranch_vccz .LBB0_895
	s_nop 7
	ds_read_b128 v[32:35], v82
	s_nop 0
	ds_read_b128 v[48:51], v82 offset:32
	ds_read_b128 v[52:55], v82 offset:64
	ds_read_b128 v[56:59], v82 offset:96
	s_setprio 1
	s_waitcnt lgkmcnt(3)
	v_mfma_f32_32x32x16_bf16 v[32:47], v[32:35], v[112:115], 0
	s_waitcnt lgkmcnt(2)
	v_mfma_f32_32x32x16_bf16 v[32:47], v[48:51], v[116:119], v[32:47]
	s_waitcnt lgkmcnt(1)
	v_mfma_f32_32x32x16_bf16 v[32:47], v[52:55], v[120:123], v[32:47]
	s_waitcnt lgkmcnt(0)
	v_mfma_f32_32x32x16_bf16 v[32:47], v[56:59], v[124:127], v[32:47]
	s_setprio 0
	ds_read_b128 v[48:51], v82 offset:4608
	ds_read_b128 v[52:55], v82 offset:4640
	ds_read_b128 v[56:59], v82 offset:4672
	ds_read_b128 v[60:63], v82 offset:4704
	s_setprio 1
	s_waitcnt lgkmcnt(3)
	v_mfma_f32_32x32x16_bf16 v[64:79], v[48:51], v[112:115], 0
	s_waitcnt lgkmcnt(2)
	v_mfma_f32_32x32x16_bf16 v[64:79], v[52:55], v[116:119], v[64:79]
	s_waitcnt lgkmcnt(1)
	v_mfma_f32_32x32x16_bf16 v[64:79], v[56:59], v[120:123], v[64:79]
	s_waitcnt lgkmcnt(0)
	v_mfma_f32_32x32x16_bf16 v[64:79], v[60:63], v[124:127], v[64:79]
	s_setprio 0
	v_max3_f32 v48, v32, s15, v33
	v_max3_f32 v48, v48, v34, v35
	v_max3_f32 v48, v48, v36, v37
	v_max3_f32 v48, v48, v38, v39
	v_max3_f32 v48, v48, v40, v41
	v_max3_f32 v48, v48, v42, v43
	v_max3_f32 v48, v48, v44, v45
	v_max3_f32 v48, v48, v46, v47
	v_mov_b32_e32 v49, v48
	v_mov_b32_e32 v50, v48
	s_nop 1
	v_permlane32_swap_b32_e32 v49, v50
	v_max_f32_e32 v48, v49, v50
	v_add_f32_e32 v49, 0x41000000, v191
	v_cmp_gt_f32_e32 vcc, v48, v49
	s_nop 1
	v_cndmask_b32_e32 v86, v191, v48, vcc
	v_max_f32_e32 v48, 0xefa18f08, v86
	v_sub_f32_e32 v32, v32, v48
	v_exp_f32_e32 v81, v32
	v_sub_f32_e32 v32, v33, v48
	v_exp_f32_e32 v85, v32
	v_sub_f32_e32 v32, v34, v48
	v_exp_f32_e32 v87, v32
	v_sub_f32_e32 v32, v35, v48
	v_exp_f32_e32 v88, v32
	v_sub_f32_e32 v33, v36, v48
	v_exp_f32_e32 v89, v33
	v_sub_f32_e32 v33, v37, v48
	v_add_f32_e32 v32, v85, v81
	v_exp_f32_e32 v90, v33
	v_sub_f32_e32 v33, v38, v48
	v_add_f32_e32 v32, v87, v32
	v_exp_f32_e32 v91, v33
	v_sub_f32_e32 v33, v39, v48
	v_add_f32_e32 v32, v88, v32
	v_exp_f32_e32 v92, v33
	v_sub_f32_e32 v33, v40, v48
	v_add_f32_e32 v32, v89, v32
	v_exp_f32_e32 v93, v33
	v_sub_f32_e32 v33, v41, v48
	v_add_f32_e32 v32, v90, v32
	v_exp_f32_e32 v94, v33
	v_sub_f32_e32 v33, v42, v48
	v_add_f32_e32 v32, v91, v32
	v_exp_f32_e32 v95, v33
	v_sub_f32_e32 v33, v43, v48
	v_add_f32_e32 v32, v92, v32
	v_exp_f32_e32 v128, v33
	v_sub_f32_e32 v33, v44, v48
	v_add_f32_e32 v32, v93, v32
	v_exp_f32_e32 v129, v33
	v_sub_f32_e32 v33, v45, v48
	v_add_f32_e32 v32, v94, v32
	v_exp_f32_e32 v130, v33
	v_sub_f32_e32 v33, v46, v48
	v_add_f32_e32 v32, v95, v32
	v_exp_f32_e32 v131, v33
	v_sub_f32_e32 v33, v47, v48
	v_add_f32_e32 v32, v128, v32
	v_exp_f32_e32 v132, v33
	v_add_f32_e32 v32, v129, v32
	v_sub_f32_e32 v49, v191, v86
	v_add_f32_e32 v32, v130, v32
	v_add_f32_e32 v32, v131, v32
	v_exp_f32_e32 v80, v49
	v_add_f32_e32 v82, v132, v32
	v_mov_b32_e32 v83, v82
	v_mov_b32_e32 v84, v82
	v_mov_b64_e32 v[62:63], v[30:31]
	s_nop 0
	v_permlane32_swap_b32_e32 v83, v84
	v_cmp_neq_f32_e32 vcc, v86, v191
	v_mov_b64_e32 v[60:61], v[28:29]
	v_mov_b64_e32 v[58:59], v[26:27]
	v_mov_b64_e32 v[56:57], v[24:25]
	v_mov_b64_e32 v[54:55], v[22:23]
	v_mov_b64_e32 v[52:53], v[20:21]
	v_mov_b64_e32 v[50:51], v[18:19]
	v_mov_b64_e32 v[48:49], v[16:17]
	v_mov_b64_e32 v[46:47], v[14:15]
	v_mov_b64_e32 v[44:45], v[12:13]
	v_mov_b64_e32 v[42:43], v[10:11]
	v_mov_b64_e32 v[40:41], v[8:9]
	v_mov_b64_e32 v[38:39], v[6:7]
	v_mov_b64_e32 v[36:37], v[4:5]
	v_mov_b64_e32 v[34:35], v[2:3]
	v_mov_b64_e32 v[32:33], v[0:1]
	s_cbranch_vccz .LBB0_892
	v_pk_mul_f32 v[62:63], v[30:31], v[80:81] op_sel_hi:[1,0]
	v_pk_mul_f32 v[60:61], v[28:29], v[80:81] op_sel_hi:[1,0]
	v_pk_mul_f32 v[58:59], v[26:27], v[80:81] op_sel_hi:[1,0]
	v_pk_mul_f32 v[56:57], v[24:25], v[80:81] op_sel_hi:[1,0]
	v_pk_mul_f32 v[54:55], v[22:23], v[80:81] op_sel_hi:[1,0]
	v_pk_mul_f32 v[52:53], v[20:21], v[80:81] op_sel_hi:[1,0]
	v_pk_mul_f32 v[50:51], v[18:19], v[80:81] op_sel_hi:[1,0]
	v_pk_mul_f32 v[48:49], v[16:17], v[80:81] op_sel_hi:[1,0]
	v_pk_mul_f32 v[46:47], v[14:15], v[80:81] op_sel_hi:[1,0]
	v_pk_mul_f32 v[44:45], v[12:13], v[80:81] op_sel_hi:[1,0]
	v_pk_mul_f32 v[42:43], v[10:11], v[80:81] op_sel_hi:[1,0]
	v_pk_mul_f32 v[40:41], v[8:9], v[80:81] op_sel_hi:[1,0]
	v_pk_mul_f32 v[38:39], v[6:7], v[80:81] op_sel_hi:[1,0]
	v_pk_mul_f32 v[36:37], v[4:5], v[80:81] op_sel_hi:[1,0]
	v_pk_mul_f32 v[34:35], v[2:3], v[80:81] op_sel_hi:[1,0]
	v_pk_mul_f32 v[32:33], v[0:1], v[80:81] op_sel_hi:[1,0]
; DI float ex2(float x) { return __builtin_amdgcn_exp2f(x); }
; template <int MM> DI void smax_step_nb(const f32x16& s, unsigned vm, float& m, float& l, f32x16 (&o)[2], bf16x8 (&pf)[2], int lane) {
;     float mx = -1e30f;
; #pragma unroll
;     for (int i = 0; i < 16; ++i) mx = fmaxf(mx, s[i]);
;     if (MM == 1) mx = vm ? mx : -1e30f;
;     mx = fmaxf(mx, shx32(mx, lane));
;     const float mn = (mx > m + 8.0f) ? mx : m;
;     float mref = fmaxf(mn, -1e29f);
;     if (MM == 1) mref = vm ? mref : 3e38f;
;     const float alpha = ex2(m - mn);
;     float p[16], rs = 0.f;
; #pragma unroll
;     for (int i = 0; i < 16; ++i) { p[i] = ex2(s[i] - mref); rs += p[i]; }
;     rs += shx32(rs, lane);
;     l = l * alpha + rs;
;     if (__builtin_amdgcn_ballot_w64(mn != m) != 0ull) {
; #pragma unroll
;         for (int i = 0; i < 16; ++i) { o[0][i] *= alpha; o[1][i] *= alpha; }
;     }
;     m = mn;
;     pack_p(p, pf);
; }
; template <int MM> DI void tile64_pipe(LAS const char* Kl, LAS const char* Vl, const bf16x8 (&qf)[4], unsigned vm, float& m, float& l, f32x16 (&o)[2], int r, int h, int lane) {
;     const f32x16 sa = qk_rows<0, 4>(Kl, 0, qf, r, h), sb = qk_rows<0, 4>(Kl, 32, qf, r, h);
;     bf16x8 pfa[2], pfb[2];
;     smax_step_nb<MM>(sa, vm, m, l, o, pfa, lane);
;     pv_rows(o, Vl, 0, pfa, lane);
;     smax_step_nb<MM>(sb, vm, m, l, o, pfb, lane);
;     pv_rows(o, Vl, 32, pfb, lane);
.LBB0_892:
	v_cvt_pk_bf16_f32 v134, v81, v85
	v_add3_u32 v81, s11, v186, v187
	v_add_u32_e32 v85, v81, v188
	v_cvt_pk_bf16_f32 v135, v87, v88
	v_cvt_pk_bf16_f32 v136, v89, v90
	v_cvt_pk_bf16_f32 v137, v91, v92
	v_cvt_pk_bf16_f32 v88, v93, v94
	v_cvt_pk_bf16_f32 v89, v95, v128
	v_cvt_pk_bf16_f32 v90, v129, v130
	v_cvt_pk_bf16_f32 v91, v131, v132
	ds_read_b64_tr_b16 v[92:93], v85 offset:9216
	ds_read_b64_tr_b16 v[94:95], v85 offset:10368
	ds_read_b64_tr_b16 v[128:129], v85 offset:11520
	ds_read_b64_tr_b16 v[130:131], v85 offset:12672
	ds_read_b64_tr_b16 v[138:139], v85 offset:9280
	ds_read_b64_tr_b16 v[140:141], v85 offset:10432
	ds_read_b64_tr_b16 v[142:143], v85 offset:11584
	ds_read_b64_tr_b16 v[144:145], v85 offset:12736
	s_setprio 1
	s_waitcnt lgkmcnt(6)
	v_mfma_f32_32x32x16_bf16 v[32:47], v[92:95], v[134:137], v[32:47]
	s_waitcnt lgkmcnt(2)
	v_mfma_f32_32x32x16_bf16 v[48:63], v[138:141], v[134:137], v[48:63]
	v_mfma_f32_32x32x16_bf16 v[32:47], v[128:131], v[88:91], v[32:47]
	s_waitcnt lgkmcnt(0)
	v_mfma_f32_32x32x16_bf16 v[48:63], v[142:145], v[88:91], v[48:63]
	s_setprio 0
	v_max3_f32 v81, v64, s15, v65
	v_max3_f32 v81, v81, v66, v67
	v_max3_f32 v81, v81, v68, v69
	v_max3_f32 v81, v81, v70, v71
	v_max3_f32 v81, v81, v72, v73
	v_max3_f32 v81, v81, v74, v75
	v_max3_f32 v81, v81, v76, v77
	v_max3_f32 v81, v81, v78, v79
	v_mov_b32_e32 v87, v81
	v_mov_b32_e32 v88, v81
	s_nop 1
	v_permlane32_swap_b32_e32 v87, v88
	v_max_f32_e32 v81, v87, v88
	v_add_f32_e32 v87, 0x41000000, v86
	v_cmp_gt_f32_e32 vcc, v81, v87
	s_nop 1
	v_cndmask_b32_e32 v81, v86, v81, vcc
	v_max_f32_e32 v89, 0xefa18f08, v81
	v_sub_f32_e32 v64, v64, v89
	v_exp_f32_e32 v87, v64
	v_sub_f32_e32 v64, v65, v89
	v_exp_f32_e32 v88, v64
	v_sub_f32_e32 v64, v66, v89
	v_exp_f32_e32 v66, v64
	v_sub_f32_e32 v64, v67, v89
	v_exp_f32_e32 v67, v64
	v_sub_f32_e32 v65, v68, v89
	v_exp_f32_e32 v68, v65
	v_sub_f32_e32 v65, v69, v89
	v_add_f32_e32 v64, v88, v87
	v_exp_f32_e32 v69, v65
	v_sub_f32_e32 v65, v70, v89
	v_add_f32_e32 v64, v66, v64
	v_exp_f32_e32 v70, v65
	v_sub_f32_e32 v65, v71, v89
	v_add_f32_e32 v64, v67, v64
	v_exp_f32_e32 v71, v65
	v_sub_f32_e32 v65, v72, v89
	v_add_f32_e32 v64, v68, v64
	v_exp_f32_e32 v72, v65
	v_sub_f32_e32 v65, v73, v89
	v_add_f32_e32 v64, v69, v64
	v_exp_f32_e32 v73, v65
	v_sub_f32_e32 v65, v74, v89
	v_add_f32_e32 v64, v70, v64
	v_exp_f32_e32 v74, v65
	v_sub_f32_e32 v65, v75, v89
	v_add_f32_e32 v64, v71, v64
	v_exp_f32_e32 v75, v65
	v_sub_f32_e32 v65, v76, v89
	v_add_f32_e32 v64, v72, v64
	v_exp_f32_e32 v76, v65
	v_sub_f32_e32 v65, v77, v89
	v_add_f32_e32 v64, v73, v64
	v_exp_f32_e32 v77, v65
	v_sub_f32_e32 v65, v78, v89
	v_add_f32_e32 v64, v74, v64
	v_exp_f32_e32 v78, v65
	v_sub_f32_e32 v65, v79, v89
	v_add_f32_e32 v64, v75, v64
	v_exp_f32_e32 v79, v65
	v_add_f32_e32 v64, v76, v64
	v_add_f32_e32 v64, v77, v64
	v_sub_f32_e32 v90, v86, v81
	v_add_f32_e32 v64, v78, v64
	v_add_f32_e32 v65, v79, v64
	v_exp_f32_e32 v64, v90
	v_mov_b32_e32 v89, v65
	v_mov_b32_e32 v90, v65
	s_nop 1
	v_permlane32_swap_b32_e32 v89, v90
	v_cmp_neq_f32_e32 vcc, v81, v86
	s_cbranch_vccz .LBB0_894
	v_pk_mul_f32 v[62:63], v[62:63], v[64:65] op_sel_hi:[1,0]
	v_pk_mul_f32 v[60:61], v[60:61], v[64:65] op_sel_hi:[1,0]
	v_pk_mul_f32 v[58:59], v[58:59], v[64:65] op_sel_hi:[1,0]
	v_pk_mul_f32 v[56:57], v[56:57], v[64:65] op_sel_hi:[1,0]
	v_pk_mul_f32 v[54:55], v[54:55], v[64:65] op_sel_hi:[1,0]
	v_pk_mul_f32 v[52:53], v[52:53], v[64:65] op_sel_hi:[1,0]
	v_pk_mul_f32 v[50:51], v[50:51], v[64:65] op_sel_hi:[1,0]
	v_pk_mul_f32 v[48:49], v[48:49], v[64:65] op_sel_hi:[1,0]
	v_pk_mul_f32 v[46:47], v[46:47], v[64:65] op_sel_hi:[1,0]
	v_pk_mul_f32 v[44:45], v[44:45], v[64:65] op_sel_hi:[1,0]
	v_pk_mul_f32 v[42:43], v[42:43], v[64:65] op_sel_hi:[1,0]
	v_pk_mul_f32 v[40:41], v[40:41], v[64:65] op_sel_hi:[1,0]
	v_pk_mul_f32 v[38:39], v[38:39], v[64:65] op_sel_hi:[1,0]
	v_pk_mul_f32 v[36:37], v[36:37], v[64:65] op_sel_hi:[1,0]
	v_pk_mul_f32 v[34:35], v[34:35], v[64:65] op_sel_hi:[1,0]
	v_pk_mul_f32 v[32:33], v[32:33], v[64:65] op_sel_hi:[1,0]

; DI float ex2(float x) { return __builtin_amdgcn_exp2f(x); }
; template <int MM> DI void smax_step(const f32x16& s, unsigned vm, float& m, float& l, f32x16 (&o)[2], bf16x8 (&pf)[2], int lane) {
;     float t[16], mx = -1e30f;
; #pragma unroll
;     for (int i = 0; i < 16; ++i) { t[i] = (MM == 0) ? s[i] : (MM == 1 ? (vm ? s[i] : -1e30f) : (((vm >> i) & 1u) ? s[i] : -1e30f)); mx = fmaxf(mx, t[i]); }
;     mx = fmaxf(mx, shx32(mx, lane));
;     const float mn = (mx > m + 8.0f) ? mx : m;
;     const float mref = fmaxf(mn, -1e29f);
;     float p[16], rs = 0.f;
; #pragma unroll
;     for (int i = 0; i < 16; ++i) { p[i] = ex2(t[i] - mref); rs += p[i]; }
;     rs += shx32(rs, lane);
;     if (__builtin_amdgcn_ballot_w64(mn != m) != 0ull) {
;         const float alpha = ex2(m - mn);
;         l *= alpha;
; #pragma unroll
;         for (int i = 0; i < 16; ++i) { o[0][i] *= alpha; o[1][i] *= alpha; }
;         m = mn;
;     }
;     l += rs;
;     pack_p(p, pf);
; }
; template <int MODE, bool PRE = false> ...
;     ...
;                 const f32x16 s = qk_rows<0, 4>(Kl, 32 * sub, qf, r, h);
;                 if (mm == 0) smax_step<0>(s, vm, m1, l1, o1, pf, lane); else if (mm == 1) smax_step<1>(s, vm, m1, l1, o1, pf, lane); else smax_step<2>(s, vm, m1, l1, o1, pf, lane);
.LBB0_906:
	s_andn2_b64 vcc, exec, s[54:55]
	s_cbranch_vccnz .LBB0_918
	v_add_u32_e32 v36, v48, v184
	ds_read_b128 v[32:35], v36
	ds_read_b128 v[52:55], v36 offset:32
	ds_read_b128 v[56:59], v36 offset:64
	ds_read_b128 v[60:63], v36 offset:96
	s_setprio 1
	s_waitcnt lgkmcnt(3)
	v_mfma_f32_32x32x16_bf16 v[32:47], v[32:35], v[112:115], 0
	s_waitcnt lgkmcnt(2)
	v_mfma_f32_32x32x16_bf16 v[32:47], v[52:55], v[116:119], v[32:47]
	s_waitcnt lgkmcnt(1)
	v_mfma_f32_32x32x16_bf16 v[32:47], v[56:59], v[120:123], v[32:47]
	s_waitcnt lgkmcnt(0)
	v_mfma_f32_32x32x16_bf16 v[32:47], v[60:63], v[124:127], v[32:47]
	s_setprio 0
	v_cmp_gt_i32_e32 vcc, 1, v50
	s_cbranch_vccnz .LBB0_910
	v_cmp_ne_u32_e32 vcc, 1, v50
	s_cbranch_vccz .LBB0_911
	v_and_b32_e32 v50, 1, v71
	v_cmp_eq_u32_e32 vcc, 1, v50
	v_and_b32_e32 v50, 2, v71
	v_and_b32_e32 v53, 4, v71
	s_nop 2
	v_cndmask_b32_e32 v51, v208, v32, vcc
	v_cmp_ne_u32_e32 vcc, 0, v50
	v_and_b32_e32 v54, 8, v71
	v_and_b32_e32 v55, 16, v71
	v_cndmask_b32_e32 v52, v208, v33, vcc
	v_cmp_ne_u32_e32 vcc, 0, v53
	v_and_b32_e32 v56, 32, v71
	v_and_b32_e32 v57, 64, v71
	v_cndmask_b32_e32 v53, v208, v34, vcc
	v_cmp_ne_u32_e32 vcc, 0, v54
	v_and_b32_e32 v58, 0x80, v71
	v_and_b32_e32 v59, 0x100, v71
	v_cndmask_b32_e32 v54, v208, v35, vcc
	v_cmp_ne_u32_e32 vcc, 0, v55
	v_and_b32_e32 v60, 0x200, v71
	v_and_b32_e32 v61, 0x400, v71
	v_cndmask_b32_e32 v55, v208, v36, vcc
	v_cmp_ne_u32_e32 vcc, 0, v56
	v_max3_f32 v50, v51, s15, v52
	v_and_b32_e32 v62, 0x800, v71
	v_cndmask_b32_e32 v56, v208, v37, vcc
	v_cmp_ne_u32_e32 vcc, 0, v57
	v_max3_f32 v50, v50, v53, v54
	v_and_b32_e32 v63, 0x1000, v71
	v_cndmask_b32_e32 v57, v208, v38, vcc
	v_cmp_ne_u32_e32 vcc, 0, v58
	v_max3_f32 v50, v50, v55, v56
	v_and_b32_e32 v65, 0x2000, v71
	v_cndmask_b32_e32 v58, v208, v39, vcc
	v_cmp_ne_u32_e32 vcc, 0, v59
	v_max3_f32 v50, v50, v57, v58
	v_and_b32_e32 v66, 0x4000, v71
	v_cndmask_b32_e32 v59, v208, v40, vcc
	v_cmp_ne_u32_e32 vcc, 0, v60
	v_and_b32_e32 v67, 0x8000, v71
	s_nop 0
	v_cndmask_b32_e32 v60, v208, v41, vcc
	v_cmp_ne_u32_e32 vcc, 0, v61
	v_max3_f32 v50, v50, v59, v60
	s_nop 0
	v_cndmask_b32_e32 v61, v208, v42, vcc
	v_cmp_ne_u32_e32 vcc, 0, v62
	s_nop 1
	v_cndmask_b32_e32 v62, v208, v43, vcc
	v_cmp_ne_u32_e32 vcc, 0, v63
	v_max3_f32 v50, v50, v61, v62
	s_nop 0
	v_cndmask_b32_e32 v63, v208, v44, vcc
	v_cmp_ne_u32_e32 vcc, 0, v65
	s_nop 1
	v_cndmask_b32_e32 v65, v208, v45, vcc
	v_cmp_ne_u32_e32 vcc, 0, v66
	v_max3_f32 v50, v50, v63, v65
	s_nop 0
	v_cndmask_b32_e32 v66, v208, v46, vcc
	v_cmp_ne_u32_e32 vcc, 0, v67
	s_nop 1
	v_cndmask_b32_e32 v67, v208, v47, vcc
	v_max3_f32 v50, v50, v66, v67
	v_mov_b32_e32 v68, v50
	v_mov_b32_e32 v69, v50
	s_nop 1
	v_permlane32_swap_b32_e32 v68, v69
	v_max_f32_e32 v50, v68, v69
	v_add_f32_e32 v68, 0x41000000, v191
	v_cmp_gt_f32_e32 vcc, v50, v68
	s_nop 1
	v_cndmask_b32_e32 v50, v191, v50, vcc
	v_max_f32_e32 v68, 0xefa18f08, v50
	v_sub_f32_e32 v51, v51, v68
	v_exp_f32_e32 v51, v51
	v_sub_f32_e32 v52, v52, v68
	v_exp_f32_e32 v52, v52
	v_sub_f32_e32 v53, v53, v68
	v_exp_f32_e32 v53, v53
	v_sub_f32_e32 v54, v54, v68
	v_exp_f32_e32 v54, v54
	v_sub_f32_e32 v55, v55, v68
	v_exp_f32_e32 v55, v55
	v_sub_f32_e32 v56, v56, v68
	v_add_f32_e32 v69, v52, v51
	v_exp_f32_e32 v56, v56
	v_sub_f32_e32 v57, v57, v68
	v_add_f32_e32 v69, v53, v69
	v_exp_f32_e32 v57, v57
	v_sub_f32_e32 v58, v58, v68
	v_add_f32_e32 v69, v54, v69
	v_exp_f32_e32 v58, v58
	v_sub_f32_e32 v59, v59, v68
	v_add_f32_e32 v69, v55, v69
	v_exp_f32_e32 v59, v59
	v_sub_f32_e32 v60, v60, v68
	v_add_f32_e32 v69, v56, v69
	v_exp_f32_e32 v60, v60
	v_sub_f32_e32 v61, v61, v68
	v_add_f32_e32 v69, v57, v69
	v_exp_f32_e32 v61, v61
	v_sub_f32_e32 v62, v62, v68
	v_add_f32_e32 v69, v58, v69
	v_exp_f32_e32 v62, v62
	v_sub_f32_e32 v63, v63, v68
	v_add_f32_e32 v69, v59, v69
	v_exp_f32_e32 v63, v63
	v_sub_f32_e32 v65, v65, v68
	v_add_f32_e32 v69, v60, v69
	v_exp_f32_e32 v65, v65
	v_sub_f32_e32 v66, v66, v68
	v_add_f32_e32 v69, v61, v69
	v_exp_f32_e32 v66, v66
	v_sub_f32_e32 v67, v67, v68
	v_add_f32_e32 v69, v62, v69
	v_exp_f32_e32 v67, v67
	v_add_f32_e32 v68, v63, v69
	v_add_f32_e32 v68, v65, v68
	v_add_f32_e32 v68, v66, v68
	v_add_f32_e32 v68, v67, v68
	v_cmp_neq_f32_e32 vcc, v50, v191
	v_mov_b32_e32 v69, v68
	v_mov_b32_e32 v70, v68
	s_cmp_lg_u64 vcc, 0
	s_nop 0
	v_permlane32_swap_b32_e32 v69, v70
	s_cselect_b64 s[54:55], -1, 0
	s_cbranch_execz .LBB0_912
	s_branch .LBB0_913

; DI float ex2(float x) { return __builtin_amdgcn_exp2f(x); }
; template <int MM> DI void smax_step(const f32x16& s, unsigned vm, float& m, float& l, f32x16 (&o)[2], bf16x8 (&pf)[2], int lane) {
;     float t[16], mx = -1e30f;
; #pragma unroll
;     for (int i = 0; i < 16; ++i) { t[i] = (MM == 0) ? s[i] : (MM == 1 ? (vm ? s[i] : -1e30f) : (((vm >> i) & 1u) ? s[i] : -1e30f)); mx = fmaxf(mx, t[i]); }
;     mx = fmaxf(mx, shx32(mx, lane));
;     const float mn = (mx > m + 8.0f) ? mx : m;
;     const float mref = fmaxf(mn, -1e29f);
;     float p[16], rs = 0.f;
; #pragma unroll
;     for (int i = 0; i < 16; ++i) { p[i] = ex2(t[i] - mref); rs += p[i]; }
;     rs += shx32(rs, lane);
;     if (__builtin_amdgcn_ballot_w64(mn != m) != 0ull) {
;         const float alpha = ex2(m - mn);
;         l *= alpha;
; #pragma unroll
;         for (int i = 0; i < 16; ++i) { o[0][i] *= alpha; o[1][i] *= alpha; }
;         m = mn;
;     }
;     l += rs;
;     pack_p(p, pf);
; }
; template <int MODE, bool PRE = false> ...
;     ...
;                 if (mm == 0) smax_step<0>(s, vm, m1, l1, o1, pf, lane); else if (mm == 1) smax_step<1>(s, vm, m1, l1, o1, pf, lane); else smax_step<2>(s, vm, m1, l1, o1, pf, lane);
.LBB0_912:
	v_cmp_eq_u32_e32 vcc, 0, v71
	s_nop 4
	v_cndmask_b32_e32 v51, v32, v208, vcc
	v_cndmask_b32_e32 v52, v33, v208, vcc
	v_max3_f32 v50, v51, s15, v52
	v_cndmask_b32_e32 v53, v34, v208, vcc
	v_cndmask_b32_e32 v54, v35, v208, vcc
	v_max3_f32 v50, v50, v53, v54
	v_cndmask_b32_e32 v55, v36, v208, vcc
	v_cndmask_b32_e32 v56, v37, v208, vcc
	v_max3_f32 v50, v50, v55, v56
	v_cndmask_b32_e32 v57, v38, v208, vcc
	v_cndmask_b32_e32 v58, v39, v208, vcc
	v_max3_f32 v50, v50, v57, v58
	v_cndmask_b32_e32 v59, v40, v208, vcc
	v_cndmask_b32_e32 v60, v41, v208, vcc
	v_max3_f32 v50, v50, v59, v60
	v_cndmask_b32_e32 v61, v42, v208, vcc
	v_cndmask_b32_e32 v62, v43, v208, vcc
	v_max3_f32 v50, v50, v61, v62
	v_cndmask_b32_e32 v63, v44, v208, vcc
	v_cndmask_b32_e32 v65, v45, v208, vcc
	v_max3_f32 v50, v50, v63, v65
	v_cndmask_b32_e32 v66, v46, v208, vcc
	v_cndmask_b32_e32 v67, v47, v208, vcc
	v_max3_f32 v50, v50, v66, v67
	v_mov_b32_e32 v68, v50
	v_mov_b32_e32 v69, v50
	s_nop 1
	v_permlane32_swap_b32_e32 v68, v69
	v_max_f32_e32 v50, v68, v69
	v_add_f32_e32 v68, 0x41000000, v191
	v_cmp_gt_f32_e32 vcc, v50, v68
	s_nop 1
	v_cndmask_b32_e32 v50, v191, v50, vcc
	v_max_f32_e32 v68, 0xefa18f08, v50
	v_sub_f32_e32 v51, v51, v68
	v_exp_f32_e32 v51, v51
	v_sub_f32_e32 v52, v52, v68
	v_exp_f32_e32 v52, v52
	v_sub_f32_e32 v53, v53, v68
	v_exp_f32_e32 v53, v53
	v_sub_f32_e32 v54, v54, v68
	v_exp_f32_e32 v54, v54
	v_sub_f32_e32 v55, v55, v68
	v_exp_f32_e32 v55, v55
	v_sub_f32_e32 v56, v56, v68
	v_add_f32_e32 v69, v52, v51
	v_exp_f32_e32 v56, v56
	v_sub_f32_e32 v57, v57, v68
	v_add_f32_e32 v69, v53, v69
	v_exp_f32_e32 v57, v57
	v_sub_f32_e32 v58, v58, v68
	v_add_f32_e32 v69, v54, v69
	v_exp_f32_e32 v58, v58
	v_sub_f32_e32 v59, v59, v68
	v_add_f32_e32 v69, v55, v69
	v_exp_f32_e32 v59, v59
	v_sub_f32_e32 v60, v60, v68
	v_add_f32_e32 v69, v56, v69
	v_exp_f32_e32 v60, v60
	v_sub_f32_e32 v61, v61, v68
	v_add_f32_e32 v69, v57, v69
	v_exp_f32_e32 v61, v61
	v_sub_f32_e32 v62, v62, v68
	v_add_f32_e32 v69, v58, v69
	v_exp_f32_e32 v62, v62
	v_sub_f32_e32 v63, v63, v68
	v_add_f32_e32 v69, v59, v69
	v_exp_f32_e32 v63, v63
	v_sub_f32_e32 v65, v65, v68
	v_add_f32_e32 v69, v60, v69
	v_exp_f32_e32 v65, v65
	v_sub_f32_e32 v66, v66, v68
	v_add_f32_e32 v69, v61, v69
	v_exp_f32_e32 v66, v66
	v_sub_f32_e32 v67, v67, v68
	v_add_f32_e32 v69, v62, v69
	v_exp_f32_e32 v67, v67
	v_add_f32_e32 v68, v63, v69
	v_add_f32_e32 v68, v65, v68
	v_add_f32_e32 v68, v66, v68
	v_add_f32_e32 v68, v67, v68
	v_cmp_neq_f32_e32 vcc, v50, v191
	v_mov_b32_e32 v69, v68
	v_mov_b32_e32 v70, v68
	s_cmp_lg_u64 vcc, 0
	s_nop 0
	v_permlane32_swap_b32_e32 v69, v70
	s_cselect_b64 s[54:55], -1, 0

; DI float ex2(float x) { return __builtin_amdgcn_exp2f(x); }
; template <int MM> DI void smax_step(const f32x16& s, unsigned vm, float& m, float& l, f32x16 (&o)[2], bf16x8 (&pf)[2], int lane) {
;     float t[16], mx = -1e30f;
; #pragma unroll
;     for (int i = 0; i < 16; ++i) { t[i] = (MM == 0) ? s[i] : (MM == 1 ? (vm ? s[i] : -1e30f) : (((vm >> i) & 1u) ? s[i] : -1e30f)); mx = fmaxf(mx, t[i]); }
;     mx = fmaxf(mx, shx32(mx, lane));
;     const float mn = (mx > m + 8.0f) ? mx : m;
;     const float mref = fmaxf(mn, -1e29f);
;     float p[16], rs = 0.f;
; #pragma unroll
;     for (int i = 0; i < 16; ++i) { p[i] = ex2(t[i] - mref); rs += p[i]; }
;     rs += shx32(rs, lane);
;     if (__builtin_amdgcn_ballot_w64(mn != m) != 0ull) {
;         const float alpha = ex2(m - mn);
;         l *= alpha;
; #pragma unroll
;         for (int i = 0; i < 16; ++i) { o[0][i] *= alpha; o[1][i] *= alpha; }
;         m = mn;
;     }
;     l += rs;
;     pack_p(p, pf);
; }
; template <int MODE, bool PRE = false> ...
;     ...
;                 if (mm == 0) smax_step<0>(s, vm, m1, l1, o1, pf, lane); else if (mm == 1) smax_step<1>(s, vm, m1, l1, o1, pf, lane); else smax_step<2>(s, vm, m1, l1, o1, pf, lane);
.LBB0_914:
	s_nop 5
	v_max3_f32 v50, v32, s15, v33
	v_max3_f32 v50, v50, v34, v35
	v_max3_f32 v50, v50, v36, v37
	v_max3_f32 v50, v50, v38, v39
	v_max3_f32 v50, v50, v40, v41
	v_max3_f32 v50, v50, v42, v43
	v_max3_f32 v50, v50, v44, v45
	v_max3_f32 v50, v50, v46, v47
	v_mov_b32_e32 v51, v50
	v_mov_b32_e32 v52, v50
	s_nop 1
	v_permlane32_swap_b32_e32 v51, v52
	v_max_f32_e32 v50, v51, v52
	v_add_f32_e32 v51, 0x41000000, v191
	v_cmp_gt_f32_e32 vcc, v50, v51
	s_nop 1
	v_cndmask_b32_e32 v50, v191, v50, vcc
	v_max_f32_e32 v67, 0xefa18f08, v50
	v_sub_f32_e32 v32, v32, v67
	v_exp_f32_e32 v51, v32
	v_sub_f32_e32 v32, v33, v67
	v_exp_f32_e32 v52, v32
	v_sub_f32_e32 v32, v34, v67
	v_exp_f32_e32 v53, v32
	v_sub_f32_e32 v32, v35, v67
	v_exp_f32_e32 v54, v32
	v_sub_f32_e32 v33, v36, v67
	v_exp_f32_e32 v55, v33
	v_sub_f32_e32 v33, v37, v67
	v_add_f32_e32 v32, v52, v51
	v_exp_f32_e32 v56, v33
	v_sub_f32_e32 v33, v38, v67
	v_add_f32_e32 v32, v53, v32
	v_exp_f32_e32 v57, v33
	v_sub_f32_e32 v33, v39, v67
	v_add_f32_e32 v32, v54, v32
	v_exp_f32_e32 v58, v33
	v_sub_f32_e32 v33, v40, v67
	v_add_f32_e32 v32, v55, v32
	v_exp_f32_e32 v59, v33
	v_sub_f32_e32 v33, v41, v67
	v_add_f32_e32 v32, v56, v32
	v_exp_f32_e32 v60, v33
	v_sub_f32_e32 v33, v42, v67
	v_add_f32_e32 v32, v57, v32
	v_exp_f32_e32 v61, v33
	v_sub_f32_e32 v33, v43, v67
	v_add_f32_e32 v32, v58, v32
	v_exp_f32_e32 v62, v33
	v_sub_f32_e32 v33, v44, v67
	v_add_f32_e32 v32, v59, v32
	v_exp_f32_e32 v63, v33
	v_sub_f32_e32 v33, v45, v67
	v_add_f32_e32 v32, v60, v32
	v_exp_f32_e32 v65, v33
	v_sub_f32_e32 v33, v46, v67
	v_add_f32_e32 v32, v61, v32
	v_exp_f32_e32 v66, v33
	v_sub_f32_e32 v33, v47, v67
	v_add_f32_e32 v32, v62, v32
	v_exp_f32_e32 v67, v33
	v_add_f32_e32 v32, v63, v32
	v_add_f32_e32 v32, v65, v32
	v_add_f32_e32 v32, v66, v32
	v_add_f32_e32 v68, v67, v32
	v_cmp_neq_f32_e32 vcc, v50, v191
	v_mov_b32_e32 v69, v68
	v_mov_b32_e32 v70, v68
	s_cmp_lg_u64 vcc, 0
	s_nop 0
	v_permlane32_swap_b32_e32 v69, v70
	s_cselect_b64 s[54:55], -1, 0

; template <int MODE, bool PRE = false> ...
;     ...
;             const int kbase = 64 * kt + 32 * sub;
;             if (kbase > q0w + 31) continue;
;             if (MODE == MODE_NWIN && kbase + 31 <= q0w - 512) continue;
;             bool full = (kbase + 31 <= q0w);
;             if (MODE == MODE_NWIN) full = full && (kbase > q0w + 31 - 512);
;             bool lsel = true;
;             if (MODE == MODE_MOBA) lsel = ((sel >> (kbase >> 8)) & 1ull) != 0ull;
;             if (MODE == MODE_NSEL) lsel = ((sel >> kt) & 1ull) != 0ull;
;             const unsigned long long selb = __builtin_amdgcn_ballot_w64(lsel);
;             if (selb == 0ull) continue;
;             int mm; unsigned vm;
;             if (full) { mm = (selb == ~0ull) ? 0 : 1; vm = lsel ? 1u : 0u; }
;             else { mm = 2; vm = 0;
; #pragma unroll
;                 for (int i = 0; i < 16; ++i) { const int kidx = kbase + (i & 3) + 8 * (i >> 2) + 4 * h; bool ok = kidx <= qpos; if (MODE == MODE_NWIN) ok = ok && (kidx > qpos - 512); vm |= ok ? (1u << i) : 0u; }
;                 if (!lsel) vm = 0;
;                 if (__builtin_amdgcn_ballot_w64(vm != 0) == 0ull) continue; }
.LBB0_918:
	s_or_b32 s10, s10, 32
	s_cmp_gt_i32 s10, s60
	s_cbranch_scc1 .LBB0_923
	v_cmp_ne_u32_e32 vcc, 0, v49
	s_cbranch_vccz .LBB0_923
	v_or_b32_e32 v32, s10, v161
	v_cmp_le_i32_e32 vcc, v32, v167
	v_or_b32_e32 v35, 3, v32
	s_nop 0
	v_cndmask_b32_e64 v33, 0, 1, vcc
	v_cmp_lt_i32_e32 vcc, v32, v167
	s_nop 1
	v_cndmask_b32_e64 v34, 0, 2, vcc
	v_or_b32_e32 v33, v34, v33
	v_or_b32_e32 v34, 2, v32
	v_cmp_gt_i32_e32 vcc, v34, v167
	s_nop 1
	v_cndmask_b32_e64 v34, 4, 0, vcc
	v_cmp_gt_i32_e32 vcc, v35, v167
	s_nop 1
	v_cndmask_b32_e64 v35, 8, 0, vcc
	v_or3_b32 v33, v33, v34, v35
	v_or_b32_e32 v34, 8, v32
	v_cmp_gt_i32_e32 vcc, v34, v167
	v_or_b32_e32 v35, 9, v32
	s_nop 0
	v_cndmask_b32_e64 v34, 16, 0, vcc
	v_cmp_gt_i32_e32 vcc, v35, v167
	s_nop 1
	v_cndmask_b32_e64 v35, 32, 0, vcc
	v_or3_b32 v33, v33, v34, v35
	v_or_b32_e32 v34, 10, v32
	v_cmp_gt_i32_e32 vcc, v34, v167
	v_or_b32_e32 v35, 11, v32
	s_nop 0
	v_cndmask_b32_e64 v34, 64, 0, vcc
	v_cmp_gt_i32_e32 vcc, v35, v167
	s_nop 1
	v_cndmask_b32_e64 v35, v196, 0, vcc
	v_or3_b32 v33, v33, v34, v35
	v_or_b32_e32 v34, 16, v32
	v_cmp_gt_i32_e32 vcc, v34, v167
	v_or_b32_e32 v35, 17, v32
	s_nop 0
	v_cndmask_b32_e64 v34, v197, 0, vcc
	v_cmp_gt_i32_e32 vcc, v35, v167
	s_nop 1
	v_cndmask_b32_e64 v35, v198, 0, vcc
	v_or3_b32 v33, v33, v34, v35
	v_or_b32_e32 v34, 18, v32
	v_cmp_gt_i32_e32 vcc, v34, v167
	v_or_b32_e32 v35, 19, v32
	s_nop 0
	v_cndmask_b32_e64 v34, v199, 0, vcc
	v_cmp_gt_i32_e32 vcc, v35, v167
	s_nop 1
	v_cndmask_b32_e64 v35, v200, 0, vcc
	v_or3_b32 v33, v33, v34, v35
	v_or_b32_e32 v34, 24, v32
	v_cmp_gt_i32_e32 vcc, v34, v167
	v_or_b32_e32 v35, 25, v32
	s_nop 0
	v_cndmask_b32_e64 v34, v201, 0, vcc
	v_cmp_gt_i32_e32 vcc, v35, v167
	s_nop 1
	v_cndmask_b32_e64 v35, v202, 0, vcc
	v_or3_b32 v33, v33, v34, v35
	v_or_b32_e32 v34, 26, v32
	v_cmp_gt_i32_e32 vcc, v34, v167
	v_or_b32_e32 v32, 27, v32
	s_nop 0
	v_cndmask_b32_e64 v34, v203, 0, vcc
	v_cmp_gt_i32_e32 vcc, v32, v167
	s_nop 1
	v_cndmask_b32_e64 v32, v204, 0, vcc
	v_or3_b32 v32, v33, v34, v32
	v_cndmask_b32_e64 v49, 0, v32, s[0:1]
	v_cmp_ne_u32_e32 vcc, 0, v49
	s_cbranch_vccz .LBB0_923
; DI float ex2(float x) { return __builtin_amdgcn_exp2f(x); }
; template <int MM> DI void smax_step(const f32x16& s, unsigned vm, float& m, float& l, f32x16 (&o)[2], bf16x8 (&pf)[2], int lane) {
;     float t[16], mx = -1e30f;
; #pragma unroll
;     for (int i = 0; i < 16; ++i) { t[i] = (MM == 0) ? s[i] : (MM == 1 ? (vm ? s[i] : -1e30f) : (((vm >> i) & 1u) ? s[i] : -1e30f)); mx = fmaxf(mx, t[i]); }
;     mx = fmaxf(mx, shx32(mx, lane));
;     const float mn = (mx > m + 8.0f) ? mx : m;
;     const float mref = fmaxf(mn, -1e29f);
;     float p[16], rs = 0.f;
; #pragma unroll
;     for (int i = 0; i < 16; ++i) { p[i] = ex2(t[i] - mref); rs += p[i]; }
;     rs += shx32(rs, lane);
;     if (__builtin_amdgcn_ballot_w64(mn != m) != 0ull) {
;         const float alpha = ex2(m - mn);
;         l *= alpha;
; #pragma unroll
;         for (int i = 0; i < 16; ++i) { o[0][i] *= alpha; o[1][i] *= alpha; }
;         m = mn;
;     }
; template <int MODE, bool PRE = false> ...
;     ...
;                 const f32x16 s = qk_rows<0, 4>(Kl, 32 * sub, qf, r, h);
;                 if (mm == 0) smax_step<0>(s, vm, m1, l1, o1, pf, lane); else if (mm == 1) smax_step<1>(s, vm, m1, l1, o1, pf, lane); else smax_step<2>(s, vm, m1, l1, o1, pf, lane);
	v_add_u32_e32 v36, v48, v189
	ds_read_b128 v[32:35], v36
	ds_read_b128 v[50:53], v36 offset:32
	ds_read_b128 v[54:57], v36 offset:64
	ds_read_b128 v[58:61], v36 offset:96
	s_setprio 1
	s_waitcnt lgkmcnt(3)
	v_mfma_f32_32x32x16_bf16 v[32:47], v[32:35], v[112:115], 0
	s_waitcnt lgkmcnt(2)
	v_mfma_f32_32x32x16_bf16 v[32:47], v[50:53], v[116:119], v[32:47]
	s_waitcnt lgkmcnt(1)
	v_mfma_f32_32x32x16_bf16 v[32:47], v[54:57], v[120:123], v[32:47]
	s_waitcnt lgkmcnt(0)
	v_mfma_f32_32x32x16_bf16 v[32:47], v[58:61], v[124:127], v[32:47]
	s_setprio 0
	v_and_b32_e32 v48, 1, v49
	v_cmp_eq_u32_e32 vcc, 1, v48
	v_and_b32_e32 v48, 2, v49
	v_and_b32_e32 v50, 4, v49
	s_nop 6
	v_cndmask_b32_e32 v32, v208, v32, vcc
	v_cmp_ne_u32_e32 vcc, 0, v48
	s_nop 1
	v_cndmask_b32_e32 v33, v208, v33, vcc
	v_cmp_ne_u32_e32 vcc, 0, v50
	v_and_b32_e32 v50, 8, v49
	v_max3_f32 v48, v32, s15, v33
	v_cndmask_b32_e32 v34, v208, v34, vcc
	v_cmp_ne_u32_e32 vcc, 0, v50
	v_and_b32_e32 v50, 16, v49
	s_nop 0
	v_cndmask_b32_e32 v35, v208, v35, vcc
	v_cmp_ne_u32_e32 vcc, 0, v50
	v_and_b32_e32 v50, 32, v49
	v_max3_f32 v48, v48, v34, v35
	v_cndmask_b32_e32 v36, v208, v36, vcc
	v_cmp_ne_u32_e32 vcc, 0, v50
	v_and_b32_e32 v50, 64, v49
	s_nop 0
	v_cndmask_b32_e32 v37, v208, v37, vcc
	v_cmp_ne_u32_e32 vcc, 0, v50
	v_and_b32_e32 v50, 0x80, v49
	v_max3_f32 v48, v48, v36, v37
	v_cndmask_b32_e32 v38, v208, v38, vcc
	v_cmp_ne_u32_e32 vcc, 0, v50
	v_and_b32_e32 v50, 0x100, v49
	s_nop 0
	v_cndmask_b32_e32 v39, v208, v39, vcc
	v_cmp_ne_u32_e32 vcc, 0, v50
	v_and_b32_e32 v50, 0x200, v49
	v_max3_f32 v48, v48, v38, v39
	v_cndmask_b32_e32 v40, v208, v40, vcc
	v_cmp_ne_u32_e32 vcc, 0, v50
	v_and_b32_e32 v50, 0x400, v49
	s_nop 0
	v_cndmask_b32_e32 v41, v208, v41, vcc
	v_cmp_ne_u32_e32 vcc, 0, v50
	v_and_b32_e32 v50, 0x800, v49
	v_max3_f32 v48, v48, v40, v41
	v_cndmask_b32_e32 v42, v208, v42, vcc
	v_cmp_ne_u32_e32 vcc, 0, v50
	v_and_b32_e32 v50, 0x1000, v49
	s_nop 0
	v_cndmask_b32_e32 v43, v208, v43, vcc
	v_cmp_ne_u32_e32 vcc, 0, v50
	v_and_b32_e32 v50, 0x2000, v49
	v_max3_f32 v48, v48, v42, v43
	v_cndmask_b32_e32 v44, v208, v44, vcc
	v_cmp_ne_u32_e32 vcc, 0, v50
	v_and_b32_e32 v50, 0x4000, v49
	v_and_b32_e32 v49, 0x8000, v49
	v_cndmask_b32_e32 v45, v208, v45, vcc
	v_cmp_ne_u32_e32 vcc, 0, v50
	v_max3_f32 v48, v48, v44, v45
	s_nop 0
	v_cndmask_b32_e32 v46, v208, v46, vcc
	v_cmp_ne_u32_e32 vcc, 0, v49
	s_nop 1
	v_cndmask_b32_e32 v47, v208, v47, vcc
	v_max3_f32 v48, v48, v46, v47
	v_mov_b32_e32 v49, v48
	v_mov_b32_e32 v50, v48
	s_nop 1
	v_permlane32_swap_b32_e32 v49, v50
	v_max_f32_e32 v48, v49, v50
	v_add_f32_e32 v49, 0x41000000, v191
	v_cmp_gt_f32_e32 vcc, v48, v49
	s_nop 1
	v_cndmask_b32_e32 v69, v191, v48, vcc
	v_max_f32_e32 v48, 0xefa18f08, v69
	v_sub_f32_e32 v32, v32, v48
	v_exp_f32_e32 v65, v32
	v_sub_f32_e32 v32, v33, v48
	v_exp_f32_e32 v66, v32
	v_sub_f32_e32 v32, v34, v48
	v_exp_f32_e32 v67, v32
	v_sub_f32_e32 v32, v35, v48
	v_exp_f32_e32 v68, v32
	v_sub_f32_e32 v33, v36, v48
	v_exp_f32_e32 v70, v33
	v_sub_f32_e32 v33, v37, v48
	v_add_f32_e32 v32, v66, v65
	v_exp_f32_e32 v71, v33
	v_sub_f32_e32 v33, v38, v48
	v_add_f32_e32 v32, v67, v32
	v_exp_f32_e32 v72, v33
	v_sub_f32_e32 v33, v39, v48
	v_add_f32_e32 v32, v68, v32
	v_exp_f32_e32 v73, v33
	v_sub_f32_e32 v33, v40, v48
	v_add_f32_e32 v32, v70, v32
	v_exp_f32_e32 v74, v33
	v_sub_f32_e32 v33, v41, v48
	v_add_f32_e32 v32, v71, v32
	v_exp_f32_e32 v75, v33
	v_sub_f32_e32 v33, v42, v48
	v_add_f32_e32 v32, v72, v32
	v_exp_f32_e32 v76, v33
	v_sub_f32_e32 v33, v43, v48
	v_add_f32_e32 v32, v73, v32
	v_exp_f32_e32 v77, v33
	v_sub_f32_e32 v33, v44, v48
	v_add_f32_e32 v32, v74, v32
	v_exp_f32_e32 v78, v33
	v_sub_f32_e32 v33, v45, v48
	v_add_f32_e32 v32, v75, v32
	v_exp_f32_e32 v79, v33
	v_sub_f32_e32 v33, v46, v48
	v_add_f32_e32 v32, v76, v32
	v_exp_f32_e32 v80, v33
	v_sub_f32_e32 v33, v47, v48
	v_add_f32_e32 v32, v77, v32
	v_exp_f32_e32 v81, v33
	v_add_f32_e32 v32, v78, v32
	v_add_f32_e32 v32, v79, v32
	v_add_f32_e32 v32, v80, v32
	v_add_f32_e32 v82, v81, v32
	v_mov_b32_e32 v83, v82
	v_mov_b32_e32 v84, v82
	s_nop 1
	v_permlane32_swap_b32_e32 v83, v84
	v_cmp_neq_f32_e32 vcc, v69, v191
	s_cbranch_vccz .LBB0_924
	v_sub_f32_e32 v32, v191, v69
	v_exp_f32_e32 v32, v32
	v_mov_b32_e32 v191, v69
	v_mul_f32_e32 v190, v190, v32
	v_pk_mul_f32 v[62:63], v[30:31], v[32:33] op_sel_hi:[1,0]
	v_pk_mul_f32 v[60:61], v[28:29], v[32:33] op_sel_hi:[1,0]
	v_pk_mul_f32 v[58:59], v[26:27], v[32:33] op_sel_hi:[1,0]
	v_pk_mul_f32 v[56:57], v[24:25], v[32:33] op_sel_hi:[1,0]
	v_pk_mul_f32 v[54:55], v[22:23], v[32:33] op_sel_hi:[1,0]
	v_pk_mul_f32 v[52:53], v[20:21], v[32:33] op_sel_hi:[1,0]
	v_pk_mul_f32 v[50:51], v[18:19], v[32:33] op_sel_hi:[1,0]
	v_pk_mul_f32 v[48:49], v[16:17], v[32:33] op_sel_hi:[1,0]
	v_pk_mul_f32 v[46:47], v[14:15], v[32:33] op_sel_hi:[1,0]
	v_pk_mul_f32 v[44:45], v[12:13], v[32:33] op_sel_hi:[1,0]
	v_pk_mul_f32 v[42:43], v[10:11], v[32:33] op_sel_hi:[1,0]
	v_pk_mul_f32 v[40:41], v[8:9], v[32:33] op_sel_hi:[1,0]
	v_pk_mul_f32 v[38:39], v[6:7], v[32:33] op_sel_hi:[1,0]
	v_pk_mul_f32 v[36:37], v[4:5], v[32:33] op_sel_hi:[1,0]
	v_pk_mul_f32 v[34:35], v[2:3], v[32:33] op_sel_hi:[1,0]
	v_pk_mul_f32 v[32:33], v[0:1], v[32:33] op_sel_hi:[1,0]
	s_branch .LBB0_925
